# GEMM K-loops: no setprio, no dup wait, LDS-DMA stage loads issued before the ds_reads in each load section
# baseline (speedup 1.0000x reference)
; #define PG8_STAGE(bufoff, gbase, voff) do { _Pragma("unroll") for (int _i = 0; _i < 2; ++_i) \
;         __builtin_amdgcn_global_load_lds((const unsigned*)((const char*)(gbase) + (voff)[_i]), (PG8_LAS unsigned*)(lds + (bufoff) + ldsw + _i * 8192), 16, 0, 0); } while (0)
; #define PG8_LDA(dst, b, h) do { _Pragma("unroll") for (int m = 0; m < 4; ++m) _Pragma("unroll") for (int k = 0; k < 2; ++k) dst[m][k] = *(const PG8_LAS bf16x8*)(lds + PG8_SA(b, h) + aoff + m * 2048 + k * 1024); } while (0)
; #define PG8_LDB(dst, b, h) do { _Pragma("unroll") for (int n = 0; n < 2; ++n) _Pragma("unroll") for (int k = 0; k < 2; ++k) dst[n][k] = *(const PG8_LAS bf16x8*)(lds + PG8_SB(b, h) + boff + n * 2048 + k * 1024); } while (0)
; #define PG8_MMA(ai, bj, At, Bt) do { __builtin_amdgcn_s_setprio(1); _Pragma("unroll") for (int m = 0; m < 4; ++m) _Pragma("unroll") for (int n = 0; n < 2; ++n) _Pragma("unroll") for (int k = 0; k < 2; ++k) \
;         acc[ai][bj][m][n] = __builtin_amdgcn_mfma_f32_16x16x32_bf16(Bt[n][k], At[m][k], acc[ai][bj][m][n], 0, 0, 0); __builtin_amdgcn_s_setprio(0); } while (0)
; #define PG8_WAIT_L(n) asm volatile("s_waitcnt lgkmcnt(" #n ")" ::: "memory")
; #define PG8_BAR __builtin_amdgcn_s_barrier()
; #define PG8_SCHED __builtin_amdgcn_sched_barrier(0)
; template <class Epi, class Sched>
; __device__ __forceinline__ void gemm_phase(PG8_LAS unsigned char* lds, const Gemm g, const Sched& S, const Epi& E) {
;     ...
;             PG8_LDB(B0, 0, 0); PG8_SCHED; PG8_LDA(At, 0, 0); PG8_STAGE(PG8_SA(1, 1), a1 + hstep, voffA);
;             PG8_WAIT_L(8); PG8_BAR; PG8_WAIT_L(0); PG8_MMA(0, 0, At, B0); PG8_BAR; PG8_SCHED;
;             PG8_LDB(B1, 0, 1); PG8_STAGE(PG8_SB(0, 0), b2, voffB);
;             PG8_BAR; PG8_WAIT_L(0); PG8_MMA(0, 1, At, B1); PG8_BAR;
;             PG8_LDA(At, 0, 1); PG8_STAGE(PG8_SA(0, 0), a2, voffA);
;             PG8_BAR; PG8_WAIT_L(0); PG8_MMA(1, 0, At, B0); PG8_BAR; PG8_SCHED;
.LBB0_195:
	s_add_u32 s30, s28, 0xfffc0080
	s_addc_u32 s31, s29, -1
	s_cmp_eq_u32 s58, 12
	s_cselect_b32 s35, s17, s31
	s_cselect_b32 s34, s54, s30
	s_cselect_b32 s31, s15, s57
	s_cselect_b32 s30, s55, s56
	v_lshl_add_u64 v[174:175], s[28:29], 0, v[136:137]
	s_add_i32 m0, s27, 0xc000
	s_nop 0
	global_load_lds_dwordx4 v[174:175], off
	v_lshl_add_u64 v[174:175], s[28:29], 0, v[138:139]
	s_add_i32 m0, s27, 0xe000
	s_nop 0
	global_load_lds_dwordx4 v[174:175], off
	ds_read_b128 v[144:147], v151
	ds_read_b128 v[156:159], v151 offset:1024
	ds_read_b128 v[160:163], v151 offset:2048
	ds_read_b128 v[166:169], v151 offset:3072
	ds_read_b128 v[170:173], v153
	ds_read_b128 v[182:185], v153 offset:1024
	ds_read_b128 v[190:193], v153 offset:2048
	ds_read_b128 v[194:197], v153 offset:3072
	ds_read_b128 v[198:201], v153 offset:4096
	ds_read_b128 v[202:205], v153 offset:5120
	ds_read_b128 v[206:209], v153 offset:6144
	ds_read_b128 v[210:213], v153 offset:7168
	s_waitcnt lgkmcnt(8)
	s_barrier
	s_waitcnt lgkmcnt(0)
	v_mfma_f32_16x16x32_bf16 v[124:127], v[144:147], v[170:173], v[124:127]
	v_mfma_f32_16x16x32_bf16 v[120:123], v[160:163], v[170:173], v[120:123]
	v_mfma_f32_16x16x32_bf16 v[108:111], v[144:147], v[190:193], v[108:111]
	v_mfma_f32_16x16x32_bf16 v[104:107], v[160:163], v[190:193], v[104:107]
	v_mfma_f32_16x16x32_bf16 v[92:95], v[144:147], v[198:201], v[92:95]
	v_mfma_f32_16x16x32_bf16 v[88:91], v[160:163], v[198:201], v[88:91]
	v_mfma_f32_16x16x32_bf16 v[76:79], v[144:147], v[206:209], v[76:79]
	v_mfma_f32_16x16x32_bf16 v[72:75], v[160:163], v[206:209], v[72:75]
	v_mfma_f32_16x16x32_bf16 v[124:127], v[156:159], v[182:185], v[124:127]
	v_mfma_f32_16x16x32_bf16 v[120:123], v[166:169], v[182:185], v[120:123]
	v_mfma_f32_16x16x32_bf16 v[108:111], v[156:159], v[194:197], v[108:111]
	v_mfma_f32_16x16x32_bf16 v[104:107], v[166:169], v[194:197], v[104:107]
	v_mfma_f32_16x16x32_bf16 v[92:95], v[156:159], v[202:205], v[92:95]
	v_mfma_f32_16x16x32_bf16 v[88:91], v[166:169], v[202:205], v[88:91]
	v_mfma_f32_16x16x32_bf16 v[76:79], v[156:159], v[210:213], v[76:79]
	v_mfma_f32_16x16x32_bf16 v[72:75], v[166:169], v[210:213], v[72:75]
	s_barrier
	s_add_i32 s59, s50, s40
	v_lshl_add_u64 v[174:175], s[30:31], 0, v[132:133]
	s_mov_b32 m0, s59
	s_nop 0
	global_load_lds_dwordx4 v[174:175], off
	v_lshl_add_u64 v[178:179], s[30:31], 0, v[128:129]
	s_add_i32 m0, s59, 0x2000
	s_nop 0
	global_load_lds_dwordx4 v[178:179], off
	ds_read_b128 v[214:217], v154
	ds_read_b128 v[218:221], v154 offset:1024
	ds_read_b128 v[222:225], v154 offset:2048
	ds_read_b128 v[226:229], v154 offset:3072
	s_barrier
	s_waitcnt lgkmcnt(0)
	v_mfma_f32_16x16x32_bf16 v[116:119], v[214:217], v[170:173], v[116:119]
	v_mfma_f32_16x16x32_bf16 v[112:115], v[222:225], v[170:173], v[112:115]
	v_mfma_f32_16x16x32_bf16 v[100:103], v[214:217], v[190:193], v[100:103]
	v_mfma_f32_16x16x32_bf16 v[96:99], v[222:225], v[190:193], v[96:99]
	v_mfma_f32_16x16x32_bf16 v[84:87], v[214:217], v[198:201], v[84:87]
	v_mfma_f32_16x16x32_bf16 v[80:83], v[222:225], v[198:201], v[80:83]
	v_mfma_f32_16x16x32_bf16 v[68:71], v[214:217], v[206:209], v[68:71]
	v_mfma_f32_16x16x32_bf16 v[64:67], v[222:225], v[206:209], v[64:67]
	v_mfma_f32_16x16x32_bf16 v[116:119], v[218:221], v[182:185], v[116:119]
	v_mfma_f32_16x16x32_bf16 v[112:115], v[226:229], v[182:185], v[112:115]
	v_mfma_f32_16x16x32_bf16 v[100:103], v[218:221], v[194:197], v[100:103]
	v_mfma_f32_16x16x32_bf16 v[96:99], v[226:229], v[194:197], v[96:99]
	v_mfma_f32_16x16x32_bf16 v[84:87], v[218:221], v[202:205], v[84:87]
	v_mfma_f32_16x16x32_bf16 v[80:83], v[226:229], v[202:205], v[80:83]
	v_mfma_f32_16x16x32_bf16 v[68:71], v[218:221], v[210:213], v[68:71]
	v_mfma_f32_16x16x32_bf16 v[64:67], v[226:229], v[210:213], v[64:67]
	s_mov_b32 m0, s27
	v_lshl_add_u64 v[186:187], s[34:35], 0, v[134:135]
	s_barrier
	global_load_lds_dwordx4 v[186:187], off
	v_lshl_add_u64 v[230:231], s[34:35], 0, v[130:131]
	s_mov_b32 m0, s43
	s_nop 0
	global_load_lds_dwordx4 v[230:231], off
	ds_read_b128 v[170:173], v153 offset:16384
	ds_read_b128 v[182:185], v153 offset:17408
	ds_read_b128 v[190:193], v153 offset:18432
	ds_read_b128 v[194:197], v153 offset:19456
	ds_read_b128 v[198:201], v153 offset:20480
	ds_read_b128 v[202:205], v153 offset:21504
	ds_read_b128 v[206:209], v153 offset:22528
	ds_read_b128 v[210:213], v153 offset:23552
	s_barrier
	s_waitcnt lgkmcnt(0)
	v_mfma_f32_16x16x32_bf16 v[60:63], v[144:147], v[170:173], v[60:63]
	v_mfma_f32_16x16x32_bf16 v[56:59], v[160:163], v[170:173], v[56:59]
	v_mfma_f32_16x16x32_bf16 v[44:47], v[144:147], v[190:193], v[44:47]
	v_mfma_f32_16x16x32_bf16 v[40:43], v[160:163], v[190:193], v[40:43]
	v_mfma_f32_16x16x32_bf16 v[28:31], v[144:147], v[198:201], v[28:31]
	v_mfma_f32_16x16x32_bf16 v[24:27], v[160:163], v[198:201], v[24:27]
	v_mfma_f32_16x16x32_bf16 v[12:15], v[144:147], v[206:209], v[12:15]
	v_mfma_f32_16x16x32_bf16 v[8:11], v[160:163], v[206:209], v[8:11]
	v_mfma_f32_16x16x32_bf16 v[60:63], v[156:159], v[182:185], v[60:63]
	v_mfma_f32_16x16x32_bf16 v[56:59], v[166:169], v[182:185], v[56:59]
	v_mfma_f32_16x16x32_bf16 v[44:47], v[156:159], v[194:197], v[44:47]
	v_mfma_f32_16x16x32_bf16 v[40:43], v[166:169], v[194:197], v[40:43]
	v_mfma_f32_16x16x32_bf16 v[28:31], v[156:159], v[202:205], v[28:31]
	v_mfma_f32_16x16x32_bf16 v[24:27], v[166:169], v[202:205], v[24:27]
	v_mfma_f32_16x16x32_bf16 v[12:15], v[156:159], v[210:213], v[12:15]
	v_mfma_f32_16x16x32_bf16 v[8:11], v[166:169], v[210:213], v[8:11]
	s_barrier
; #define PG8_STAGE(bufoff, gbase, voff) do { _Pragma("unroll") for (int _i = 0; _i < 2; ++_i) \
;         __builtin_amdgcn_global_load_lds((const unsigned*)((const char*)(gbase) + (voff)[_i]), (PG8_LAS unsigned*)(lds + (bufoff) + ldsw + _i * 8192), 16, 0, 0); } while (0)
; #define PG8_LDA(dst, b, h) do { _Pragma("unroll") for (int m = 0; m < 4; ++m) _Pragma("unroll") for (int k = 0; k < 2; ++k) dst[m][k] = *(const PG8_LAS bf16x8*)(lds + PG8_SA(b, h) + aoff + m * 2048 + k * 1024); } while (0)
; #define PG8_LDB(dst, b, h) do { _Pragma("unroll") for (int n = 0; n < 2; ++n) _Pragma("unroll") for (int k = 0; k < 2; ++k) dst[n][k] = *(const PG8_LAS bf16x8*)(lds + PG8_SB(b, h) + boff + n * 2048 + k * 1024); } while (0)
; #define PG8_MMA(ai, bj, At, Bt) do { __builtin_amdgcn_s_setprio(1); _Pragma("unroll") for (int m = 0; m < 4; ++m) _Pragma("unroll") for (int n = 0; n < 2; ++n) _Pragma("unroll") for (int k = 0; k < 2; ++k) \
;         acc[ai][bj][m][n] = __builtin_amdgcn_mfma_f32_16x16x32_bf16(Bt[n][k], At[m][k], acc[ai][bj][m][n], 0, 0, 0); __builtin_amdgcn_s_setprio(0); } while (0)
; #define PG8_WAIT_V(n) asm volatile("s_waitcnt vmcnt(" #n ")" ::: "memory")
; #define PG8_WAIT_L(n) asm volatile("s_waitcnt lgkmcnt(" #n ")" ::: "memory")
; #define PG8_BAR __builtin_amdgcn_s_barrier()
; #define PG8_SCHED __builtin_amdgcn_sched_barrier(0)
; template <class Epi, class Sched>
; __device__ __forceinline__ void gemm_phase(PG8_LAS unsigned char* lds, const Gemm g, const Sched& S, const Epi& E) {
;     ...
;             PG8_STAGE(PG8_SB(0, 1), b2 + hstep, voffB);
;             PG8_WAIT_V(6); PG8_BAR; PG8_MMA(1, 1, At, B1); PG8_BAR;
;             PG8_LDB(B0, 1, 0); PG8_SCHED; PG8_LDA(At, 1, 0); PG8_STAGE(PG8_SA(0, 1), a2 + hstep, voffA);
;             PG8_WAIT_L(8); PG8_BAR; PG8_WAIT_L(0); PG8_MMA(0, 0, At, B0); PG8_BAR; PG8_SCHED;
;             PG8_LDB(B1, 1, 1); PG8_STAGE(PG8_SB(1, 0), b3, voffB);
;             PG8_BAR; PG8_WAIT_L(0); PG8_MMA(0, 1, At, B1); PG8_BAR;
;             PG8_LDA(At, 1, 1); PG8_STAGE(PG8_SA(1, 0), a3, voffA);
;             PG8_BAR; PG8_WAIT_L(0); PG8_MMA(1, 0, At, B0); PG8_BAR; PG8_SCHED;
	s_add_u32 s60, s30, 0x40000
	s_addc_u32 s61, s31, 0
	s_add_i32 s59, s51, s40
	v_lshl_add_u64 v[144:145], s[60:61], 0, v[132:133]
	s_mov_b32 m0, s59
	s_nop 0
	global_load_lds_dwordx4 v[144:145], off
	v_lshl_add_u64 v[144:145], s[60:61], 0, v[128:129]
	s_add_i32 m0, s59, 0x2000
	s_nop 0
	global_load_lds_dwordx4 v[144:145], off
	s_waitcnt vmcnt(6)
	s_barrier
	v_mfma_f32_16x16x32_bf16 v[52:55], v[214:217], v[170:173], v[52:55]
	v_mfma_f32_16x16x32_bf16 v[48:51], v[222:225], v[170:173], v[48:51]
	v_mfma_f32_16x16x32_bf16 v[36:39], v[214:217], v[190:193], v[36:39]
	v_mfma_f32_16x16x32_bf16 v[32:35], v[222:225], v[190:193], v[32:35]
	v_mfma_f32_16x16x32_bf16 v[20:23], v[214:217], v[198:201], v[20:23]
	v_mfma_f32_16x16x32_bf16 v[16:19], v[222:225], v[198:201], v[16:19]
	v_mfma_f32_16x16x32_bf16 v[4:7], v[214:217], v[206:209], v[4:7]
	v_mfma_f32_16x16x32_bf16 v[0:3], v[222:225], v[206:209], v[0:3]
	v_mfma_f32_16x16x32_bf16 v[52:55], v[218:221], v[182:185], v[52:55]
	v_mfma_f32_16x16x32_bf16 v[48:51], v[226:229], v[182:185], v[48:51]
	v_mfma_f32_16x16x32_bf16 v[36:39], v[218:221], v[194:197], v[36:39]
	v_mfma_f32_16x16x32_bf16 v[32:35], v[226:229], v[194:197], v[32:35]
	v_mfma_f32_16x16x32_bf16 v[20:23], v[218:221], v[202:205], v[20:23]
	v_mfma_f32_16x16x32_bf16 v[16:19], v[226:229], v[202:205], v[16:19]
	v_mfma_f32_16x16x32_bf16 v[4:7], v[218:221], v[210:213], v[4:7]
	v_mfma_f32_16x16x32_bf16 v[0:3], v[226:229], v[210:213], v[0:3]
	s_add_i32 s59, 0, 0x18000
	v_add_u32_e32 v155, s59, v149
	s_barrier
	s_add_u32 s34, s34, 0x40000
	s_addc_u32 s35, s35, 0
	s_mov_b32 m0, s44
	v_lshl_add_u64 v[214:215], s[34:35], 0, v[134:135]
	global_load_lds_dwordx4 v[214:215], off
	v_lshl_add_u64 v[214:215], s[34:35], 0, v[130:131]
	s_mov_b32 m0, s45
	s_nop 0
	global_load_lds_dwordx4 v[214:215], off
	ds_read_b128 v[144:147], v155
	ds_read_b128 v[156:159], v155 offset:1024
	ds_read_b128 v[160:163], v155 offset:2048
	ds_read_b128 v[166:169], v155 offset:3072
	ds_read_b128 v[170:173], v153 offset:32768
	ds_read_b128 v[182:185], v153 offset:33792
	ds_read_b128 v[190:193], v153 offset:34816
	ds_read_b128 v[194:197], v153 offset:35840
	ds_read_b128 v[198:201], v153 offset:36864
	ds_read_b128 v[202:205], v153 offset:37888
	ds_read_b128 v[206:209], v153 offset:38912
	ds_read_b128 v[210:213], v153 offset:39936
	s_waitcnt lgkmcnt(8)
	s_barrier
	s_waitcnt lgkmcnt(0)
	v_mfma_f32_16x16x32_bf16 v[124:127], v[144:147], v[170:173], v[124:127]
	v_mfma_f32_16x16x32_bf16 v[120:123], v[160:163], v[170:173], v[120:123]
	v_mfma_f32_16x16x32_bf16 v[108:111], v[144:147], v[190:193], v[108:111]
	v_mfma_f32_16x16x32_bf16 v[104:107], v[160:163], v[190:193], v[104:107]
	v_mfma_f32_16x16x32_bf16 v[92:95], v[144:147], v[198:201], v[92:95]
	v_mfma_f32_16x16x32_bf16 v[88:91], v[160:163], v[198:201], v[88:91]
	v_mfma_f32_16x16x32_bf16 v[76:79], v[144:147], v[206:209], v[76:79]
	v_mfma_f32_16x16x32_bf16 v[72:75], v[160:163], v[206:209], v[72:75]
	v_mfma_f32_16x16x32_bf16 v[124:127], v[156:159], v[182:185], v[124:127]
	v_mfma_f32_16x16x32_bf16 v[120:123], v[166:169], v[182:185], v[120:123]
	v_mfma_f32_16x16x32_bf16 v[108:111], v[156:159], v[194:197], v[108:111]
	v_mfma_f32_16x16x32_bf16 v[104:107], v[166:169], v[194:197], v[104:107]
	v_mfma_f32_16x16x32_bf16 v[92:95], v[156:159], v[202:205], v[92:95]
	v_mfma_f32_16x16x32_bf16 v[88:91], v[166:169], v[202:205], v[88:91]
	v_mfma_f32_16x16x32_bf16 v[76:79], v[156:159], v[210:213], v[76:79]
	v_mfma_f32_16x16x32_bf16 v[72:75], v[166:169], v[210:213], v[72:75]
	s_barrier
	s_add_i32 s34, 0, 0x1c000
	s_add_i32 s35, s59, s40
	v_add_u32_e32 v155, s34, v149
	v_lshl_add_u64 v[174:175], v[174:175], 0, s[10:11]
	s_mov_b32 m0, s35
	s_nop 0
	global_load_lds_dwordx4 v[174:175], off
	v_lshl_add_u64 v[174:175], v[178:179], 0, s[10:11]
	s_add_i32 m0, s35, 0x2000
	s_nop 0
	global_load_lds_dwordx4 v[174:175], off
	ds_read_b128 v[214:217], v155
	ds_read_b128 v[218:221], v155 offset:1024
	ds_read_b128 v[222:225], v155 offset:2048
	ds_read_b128 v[226:229], v155 offset:3072
	s_barrier
	s_waitcnt lgkmcnt(0)
	v_mfma_f32_16x16x32_bf16 v[116:119], v[214:217], v[170:173], v[116:119]
	v_mfma_f32_16x16x32_bf16 v[112:115], v[222:225], v[170:173], v[112:115]
	v_mfma_f32_16x16x32_bf16 v[100:103], v[214:217], v[190:193], v[100:103]
	v_mfma_f32_16x16x32_bf16 v[96:99], v[222:225], v[190:193], v[96:99]
	v_mfma_f32_16x16x32_bf16 v[84:87], v[214:217], v[198:201], v[84:87]
	v_mfma_f32_16x16x32_bf16 v[80:83], v[222:225], v[198:201], v[80:83]
	v_mfma_f32_16x16x32_bf16 v[68:71], v[214:217], v[206:209], v[68:71]
	v_mfma_f32_16x16x32_bf16 v[64:67], v[222:225], v[206:209], v[64:67]
	v_mfma_f32_16x16x32_bf16 v[116:119], v[218:221], v[182:185], v[116:119]
	v_mfma_f32_16x16x32_bf16 v[112:115], v[226:229], v[182:185], v[112:115]
	v_mfma_f32_16x16x32_bf16 v[100:103], v[218:221], v[194:197], v[100:103]
	v_mfma_f32_16x16x32_bf16 v[96:99], v[226:229], v[194:197], v[96:99]
	v_mfma_f32_16x16x32_bf16 v[84:87], v[218:221], v[202:205], v[84:87]
	v_mfma_f32_16x16x32_bf16 v[80:83], v[226:229], v[202:205], v[80:83]
	v_mfma_f32_16x16x32_bf16 v[68:71], v[218:221], v[210:213], v[68:71]
	v_mfma_f32_16x16x32_bf16 v[64:67], v[226:229], v[210:213], v[64:67]
	s_mov_b32 m0, s47
	v_lshl_add_u64 v[174:175], v[186:187], 0, s[10:11]
	s_barrier
	global_load_lds_dwordx4 v[174:175], off
	v_lshl_add_u64 v[174:175], v[230:231], 0, s[10:11]
	s_mov_b32 m0, s48
	s_nop 0
	global_load_lds_dwordx4 v[174:175], off
	ds_read_b128 v[170:173], v153 offset:49152
	ds_read_b128 v[182:185], v153 offset:50176
	ds_read_b128 v[190:193], v153 offset:51200
	ds_read_b128 v[194:197], v153 offset:52224
	ds_read_b128 v[198:201], v153 offset:53248
	ds_read_b128 v[202:205], v153 offset:54272
	ds_read_b128 v[206:209], v153 offset:55296
	ds_read_b128 v[210:213], v153 offset:56320
	s_barrier
; #define PG8_STAGE(bufoff, gbase, voff) do { _Pragma("unroll") for (int _i = 0; _i < 2; ++_i) \
;         __builtin_amdgcn_global_load_lds((const unsigned*)((const char*)(gbase) + (voff)[_i]), (PG8_LAS unsigned*)(lds + (bufoff) + ldsw + _i * 8192), 16, 0, 0); } while (0)
; #define PG8_MMA(ai, bj, At, Bt) do { __builtin_amdgcn_s_setprio(1); _Pragma("unroll") for (int m = 0; m < 4; ++m) _Pragma("unroll") for (int n = 0; n < 2; ++n) _Pragma("unroll") for (int k = 0; k < 2; ++k) \
;         acc[ai][bj][m][n] = __builtin_amdgcn_mfma_f32_16x16x32_bf16(Bt[n][k], At[m][k], acc[ai][bj][m][n], 0, 0, 0); __builtin_amdgcn_s_setprio(0); } while (0)
; #define PG8_WAIT_V(n) asm volatile("s_waitcnt vmcnt(" #n ")" ::: "memory")
; #define PG8_WAIT_L(n) asm volatile("s_waitcnt lgkmcnt(" #n ")" ::: "memory")
; #define PG8_BAR __builtin_amdgcn_s_barrier()
; #define PG8_SCHED __builtin_amdgcn_sched_barrier(0)
;     __device__ __forceinline__ void operator()(const f32x4 (&acc)[2][2][4][2], const Unit& u, int wr, int wc, int fr, int fq) const {
;         const int row0 = u.pm * BM + wr * 64 + fr, col0 = u.pn * HALF + wc * 32 + 8 * fq;
; #pragma unroll
;         for (int ai = 0; ai < 2; ++ai)
; #pragma unroll
;             for (int m = 0; m < 4; ++m) { bf16_t* rowp = O + (size_t)(row0 + ai * HALF + m * 16) * ldc + col0;
;                 f32x4 v0, v1;
; #pragma unroll
;                 for (int j = 0; j < 1; ++j) { v0 = acc[ai][0][m][0] * sigmoid4(acc[ai][0][m][0]) * acc[ai][1][m][0]; v1 = acc[ai][0][m][1] * sigmoid4(acc[ai][0][m][1]) * acc[ai][1][m][1]; }
; template <class Epi, class Sched>
; __device__ __forceinline__ void gemm_phase(PG8_LAS unsigned char* lds, const Gemm g, const Sched& S, const Epi& E) {
;     ...
;             PG8_BAR; PG8_WAIT_L(0); PG8_MMA(1, 0, At, B0); PG8_BAR; PG8_SCHED;
;             PG8_STAGE(PG8_SB(1, 1), b3 + hstep, voffB);
;             PG8_WAIT_V(6); PG8_BAR; PG8_MMA(1, 1, At, B1); PG8_BAR;
	s_waitcnt lgkmcnt(0)
	v_mfma_f32_16x16x32_bf16 v[60:63], v[144:147], v[170:173], v[60:63]
	v_mfma_f32_16x16x32_bf16 v[56:59], v[160:163], v[170:173], v[56:59]
	v_mfma_f32_16x16x32_bf16 v[44:47], v[144:147], v[190:193], v[44:47]
	v_mfma_f32_16x16x32_bf16 v[40:43], v[160:163], v[190:193], v[40:43]
	v_mfma_f32_16x16x32_bf16 v[28:31], v[144:147], v[198:201], v[28:31]
	v_mfma_f32_16x16x32_bf16 v[24:27], v[160:163], v[198:201], v[24:27]
	v_mfma_f32_16x16x32_bf16 v[12:15], v[144:147], v[206:209], v[12:15]
	v_mfma_f32_16x16x32_bf16 v[8:11], v[160:163], v[206:209], v[8:11]
	v_mfma_f32_16x16x32_bf16 v[60:63], v[156:159], v[182:185], v[60:63]
	v_mfma_f32_16x16x32_bf16 v[56:59], v[166:169], v[182:185], v[56:59]
	v_mfma_f32_16x16x32_bf16 v[44:47], v[156:159], v[194:197], v[44:47]
	v_mfma_f32_16x16x32_bf16 v[40:43], v[166:169], v[194:197], v[40:43]
	v_mfma_f32_16x16x32_bf16 v[28:31], v[156:159], v[202:205], v[28:31]
	v_mfma_f32_16x16x32_bf16 v[24:27], v[166:169], v[202:205], v[24:27]
	v_mfma_f32_16x16x32_bf16 v[12:15], v[156:159], v[210:213], v[12:15]
	v_mfma_f32_16x16x32_bf16 v[8:11], v[166:169], v[210:213], v[8:11]
	s_barrier
	s_add_u32 s30, s30, 0x40080
	s_addc_u32 s31, s31, 0
	s_add_i32 s34, s34, s40
	v_lshl_add_u64 v[144:145], s[30:31], 0, v[132:133]
	s_mov_b32 m0, s34
	s_nop 0
	global_load_lds_dwordx4 v[144:145], off
	v_lshl_add_u64 v[144:145], s[30:31], 0, v[128:129]
	s_add_i32 m0, s34, 0x2000
	s_nop 0
	global_load_lds_dwordx4 v[144:145], off
	s_waitcnt vmcnt(6)
	s_barrier
	v_mfma_f32_16x16x32_bf16 v[52:55], v[214:217], v[170:173], v[52:55]
	v_mfma_f32_16x16x32_bf16 v[48:51], v[222:225], v[170:173], v[48:51]
	v_mfma_f32_16x16x32_bf16 v[36:39], v[214:217], v[190:193], v[36:39]
	v_mfma_f32_16x16x32_bf16 v[32:35], v[222:225], v[190:193], v[32:35]
	v_mfma_f32_16x16x32_bf16 v[20:23], v[214:217], v[198:201], v[20:23]
	v_mfma_f32_16x16x32_bf16 v[16:19], v[222:225], v[198:201], v[16:19]
	v_mfma_f32_16x16x32_bf16 v[4:7], v[214:217], v[206:209], v[4:7]
	v_mfma_f32_16x16x32_bf16 v[0:3], v[222:225], v[206:209], v[0:3]
	v_mfma_f32_16x16x32_bf16 v[52:55], v[218:221], v[182:185], v[52:55]
	v_mfma_f32_16x16x32_bf16 v[48:51], v[226:229], v[182:185], v[48:51]
	v_mfma_f32_16x16x32_bf16 v[36:39], v[218:221], v[194:197], v[36:39]
	v_mfma_f32_16x16x32_bf16 v[32:35], v[226:229], v[194:197], v[32:35]
	v_mfma_f32_16x16x32_bf16 v[20:23], v[218:221], v[202:205], v[20:23]
	v_mfma_f32_16x16x32_bf16 v[16:19], v[226:229], v[202:205], v[16:19]
	v_mfma_f32_16x16x32_bf16 v[4:7], v[218:221], v[210:213], v[4:7]
	v_mfma_f32_16x16x32_bf16 v[0:3], v[226:229], v[210:213], v[0:3]
	s_add_i32 s58, s58, 2
	s_add_u32 s28, s28, 0x100
	s_addc_u32 s29, s29, 0
	s_add_u32 s56, s56, 0x100
	s_addc_u32 s57, s57, 0
	s_cmp_gt_u32 s58, 13
	s_barrier
	s_cbranch_scc0 .LBB0_195
	v_max_f32_e32 v144, v124, v124
	v_max_f32_e32 v144, 0xc1a00000, v144
	v_mul_f32_e32 v144, 0xbfb8aa3b, v144
	v_exp_f32_e32 v157, v144
	v_max_f32_e32 v144, v125, v125
	v_max_f32_e32 v144, 0xc1a00000, v144
	v_mul_f32_e32 v144, 0xbfb8aa3b, v144
	v_exp_f32_e32 v156, v144
	v_max_f32_e32 v144, v126, v126
	v_max_f32_e32 v144, 0xc1a00000, v144
	v_mul_f32_e32 v144, 0xbfb8aa3b, v144
	v_exp_f32_e32 v159, v144
	v_max_f32_e32 v144, v127, v127
	v_max_f32_e32 v144, 0xc1a00000, v144
	v_mul_f32_e32 v144, 0xbfb8aa3b, v144
	v_exp_f32_e32 v158, v144
	v_pk_add_f32 v[156:157], v[156:157], 1.0 op_sel_hi:[1,0]
	v_lshl_or_b32 v146, s53, 7, v150
	v_mov_b32_e32 v160, v157
	v_pk_add_f32 v[158:159], v[158:159], 1.0 op_sel_hi:[1,0]
	v_mov_b32_e32 v162, v156
	v_mov_b32_e32 v161, v159
	v_mov_b32_e32 v163, v158
	v_pk_mul_f32 v[160:161], v[160:161], v[162:163]
	v_lshl_add_u32 v155, s26, 8, v148
	v_mul_f32_e32 v162, v160, v161
	v_rcp_f32_e32 v166, v162
	v_ashrrev_i32_e32 v147, 31, v146
	v_mov_b64_e32 v[144:145], s[4:5]
	v_mad_i64_i32 v[162:163], s[28:29], v155, s52, v[144:145]
	v_mul_f32_e32 v160, v160, v166
	v_mul_f32_e32 v164, v161, v166
	v_pk_mul_f32 v[158:159], v[158:159], v[160:161] op_sel_hi:[1,0]
	v_max_f32_e32 v160, v120, v120
	v_max_f32_e32 v166, v122, v122
	v_max_f32_e32 v160, 0xc1a00000, v160
	v_max_f32_e32 v166, 0xc1a00000, v166
	v_mul_f32_e32 v160, 0xbfb8aa3b, v160
	v_mul_f32_e32 v166, 0xbfb8aa3b, v166
	v_exp_f32_e32 v161, v160
	v_max_f32_e32 v160, v121, v121
	v_exp_f32_e32 v167, v166
	v_max_f32_e32 v166, v123, v123
	v_max_f32_e32 v160, 0xc1a00000, v160
	v_max_f32_e32 v166, 0xc1a00000, v166
	v_mul_f32_e32 v160, 0xbfb8aa3b, v160
	v_mul_f32_e32 v166, 0xbfb8aa3b, v166
	v_exp_f32_e32 v160, v160
	v_exp_f32_e32 v166, v166
	v_pk_mul_f32 v[156:157], v[156:157], v[164:165] op_sel_hi:[1,0]
	v_pk_mul_f32 v[126:127], v[126:127], v[158:159]
	v_pk_mul_f32 v[124:125], v[124:125], v[156:157]
	v_pk_add_f32 v[156:157], v[160:161], 1.0 op_sel_hi:[1,0]
	v_pk_add_f32 v[160:161], v[166:167], 1.0 op_sel_hi:[1,0]
	v_mov_b32_e32 v166, v157
	v_mov_b32_e32 v167, v161
	v_mov_b32_e32 v168, v156
	v_mov_b32_e32 v169, v160
	v_pk_mul_f32 v[166:167], v[166:167], v[168:169]
	v_pk_mul_f32 v[118:119], v[126:127], v[118:119]
	v_mul_f32_e32 v164, v166, v167
	v_rcp_f32_e32 v164, v164
	v_pk_mul_f32 v[116:117], v[124:125], v[116:117]
	v_lshlrev_b64 v[146:147], 1, v[146:147]
	v_lshl_add_u64 v[162:163], v[162:163], 0, v[146:147]
	v_mul_f32_e32 v124, v167, v164
	v_mul_f32_e32 v126, v166, v164
	v_pk_mul_f32 v[126:127], v[160:161], v[126:127] op_sel_hi:[1,0]
	v_pk_mul_f32 v[124:125], v[156:157], v[124:125] op_sel_hi:[1,0]
	v_pk_mul_f32 v[122:123], v[122:123], v[126:127]
	v_pk_mul_f32 v[120:121], v[120:121], v[124:125]
	v_pk_mul_f32 v[122:123], v[122:123], v[114:115]
	v_pk_mul_f32 v[114:115], v[120:121], v[112:113]
	v_cvt_pk_bf16_f32 v112, v116, v117
	v_cvt_pk_bf16_f32 v113, v118, v119
; __device__ __forceinline__ unsigned cvt_pk_bf16(float lo, float hi) { unsigned r; asm volatile("v_cvt_pk_bf16_f32 %0, %1, %2" : "=v"(r) : "v"(lo), "v"(hi)); return r; }
;     __device__ __forceinline__ void operator()(const f32x4 (&acc)[2][2][4][2], const Unit& u, int wr, int wc, int fr, int fq) const {
;         const int row0 = u.pm * BM + wr * 64 + fr, col0 = u.pn * HALF + wc * 32 + 8 * fq;
; #pragma unroll
;         for (int ai = 0; ai < 2; ++ai)
; #pragma unroll
;             for (int m = 0; m < 4; ++m) { bf16_t* rowp = O + (size_t)(row0 + ai * HALF + m * 16) * ldc + col0;
;                 f32x4 v0, v1;
; #pragma unroll
;                 for (int j = 0; j < 1; ++j) { v0 = acc[ai][0][m][0] * sigmoid4(acc[ai][0][m][0]) * acc[ai][1][m][0]; v1 = acc[ai][0][m][1] * sigmoid4(acc[ai][0][m][1]) * acc[ai][1][m][1]; }
;                 u32x4 w; w.x = cvt_pk_bf16(v0[0], v0[1]); w.y = cvt_pk_bf16(v0[2], v0[3]); w.z = cvt_pk_bf16(v1[0], v1[1]); w.w = cvt_pk_bf16(v1[2], v1[3]);
;                 *(u32x4*)rowp = w; }
	v_max_f32_e32 v116, v108, v108
	v_max_f32_e32 v118, v110, v110
	v_max_f32_e32 v116, 0xc1a00000, v116
	v_max_f32_e32 v118, 0xc1a00000, v118
	v_mul_f32_e32 v116, 0xbfb8aa3b, v116
	v_mul_f32_e32 v118, 0xbfb8aa3b, v118
	v_exp_f32_e32 v117, v116
	v_max_f32_e32 v116, v109, v109
	v_exp_f32_e32 v119, v118
	v_max_f32_e32 v118, v111, v111
	v_max_f32_e32 v116, 0xc1a00000, v116
	v_max_f32_e32 v118, 0xc1a00000, v118
	v_mul_f32_e32 v116, 0xbfb8aa3b, v116
	v_mul_f32_e32 v118, 0xbfb8aa3b, v118
	v_exp_f32_e32 v116, v116
	v_exp_f32_e32 v118, v118
	v_cvt_pk_bf16_f32 v114, v114, v115
	v_cvt_pk_bf16_f32 v115, v122, v123
	global_store_dwordx4 v[162:163], v[112:115], off
	v_or_b32_e32 v120, 16, v155
	s_and_b64 vcc, exec, s[2:3]
	v_pk_add_f32 v[112:113], v[116:117], 1.0 op_sel_hi:[1,0]
	v_pk_add_f32 v[114:115], v[118:119], 1.0 op_sel_hi:[1,0]
	v_mov_b32_e32 v116, v113
	v_mov_b32_e32 v117, v115
	v_mov_b32_e32 v118, v112
	v_mov_b32_e32 v119, v114
	v_pk_mul_f32 v[116:117], v[116:117], v[118:119]
	s_mov_b32 s53, s14
	v_mul_f32_e32 v118, v116, v117
	v_rcp_f32_e32 v121, v118
	v_mad_i64_i32 v[118:119], s[28:29], v120, s52, v[144:145]
	v_lshl_add_u64 v[118:119], v[118:119], 0, v[146:147]
	v_mul_f32_e32 v116, v116, v121
	v_mul_f32_e32 v120, v117, v121
	v_pk_mul_f32 v[114:115], v[114:115], v[116:117] op_sel_hi:[1,0]
	v_max_f32_e32 v116, v104, v104
	v_max_f32_e32 v121, v106, v106
	v_max_f32_e32 v116, 0xc1a00000, v116
	v_max_f32_e32 v121, 0xc1a00000, v121
	v_mul_f32_e32 v116, 0xbfb8aa3b, v116
	v_mul_f32_e32 v121, 0xbfb8aa3b, v121
	v_exp_f32_e32 v117, v116
	v_max_f32_e32 v116, v105, v105
	v_exp_f32_e32 v123, v121
	v_max_f32_e32 v121, v107, v107
	v_max_f32_e32 v116, 0xc1a00000, v116
	v_max_f32_e32 v121, 0xc1a00000, v121
	v_mul_f32_e32 v116, 0xbfb8aa3b, v116
	v_mul_f32_e32 v121, 0xbfb8aa3b, v121
	v_exp_f32_e32 v116, v116
	v_exp_f32_e32 v122, v121
	v_pk_mul_f32 v[112:113], v[112:113], v[120:121] op_sel_hi:[1,0]
	v_pk_mul_f32 v[110:111], v[110:111], v[114:115]
	v_pk_mul_f32 v[108:109], v[108:109], v[112:113]
	v_pk_add_f32 v[112:113], v[116:117], 1.0 op_sel_hi:[1,0]
	v_pk_add_f32 v[116:117], v[122:123], 1.0 op_sel_hi:[1,0]
	v_mov_b32_e32 v120, v113
	v_mov_b32_e32 v121, v117
	v_mov_b32_e32 v122, v112
	v_mov_b32_e32 v123, v116
	v_pk_mul_f32 v[120:121], v[120:121], v[122:123]
	v_pk_mul_f32 v[102:103], v[110:111], v[102:103]
	v_mul_f32_e32 v122, v120, v121
	v_rcp_f32_e32 v122, v122
	v_pk_mul_f32 v[100:101], v[108:109], v[100:101]
	s_mov_b32 s26, s16
	s_mov_b64 s[30:31], s[24:25]
	v_mul_f32_e32 v108, v121, v122
	v_mul_f32_e32 v110, v120, v122
	v_pk_mul_f32 v[110:111], v[116:117], v[110:111] op_sel_hi:[1,0]
	v_pk_mul_f32 v[108:109], v[112:113], v[108:109] op_sel_hi:[1,0]
	v_pk_mul_f32 v[106:107], v[106:107], v[110:111]
	v_pk_mul_f32 v[104:105], v[104:105], v[108:109]
	v_pk_mul_f32 v[106:107], v[106:107], v[98:99]
	v_pk_mul_f32 v[98:99], v[104:105], v[96:97]
	v_cvt_pk_bf16_f32 v96, v100, v101
	v_cvt_pk_bf16_f32 v97, v102, v103
	v_max_f32_e32 v100, v92, v92
	v_max_f32_e32 v102, v94, v94
	v_max_f32_e32 v100, 0xc1a00000, v100
	v_max_f32_e32 v102, 0xc1a00000, v102
	v_mul_f32_e32 v100, 0xbfb8aa3b, v100
	v_mul_f32_e32 v102, 0xbfb8aa3b, v102
	v_exp_f32_e32 v101, v100
	v_max_f32_e32 v100, v93, v93
	v_exp_f32_e32 v103, v102
	v_max_f32_e32 v102, v95, v95
	v_max_f32_e32 v100, 0xc1a00000, v100
	v_max_f32_e32 v102, 0xc1a00000, v102
	v_mul_f32_e32 v100, 0xbfb8aa3b, v100
	v_mul_f32_e32 v102, 0xbfb8aa3b, v102
	v_exp_f32_e32 v100, v100
	v_exp_f32_e32 v102, v102
	v_cvt_pk_bf16_f32 v98, v98, v99
	v_cvt_pk_bf16_f32 v99, v106, v107
	global_store_dwordx4 v[118:119], v[96:99], off
	v_or_b32_e32 v104, 32, v155
	s_nop 0
	v_pk_add_f32 v[96:97], v[100:101], 1.0 op_sel_hi:[1,0]
	v_pk_add_f32 v[98:99], v[102:103], 1.0 op_sel_hi:[1,0]
	v_mov_b32_e32 v100, v97
	v_mov_b32_e32 v101, v99
	v_mov_b32_e32 v102, v96
	v_mov_b32_e32 v103, v98
	v_pk_mul_f32 v[100:101], v[100:101], v[102:103]
	s_nop 0
	v_mul_f32_e32 v102, v100, v101
	v_rcp_f32_e32 v105, v102
	v_mad_i64_i32 v[102:103], s[28:29], v104, s52, v[144:145]
	v_lshl_add_u64 v[102:103], v[102:103], 0, v[146:147]
	v_mul_f32_e32 v100, v100, v105
	v_mul_f32_e32 v104, v101, v105
	v_pk_mul_f32 v[98:99], v[98:99], v[100:101] op_sel_hi:[1,0]
	v_max_f32_e32 v100, v88, v88
	v_max_f32_e32 v105, v90, v90
	v_max_f32_e32 v100, 0xc1a00000, v100
	v_max_f32_e32 v105, 0xc1a00000, v105
	v_mul_f32_e32 v100, 0xbfb8aa3b, v100
	v_mul_f32_e32 v105, 0xbfb8aa3b, v105
	v_exp_f32_e32 v101, v100
	v_max_f32_e32 v100, v89, v89
	v_exp_f32_e32 v107, v105
	v_max_f32_e32 v105, v91, v91
	v_max_f32_e32 v100, 0xc1a00000, v100
	v_max_f32_e32 v105, 0xc1a00000, v105
	v_mul_f32_e32 v100, 0xbfb8aa3b, v100
	v_mul_f32_e32 v105, 0xbfb8aa3b, v105
	v_exp_f32_e32 v100, v100
	v_exp_f32_e32 v106, v105
	v_pk_mul_f32 v[96:97], v[96:97], v[104:105] op_sel_hi:[1,0]
	v_pk_mul_f32 v[94:95], v[94:95], v[98:99]
	v_pk_mul_f32 v[92:93], v[92:93], v[96:97]
	v_pk_add_f32 v[96:97], v[100:101], 1.0 op_sel_hi:[1,0]
	v_pk_add_f32 v[100:101], v[106:107], 1.0 op_sel_hi:[1,0]
	v_mov_b32_e32 v104, v97
	v_mov_b32_e32 v105, v101
	v_mov_b32_e32 v106, v96
	v_mov_b32_e32 v107, v100
	v_pk_mul_f32 v[104:105], v[104:105], v[106:107]
	v_pk_mul_f32 v[86:87], v[94:95], v[86:87]
	v_mul_f32_e32 v106, v104, v105
	v_rcp_f32_e32 v106, v106
	v_pk_mul_f32 v[84:85], v[92:93], v[84:85]
	v_mul_f32_e32 v92, v105, v106
	v_mul_f32_e32 v94, v104, v106
	v_pk_mul_f32 v[94:95], v[100:101], v[94:95] op_sel_hi:[1,0]
	v_pk_mul_f32 v[92:93], v[96:97], v[92:93] op_sel_hi:[1,0]
	v_pk_mul_f32 v[90:91], v[90:91], v[94:95]
	v_pk_mul_f32 v[88:89], v[88:89], v[92:93]
	v_pk_mul_f32 v[90:91], v[90:91], v[82:83]
	v_pk_mul_f32 v[82:83], v[88:89], v[80:81]
	v_cvt_pk_bf16_f32 v80, v84, v85
; __device__ __forceinline__ unsigned cvt_pk_bf16(float lo, float hi) { unsigned r; asm volatile("v_cvt_pk_bf16_f32 %0, %1, %2" : "=v"(r) : "v"(lo), "v"(hi)); return r; }
;     __device__ __forceinline__ void operator()(const f32x4 (&acc)[2][2][4][2], const Unit& u, int wr, int wc, int fr, int fq) const {
;         const int row0 = u.pm * BM + wr * 64 + fr, col0 = u.pn * HALF + wc * 32 + 8 * fq;
; #pragma unroll
;         for (int ai = 0; ai < 2; ++ai)
; #pragma unroll
;             for (int m = 0; m < 4; ++m) { bf16_t* rowp = O + (size_t)(row0 + ai * HALF + m * 16) * ldc + col0;
;                 f32x4 v0, v1;
; #pragma unroll
;                 for (int j = 0; j < 1; ++j) { v0 = acc[ai][0][m][0] * sigmoid4(acc[ai][0][m][0]) * acc[ai][1][m][0]; v1 = acc[ai][0][m][1] * sigmoid4(acc[ai][0][m][1]) * acc[ai][1][m][1]; }
;                 u32x4 w; w.x = cvt_pk_bf16(v0[0], v0[1]); w.y = cvt_pk_bf16(v0[2], v0[3]); w.z = cvt_pk_bf16(v1[0], v1[1]); w.w = cvt_pk_bf16(v1[2], v1[3]);
;                 *(u32x4*)rowp = w; }
	v_cvt_pk_bf16_f32 v81, v86, v87
	v_max_f32_e32 v84, v76, v76
	v_max_f32_e32 v86, v78, v78
	v_max_f32_e32 v84, 0xc1a00000, v84
	v_max_f32_e32 v86, 0xc1a00000, v86
	v_mul_f32_e32 v84, 0xbfb8aa3b, v84
	v_mul_f32_e32 v86, 0xbfb8aa3b, v86
	v_exp_f32_e32 v85, v84
	v_max_f32_e32 v84, v77, v77
	v_exp_f32_e32 v87, v86
	v_max_f32_e32 v86, v79, v79
	v_max_f32_e32 v84, 0xc1a00000, v84
	v_max_f32_e32 v86, 0xc1a00000, v86
	v_mul_f32_e32 v84, 0xbfb8aa3b, v84
	v_mul_f32_e32 v86, 0xbfb8aa3b, v86
	v_exp_f32_e32 v84, v84
	v_exp_f32_e32 v86, v86
	v_cvt_pk_bf16_f32 v82, v82, v83
	v_cvt_pk_bf16_f32 v83, v90, v91
	global_store_dwordx4 v[102:103], v[80:83], off
	v_or_b32_e32 v88, 48, v155
	s_nop 0
	v_pk_add_f32 v[80:81], v[84:85], 1.0 op_sel_hi:[1,0]
	v_pk_add_f32 v[82:83], v[86:87], 1.0 op_sel_hi:[1,0]
	v_mov_b32_e32 v84, v81
	v_mov_b32_e32 v85, v83
	v_mov_b32_e32 v86, v80
	v_mov_b32_e32 v87, v82
	v_pk_mul_f32 v[84:85], v[84:85], v[86:87]
	s_nop 0
	v_mul_f32_e32 v86, v84, v85
	v_rcp_f32_e32 v89, v86
	v_mad_i64_i32 v[86:87], s[28:29], v88, s52, v[144:145]
	v_lshl_add_u64 v[86:87], v[86:87], 0, v[146:147]
	v_mul_f32_e32 v84, v84, v89
	v_mul_f32_e32 v88, v85, v89
	v_pk_mul_f32 v[82:83], v[82:83], v[84:85] op_sel_hi:[1,0]
	v_max_f32_e32 v84, v72, v72
	v_max_f32_e32 v89, v74, v74
	v_max_f32_e32 v84, 0xc1a00000, v84
	v_max_f32_e32 v89, 0xc1a00000, v89
	v_mul_f32_e32 v84, 0xbfb8aa3b, v84
	v_mul_f32_e32 v89, 0xbfb8aa3b, v89
	v_exp_f32_e32 v85, v84
	v_max_f32_e32 v84, v73, v73
	v_exp_f32_e32 v91, v89
	v_max_f32_e32 v89, v75, v75
	v_max_f32_e32 v84, 0xc1a00000, v84
	v_max_f32_e32 v89, 0xc1a00000, v89
	v_mul_f32_e32 v84, 0xbfb8aa3b, v84
	v_mul_f32_e32 v89, 0xbfb8aa3b, v89
	v_exp_f32_e32 v84, v84
	v_exp_f32_e32 v90, v89
	v_pk_mul_f32 v[80:81], v[80:81], v[88:89] op_sel_hi:[1,0]
	v_pk_mul_f32 v[78:79], v[78:79], v[82:83]
	v_pk_mul_f32 v[76:77], v[76:77], v[80:81]
	v_pk_add_f32 v[80:81], v[84:85], 1.0 op_sel_hi:[1,0]
	v_pk_add_f32 v[84:85], v[90:91], 1.0 op_sel_hi:[1,0]
	v_mov_b32_e32 v88, v81
	v_mov_b32_e32 v89, v85
	v_mov_b32_e32 v90, v80
	v_mov_b32_e32 v91, v84
	v_pk_mul_f32 v[88:89], v[88:89], v[90:91]
	v_pk_mul_f32 v[70:71], v[78:79], v[70:71]
	v_mul_f32_e32 v90, v88, v89
	v_rcp_f32_e32 v90, v90
	v_pk_mul_f32 v[68:69], v[76:77], v[68:69]
	v_mul_f32_e32 v76, v89, v90
	v_mul_f32_e32 v78, v88, v90
	v_pk_mul_f32 v[78:79], v[84:85], v[78:79] op_sel_hi:[1,0]
	v_pk_mul_f32 v[76:77], v[80:81], v[76:77] op_sel_hi:[1,0]
	v_pk_mul_f32 v[74:75], v[74:75], v[78:79]
	v_pk_mul_f32 v[72:73], v[72:73], v[76:77]
	v_pk_mul_f32 v[74:75], v[74:75], v[66:67]
	v_pk_mul_f32 v[66:67], v[72:73], v[64:65]
	v_cvt_pk_bf16_f32 v64, v68, v69
	v_cvt_pk_bf16_f32 v65, v70, v71
	v_max_f32_e32 v68, v60, v60
	v_max_f32_e32 v70, v62, v62
	v_max_f32_e32 v68, 0xc1a00000, v68
	v_max_f32_e32 v70, 0xc1a00000, v70
	v_mul_f32_e32 v68, 0xbfb8aa3b, v68
	v_mul_f32_e32 v70, 0xbfb8aa3b, v70
	v_exp_f32_e32 v69, v68
	v_max_f32_e32 v68, v61, v61
	v_exp_f32_e32 v71, v70
	v_max_f32_e32 v70, v63, v63
	v_max_f32_e32 v68, 0xc1a00000, v68
	v_max_f32_e32 v70, 0xc1a00000, v70
	v_mul_f32_e32 v68, 0xbfb8aa3b, v68
	v_mul_f32_e32 v70, 0xbfb8aa3b, v70
	v_exp_f32_e32 v68, v68
	v_exp_f32_e32 v70, v70
	v_cvt_pk_bf16_f32 v66, v66, v67
	v_cvt_pk_bf16_f32 v67, v74, v75
	global_store_dwordx4 v[86:87], v[64:67], off
	v_add_u32_e32 v72, 0x80, v155
	s_nop 0
	v_pk_add_f32 v[64:65], v[68:69], 1.0 op_sel_hi:[1,0]
	v_pk_add_f32 v[66:67], v[70:71], 1.0 op_sel_hi:[1,0]
	v_mov_b32_e32 v68, v65
	v_mov_b32_e32 v69, v67
	v_mov_b32_e32 v70, v64
	v_mov_b32_e32 v71, v66
	v_pk_mul_f32 v[68:69], v[68:69], v[70:71]
	s_nop 0
	v_mul_f32_e32 v70, v68, v69
	v_rcp_f32_e32 v73, v70
	v_mad_i64_i32 v[70:71], s[28:29], v72, s52, v[144:145]
	v_lshl_add_u64 v[70:71], v[70:71], 0, v[146:147]
	v_mul_f32_e32 v68, v68, v73
	v_mul_f32_e32 v72, v69, v73
	v_pk_mul_f32 v[66:67], v[66:67], v[68:69] op_sel_hi:[1,0]
	v_max_f32_e32 v68, v56, v56
	v_max_f32_e32 v73, v58, v58
	v_max_f32_e32 v68, 0xc1a00000, v68
	v_max_f32_e32 v73, 0xc1a00000, v73
	v_mul_f32_e32 v68, 0xbfb8aa3b, v68
	v_mul_f32_e32 v73, 0xbfb8aa3b, v73
	v_exp_f32_e32 v69, v68
	v_max_f32_e32 v68, v57, v57
	v_exp_f32_e32 v75, v73
	v_max_f32_e32 v73, v59, v59
	v_max_f32_e32 v68, 0xc1a00000, v68
	v_max_f32_e32 v73, 0xc1a00000, v73
	v_mul_f32_e32 v68, 0xbfb8aa3b, v68
	v_mul_f32_e32 v73, 0xbfb8aa3b, v73
	v_exp_f32_e32 v68, v68
	v_exp_f32_e32 v74, v73
	v_pk_mul_f32 v[64:65], v[64:65], v[72:73] op_sel_hi:[1,0]
	v_pk_mul_f32 v[62:63], v[62:63], v[66:67]
	v_pk_mul_f32 v[60:61], v[60:61], v[64:65]
	v_pk_add_f32 v[64:65], v[68:69], 1.0 op_sel_hi:[1,0]
	v_pk_add_f32 v[68:69], v[74:75], 1.0 op_sel_hi:[1,0]
	v_mov_b32_e32 v72, v65
	v_mov_b32_e32 v73, v69
	v_mov_b32_e32 v74, v64
	v_mov_b32_e32 v75, v68
	v_pk_mul_f32 v[72:73], v[72:73], v[74:75]
	v_pk_mul_f32 v[54:55], v[62:63], v[54:55]
	v_mul_f32_e32 v74, v72, v73
	v_rcp_f32_e32 v74, v74
	v_pk_mul_f32 v[52:53], v[60:61], v[52:53]
	v_mul_f32_e32 v60, v73, v74
	v_mul_f32_e32 v62, v72, v74
	v_pk_mul_f32 v[62:63], v[68:69], v[62:63] op_sel_hi:[1,0]
	v_pk_mul_f32 v[60:61], v[64:65], v[60:61] op_sel_hi:[1,0]
	v_pk_mul_f32 v[58:59], v[58:59], v[62:63]
	v_pk_mul_f32 v[56:57], v[56:57], v[60:61]
	v_pk_mul_f32 v[58:59], v[58:59], v[50:51]
	v_pk_mul_f32 v[50:51], v[56:57], v[48:49]
	v_cvt_pk_bf16_f32 v48, v52, v53
	v_cvt_pk_bf16_f32 v49, v54, v55
	v_max_f32_e32 v52, v44, v44
	v_max_f32_e32 v54, v46, v46
	v_max_f32_e32 v52, 0xc1a00000, v52
	v_max_f32_e32 v54, 0xc1a00000, v54
	v_mul_f32_e32 v52, 0xbfb8aa3b, v52
	v_mul_f32_e32 v54, 0xbfb8aa3b, v54
	v_exp_f32_e32 v53, v52
	v_max_f32_e32 v52, v45, v45
	v_exp_f32_e32 v55, v54
	v_max_f32_e32 v54, v47, v47
	v_max_f32_e32 v52, 0xc1a00000, v52
; __device__ __forceinline__ unsigned cvt_pk_bf16(float lo, float hi) { unsigned r; asm volatile("v_cvt_pk_bf16_f32 %0, %1, %2" : "=v"(r) : "v"(lo), "v"(hi)); return r; }
;     __device__ __forceinline__ void operator()(const f32x4 (&acc)[2][2][4][2], const Unit& u, int wr, int wc, int fr, int fq) const {
;         const int row0 = u.pm * BM + wr * 64 + fr, col0 = u.pn * HALF + wc * 32 + 8 * fq;
; #pragma unroll
;         for (int ai = 0; ai < 2; ++ai)
; #pragma unroll
;             for (int m = 0; m < 4; ++m) { bf16_t* rowp = O + (size_t)(row0 + ai * HALF + m * 16) * ldc + col0;
;                 f32x4 v0, v1;
; #pragma unroll
;                 for (int j = 0; j < 1; ++j) { v0 = acc[ai][0][m][0] * sigmoid4(acc[ai][0][m][0]) * acc[ai][1][m][0]; v1 = acc[ai][0][m][1] * sigmoid4(acc[ai][0][m][1]) * acc[ai][1][m][1]; }
;                 u32x4 w; w.x = cvt_pk_bf16(v0[0], v0[1]); w.y = cvt_pk_bf16(v0[2], v0[3]); w.z = cvt_pk_bf16(v1[0], v1[1]); w.w = cvt_pk_bf16(v1[2], v1[3]);
;                 *(u32x4*)rowp = w; }
	v_max_f32_e32 v54, 0xc1a00000, v54
	v_mul_f32_e32 v52, 0xbfb8aa3b, v52
	v_mul_f32_e32 v54, 0xbfb8aa3b, v54
	v_exp_f32_e32 v52, v52
	v_exp_f32_e32 v54, v54
	v_cvt_pk_bf16_f32 v50, v50, v51
	v_cvt_pk_bf16_f32 v51, v58, v59
	global_store_dwordx4 v[70:71], v[48:51], off
	v_add_u32_e32 v56, 0x90, v155
	s_nop 0
	v_pk_add_f32 v[48:49], v[52:53], 1.0 op_sel_hi:[1,0]
	v_pk_add_f32 v[50:51], v[54:55], 1.0 op_sel_hi:[1,0]
	v_mov_b32_e32 v52, v49
	v_mov_b32_e32 v53, v51
	v_mov_b32_e32 v54, v48
	v_mov_b32_e32 v55, v50
	v_pk_mul_f32 v[52:53], v[52:53], v[54:55]
	s_nop 0
	v_mul_f32_e32 v54, v52, v53
	v_rcp_f32_e32 v57, v54
	v_mad_i64_i32 v[54:55], s[28:29], v56, s52, v[144:145]
	v_lshl_add_u64 v[54:55], v[54:55], 0, v[146:147]
	v_mul_f32_e32 v52, v52, v57
	v_mul_f32_e32 v56, v53, v57
	v_pk_mul_f32 v[50:51], v[50:51], v[52:53] op_sel_hi:[1,0]
	v_max_f32_e32 v52, v40, v40
	v_max_f32_e32 v57, v42, v42
	v_max_f32_e32 v52, 0xc1a00000, v52
	v_max_f32_e32 v57, 0xc1a00000, v57
	v_mul_f32_e32 v52, 0xbfb8aa3b, v52
	v_mul_f32_e32 v57, 0xbfb8aa3b, v57
	v_exp_f32_e32 v53, v52
	v_max_f32_e32 v52, v41, v41
	v_exp_f32_e32 v59, v57
	v_max_f32_e32 v57, v43, v43
	v_max_f32_e32 v52, 0xc1a00000, v52
	v_max_f32_e32 v57, 0xc1a00000, v57
	v_mul_f32_e32 v52, 0xbfb8aa3b, v52
	v_mul_f32_e32 v57, 0xbfb8aa3b, v57
	v_exp_f32_e32 v52, v52
	v_exp_f32_e32 v58, v57
	v_pk_mul_f32 v[48:49], v[48:49], v[56:57] op_sel_hi:[1,0]
	v_pk_mul_f32 v[46:47], v[46:47], v[50:51]
	v_pk_mul_f32 v[44:45], v[44:45], v[48:49]
	v_pk_add_f32 v[48:49], v[52:53], 1.0 op_sel_hi:[1,0]
	v_pk_add_f32 v[52:53], v[58:59], 1.0 op_sel_hi:[1,0]
	v_mov_b32_e32 v56, v49
	v_mov_b32_e32 v57, v53
	v_mov_b32_e32 v58, v48
	v_mov_b32_e32 v59, v52
	v_pk_mul_f32 v[56:57], v[56:57], v[58:59]
	v_pk_mul_f32 v[38:39], v[46:47], v[38:39]
	v_mul_f32_e32 v58, v56, v57
	v_rcp_f32_e32 v58, v58
	v_pk_mul_f32 v[36:37], v[44:45], v[36:37]
	v_mul_f32_e32 v44, v57, v58
	v_mul_f32_e32 v46, v56, v58
	v_pk_mul_f32 v[46:47], v[52:53], v[46:47] op_sel_hi:[1,0]
	v_pk_mul_f32 v[44:45], v[48:49], v[44:45] op_sel_hi:[1,0]
	v_pk_mul_f32 v[42:43], v[42:43], v[46:47]
	v_pk_mul_f32 v[40:41], v[40:41], v[44:45]
	v_pk_mul_f32 v[42:43], v[42:43], v[34:35]
	v_pk_mul_f32 v[34:35], v[40:41], v[32:33]
	v_cvt_pk_bf16_f32 v32, v36, v37
	v_cvt_pk_bf16_f32 v33, v38, v39
	v_max_f32_e32 v36, v28, v28
	v_max_f32_e32 v38, v30, v30
	v_max_f32_e32 v36, 0xc1a00000, v36
	v_max_f32_e32 v38, 0xc1a00000, v38
	v_mul_f32_e32 v36, 0xbfb8aa3b, v36
	v_mul_f32_e32 v38, 0xbfb8aa3b, v38
	v_exp_f32_e32 v37, v36
	v_max_f32_e32 v36, v29, v29
	v_exp_f32_e32 v39, v38
	v_max_f32_e32 v38, v31, v31
	v_max_f32_e32 v36, 0xc1a00000, v36
	v_max_f32_e32 v38, 0xc1a00000, v38
	v_mul_f32_e32 v36, 0xbfb8aa3b, v36
	v_mul_f32_e32 v38, 0xbfb8aa3b, v38
	v_exp_f32_e32 v36, v36
	v_exp_f32_e32 v38, v38
	v_cvt_pk_bf16_f32 v34, v34, v35
	v_cvt_pk_bf16_f32 v35, v42, v43
	global_store_dwordx4 v[54:55], v[32:35], off
	v_add_u32_e32 v40, 0xa0, v155
	s_nop 0
	v_pk_add_f32 v[32:33], v[36:37], 1.0 op_sel_hi:[1,0]
	v_pk_add_f32 v[34:35], v[38:39], 1.0 op_sel_hi:[1,0]
	v_mov_b32_e32 v36, v33
	v_mov_b32_e32 v37, v35
	v_mov_b32_e32 v38, v32
	v_mov_b32_e32 v39, v34
	v_pk_mul_f32 v[36:37], v[36:37], v[38:39]
	s_nop 0
	v_mul_f32_e32 v38, v36, v37
	v_rcp_f32_e32 v41, v38
	v_mad_i64_i32 v[38:39], s[28:29], v40, s52, v[144:145]
	v_lshl_add_u64 v[38:39], v[38:39], 0, v[146:147]
	v_mul_f32_e32 v36, v36, v41
	v_mul_f32_e32 v40, v37, v41
	v_pk_mul_f32 v[34:35], v[34:35], v[36:37] op_sel_hi:[1,0]
	v_max_f32_e32 v36, v24, v24
	v_max_f32_e32 v41, v26, v26
	v_max_f32_e32 v36, 0xc1a00000, v36
	v_max_f32_e32 v41, 0xc1a00000, v41
	v_mul_f32_e32 v36, 0xbfb8aa3b, v36
	v_mul_f32_e32 v41, 0xbfb8aa3b, v41
	v_exp_f32_e32 v37, v36
	v_max_f32_e32 v36, v25, v25
	v_exp_f32_e32 v43, v41
	v_max_f32_e32 v41, v27, v27
	v_max_f32_e32 v36, 0xc1a00000, v36
	v_max_f32_e32 v41, 0xc1a00000, v41
	v_mul_f32_e32 v36, 0xbfb8aa3b, v36
; __device__ __forceinline__ unsigned cvt_pk_bf16(float lo, float hi) { unsigned r; asm volatile("v_cvt_pk_bf16_f32 %0, %1, %2" : "=v"(r) : "v"(lo), "v"(hi)); return r; }
; #define PG8_WAIT_V(n) asm volatile("s_waitcnt vmcnt(" #n ")" ::: "memory")
; #define PG8_BAR __builtin_amdgcn_s_barrier()
;     __device__ __forceinline__ void operator()(const f32x4 (&acc)[2][2][4][2], const Unit& u, int wr, int wc, int fr, int fq) const {
;         const int row0 = u.pm * BM + wr * 64 + fr, col0 = u.pn * HALF + wc * 32 + 8 * fq;
; #pragma unroll
;         for (int ai = 0; ai < 2; ++ai)
; #pragma unroll
;             for (int m = 0; m < 4; ++m) { bf16_t* rowp = O + (size_t)(row0 + ai * HALF + m * 16) * ldc + col0;
;                 f32x4 v0, v1;
; #pragma unroll
;                 for (int j = 0; j < 1; ++j) { v0 = acc[ai][0][m][0] * sigmoid4(acc[ai][0][m][0]) * acc[ai][1][m][0]; v1 = acc[ai][0][m][1] * sigmoid4(acc[ai][0][m][1]) * acc[ai][1][m][1]; }
;                 u32x4 w; w.x = cvt_pk_bf16(v0[0], v0[1]); w.y = cvt_pk_bf16(v0[2], v0[3]); w.z = cvt_pk_bf16(v1[0], v1[1]); w.w = cvt_pk_bf16(v1[2], v1[3]);
;                 *(u32x4*)rowp = w; }
; template <class Epi, class Sched>
; __device__ __forceinline__ void gemm_phase(PG8_LAS unsigned char* lds, const Gemm g, const Sched& S, const Epi& E) {
;     ...
;     PG8_WAIT_V(0);
;     if (wr == 0) PG8_BAR;
;     PG8_BAR;
	v_mul_f32_e32 v41, 0xbfb8aa3b, v41
	v_exp_f32_e32 v36, v36
	v_exp_f32_e32 v42, v41
	v_pk_mul_f32 v[32:33], v[32:33], v[40:41] op_sel_hi:[1,0]
	v_pk_mul_f32 v[30:31], v[30:31], v[34:35]
	v_pk_mul_f32 v[28:29], v[28:29], v[32:33]
	v_pk_add_f32 v[32:33], v[36:37], 1.0 op_sel_hi:[1,0]
	v_pk_add_f32 v[36:37], v[42:43], 1.0 op_sel_hi:[1,0]
	v_mov_b32_e32 v40, v33
	v_mov_b32_e32 v41, v37
	v_mov_b32_e32 v42, v32
	v_mov_b32_e32 v43, v36
	v_pk_mul_f32 v[40:41], v[40:41], v[42:43]
	v_pk_mul_f32 v[22:23], v[30:31], v[22:23]
	v_mul_f32_e32 v42, v40, v41
	v_rcp_f32_e32 v42, v42
	v_pk_mul_f32 v[20:21], v[28:29], v[20:21]
	v_mul_f32_e32 v28, v41, v42
	v_mul_f32_e32 v30, v40, v42
	v_pk_mul_f32 v[30:31], v[36:37], v[30:31] op_sel_hi:[1,0]
	v_pk_mul_f32 v[28:29], v[32:33], v[28:29] op_sel_hi:[1,0]
	v_pk_mul_f32 v[26:27], v[26:27], v[30:31]
	v_pk_mul_f32 v[24:25], v[24:25], v[28:29]
	v_pk_mul_f32 v[26:27], v[26:27], v[18:19]
	v_pk_mul_f32 v[18:19], v[24:25], v[16:17]
	v_cvt_pk_bf16_f32 v16, v20, v21
	v_cvt_pk_bf16_f32 v17, v22, v23
	v_max_f32_e32 v20, v12, v12
	v_max_f32_e32 v22, v14, v14
	v_max_f32_e32 v20, 0xc1a00000, v20
	v_max_f32_e32 v22, 0xc1a00000, v22
	v_mul_f32_e32 v20, 0xbfb8aa3b, v20
	v_mul_f32_e32 v22, 0xbfb8aa3b, v22
	v_exp_f32_e32 v21, v20
	v_max_f32_e32 v20, v13, v13
	v_exp_f32_e32 v23, v22
	v_max_f32_e32 v22, v15, v15
	v_max_f32_e32 v20, 0xc1a00000, v20
	v_max_f32_e32 v22, 0xc1a00000, v22
	v_mul_f32_e32 v20, 0xbfb8aa3b, v20
	v_mul_f32_e32 v22, 0xbfb8aa3b, v22
	v_exp_f32_e32 v20, v20
	v_exp_f32_e32 v22, v22
	v_cvt_pk_bf16_f32 v18, v18, v19
	v_cvt_pk_bf16_f32 v19, v26, v27
	global_store_dwordx4 v[38:39], v[16:19], off
	v_add_u32_e32 v24, 0xb0, v155
	s_nop 0
	v_pk_add_f32 v[16:17], v[20:21], 1.0 op_sel_hi:[1,0]
	v_pk_add_f32 v[18:19], v[22:23], 1.0 op_sel_hi:[1,0]
	v_mov_b32_e32 v20, v17
	v_mov_b32_e32 v21, v19
	v_mov_b32_e32 v22, v16
	v_mov_b32_e32 v23, v18
	v_pk_mul_f32 v[20:21], v[20:21], v[22:23]
	s_nop 0
	v_mul_f32_e32 v22, v20, v21
	v_rcp_f32_e32 v25, v22
	v_mad_i64_i32 v[22:23], s[28:29], v24, s52, v[144:145]
	v_lshl_add_u64 v[22:23], v[22:23], 0, v[146:147]
	v_mul_f32_e32 v20, v20, v25
	v_mul_f32_e32 v24, v21, v25
	v_pk_mul_f32 v[18:19], v[18:19], v[20:21] op_sel_hi:[1,0]
	v_max_f32_e32 v20, v8, v8
	v_max_f32_e32 v25, v10, v10
	v_max_f32_e32 v20, 0xc1a00000, v20
	v_max_f32_e32 v25, 0xc1a00000, v25
	v_mul_f32_e32 v20, 0xbfb8aa3b, v20
	v_mul_f32_e32 v25, 0xbfb8aa3b, v25
	v_exp_f32_e32 v21, v20
	v_max_f32_e32 v20, v9, v9
	v_exp_f32_e32 v27, v25
	v_max_f32_e32 v25, v11, v11
	v_max_f32_e32 v20, 0xc1a00000, v20
	v_max_f32_e32 v25, 0xc1a00000, v25
	v_mul_f32_e32 v20, 0xbfb8aa3b, v20
	v_mul_f32_e32 v25, 0xbfb8aa3b, v25
	v_exp_f32_e32 v20, v20
	v_exp_f32_e32 v26, v25
	v_pk_mul_f32 v[16:17], v[16:17], v[24:25] op_sel_hi:[1,0]
	v_pk_mul_f32 v[14:15], v[14:15], v[18:19]
	v_pk_mul_f32 v[12:13], v[12:13], v[16:17]
	v_pk_add_f32 v[16:17], v[20:21], 1.0 op_sel_hi:[1,0]
	v_pk_add_f32 v[20:21], v[26:27], 1.0 op_sel_hi:[1,0]
	v_mov_b32_e32 v24, v17
	v_mov_b32_e32 v25, v21
	v_mov_b32_e32 v26, v16
	v_mov_b32_e32 v27, v20
	v_pk_mul_f32 v[24:25], v[24:25], v[26:27]
	v_pk_mul_f32 v[6:7], v[14:15], v[6:7]
	v_mul_f32_e32 v26, v24, v25
	v_rcp_f32_e32 v26, v26
	v_pk_mul_f32 v[4:5], v[12:13], v[4:5]
	s_mov_b64 s[28:29], s[18:19]
	v_mul_f32_e32 v12, v25, v26
	v_mul_f32_e32 v14, v24, v26
	v_pk_mul_f32 v[14:15], v[20:21], v[14:15] op_sel_hi:[1,0]
	v_pk_mul_f32 v[12:13], v[16:17], v[12:13] op_sel_hi:[1,0]
	v_pk_mul_f32 v[10:11], v[10:11], v[14:15]
	v_pk_mul_f32 v[8:9], v[8:9], v[12:13]
	v_pk_mul_f32 v[10:11], v[10:11], v[2:3]
	v_pk_mul_f32 v[2:3], v[8:9], v[0:1]
	v_cvt_pk_bf16_f32 v0, v4, v5
	v_cvt_pk_bf16_f32 v1, v6, v7
	s_nop 0
	v_cvt_pk_bf16_f32 v2, v2, v3
	v_cvt_pk_bf16_f32 v3, v10, v11
	global_store_dwordx4 v[22:23], v[0:3], off
	s_cbranch_vccz .LBB0_192
	s_waitcnt vmcnt(0)
	s_cmpk_gt_u32 s37, 0xff
	s_cbranch_scc1 .LBB0_199
	s_barrier

; #define PG8_STAGE(bufoff, gbase, voff) do { _Pragma("unroll") for (int _i = 0; _i < 2; ++_i) \
;         __builtin_amdgcn_global_load_lds((const unsigned*)((const char*)(gbase) + (voff)[_i]), (PG8_LAS unsigned*)(lds + (bufoff) + ldsw + _i * 8192), 16, 0, 0); } while (0)
; #define PG8_LDA(dst, b, h) do { _Pragma("unroll") for (int m = 0; m < 4; ++m) _Pragma("unroll") for (int k = 0; k < 2; ++k) dst[m][k] = *(const PG8_LAS bf16x8*)(lds + PG8_SA(b, h) + aoff + m * 2048 + k * 1024); } while (0)
; #define PG8_LDB(dst, b, h) do { _Pragma("unroll") for (int n = 0; n < 2; ++n) _Pragma("unroll") for (int k = 0; k < 2; ++k) dst[n][k] = *(const PG8_LAS bf16x8*)(lds + PG8_SB(b, h) + boff + n * 2048 + k * 1024); } while (0)
; #define PG8_MMA(ai, bj, At, Bt) do { __builtin_amdgcn_s_setprio(1); _Pragma("unroll") for (int m = 0; m < 4; ++m) _Pragma("unroll") for (int n = 0; n < 2; ++n) _Pragma("unroll") for (int k = 0; k < 2; ++k) \
;         acc[ai][bj][m][n] = __builtin_amdgcn_mfma_f32_16x16x32_bf16(Bt[n][k], At[m][k], acc[ai][bj][m][n], 0, 0, 0); __builtin_amdgcn_s_setprio(0); } while (0)
; #define PG8_WAIT_L(n) asm volatile("s_waitcnt lgkmcnt(" #n ")" ::: "memory")
; #define PG8_BAR __builtin_amdgcn_s_barrier()
; #define PG8_SCHED __builtin_amdgcn_sched_barrier(0)
; template <class Epi, class Sched>
; __device__ __forceinline__ void gemm_phase(PG8_LAS unsigned char* lds, const Gemm g, const Sched& S, const Epi& E) {
;     ...
;             PG8_LDB(B0, 0, 0); PG8_SCHED; PG8_LDA(At, 0, 0); PG8_STAGE(PG8_SA(1, 1), a1 + hstep, voffA);
;             PG8_WAIT_L(8); PG8_BAR; PG8_WAIT_L(0); PG8_MMA(0, 0, At, B0); PG8_BAR; PG8_SCHED;
;             PG8_LDB(B1, 0, 1); PG8_STAGE(PG8_SB(0, 0), b2, voffB);
;             PG8_BAR; PG8_WAIT_L(0); PG8_MMA(0, 1, At, B1); PG8_BAR;
;             PG8_LDA(At, 0, 1); PG8_STAGE(PG8_SA(0, 0), a2, voffA);
;             PG8_BAR; PG8_WAIT_L(0); PG8_MMA(1, 0, At, B0); PG8_BAR; PG8_SCHED;
.LBB0_286:
	s_add_u32 s24, s22, 0x100
	s_addc_u32 s25, s23, 0
	s_cmp_eq_u32 s57, 40
	s_cselect_b32 s29, s1, s25
	s_cselect_b32 s28, s0, s24
	s_cselect_b32 s27, s5, s56
	s_cselect_b32 s26, s4, s55
	v_lshl_add_u64 v[144:145], s[22:23], 0, v[136:137]
	s_add_i32 m0, s38, 0xc000
	s_nop 0
	global_load_lds_dwordx4 v[144:145], off
	v_lshl_add_u64 v[144:145], s[22:23], 0, v[138:139]
	s_add_i32 m0, s38, 0xe000
	s_nop 0
	global_load_lds_dwordx4 v[144:145], off
	ds_read_b128 v[154:157], v149
	ds_read_b128 v[158:161], v149 offset:1024
	ds_read_b128 v[166:169], v149 offset:2048
	ds_read_b128 v[170:173], v149 offset:3072
	ds_read_b128 v[182:185], v150
	ds_read_b128 v[190:193], v150 offset:1024
	ds_read_b128 v[194:197], v150 offset:2048
	ds_read_b128 v[198:201], v150 offset:3072
	ds_read_b128 v[202:205], v150 offset:4096
	ds_read_b128 v[206:209], v150 offset:5120
	ds_read_b128 v[210:213], v150 offset:6144
	ds_read_b128 v[214:217], v150 offset:7168
	s_waitcnt lgkmcnt(8)
	s_barrier
	s_waitcnt lgkmcnt(0)
	v_mfma_f32_16x16x32_bf16 v[124:127], v[154:157], v[182:185], v[124:127]
	v_mfma_f32_16x16x32_bf16 v[120:123], v[166:169], v[182:185], v[120:123]
	v_mfma_f32_16x16x32_bf16 v[108:111], v[154:157], v[194:197], v[108:111]
	v_mfma_f32_16x16x32_bf16 v[104:107], v[166:169], v[194:197], v[104:107]
	v_mfma_f32_16x16x32_bf16 v[92:95], v[154:157], v[202:205], v[92:95]
	v_mfma_f32_16x16x32_bf16 v[88:91], v[166:169], v[202:205], v[88:91]
	v_mfma_f32_16x16x32_bf16 v[76:79], v[154:157], v[210:213], v[76:79]
	v_mfma_f32_16x16x32_bf16 v[72:75], v[166:169], v[210:213], v[72:75]
	v_mfma_f32_16x16x32_bf16 v[124:127], v[158:161], v[190:193], v[124:127]
	v_mfma_f32_16x16x32_bf16 v[120:123], v[170:173], v[190:193], v[120:123]
	v_mfma_f32_16x16x32_bf16 v[108:111], v[158:161], v[198:201], v[108:111]
	v_mfma_f32_16x16x32_bf16 v[104:107], v[170:173], v[198:201], v[104:107]
	v_mfma_f32_16x16x32_bf16 v[92:95], v[158:161], v[206:209], v[92:95]
	v_mfma_f32_16x16x32_bf16 v[88:91], v[170:173], v[206:209], v[88:91]
	v_mfma_f32_16x16x32_bf16 v[76:79], v[158:161], v[214:217], v[76:79]
	v_mfma_f32_16x16x32_bf16 v[72:75], v[170:173], v[214:217], v[72:75]
	s_barrier
	s_add_i32 s22, s46, s37
	v_lshl_add_u64 v[144:145], s[26:27], 0, v[130:131]
	s_mov_b32 m0, s22
	s_nop 0
	global_load_lds_dwordx4 v[144:145], off
	v_lshl_add_u64 v[162:163], s[26:27], 0, v[134:135]
	s_add_i32 m0, s22, 0x2000
	s_nop 0
	global_load_lds_dwordx4 v[162:163], off
	ds_read_b128 v[218:221], v151
	ds_read_b128 v[222:225], v151 offset:1024
	ds_read_b128 v[226:229], v151 offset:2048
	ds_read_b128 v[230:233], v151 offset:3072
	s_barrier
	s_waitcnt lgkmcnt(0)
	v_mfma_f32_16x16x32_bf16 v[116:119], v[218:221], v[182:185], v[116:119]
	v_mfma_f32_16x16x32_bf16 v[112:115], v[226:229], v[182:185], v[112:115]
	v_mfma_f32_16x16x32_bf16 v[100:103], v[218:221], v[194:197], v[100:103]
	v_mfma_f32_16x16x32_bf16 v[96:99], v[226:229], v[194:197], v[96:99]
	v_mfma_f32_16x16x32_bf16 v[84:87], v[218:221], v[202:205], v[84:87]
	v_mfma_f32_16x16x32_bf16 v[80:83], v[226:229], v[202:205], v[80:83]
	v_mfma_f32_16x16x32_bf16 v[68:71], v[218:221], v[210:213], v[68:71]
	v_mfma_f32_16x16x32_bf16 v[64:67], v[226:229], v[210:213], v[64:67]
	v_mfma_f32_16x16x32_bf16 v[116:119], v[222:225], v[190:193], v[116:119]
	v_mfma_f32_16x16x32_bf16 v[112:115], v[230:233], v[190:193], v[112:115]
	v_mfma_f32_16x16x32_bf16 v[100:103], v[222:225], v[198:201], v[100:103]
	v_mfma_f32_16x16x32_bf16 v[96:99], v[230:233], v[198:201], v[96:99]
	v_mfma_f32_16x16x32_bf16 v[84:87], v[222:225], v[206:209], v[84:87]
	v_mfma_f32_16x16x32_bf16 v[80:83], v[230:233], v[206:209], v[80:83]
	v_mfma_f32_16x16x32_bf16 v[68:71], v[222:225], v[214:217], v[68:71]
	v_mfma_f32_16x16x32_bf16 v[64:67], v[230:233], v[214:217], v[64:67]
	s_mov_b32 m0, s38
	v_lshl_add_u64 v[174:175], s[28:29], 0, v[128:129]
	s_barrier
	global_load_lds_dwordx4 v[174:175], off
	v_lshl_add_u64 v[178:179], s[28:29], 0, v[132:133]
	s_mov_b32 m0, s39
	s_nop 0
	global_load_lds_dwordx4 v[178:179], off
	ds_read_b128 v[182:185], v150 offset:16384
	ds_read_b128 v[190:193], v150 offset:17408
	ds_read_b128 v[194:197], v150 offset:18432
	ds_read_b128 v[198:201], v150 offset:19456
	ds_read_b128 v[202:205], v150 offset:20480
	ds_read_b128 v[206:209], v150 offset:21504
	ds_read_b128 v[210:213], v150 offset:22528
	ds_read_b128 v[214:217], v150 offset:23552
	s_barrier
	s_waitcnt lgkmcnt(0)
	v_mfma_f32_16x16x32_bf16 v[60:63], v[154:157], v[182:185], v[60:63]
	v_mfma_f32_16x16x32_bf16 v[56:59], v[166:169], v[182:185], v[56:59]
	v_mfma_f32_16x16x32_bf16 v[48:51], v[154:157], v[194:197], v[48:51]
	v_mfma_f32_16x16x32_bf16 v[40:43], v[166:169], v[194:197], v[40:43]
	v_mfma_f32_16x16x32_bf16 v[32:35], v[154:157], v[202:205], v[32:35]
	v_mfma_f32_16x16x32_bf16 v[24:27], v[166:169], v[202:205], v[24:27]
	v_mfma_f32_16x16x32_bf16 v[16:19], v[154:157], v[210:213], v[16:19]
	v_mfma_f32_16x16x32_bf16 v[8:11], v[166:169], v[210:213], v[8:11]
	v_mfma_f32_16x16x32_bf16 v[60:63], v[158:161], v[190:193], v[60:63]
	v_mfma_f32_16x16x32_bf16 v[56:59], v[170:173], v[190:193], v[56:59]
	v_mfma_f32_16x16x32_bf16 v[48:51], v[158:161], v[198:201], v[48:51]
	v_mfma_f32_16x16x32_bf16 v[40:43], v[170:173], v[198:201], v[40:43]
	v_mfma_f32_16x16x32_bf16 v[32:35], v[158:161], v[206:209], v[32:35]
	v_mfma_f32_16x16x32_bf16 v[24:27], v[170:173], v[206:209], v[24:27]
	v_mfma_f32_16x16x32_bf16 v[16:19], v[158:161], v[214:217], v[16:19]
	v_mfma_f32_16x16x32_bf16 v[8:11], v[170:173], v[214:217], v[8:11]
	s_barrier
; #define PG8_STAGE(bufoff, gbase, voff) do { _Pragma("unroll") for (int _i = 0; _i < 2; ++_i) \
;         __builtin_amdgcn_global_load_lds((const unsigned*)((const char*)(gbase) + (voff)[_i]), (PG8_LAS unsigned*)(lds + (bufoff) + ldsw + _i * 8192), 16, 0, 0); } while (0)
; #define PG8_LDA(dst, b, h) do { _Pragma("unroll") for (int m = 0; m < 4; ++m) _Pragma("unroll") for (int k = 0; k < 2; ++k) dst[m][k] = *(const PG8_LAS bf16x8*)(lds + PG8_SA(b, h) + aoff + m * 2048 + k * 1024); } while (0)
; #define PG8_LDB(dst, b, h) do { _Pragma("unroll") for (int n = 0; n < 2; ++n) _Pragma("unroll") for (int k = 0; k < 2; ++k) dst[n][k] = *(const PG8_LAS bf16x8*)(lds + PG8_SB(b, h) + boff + n * 2048 + k * 1024); } while (0)
; #define PG8_MMA(ai, bj, At, Bt) do { __builtin_amdgcn_s_setprio(1); _Pragma("unroll") for (int m = 0; m < 4; ++m) _Pragma("unroll") for (int n = 0; n < 2; ++n) _Pragma("unroll") for (int k = 0; k < 2; ++k) \
;         acc[ai][bj][m][n] = __builtin_amdgcn_mfma_f32_16x16x32_bf16(Bt[n][k], At[m][k], acc[ai][bj][m][n], 0, 0, 0); __builtin_amdgcn_s_setprio(0); } while (0)
; #define PG8_WAIT_V(n) asm volatile("s_waitcnt vmcnt(" #n ")" ::: "memory")
; #define PG8_WAIT_L(n) asm volatile("s_waitcnt lgkmcnt(" #n ")" ::: "memory")
; #define PG8_BAR __builtin_amdgcn_s_barrier()
; #define PG8_SCHED __builtin_amdgcn_sched_barrier(0)
; template <class Epi, class Sched>
; __device__ __forceinline__ void gemm_phase(PG8_LAS unsigned char* lds, const Gemm g, const Sched& S, const Epi& E) {
;     ...
;             PG8_STAGE(PG8_SB(0, 1), b2 + hstep, voffB);
;             PG8_WAIT_V(6); PG8_BAR; PG8_MMA(1, 1, At, B1); PG8_BAR;
;             PG8_LDB(B0, 1, 0); PG8_SCHED; PG8_LDA(At, 1, 0); PG8_STAGE(PG8_SA(0, 1), a2 + hstep, voffA);
;             PG8_WAIT_L(8); PG8_BAR; PG8_WAIT_L(0); PG8_MMA(0, 0, At, B0); PG8_BAR; PG8_SCHED;
;             PG8_LDB(B1, 1, 1); PG8_STAGE(PG8_SB(1, 0), b3, voffB);
;             PG8_BAR; PG8_WAIT_L(0); PG8_MMA(0, 1, At, B1); PG8_BAR;
;             PG8_LDA(At, 1, 1); PG8_STAGE(PG8_SA(1, 0), a3, voffA);
;             PG8_BAR; PG8_WAIT_L(0); PG8_MMA(1, 0, At, B0); PG8_BAR; PG8_SCHED;
	s_add_u32 s22, s26, 0xb0000
	s_addc_u32 s23, s27, 0
	s_add_i32 s58, s47, s37
	v_lshl_add_u64 v[154:155], s[22:23], 0, v[130:131]
	s_mov_b32 m0, s58
	s_nop 0
	global_load_lds_dwordx4 v[154:155], off
	v_lshl_add_u64 v[154:155], s[22:23], 0, v[134:135]
	s_add_i32 m0, s58, 0x2000
	s_nop 0
	global_load_lds_dwordx4 v[154:155], off
	s_waitcnt vmcnt(6)
	s_barrier
	v_mfma_f32_16x16x32_bf16 v[52:55], v[218:221], v[182:185], v[52:55]
	v_mfma_f32_16x16x32_bf16 v[44:47], v[226:229], v[182:185], v[44:47]
	v_mfma_f32_16x16x32_bf16 v[36:39], v[218:221], v[194:197], v[36:39]
	v_mfma_f32_16x16x32_bf16 v[28:31], v[226:229], v[194:197], v[28:31]
	v_mfma_f32_16x16x32_bf16 v[20:23], v[218:221], v[202:205], v[20:23]
	v_mfma_f32_16x16x32_bf16 v[12:15], v[226:229], v[202:205], v[12:15]
	v_mfma_f32_16x16x32_bf16 v[4:7], v[218:221], v[210:213], v[4:7]
	v_mfma_f32_16x16x32_bf16 v[0:3], v[226:229], v[210:213], v[0:3]
	v_mfma_f32_16x16x32_bf16 v[52:55], v[222:225], v[190:193], v[52:55]
	v_mfma_f32_16x16x32_bf16 v[44:47], v[230:233], v[190:193], v[44:47]
	v_mfma_f32_16x16x32_bf16 v[36:39], v[222:225], v[198:201], v[36:39]
	v_mfma_f32_16x16x32_bf16 v[28:31], v[230:233], v[198:201], v[28:31]
	v_mfma_f32_16x16x32_bf16 v[20:23], v[222:225], v[206:209], v[20:23]
	v_mfma_f32_16x16x32_bf16 v[12:15], v[230:233], v[206:209], v[12:15]
	v_mfma_f32_16x16x32_bf16 v[4:7], v[222:225], v[214:217], v[4:7]
	v_mfma_f32_16x16x32_bf16 v[0:3], v[230:233], v[214:217], v[0:3]
	s_add_i32 s58, 0, 0x18000
	v_add_u32_e32 v153, s58, v147
	s_barrier
	s_add_u32 s22, s28, 0xb0000
	s_addc_u32 s23, s29, 0
	s_mov_b32 m0, s40
	v_lshl_add_u64 v[186:187], s[22:23], 0, v[128:129]
	global_load_lds_dwordx4 v[186:187], off
	v_lshl_add_u64 v[186:187], s[22:23], 0, v[132:133]
	s_mov_b32 m0, s41
	s_nop 0
	global_load_lds_dwordx4 v[186:187], off
	ds_read_b128 v[154:157], v153
	ds_read_b128 v[158:161], v153 offset:1024
	ds_read_b128 v[166:169], v153 offset:2048
	ds_read_b128 v[170:173], v153 offset:3072
	ds_read_b128 v[182:185], v150 offset:32768
	ds_read_b128 v[190:193], v150 offset:33792
	ds_read_b128 v[194:197], v150 offset:34816
	ds_read_b128 v[198:201], v150 offset:35840
	ds_read_b128 v[202:205], v150 offset:36864
	ds_read_b128 v[206:209], v150 offset:37888
	ds_read_b128 v[210:213], v150 offset:38912
	ds_read_b128 v[214:217], v150 offset:39936
	s_waitcnt lgkmcnt(8)
	s_barrier
	s_waitcnt lgkmcnt(0)
	v_mfma_f32_16x16x32_bf16 v[124:127], v[154:157], v[182:185], v[124:127]
	v_mfma_f32_16x16x32_bf16 v[120:123], v[166:169], v[182:185], v[120:123]
	v_mfma_f32_16x16x32_bf16 v[108:111], v[154:157], v[194:197], v[108:111]
	v_mfma_f32_16x16x32_bf16 v[104:107], v[166:169], v[194:197], v[104:107]
	v_mfma_f32_16x16x32_bf16 v[92:95], v[154:157], v[202:205], v[92:95]
	v_mfma_f32_16x16x32_bf16 v[88:91], v[166:169], v[202:205], v[88:91]
	v_mfma_f32_16x16x32_bf16 v[76:79], v[154:157], v[210:213], v[76:79]
	v_mfma_f32_16x16x32_bf16 v[72:75], v[166:169], v[210:213], v[72:75]
	v_mfma_f32_16x16x32_bf16 v[124:127], v[158:161], v[190:193], v[124:127]
	v_mfma_f32_16x16x32_bf16 v[120:123], v[170:173], v[190:193], v[120:123]
	v_mfma_f32_16x16x32_bf16 v[108:111], v[158:161], v[198:201], v[108:111]
	v_mfma_f32_16x16x32_bf16 v[104:107], v[170:173], v[198:201], v[104:107]
	v_mfma_f32_16x16x32_bf16 v[92:95], v[158:161], v[206:209], v[92:95]
	v_mfma_f32_16x16x32_bf16 v[88:91], v[170:173], v[206:209], v[88:91]
	v_mfma_f32_16x16x32_bf16 v[76:79], v[158:161], v[214:217], v[76:79]
	v_mfma_f32_16x16x32_bf16 v[72:75], v[170:173], v[214:217], v[72:75]
	s_barrier
	s_add_i32 s28, 0, 0x1c000
	s_add_i32 s22, s58, s37
	v_add_u32_e32 v153, s28, v147
	v_lshl_add_u64 v[144:145], v[144:145], 0, s[14:15]
	s_mov_b32 m0, s22
	s_nop 0
	global_load_lds_dwordx4 v[144:145], off
	v_lshl_add_u64 v[144:145], v[162:163], 0, s[14:15]
	s_add_i32 m0, s22, 0x2000
	s_nop 0
	global_load_lds_dwordx4 v[144:145], off
	ds_read_b128 v[218:221], v153
	ds_read_b128 v[222:225], v153 offset:1024
	ds_read_b128 v[226:229], v153 offset:2048
	ds_read_b128 v[230:233], v153 offset:3072
	s_barrier
	s_waitcnt lgkmcnt(0)
	v_mfma_f32_16x16x32_bf16 v[116:119], v[218:221], v[182:185], v[116:119]
	v_mfma_f32_16x16x32_bf16 v[112:115], v[226:229], v[182:185], v[112:115]
	v_mfma_f32_16x16x32_bf16 v[100:103], v[218:221], v[194:197], v[100:103]
	v_mfma_f32_16x16x32_bf16 v[96:99], v[226:229], v[194:197], v[96:99]
	v_mfma_f32_16x16x32_bf16 v[84:87], v[218:221], v[202:205], v[84:87]
	v_mfma_f32_16x16x32_bf16 v[80:83], v[226:229], v[202:205], v[80:83]
	v_mfma_f32_16x16x32_bf16 v[68:71], v[218:221], v[210:213], v[68:71]
	v_mfma_f32_16x16x32_bf16 v[64:67], v[226:229], v[210:213], v[64:67]
	v_mfma_f32_16x16x32_bf16 v[116:119], v[222:225], v[190:193], v[116:119]
	v_mfma_f32_16x16x32_bf16 v[112:115], v[230:233], v[190:193], v[112:115]
	v_mfma_f32_16x16x32_bf16 v[100:103], v[222:225], v[198:201], v[100:103]
	v_mfma_f32_16x16x32_bf16 v[96:99], v[230:233], v[198:201], v[96:99]
	v_mfma_f32_16x16x32_bf16 v[84:87], v[222:225], v[206:209], v[84:87]
	v_mfma_f32_16x16x32_bf16 v[80:83], v[230:233], v[206:209], v[80:83]
	v_mfma_f32_16x16x32_bf16 v[68:71], v[222:225], v[214:217], v[68:71]
	v_mfma_f32_16x16x32_bf16 v[64:67], v[230:233], v[214:217], v[64:67]
	s_mov_b32 m0, s43
	v_lshl_add_u64 v[144:145], v[174:175], 0, s[14:15]
	s_barrier
	global_load_lds_dwordx4 v[144:145], off
	v_lshl_add_u64 v[144:145], v[178:179], 0, s[14:15]
	s_mov_b32 m0, s44
	s_nop 0
	global_load_lds_dwordx4 v[144:145], off
	ds_read_b128 v[182:185], v150 offset:49152
	ds_read_b128 v[190:193], v150 offset:50176
	ds_read_b128 v[194:197], v150 offset:51200
	ds_read_b128 v[198:201], v150 offset:52224
	ds_read_b128 v[202:205], v150 offset:53248
	ds_read_b128 v[206:209], v150 offset:54272
	ds_read_b128 v[210:213], v150 offset:55296
	ds_read_b128 v[214:217], v150 offset:56320
	s_barrier
; __device__ __forceinline__ unsigned cvt_pk_bf16(float lo, float hi) { unsigned r; asm volatile("v_cvt_pk_bf16_f32 %0, %1, %2" : "=v"(r) : "v"(lo), "v"(hi)); return r; }
; __device__ __forceinline__ float flogsig16(float x) { return (fminf(x, 0.f) - __logf(1.0f + __expf(-fabsf(x)))) * 0.0625f; }
; #define PG8_WAIT_V(n) asm volatile("s_waitcnt vmcnt(" #n ")" ::: "memory")
; #define PG8_WAIT_L(n) asm volatile("s_waitcnt lgkmcnt(" #n ")" ::: "memory")
;     __device__ __forceinline__ void operator()(const f32x4 (&acc)[2][2][4][2], const Unit& u, int wr, int wc, int fr, int fq) const {
;     ...
;         const int row0 = u.pm * BM + wr * 64 + fr, col0 = u.pn * BM + wc * 32 + 8 * fq, bcol0 = wc * 32 + 8 * fq;
;         f32x4 bv[2][2];
; #pragma unroll
;         for (int bj = 0; bj < 2; ++bj)
; #pragma unroll
;             for (int n = 0; n < 2; ++n) bv[bj][n] = bias ? *(const f32x4*)(bias + bcol0 + bj * HALF + 4 * n) : (f32x4){0.f, 0.f, 0.f, 0.f};
; #pragma unroll
;         for (int ai = 0; ai < 2; ++ai)
; #pragma unroll
;             for (int m = 0; m < 4; ++m) { bf16_t* rowp = O + (size_t)(row0 + ai * HALF + m * 16) * ldc + col0;
; #pragma unroll
;                 for (int bj = 0; bj < 2; ++bj) { f32x4 v0 = acc[ai][bj][m][0] + bv[bj][0], v1 = acc[ai][bj][m][1] + bv[bj][1];
;                     if (act == 1) {
; #pragma unroll
;                         for (int j = 0; j < 1; ++j) { v0 = v0 * sigmoid4(v0); v1 = v1 * sigmoid4(v1); } }
;                     else if (act == 2) {
; #pragma unroll
;                         for (int j = 0; j < 1; ++j) { v0 = sigmoid4(v0); v1 = sigmoid4(v1); } }
;                     else if (act == 3) {
; #pragma unroll
;                         for (int j = 0; j < 4; ++j) { v0[j] = flogsig16(v0[j]); v1[j] = flogsig16(v1[j]); } }
;                     u32x4 w; w.x = cvt_pk_bf16(v0[0], v0[1]); w.y = cvt_pk_bf16(v0[2], v0[3]); w.z = cvt_pk_bf16(v1[0], v1[1]); w.w = cvt_pk_bf16(v1[2], v1[3]);
;                     *(u32x4*)(rowp + bj * HALF) = w; } }
; template <class Epi, class Sched>
; __device__ __forceinline__ void gemm_phase(PG8_LAS unsigned char* lds, const Gemm g, const Sched& S, const Epi& E) {
;     ...
;             PG8_BAR; PG8_WAIT_L(0); PG8_MMA(1, 0, At, B0); PG8_BAR; PG8_SCHED;
;             PG8_STAGE(PG8_SB(1, 1), b3 + hstep, voffB);
;             PG8_WAIT_V(6); PG8_BAR; PG8_MMA(1, 1, At, B1); PG8_BAR;
	s_waitcnt lgkmcnt(0)
	v_mfma_f32_16x16x32_bf16 v[60:63], v[154:157], v[182:185], v[60:63]
	v_mfma_f32_16x16x32_bf16 v[56:59], v[166:169], v[182:185], v[56:59]
	v_mfma_f32_16x16x32_bf16 v[48:51], v[154:157], v[194:197], v[48:51]
	v_mfma_f32_16x16x32_bf16 v[40:43], v[166:169], v[194:197], v[40:43]
	v_mfma_f32_16x16x32_bf16 v[32:35], v[154:157], v[202:205], v[32:35]
	v_mfma_f32_16x16x32_bf16 v[24:27], v[166:169], v[202:205], v[24:27]
	v_mfma_f32_16x16x32_bf16 v[16:19], v[154:157], v[210:213], v[16:19]
	v_mfma_f32_16x16x32_bf16 v[8:11], v[166:169], v[210:213], v[8:11]
	v_mfma_f32_16x16x32_bf16 v[60:63], v[158:161], v[190:193], v[60:63]
	v_mfma_f32_16x16x32_bf16 v[56:59], v[170:173], v[190:193], v[56:59]
	v_mfma_f32_16x16x32_bf16 v[48:51], v[158:161], v[198:201], v[48:51]
	v_mfma_f32_16x16x32_bf16 v[40:43], v[170:173], v[198:201], v[40:43]
	v_mfma_f32_16x16x32_bf16 v[32:35], v[158:161], v[206:209], v[32:35]
	v_mfma_f32_16x16x32_bf16 v[24:27], v[170:173], v[206:209], v[24:27]
	v_mfma_f32_16x16x32_bf16 v[16:19], v[158:161], v[214:217], v[16:19]
	v_mfma_f32_16x16x32_bf16 v[8:11], v[170:173], v[214:217], v[8:11]
	s_barrier
	s_add_u32 s22, s26, 0xb0080
	s_addc_u32 s23, s27, 0
	s_add_i32 s26, s28, s37
	v_lshl_add_u64 v[144:145], s[22:23], 0, v[130:131]
	s_mov_b32 m0, s26
	s_nop 0
	global_load_lds_dwordx4 v[144:145], off
	v_lshl_add_u64 v[144:145], s[22:23], 0, v[134:135]
	s_add_i32 m0, s26, 0x2000
	s_nop 0
	global_load_lds_dwordx4 v[144:145], off
	s_waitcnt vmcnt(6)
	s_barrier
	v_mfma_f32_16x16x32_bf16 v[52:55], v[218:221], v[182:185], v[52:55]
	v_mfma_f32_16x16x32_bf16 v[44:47], v[226:229], v[182:185], v[44:47]
	v_mfma_f32_16x16x32_bf16 v[36:39], v[218:221], v[194:197], v[36:39]
	v_mfma_f32_16x16x32_bf16 v[28:31], v[226:229], v[194:197], v[28:31]
	v_mfma_f32_16x16x32_bf16 v[20:23], v[218:221], v[202:205], v[20:23]
	v_mfma_f32_16x16x32_bf16 v[12:15], v[226:229], v[202:205], v[12:15]
	v_mfma_f32_16x16x32_bf16 v[4:7], v[218:221], v[210:213], v[4:7]
	v_mfma_f32_16x16x32_bf16 v[0:3], v[226:229], v[210:213], v[0:3]
	v_mfma_f32_16x16x32_bf16 v[52:55], v[222:225], v[190:193], v[52:55]
	v_mfma_f32_16x16x32_bf16 v[44:47], v[230:233], v[190:193], v[44:47]
	v_mfma_f32_16x16x32_bf16 v[36:39], v[222:225], v[198:201], v[36:39]
	v_mfma_f32_16x16x32_bf16 v[28:31], v[230:233], v[198:201], v[28:31]
	v_mfma_f32_16x16x32_bf16 v[20:23], v[222:225], v[206:209], v[20:23]
	v_mfma_f32_16x16x32_bf16 v[12:15], v[230:233], v[206:209], v[12:15]
	v_mfma_f32_16x16x32_bf16 v[4:7], v[222:225], v[214:217], v[4:7]
	v_mfma_f32_16x16x32_bf16 v[0:3], v[230:233], v[214:217], v[0:3]
	s_add_i32 s57, s57, 2
	s_add_u32 s55, s55, 0x100
	s_addc_u32 s56, s56, 0
	s_cmp_gt_u32 s57, 41
	s_mov_b64 s[22:23], s[24:25]
	s_barrier
	s_cbranch_scc0 .LBB0_286
	v_lshl_add_u32 v154, s53, 8, v146
	v_lshl_or_b32 v144, s54, 8, v148
	v_ashrrev_i32_e32 v155, 31, v154
	v_ashrrev_i32_e32 v145, 31, v144
	v_lshlrev_b64 v[156:157], 11, v[154:155]
	v_lshl_add_u64 v[156:157], s[10:11], 0, v[156:157]
	v_lshlrev_b64 v[158:159], 1, v[144:145]
	v_lshl_add_u64 v[144:145], v[156:157], 0, v[158:159]
	v_pk_add_f32 v[126:127], v[126:127], 0 op_sel_hi:[1,0]
	v_pk_add_f32 v[124:125], v[124:125], 0 op_sel_hi:[1,0]
	v_pk_add_f32 v[156:157], v[122:123], 0 op_sel_hi:[1,0]
	v_pk_add_f32 v[122:123], v[120:121], 0 op_sel_hi:[1,0]
	v_cvt_pk_bf16_f32 v120, v124, v125
	v_cvt_pk_bf16_f32 v121, v126, v127
	v_pk_add_f32 v[116:117], v[116:117], 0 op_sel_hi:[1,0]
	v_cvt_pk_bf16_f32 v122, v122, v123
	v_cvt_pk_bf16_f32 v123, v156, v157
	global_store_dwordx4 v[144:145], v[120:123], off
	v_pk_add_f32 v[118:119], v[118:119], 0 op_sel_hi:[1,0]
	v_pk_add_f32 v[110:111], v[110:111], 0 op_sel_hi:[1,0]
	v_pk_add_f32 v[120:121], v[114:115], 0 op_sel_hi:[1,0]
	v_pk_add_f32 v[114:115], v[112:113], 0 op_sel_hi:[1,0]
	v_cvt_pk_bf16_f32 v112, v116, v117
	v_cvt_pk_bf16_f32 v113, v118, v119
	v_pk_add_f32 v[108:109], v[108:109], 0 op_sel_hi:[1,0]
	v_cvt_pk_bf16_f32 v114, v114, v115
	v_cvt_pk_bf16_f32 v115, v120, v121
	global_store_dwordx4 v[144:145], v[112:115], off offset:256
	v_pk_add_f32 v[100:101], v[100:101], 0 op_sel_hi:[1,0]
	v_pk_add_f32 v[102:103], v[102:103], 0 op_sel_hi:[1,0]
	v_or_b32_e32 v112, 16, v154
	v_ashrrev_i32_e32 v113, 31, v112
	v_lshlrev_b64 v[112:113], 11, v[112:113]
	v_lshl_add_u64 v[112:113], s[10:11], 0, v[112:113]
	v_lshl_add_u64 v[112:113], v[112:113], 0, v[158:159]
	v_pk_add_f32 v[114:115], v[106:107], 0 op_sel_hi:[1,0]
	v_pk_add_f32 v[106:107], v[104:105], 0 op_sel_hi:[1,0]
	v_cvt_pk_bf16_f32 v104, v108, v109
	v_cvt_pk_bf16_f32 v105, v110, v111
	v_pk_add_f32 v[94:95], v[94:95], 0 op_sel_hi:[1,0]
	v_cvt_pk_bf16_f32 v106, v106, v107
	v_cvt_pk_bf16_f32 v107, v114, v115
	global_store_dwordx4 v[112:113], v[104:107], off
	v_pk_add_f32 v[92:93], v[92:93], 0 op_sel_hi:[1,0]
	v_pk_add_f32 v[84:85], v[84:85], 0 op_sel_hi:[1,0]
	v_pk_add_f32 v[104:105], v[98:99], 0 op_sel_hi:[1,0]
	v_pk_add_f32 v[98:99], v[96:97], 0 op_sel_hi:[1,0]
	v_cvt_pk_bf16_f32 v96, v100, v101
	v_cvt_pk_bf16_f32 v97, v102, v103
	v_pk_add_f32 v[86:87], v[86:87], 0 op_sel_hi:[1,0]
	v_cvt_pk_bf16_f32 v98, v98, v99
	v_cvt_pk_bf16_f32 v99, v104, v105
	global_store_dwordx4 v[112:113], v[96:99], off offset:256
	v_pk_add_f32 v[78:79], v[78:79], 0 op_sel_hi:[1,0]
	v_pk_add_f32 v[76:77], v[76:77], 0 op_sel_hi:[1,0]
	v_or_b32_e32 v96, 32, v154
	v_ashrrev_i32_e32 v97, 31, v96
	v_lshlrev_b64 v[96:97], 11, v[96:97]
	v_lshl_add_u64 v[96:97], s[10:11], 0, v[96:97]
	v_lshl_add_u64 v[96:97], v[96:97], 0, v[158:159]
; __device__ __forceinline__ unsigned cvt_pk_bf16(float lo, float hi) { unsigned r; asm volatile("v_cvt_pk_bf16_f32 %0, %1, %2" : "=v"(r) : "v"(lo), "v"(hi)); return r; }
; __device__ __forceinline__ float flogsig16(float x) { return (fminf(x, 0.f) - __logf(1.0f + __expf(-fabsf(x)))) * 0.0625f; }
; #define PG8_WAIT_V(n) asm volatile("s_waitcnt vmcnt(" #n ")" ::: "memory")
; #define PG8_BAR __builtin_amdgcn_s_barrier()
;     __device__ __forceinline__ void operator()(const f32x4 (&acc)[2][2][4][2], const Unit& u, int wr, int wc, int fr, int fq) const {
;     ...
;             for (int m = 0; m < 4; ++m) { bf16_t* rowp = O + (size_t)(row0 + ai * HALF + m * 16) * ldc + col0;
; #pragma unroll
;                 for (int bj = 0; bj < 2; ++bj) { f32x4 v0 = acc[ai][bj][m][0] + bv[bj][0], v1 = acc[ai][bj][m][1] + bv[bj][1];
;                     if (act == 1) {
; #pragma unroll
;                         for (int j = 0; j < 1; ++j) { v0 = v0 * sigmoid4(v0); v1 = v1 * sigmoid4(v1); } }
;                     else if (act == 2) {
; #pragma unroll
;                         for (int j = 0; j < 1; ++j) { v0 = sigmoid4(v0); v1 = sigmoid4(v1); } }
;                     else if (act == 3) {
; #pragma unroll
;                         for (int j = 0; j < 4; ++j) { v0[j] = flogsig16(v0[j]); v1[j] = flogsig16(v1[j]); } }
;                     u32x4 w; w.x = cvt_pk_bf16(v0[0], v0[1]); w.y = cvt_pk_bf16(v0[2], v0[3]); w.z = cvt_pk_bf16(v1[0], v1[1]); w.w = cvt_pk_bf16(v1[2], v1[3]);
;                     *(u32x4*)(rowp + bj * HALF) = w; } }
; template <class Epi, class Sched>
; __device__ __forceinline__ void gemm_phase(PG8_LAS unsigned char* lds, const Gemm g, const Sched& S, const Epi& E) {
;     ...
;         if (!has_next) break;
; #pragma unroll
;         for (int a = 0; a < 2; ++a)
; #pragma unroll
;             for (int b = 0; b < 2; ++b)
; #pragma unroll
;                 for (int m = 0; m < 4; ++m)
; #pragma unroll
;                     for (int n = 0; n < 2; ++n) acc[a][b][m][n] = (f32x4){0.f, 0.f, 0.f, 0.f};
;         cur = nxt; cA = nA; cB = nB; ++ui;
;     }
;     PG8_WAIT_V(0);
;     if (wr == 0) PG8_BAR;
;     PG8_BAR;
	v_pk_add_f32 v[98:99], v[90:91], 0 op_sel_hi:[1,0]
	v_pk_add_f32 v[90:91], v[88:89], 0 op_sel_hi:[1,0]
	v_cvt_pk_bf16_f32 v88, v92, v93
	v_cvt_pk_bf16_f32 v89, v94, v95
	v_pk_add_f32 v[70:71], v[70:71], 0 op_sel_hi:[1,0]
	v_cvt_pk_bf16_f32 v90, v90, v91
	v_cvt_pk_bf16_f32 v91, v98, v99
	global_store_dwordx4 v[96:97], v[88:91], off
	v_pk_add_f32 v[68:69], v[68:69], 0 op_sel_hi:[1,0]
	s_mov_b64 s[22:23], 0x40000
	v_pk_add_f32 v[88:89], v[82:83], 0 op_sel_hi:[1,0]
	v_pk_add_f32 v[82:83], v[80:81], 0 op_sel_hi:[1,0]
	v_cvt_pk_bf16_f32 v80, v84, v85
	v_cvt_pk_bf16_f32 v81, v86, v87
	v_pk_add_f32 v[60:61], v[60:61], 0 op_sel_hi:[1,0]
	v_cvt_pk_bf16_f32 v82, v82, v83
	v_cvt_pk_bf16_f32 v83, v88, v89
	global_store_dwordx4 v[96:97], v[80:83], off offset:256
	v_pk_add_f32 v[62:63], v[62:63], 0 op_sel_hi:[1,0]
	v_pk_add_f32 v[54:55], v[54:55], 0 op_sel_hi:[1,0]
	v_or_b32_e32 v80, 48, v154
	v_ashrrev_i32_e32 v81, 31, v80
	v_lshlrev_b64 v[80:81], 11, v[80:81]
	v_lshl_add_u64 v[80:81], s[10:11], 0, v[80:81]
	v_lshl_add_u64 v[80:81], v[80:81], 0, v[158:159]
	v_pk_add_f32 v[82:83], v[74:75], 0 op_sel_hi:[1,0]
	v_pk_add_f32 v[74:75], v[72:73], 0 op_sel_hi:[1,0]
	v_cvt_pk_bf16_f32 v72, v76, v77
	v_cvt_pk_bf16_f32 v73, v78, v79
	v_pk_add_f32 v[52:53], v[52:53], 0 op_sel_hi:[1,0]
	v_cvt_pk_bf16_f32 v74, v74, v75
	v_cvt_pk_bf16_f32 v75, v82, v83
	global_store_dwordx4 v[80:81], v[72:75], off
	v_pk_add_f32 v[48:49], v[48:49], 0 op_sel_hi:[1,0]
	v_pk_add_f32 v[38:39], v[38:39], 0 op_sel_hi:[1,0]
	v_pk_add_f32 v[72:73], v[66:67], 0 op_sel_hi:[1,0]
	v_pk_add_f32 v[66:67], v[64:65], 0 op_sel_hi:[1,0]
	v_cvt_pk_bf16_f32 v64, v68, v69
	v_cvt_pk_bf16_f32 v65, v70, v71
	v_pk_add_f32 v[36:37], v[36:37], 0 op_sel_hi:[1,0]
	v_cvt_pk_bf16_f32 v66, v66, v67
	v_cvt_pk_bf16_f32 v67, v72, v73
	global_store_dwordx4 v[80:81], v[64:67], off offset:256
	v_pk_add_f32 v[32:33], v[32:33], 0 op_sel_hi:[1,0]
	v_pk_add_f32 v[22:23], v[22:23], 0 op_sel_hi:[1,0]
	v_lshl_add_u64 v[64:65], v[144:145], 0, s[22:23]
	s_mov_b32 s22, 0x40000
	v_pk_add_f32 v[66:67], v[58:59], 0 op_sel_hi:[1,0]
	v_pk_add_f32 v[58:59], v[56:57], 0 op_sel_hi:[1,0]
	v_cvt_pk_bf16_f32 v56, v60, v61
	v_add_co_u32_e32 v60, vcc, s22, v144
	v_cvt_pk_bf16_f32 v57, v62, v63
	v_cvt_pk_bf16_f32 v58, v58, v59
	v_cvt_pk_bf16_f32 v59, v66, v67
	s_mov_b64 s[22:23], 0x48000
	s_nop 0
	v_addc_co_u32_e32 v61, vcc, 0, v145, vcc
	global_store_dwordx4 v[60:61], v[56:59], off
	v_pk_add_f32 v[20:21], v[20:21], 0 op_sel_hi:[1,0]
	v_pk_add_f32 v[16:17], v[16:17], 0 op_sel_hi:[1,0]
	v_pk_add_f32 v[56:57], v[46:47], 0 op_sel_hi:[1,0]
	v_pk_add_f32 v[46:47], v[44:45], 0 op_sel_hi:[1,0]
	v_cvt_pk_bf16_f32 v44, v52, v53
	v_cvt_pk_bf16_f32 v45, v54, v55
	s_mov_b32 s54, s51
	v_cvt_pk_bf16_f32 v46, v46, v47
	v_cvt_pk_bf16_f32 v47, v56, v57
	global_store_dwordx4 v[64:65], v[44:47], off offset:256
	s_mov_b32 s53, s52
	s_mov_b64 s[24:25], s[4:5]
	v_pk_add_f32 v[46:47], v[50:51], 0 op_sel_hi:[1,0]
	v_pk_add_f32 v[50:51], v[42:43], 0 op_sel_hi:[1,0]
	v_pk_add_f32 v[42:43], v[40:41], 0 op_sel_hi:[1,0]
	v_cvt_pk_bf16_f32 v40, v48, v49
	v_cvt_pk_bf16_f32 v41, v46, v47
	v_add_co_u32_e32 v46, vcc, s48, v144
	v_cvt_pk_bf16_f32 v42, v42, v43
	v_cvt_pk_bf16_f32 v43, v50, v51
	v_lshl_add_u64 v[44:45], v[144:145], 0, s[22:23]
	s_nop 0
	v_addc_co_u32_e32 v47, vcc, 0, v145, vcc
	global_store_dwordx4 v[46:47], v[40:43], off
	s_mov_b64 s[22:23], s[0:1]
	v_pk_add_f32 v[6:7], v[6:7], 0 op_sel_hi:[1,0]
	v_pk_add_f32 v[40:41], v[30:31], 0 op_sel_hi:[1,0]
	v_pk_add_f32 v[30:31], v[28:29], 0 op_sel_hi:[1,0]
	v_cvt_pk_bf16_f32 v28, v36, v37
	v_cvt_pk_bf16_f32 v29, v38, v39
	v_pk_add_f32 v[4:5], v[4:5], 0 op_sel_hi:[1,0]
	v_cvt_pk_bf16_f32 v30, v30, v31
	v_cvt_pk_bf16_f32 v31, v40, v41
	global_store_dwordx4 v[44:45], v[28:31], off offset:256
	s_nop 1
	v_pk_add_f32 v[30:31], v[34:35], 0 op_sel_hi:[1,0]
	v_pk_add_f32 v[34:35], v[26:27], 0 op_sel_hi:[1,0]
	v_pk_add_f32 v[26:27], v[24:25], 0 op_sel_hi:[1,0]
	v_cvt_pk_bf16_f32 v24, v32, v33
	v_cvt_pk_bf16_f32 v25, v30, v31
	v_add_co_u32_e32 v30, vcc, s49, v144
	v_cvt_pk_bf16_f32 v26, v26, v27
	v_cvt_pk_bf16_f32 v27, v34, v35
	v_lshl_add_u64 v[28:29], v[144:145], 0, s[16:17]
	s_nop 0
	v_addc_co_u32_e32 v31, vcc, 0, v145, vcc
	global_store_dwordx4 v[30:31], v[24:27], off
	s_nop 1
	v_pk_add_f32 v[24:25], v[14:15], 0 op_sel_hi:[1,0]
	v_pk_add_f32 v[14:15], v[12:13], 0 op_sel_hi:[1,0]
	v_cvt_pk_bf16_f32 v12, v20, v21
	v_cvt_pk_bf16_f32 v13, v22, v23
	s_nop 0
	v_cvt_pk_bf16_f32 v14, v14, v15
	v_cvt_pk_bf16_f32 v15, v24, v25
	global_store_dwordx4 v[28:29], v[12:15], off offset:256
	s_nop 1
	v_pk_add_f32 v[14:15], v[18:19], 0 op_sel_hi:[1,0]
	v_pk_add_f32 v[18:19], v[10:11], 0 op_sel_hi:[1,0]
	v_pk_add_f32 v[10:11], v[8:9], 0 op_sel_hi:[1,0]
	v_cvt_pk_bf16_f32 v8, v16, v17
	v_cvt_pk_bf16_f32 v9, v14, v15
	v_add_co_u32_e32 v14, vcc, s50, v144
	v_lshl_add_u64 v[12:13], v[144:145], 0, s[18:19]
	s_nop 0
	v_addc_co_u32_e32 v15, vcc, 0, v145, vcc
	v_cvt_pk_bf16_f32 v10, v10, v11
	v_cvt_pk_bf16_f32 v11, v18, v19
	global_store_dwordx4 v[14:15], v[8:11], off
	s_and_b64 vcc, exec, s[2:3]
	s_nop 0
	v_pk_add_f32 v[8:9], v[2:3], 0 op_sel_hi:[1,0]
	v_pk_add_f32 v[2:3], v[0:1], 0 op_sel_hi:[1,0]
	v_cvt_pk_bf16_f32 v0, v4, v5
	v_cvt_pk_bf16_f32 v1, v6, v7
	s_nop 0
	v_cvt_pk_bf16_f32 v2, v2, v3
	v_cvt_pk_bf16_f32 v3, v8, v9
	global_store_dwordx4 v[12:13], v[0:3], off offset:256
	s_cbranch_vccz .LBB0_275
	s_waitcnt vmcnt(0)
	s_cmpk_gt_u32 s31, 0xff
	s_cbranch_scc1 .LBB0_290
	s_barrier

; #define PG8_STAGE(bufoff, gbase, voff) do { _Pragma("unroll") for (int _i = 0; _i < 2; ++_i) \
;         __builtin_amdgcn_global_load_lds((const unsigned*)((const char*)(gbase) + (voff)[_i]), (PG8_LAS unsigned*)(lds + (bufoff) + ldsw + _i * 8192), 16, 0, 0); } while (0)
; #define PG8_LDA(dst, b, h) do { _Pragma("unroll") for (int m = 0; m < 4; ++m) _Pragma("unroll") for (int k = 0; k < 2; ++k) dst[m][k] = *(const PG8_LAS bf16x8*)(lds + PG8_SA(b, h) + aoff + m * 2048 + k * 1024); } while (0)
; #define PG8_LDB(dst, b, h) do { _Pragma("unroll") for (int n = 0; n < 2; ++n) _Pragma("unroll") for (int k = 0; k < 2; ++k) dst[n][k] = *(const PG8_LAS bf16x8*)(lds + PG8_SB(b, h) + boff + n * 2048 + k * 1024); } while (0)
; #define PG8_MMA(ai, bj, At, Bt) do { __builtin_amdgcn_s_setprio(1); _Pragma("unroll") for (int m = 0; m < 4; ++m) _Pragma("unroll") for (int n = 0; n < 2; ++n) _Pragma("unroll") for (int k = 0; k < 2; ++k) \
;         acc[ai][bj][m][n] = __builtin_amdgcn_mfma_f32_16x16x32_bf16(Bt[n][k], At[m][k], acc[ai][bj][m][n], 0, 0, 0); __builtin_amdgcn_s_setprio(0); } while (0)
; #define PG8_WAIT_V(n) asm volatile("s_waitcnt vmcnt(" #n ")" ::: "memory")
; #define PG8_WAIT_L(n) asm volatile("s_waitcnt lgkmcnt(" #n ")" ::: "memory")
; #define PG8_BAR __builtin_amdgcn_s_barrier()
; #define PG8_SCHED __builtin_amdgcn_sched_barrier(0)
; template <class Epi, class Sched>
; __device__ __forceinline__ void gemm_phase(PG8_LAS unsigned char* lds, const Gemm g, const Sched& S, const Epi& E) {
;     ...
;             PG8_LDB(B0, 0, 0); PG8_SCHED; PG8_LDA(At, 0, 0); PG8_STAGE(PG8_SA(1, 1), a1 + hstep, voffA);
;             PG8_WAIT_L(8); PG8_BAR; PG8_WAIT_L(0); PG8_MMA(0, 0, At, B0); PG8_BAR; PG8_SCHED;
;             PG8_LDB(B1, 0, 1); PG8_STAGE(PG8_SB(0, 0), b2, voffB);
;             PG8_BAR; PG8_WAIT_L(0); PG8_MMA(0, 1, At, B1); PG8_BAR;
;             PG8_LDA(At, 0, 1); PG8_STAGE(PG8_SA(0, 0), a2, voffA);
;             PG8_BAR; PG8_WAIT_L(0); PG8_MMA(1, 0, At, B0); PG8_BAR; PG8_SCHED;
;             PG8_STAGE(PG8_SB(0, 1), b2 + hstep, voffB);
;             PG8_WAIT_V(6); PG8_BAR; PG8_MMA(1, 1, At, B1); PG8_BAR;
.LBB0_416:
	s_add_u32 s4, s0, 0xfffc0080
	s_addc_u32 s5, s1, -1
	s_cmp_eq_u32 s53, 12
	s_cselect_b32 s29, s7, s5
	s_cselect_b32 s28, s10, s4
	s_cselect_b32 s5, s19, s52
	s_cselect_b32 s4, s21, s51
	v_lshl_add_u64 v[174:175], s[0:1], 0, v[166:167]
	s_add_i32 m0, s27, 0xc000
	s_nop 0
	global_load_lds_dwordx4 v[174:175], off
	v_lshl_add_u64 v[174:175], s[0:1], 0, v[168:169]
	s_add_i32 m0, s27, 0xe000
	s_nop 0
	global_load_lds_dwordx4 v[174:175], off
	ds_read_b128 v[24:27], v186
	ds_read_b128 v[28:31], v186 offset:1024
	ds_read_b128 v[40:43], v186 offset:2048
	ds_read_b128 v[44:47], v186 offset:3072
	ds_read_b128 v[144:147], v187
	ds_read_b128 v[148:151], v187 offset:1024
	ds_read_b128 v[182:185], v187 offset:2048
	ds_read_b128 v[192:195], v187 offset:3072
	ds_read_b128 v[196:199], v187 offset:4096
	ds_read_b128 v[200:203], v187 offset:5120
	ds_read_b128 v[204:207], v187 offset:6144
	ds_read_b128 v[208:211], v187 offset:7168
	s_waitcnt lgkmcnt(8)
	s_barrier
	s_waitcnt lgkmcnt(0)
	v_mfma_f32_16x16x32_bf16 v[140:143], v[24:27], v[144:147], v[140:143]
	v_mfma_f32_16x16x32_bf16 v[136:139], v[40:43], v[144:147], v[136:139]
	v_mfma_f32_16x16x32_bf16 v[124:127], v[24:27], v[182:185], v[124:127]
	v_mfma_f32_16x16x32_bf16 v[120:123], v[40:43], v[182:185], v[120:123]
	v_mfma_f32_16x16x32_bf16 v[108:111], v[24:27], v[196:199], v[108:111]
	v_mfma_f32_16x16x32_bf16 v[104:107], v[40:43], v[196:199], v[104:107]
	v_mfma_f32_16x16x32_bf16 v[92:95], v[24:27], v[204:207], v[92:95]
	v_mfma_f32_16x16x32_bf16 v[88:91], v[40:43], v[204:207], v[88:91]
	v_mfma_f32_16x16x32_bf16 v[140:143], v[28:31], v[148:151], v[140:143]
	v_mfma_f32_16x16x32_bf16 v[136:139], v[44:47], v[148:151], v[136:139]
	v_mfma_f32_16x16x32_bf16 v[124:127], v[28:31], v[192:195], v[124:127]
	v_mfma_f32_16x16x32_bf16 v[120:123], v[44:47], v[192:195], v[120:123]
	v_mfma_f32_16x16x32_bf16 v[108:111], v[28:31], v[200:203], v[108:111]
	v_mfma_f32_16x16x32_bf16 v[104:107], v[44:47], v[200:203], v[104:107]
	v_mfma_f32_16x16x32_bf16 v[92:95], v[28:31], v[208:211], v[92:95]
	v_mfma_f32_16x16x32_bf16 v[88:91], v[44:47], v[208:211], v[88:91]
	s_barrier
	s_add_i32 s54, s43, s35
	v_lshl_add_u64 v[174:175], s[4:5], 0, v[156:157]
	s_mov_b32 m0, s54
	s_nop 0
	global_load_lds_dwordx4 v[174:175], off
	v_lshl_add_u64 v[228:229], s[4:5], 0, v[160:161]
	s_add_i32 m0, s54, 0x2000
	s_nop 0
	global_load_lds_dwordx4 v[228:229], off
	ds_read_b128 v[212:215], v189
	ds_read_b128 v[216:219], v189 offset:1024
	ds_read_b128 v[220:223], v189 offset:2048
	ds_read_b128 v[224:227], v189 offset:3072
	s_barrier
	s_waitcnt lgkmcnt(0)
	v_mfma_f32_16x16x32_bf16 v[132:135], v[212:215], v[144:147], v[132:135]
	v_mfma_f32_16x16x32_bf16 v[128:131], v[220:223], v[144:147], v[128:131]
	v_mfma_f32_16x16x32_bf16 v[116:119], v[212:215], v[182:185], v[116:119]
	v_mfma_f32_16x16x32_bf16 v[112:115], v[220:223], v[182:185], v[112:115]
	v_mfma_f32_16x16x32_bf16 v[100:103], v[212:215], v[196:199], v[100:103]
	v_mfma_f32_16x16x32_bf16 v[96:99], v[220:223], v[196:199], v[96:99]
	v_mfma_f32_16x16x32_bf16 v[84:87], v[212:215], v[204:207], v[84:87]
	v_mfma_f32_16x16x32_bf16 v[80:83], v[220:223], v[204:207], v[80:83]
	v_mfma_f32_16x16x32_bf16 v[132:135], v[216:219], v[148:151], v[132:135]
	v_mfma_f32_16x16x32_bf16 v[128:131], v[224:227], v[148:151], v[128:131]
	v_mfma_f32_16x16x32_bf16 v[116:119], v[216:219], v[192:195], v[116:119]
	v_mfma_f32_16x16x32_bf16 v[112:115], v[224:227], v[192:195], v[112:115]
	v_mfma_f32_16x16x32_bf16 v[100:103], v[216:219], v[200:203], v[100:103]
	v_mfma_f32_16x16x32_bf16 v[96:99], v[224:227], v[200:203], v[96:99]
	v_mfma_f32_16x16x32_bf16 v[84:87], v[216:219], v[208:211], v[84:87]
	v_mfma_f32_16x16x32_bf16 v[80:83], v[224:227], v[208:211], v[80:83]
	s_mov_b32 m0, s27
	v_lshl_add_u64 v[230:231], s[28:29], 0, v[154:155]
	s_barrier
	global_load_lds_dwordx4 v[230:231], off
	v_lshl_add_u64 v[232:233], s[28:29], 0, v[158:159]
	s_mov_b32 m0, s36
	s_nop 0
	global_load_lds_dwordx4 v[232:233], off
	ds_read_b128 v[144:147], v187 offset:16384
	ds_read_b128 v[148:151], v187 offset:17408
	ds_read_b128 v[182:185], v187 offset:18432
	ds_read_b128 v[192:195], v187 offset:19456
	ds_read_b128 v[196:199], v187 offset:20480
	ds_read_b128 v[200:203], v187 offset:21504
	ds_read_b128 v[204:207], v187 offset:22528
	ds_read_b128 v[208:211], v187 offset:23552
	s_barrier
	s_waitcnt lgkmcnt(0)
	v_mfma_f32_16x16x32_bf16 v[76:79], v[24:27], v[144:147], v[76:79]
	v_mfma_f32_16x16x32_bf16 v[72:75], v[40:43], v[144:147], v[72:75]
	v_mfma_f32_16x16x32_bf16 v[60:63], v[24:27], v[182:185], v[60:63]
	v_mfma_f32_16x16x32_bf16 v[56:59], v[40:43], v[182:185], v[56:59]
	v_mfma_f32_16x16x32_bf16 v[36:39], v[24:27], v[196:199], v[36:39]
	v_mfma_f32_16x16x32_bf16 v[32:35], v[40:43], v[196:199], v[32:35]
	v_mfma_f32_16x16x32_bf16 v[12:15], v[24:27], v[204:207], v[12:15]
	v_mfma_f32_16x16x32_bf16 v[8:11], v[40:43], v[204:207], v[8:11]
	v_mfma_f32_16x16x32_bf16 v[76:79], v[28:31], v[148:151], v[76:79]
	v_mfma_f32_16x16x32_bf16 v[72:75], v[44:47], v[148:151], v[72:75]
	v_mfma_f32_16x16x32_bf16 v[60:63], v[28:31], v[192:195], v[60:63]
	v_mfma_f32_16x16x32_bf16 v[56:59], v[44:47], v[192:195], v[56:59]
	v_mfma_f32_16x16x32_bf16 v[36:39], v[28:31], v[200:203], v[36:39]
	v_mfma_f32_16x16x32_bf16 v[32:35], v[44:47], v[200:203], v[32:35]
	v_mfma_f32_16x16x32_bf16 v[12:15], v[28:31], v[208:211], v[12:15]
	v_mfma_f32_16x16x32_bf16 v[8:11], v[44:47], v[208:211], v[8:11]
	s_barrier
	s_add_u32 s54, s4, 0x40000
	s_addc_u32 s55, s5, 0
	s_add_i32 s56, s44, s35
	v_lshl_add_u64 v[24:25], s[54:55], 0, v[156:157]
	s_mov_b32 m0, s56
	s_nop 0
	global_load_lds_dwordx4 v[24:25], off
	v_lshl_add_u64 v[24:25], s[54:55], 0, v[160:161]
	s_add_i32 m0, s56, 0x2000
	s_nop 0
	global_load_lds_dwordx4 v[24:25], off
	s_waitcnt vmcnt(6)
	s_barrier
; #define PG8_STAGE(bufoff, gbase, voff) do { _Pragma("unroll") for (int _i = 0; _i < 2; ++_i) \
;         __builtin_amdgcn_global_load_lds((const unsigned*)((const char*)(gbase) + (voff)[_i]), (PG8_LAS unsigned*)(lds + (bufoff) + ldsw + _i * 8192), 16, 0, 0); } while (0)
; #define PG8_LDA(dst, b, h) do { _Pragma("unroll") for (int m = 0; m < 4; ++m) _Pragma("unroll") for (int k = 0; k < 2; ++k) dst[m][k] = *(const PG8_LAS bf16x8*)(lds + PG8_SA(b, h) + aoff + m * 2048 + k * 1024); } while (0)
; #define PG8_LDB(dst, b, h) do { _Pragma("unroll") for (int n = 0; n < 2; ++n) _Pragma("unroll") for (int k = 0; k < 2; ++k) dst[n][k] = *(const PG8_LAS bf16x8*)(lds + PG8_SB(b, h) + boff + n * 2048 + k * 1024); } while (0)
; #define PG8_MMA(ai, bj, At, Bt) do { __builtin_amdgcn_s_setprio(1); _Pragma("unroll") for (int m = 0; m < 4; ++m) _Pragma("unroll") for (int n = 0; n < 2; ++n) _Pragma("unroll") for (int k = 0; k < 2; ++k) \
;         acc[ai][bj][m][n] = __builtin_amdgcn_mfma_f32_16x16x32_bf16(Bt[n][k], At[m][k], acc[ai][bj][m][n], 0, 0, 0); __builtin_amdgcn_s_setprio(0); } while (0)
; #define PG8_WAIT_V(n) asm volatile("s_waitcnt vmcnt(" #n ")" ::: "memory")
; #define PG8_WAIT_L(n) asm volatile("s_waitcnt lgkmcnt(" #n ")" ::: "memory")
; #define PG8_BAR __builtin_amdgcn_s_barrier()
; #define PG8_SCHED __builtin_amdgcn_sched_barrier(0)
; template <class Epi, class Sched>
; __device__ __forceinline__ void gemm_phase(PG8_LAS unsigned char* lds, const Gemm g, const Sched& S, const Epi& E) {
;     ...
;             PG8_WAIT_V(6); PG8_BAR; PG8_MMA(1, 1, At, B1); PG8_BAR;
;             PG8_LDB(B0, 1, 0); PG8_SCHED; PG8_LDA(At, 1, 0); PG8_STAGE(PG8_SA(0, 1), a2 + hstep, voffA);
;             PG8_WAIT_L(8); PG8_BAR; PG8_WAIT_L(0); PG8_MMA(0, 0, At, B0); PG8_BAR; PG8_SCHED;
;             PG8_LDB(B1, 1, 1); PG8_STAGE(PG8_SB(1, 0), b3, voffB);
;             PG8_BAR; PG8_WAIT_L(0); PG8_MMA(0, 1, At, B1); PG8_BAR;
	v_mfma_f32_16x16x32_bf16 v[20:23], v[212:215], v[196:199], v[20:23]
	v_mfma_f32_16x16x32_bf16 v[16:19], v[220:223], v[196:199], v[16:19]
	v_mfma_f32_16x16x32_bf16 v[4:7], v[212:215], v[204:207], v[4:7]
	v_mfma_f32_16x16x32_bf16 v[0:3], v[220:223], v[204:207], v[0:3]
	v_mfma_f32_16x16x32_bf16 v[24:27], v[212:215], v[144:147], v[68:71]
	v_mfma_f32_16x16x32_bf16 v[28:31], v[220:223], v[144:147], v[64:67]
	v_mfma_f32_16x16x32_bf16 v[40:43], v[212:215], v[182:185], v[52:55]
	v_mfma_f32_16x16x32_bf16 v[44:47], v[220:223], v[182:185], v[48:51]
	v_mfma_f32_16x16x32_bf16 v[20:23], v[216:219], v[200:203], v[20:23]
	v_mfma_f32_16x16x32_bf16 v[16:19], v[224:227], v[200:203], v[16:19]
	v_mfma_f32_16x16x32_bf16 v[4:7], v[216:219], v[208:211], v[4:7]
	v_mfma_f32_16x16x32_bf16 v[0:3], v[224:227], v[208:211], v[0:3]
	v_mfma_f32_16x16x32_bf16 v[24:27], v[216:219], v[148:151], v[24:27]
	v_mfma_f32_16x16x32_bf16 v[28:31], v[224:227], v[148:151], v[28:31]
	v_mfma_f32_16x16x32_bf16 v[40:43], v[216:219], v[192:195], v[40:43]
	v_mfma_f32_16x16x32_bf16 v[44:47], v[224:227], v[192:195], v[44:47]
	s_add_i32 s54, 0, 0x18000
	v_add_u32_e32 v68, s54, v179
	s_barrier
	s_add_u32 s28, s28, 0x40000
	s_addc_u32 s29, s29, 0
	s_mov_b32 m0, s37
	v_lshl_add_u64 v[212:213], s[28:29], 0, v[154:155]
	global_load_lds_dwordx4 v[212:213], off
	v_lshl_add_u64 v[212:213], s[28:29], 0, v[158:159]
	s_mov_b32 m0, s38
	s_nop 0
	global_load_lds_dwordx4 v[212:213], off
	ds_read_b128 v[48:51], v68
	ds_read_b128 v[52:55], v68 offset:1024
	ds_read_b128 v[64:67], v68 offset:2048
	ds_read_b128 v[68:71], v68 offset:3072
	ds_read_b128 v[144:147], v187 offset:32768
	ds_read_b128 v[148:151], v187 offset:33792
	ds_read_b128 v[182:185], v187 offset:34816
	ds_read_b128 v[192:195], v187 offset:35840
	ds_read_b128 v[196:199], v187 offset:36864
	ds_read_b128 v[200:203], v187 offset:37888
	ds_read_b128 v[204:207], v187 offset:38912
	ds_read_b128 v[208:211], v187 offset:39936
	s_waitcnt lgkmcnt(8)
	s_barrier
	s_waitcnt lgkmcnt(0)
	v_mfma_f32_16x16x32_bf16 v[140:143], v[48:51], v[144:147], v[140:143]
	v_mfma_f32_16x16x32_bf16 v[136:139], v[64:67], v[144:147], v[136:139]
	v_mfma_f32_16x16x32_bf16 v[124:127], v[48:51], v[182:185], v[124:127]
	v_mfma_f32_16x16x32_bf16 v[120:123], v[64:67], v[182:185], v[120:123]
	v_mfma_f32_16x16x32_bf16 v[108:111], v[48:51], v[196:199], v[108:111]
	v_mfma_f32_16x16x32_bf16 v[104:107], v[64:67], v[196:199], v[104:107]
	v_mfma_f32_16x16x32_bf16 v[92:95], v[48:51], v[204:207], v[92:95]
	v_mfma_f32_16x16x32_bf16 v[88:91], v[64:67], v[204:207], v[88:91]
	v_mfma_f32_16x16x32_bf16 v[140:143], v[52:55], v[148:151], v[140:143]
	v_mfma_f32_16x16x32_bf16 v[136:139], v[68:71], v[148:151], v[136:139]
	v_mfma_f32_16x16x32_bf16 v[124:127], v[52:55], v[192:195], v[124:127]
	v_mfma_f32_16x16x32_bf16 v[120:123], v[68:71], v[192:195], v[120:123]
	v_mfma_f32_16x16x32_bf16 v[108:111], v[52:55], v[200:203], v[108:111]
	v_mfma_f32_16x16x32_bf16 v[104:107], v[68:71], v[200:203], v[104:107]
	v_mfma_f32_16x16x32_bf16 v[92:95], v[52:55], v[208:211], v[92:95]
	v_mfma_f32_16x16x32_bf16 v[88:91], v[68:71], v[208:211], v[88:91]
	s_barrier
	s_add_i32 s28, 0, 0x1c000
	s_add_i32 s29, s54, s35
	v_add_u32_e32 v162, s28, v179
	v_lshl_add_u64 v[174:175], v[174:175], 0, s[14:15]
	s_mov_b32 m0, s29
	s_nop 0
	global_load_lds_dwordx4 v[174:175], off
	v_lshl_add_u64 v[174:175], v[228:229], 0, s[14:15]
	s_add_i32 m0, s29, 0x2000
	s_nop 0
	global_load_lds_dwordx4 v[174:175], off
	ds_read_b128 v[212:215], v162
	ds_read_b128 v[216:219], v162 offset:1024
	ds_read_b128 v[220:223], v162 offset:2048
	ds_read_b128 v[224:227], v162 offset:3072
	s_barrier
	s_waitcnt lgkmcnt(0)
	v_mfma_f32_16x16x32_bf16 v[132:135], v[212:215], v[144:147], v[132:135]
	v_mfma_f32_16x16x32_bf16 v[128:131], v[220:223], v[144:147], v[128:131]
	v_mfma_f32_16x16x32_bf16 v[116:119], v[212:215], v[182:185], v[116:119]
	v_mfma_f32_16x16x32_bf16 v[112:115], v[220:223], v[182:185], v[112:115]
	v_mfma_f32_16x16x32_bf16 v[100:103], v[212:215], v[196:199], v[100:103]
	v_mfma_f32_16x16x32_bf16 v[96:99], v[220:223], v[196:199], v[96:99]
	v_mfma_f32_16x16x32_bf16 v[84:87], v[212:215], v[204:207], v[84:87]
	v_mfma_f32_16x16x32_bf16 v[80:83], v[220:223], v[204:207], v[80:83]
	v_mfma_f32_16x16x32_bf16 v[132:135], v[216:219], v[148:151], v[132:135]
	v_mfma_f32_16x16x32_bf16 v[128:131], v[224:227], v[148:151], v[128:131]
	v_mfma_f32_16x16x32_bf16 v[116:119], v[216:219], v[192:195], v[116:119]
	v_mfma_f32_16x16x32_bf16 v[112:115], v[224:227], v[192:195], v[112:115]
	v_mfma_f32_16x16x32_bf16 v[100:103], v[216:219], v[200:203], v[100:103]
	v_mfma_f32_16x16x32_bf16 v[96:99], v[224:227], v[200:203], v[96:99]
	v_mfma_f32_16x16x32_bf16 v[84:87], v[216:219], v[208:211], v[84:87]
	v_mfma_f32_16x16x32_bf16 v[80:83], v[224:227], v[208:211], v[80:83]
	s_mov_b32 m0, s39
	v_lshl_add_u64 v[174:175], v[230:231], 0, s[14:15]
	s_barrier
; #define PG8_STAGE(bufoff, gbase, voff) do { _Pragma("unroll") for (int _i = 0; _i < 2; ++_i) \
;         __builtin_amdgcn_global_load_lds((const unsigned*)((const char*)(gbase) + (voff)[_i]), (PG8_LAS unsigned*)(lds + (bufoff) + ldsw + _i * 8192), 16, 0, 0); } while (0)
; #define PG8_LDA(dst, b, h) do { _Pragma("unroll") for (int m = 0; m < 4; ++m) _Pragma("unroll") for (int k = 0; k < 2; ++k) dst[m][k] = *(const PG8_LAS bf16x8*)(lds + PG8_SA(b, h) + aoff + m * 2048 + k * 1024); } while (0)
; #define PG8_MMA(ai, bj, At, Bt) do { __builtin_amdgcn_s_setprio(1); _Pragma("unroll") for (int m = 0; m < 4; ++m) _Pragma("unroll") for (int n = 0; n < 2; ++n) _Pragma("unroll") for (int k = 0; k < 2; ++k) \
;         acc[ai][bj][m][n] = __builtin_amdgcn_mfma_f32_16x16x32_bf16(Bt[n][k], At[m][k], acc[ai][bj][m][n], 0, 0, 0); __builtin_amdgcn_s_setprio(0); } while (0)
; #define PG8_WAIT_V(n) asm volatile("s_waitcnt vmcnt(" #n ")" ::: "memory")
; #define PG8_WAIT_L(n) asm volatile("s_waitcnt lgkmcnt(" #n ")" ::: "memory")
; #define PG8_BAR __builtin_amdgcn_s_barrier()
; #define PG8_SCHED __builtin_amdgcn_sched_barrier(0)
;     __device__ __forceinline__ void operator()(const f32x4 (&acc)[2][2][4][2], const Unit& u, int wr, int wc, int fr, int fq) const {
;     ...
;         if (mode == 1) { if (u.pn >= 8 && u.pn < 12) act = 1; else if (u.pn >= 12) { act = 3; bias = (u.pn >= 14) ? bias_b + (u.pn - 14) * 256 : bias_f + (u.pn - 12) * 256; } }
; template <class Epi, class Sched>
; __device__ __forceinline__ void gemm_phase(PG8_LAS unsigned char* lds, const Gemm g, const Sched& S, const Epi& E) {
;     ...
;             PG8_LDA(At, 1, 1); PG8_STAGE(PG8_SA(1, 0), a3, voffA);
;             PG8_BAR; PG8_WAIT_L(0); PG8_MMA(1, 0, At, B0); PG8_BAR; PG8_SCHED;
;             PG8_STAGE(PG8_SB(1, 1), b3 + hstep, voffB);
;             PG8_WAIT_V(6); PG8_BAR; PG8_MMA(1, 1, At, B1); PG8_BAR;
	global_load_lds_dwordx4 v[174:175], off
	v_lshl_add_u64 v[174:175], v[232:233], 0, s[14:15]
	s_mov_b32 m0, s40
	s_nop 0
	global_load_lds_dwordx4 v[174:175], off
	ds_read_b128 v[144:147], v187 offset:49152
	ds_read_b128 v[148:151], v187 offset:50176
	ds_read_b128 v[182:185], v187 offset:51200
	ds_read_b128 v[192:195], v187 offset:52224
	ds_read_b128 v[196:199], v187 offset:53248
	ds_read_b128 v[200:203], v187 offset:54272
	ds_read_b128 v[204:207], v187 offset:55296
	ds_read_b128 v[208:211], v187 offset:56320
	s_barrier
	s_waitcnt lgkmcnt(0)
	v_mfma_f32_16x16x32_bf16 v[76:79], v[48:51], v[144:147], v[76:79]
	v_mfma_f32_16x16x32_bf16 v[72:75], v[64:67], v[144:147], v[72:75]
	v_mfma_f32_16x16x32_bf16 v[60:63], v[48:51], v[182:185], v[60:63]
	v_mfma_f32_16x16x32_bf16 v[56:59], v[64:67], v[182:185], v[56:59]
	v_mfma_f32_16x16x32_bf16 v[36:39], v[48:51], v[196:199], v[36:39]
	v_mfma_f32_16x16x32_bf16 v[32:35], v[64:67], v[196:199], v[32:35]
	v_mfma_f32_16x16x32_bf16 v[12:15], v[48:51], v[204:207], v[12:15]
	v_mfma_f32_16x16x32_bf16 v[8:11], v[64:67], v[204:207], v[8:11]
	v_mfma_f32_16x16x32_bf16 v[76:79], v[52:55], v[148:151], v[76:79]
	v_mfma_f32_16x16x32_bf16 v[72:75], v[68:71], v[148:151], v[72:75]
	v_mfma_f32_16x16x32_bf16 v[60:63], v[52:55], v[192:195], v[60:63]
	v_mfma_f32_16x16x32_bf16 v[56:59], v[68:71], v[192:195], v[56:59]
	v_mfma_f32_16x16x32_bf16 v[36:39], v[52:55], v[200:203], v[36:39]
	v_mfma_f32_16x16x32_bf16 v[32:35], v[68:71], v[200:203], v[32:35]
	v_mfma_f32_16x16x32_bf16 v[12:15], v[52:55], v[208:211], v[12:15]
	v_mfma_f32_16x16x32_bf16 v[8:11], v[68:71], v[208:211], v[8:11]
	s_barrier
	s_add_u32 s4, s4, 0x40080
	s_addc_u32 s5, s5, 0
	s_add_i32 s28, s28, s35
	v_lshl_add_u64 v[48:49], s[4:5], 0, v[156:157]
	s_mov_b32 m0, s28
	s_nop 0
	global_load_lds_dwordx4 v[48:49], off
	v_lshl_add_u64 v[48:49], s[4:5], 0, v[160:161]
	s_add_i32 m0, s28, 0x2000
	s_nop 0
	global_load_lds_dwordx4 v[48:49], off
	s_waitcnt vmcnt(6)
	s_barrier
	v_mfma_f32_16x16x32_bf16 v[24:27], v[212:215], v[144:147], v[24:27]
	v_mfma_f32_16x16x32_bf16 v[68:71], v[216:219], v[148:151], v[24:27]
	v_mfma_f32_16x16x32_bf16 v[24:27], v[220:223], v[144:147], v[28:31]
	v_mfma_f32_16x16x32_bf16 v[64:67], v[224:227], v[148:151], v[24:27]
	v_mfma_f32_16x16x32_bf16 v[24:27], v[212:215], v[182:185], v[40:43]
	v_mfma_f32_16x16x32_bf16 v[52:55], v[216:219], v[192:195], v[24:27]
	v_mfma_f32_16x16x32_bf16 v[24:27], v[220:223], v[182:185], v[44:47]
	v_mfma_f32_16x16x32_bf16 v[20:23], v[212:215], v[196:199], v[20:23]
	v_mfma_f32_16x16x32_bf16 v[16:19], v[220:223], v[196:199], v[16:19]
	v_mfma_f32_16x16x32_bf16 v[4:7], v[212:215], v[204:207], v[4:7]
	v_mfma_f32_16x16x32_bf16 v[0:3], v[220:223], v[204:207], v[0:3]
	v_mfma_f32_16x16x32_bf16 v[48:51], v[224:227], v[192:195], v[24:27]
	v_mfma_f32_16x16x32_bf16 v[20:23], v[216:219], v[200:203], v[20:23]
	v_mfma_f32_16x16x32_bf16 v[16:19], v[224:227], v[200:203], v[16:19]
	v_mfma_f32_16x16x32_bf16 v[4:7], v[216:219], v[208:211], v[4:7]
	v_mfma_f32_16x16x32_bf16 v[0:3], v[224:227], v[208:211], v[0:3]
	s_add_i32 s53, s53, 2
	s_add_u32 s0, s0, 0x100
	s_addc_u32 s1, s1, 0
	s_add_u32 s51, s51, 0x100
	s_addc_u32 s52, s52, 0
	s_cmp_gt_u32 s53, 13
	s_barrier
	s_cbranch_scc0 .LBB0_416
	s_cmp_gt_i32 s26, 11
	s_cselect_b64 s[4:5], -1, 0
	s_cmp_lt_i32 s26, 12
	s_mov_b64 s[0:1], 0
	s_cbranch_scc1 .LBB0_422
	s_lshl_b32 s10, s26, 8
	s_cmp_lt_u32 s26, 14
	s_mov_b64 s[28:29], -1
	s_cbranch_scc0 .LBB0_420
	s_lshl_b64 s[0:1], s[10:11], 2
	v_readlane_b32 s52, v245, 0
	v_readlane_b32 s53, v245, 1
	s_add_u32 s0, s52, s0
	s_addc_u32 s1, s53, s1
	s_add_u32 s0, s0, 0xffffd000
	v_readlane_b32 s54, v245, 2
	v_readlane_b32 s55, v245, 3
	v_readlane_b32 s56, v245, 4
	v_readlane_b32 s57, v245, 5
	v_readlane_b32 s58, v245, 6
	v_readlane_b32 s59, v245, 7
	v_readlane_b32 s60, v245, 8
	v_readlane_b32 s61, v245, 9
	v_readlane_b32 s62, v245, 10
	v_readlane_b32 s63, v245, 11
	v_readlane_b32 s64, v245, 12
	v_readlane_b32 s65, v245, 13
	v_readlane_b32 s66, v245, 14
	v_readlane_b32 s67, v245, 15
	s_addc_u32 s1, s1, -1
	s_mov_b64 s[28:29], 0

; #define PG8_STAGE(bufoff, gbase, voff) do { _Pragma("unroll") for (int _i = 0; _i < 2; ++_i) \
;         __builtin_amdgcn_global_load_lds((const unsigned*)((const char*)(gbase) + (voff)[_i]), (PG8_LAS unsigned*)(lds + (bufoff) + ldsw + _i * 8192), 16, 0, 0); } while (0)
; #define PG8_LDA(dst, b, h) do { _Pragma("unroll") for (int m = 0; m < 4; ++m) _Pragma("unroll") for (int k = 0; k < 2; ++k) dst[m][k] = *(const PG8_LAS bf16x8*)(lds + PG8_SA(b, h) + aoff + m * 2048 + k * 1024); } while (0)
; #define PG8_LDB(dst, b, h) do { _Pragma("unroll") for (int n = 0; n < 2; ++n) _Pragma("unroll") for (int k = 0; k < 2; ++k) dst[n][k] = *(const PG8_LAS bf16x8*)(lds + PG8_SB(b, h) + boff + n * 2048 + k * 1024); } while (0)
; #define PG8_MMA(ai, bj, At, Bt) do { __builtin_amdgcn_s_setprio(1); _Pragma("unroll") for (int m = 0; m < 4; ++m) _Pragma("unroll") for (int n = 0; n < 2; ++n) _Pragma("unroll") for (int k = 0; k < 2; ++k) \
;         acc[ai][bj][m][n] = __builtin_amdgcn_mfma_f32_16x16x32_bf16(Bt[n][k], At[m][k], acc[ai][bj][m][n], 0, 0, 0); __builtin_amdgcn_s_setprio(0); } while (0)
; #define PG8_WAIT_L(n) asm volatile("s_waitcnt lgkmcnt(" #n ")" ::: "memory")
; #define PG8_BAR __builtin_amdgcn_s_barrier()
; #define PG8_SCHED __builtin_amdgcn_sched_barrier(0)
; template <class Epi, class Sched>
; __device__ __forceinline__ void gemm_phase(PG8_LAS unsigned char* lds, const Gemm g, const Sched& S, const Epi& E) {
;     ...
;             PG8_LDB(B0, 0, 0); PG8_SCHED; PG8_LDA(At, 0, 0); PG8_STAGE(PG8_SA(1, 1), a1 + hstep, voffA);
;             PG8_WAIT_L(8); PG8_BAR; PG8_WAIT_L(0); PG8_MMA(0, 0, At, B0); PG8_BAR; PG8_SCHED;
;             PG8_LDB(B1, 0, 1); PG8_STAGE(PG8_SB(0, 0), b2, voffB);
;             PG8_BAR; PG8_WAIT_L(0); PG8_MMA(0, 1, At, B1); PG8_BAR;
;             PG8_LDA(At, 0, 1); PG8_STAGE(PG8_SA(0, 0), a2, voffA);
;             PG8_BAR; PG8_WAIT_L(0); PG8_MMA(1, 0, At, B0); PG8_BAR; PG8_SCHED;
.LBB0_724:
	s_add_u32 s20, s18, 0xfffc0080
	s_addc_u32 s21, s19, -1
	s_cmp_eq_u32 s48, 12
	s_cselect_b32 s23, s5, s21
	s_cselect_b32 s22, s11, s20
	s_cselect_b32 s21, s9, s47
	s_cselect_b32 s20, s45, s46
	v_lshl_add_u64 v[174:175], s[18:19], 0, v[136:137]
	s_add_i32 m0, s17, 0xc000
	s_nop 0
	global_load_lds_dwordx4 v[174:175], off
	v_lshl_add_u64 v[174:175], s[18:19], 0, v[138:139]
	s_add_i32 m0, s17, 0xe000
	s_nop 0
	global_load_lds_dwordx4 v[174:175], off
	ds_read_b128 v[144:147], v151
	ds_read_b128 v[156:159], v151 offset:1024
	ds_read_b128 v[160:163], v151 offset:2048
	ds_read_b128 v[166:169], v151 offset:3072
	ds_read_b128 v[170:173], v153
	ds_read_b128 v[182:185], v153 offset:1024
	ds_read_b128 v[190:193], v153 offset:2048
	ds_read_b128 v[194:197], v153 offset:3072
	ds_read_b128 v[198:201], v153 offset:4096
	ds_read_b128 v[202:205], v153 offset:5120
	ds_read_b128 v[206:209], v153 offset:6144
	ds_read_b128 v[210:213], v153 offset:7168
	s_waitcnt lgkmcnt(8)
	s_barrier
	s_waitcnt lgkmcnt(0)
	v_mfma_f32_16x16x32_bf16 v[124:127], v[144:147], v[170:173], v[124:127]
	v_mfma_f32_16x16x32_bf16 v[120:123], v[160:163], v[170:173], v[120:123]
	v_mfma_f32_16x16x32_bf16 v[108:111], v[144:147], v[190:193], v[108:111]
	v_mfma_f32_16x16x32_bf16 v[104:107], v[160:163], v[190:193], v[104:107]
	v_mfma_f32_16x16x32_bf16 v[92:95], v[144:147], v[198:201], v[92:95]
	v_mfma_f32_16x16x32_bf16 v[88:91], v[160:163], v[198:201], v[88:91]
	v_mfma_f32_16x16x32_bf16 v[76:79], v[144:147], v[206:209], v[76:79]
	v_mfma_f32_16x16x32_bf16 v[72:75], v[160:163], v[206:209], v[72:75]
	v_mfma_f32_16x16x32_bf16 v[124:127], v[156:159], v[182:185], v[124:127]
	v_mfma_f32_16x16x32_bf16 v[120:123], v[166:169], v[182:185], v[120:123]
	v_mfma_f32_16x16x32_bf16 v[108:111], v[156:159], v[194:197], v[108:111]
	v_mfma_f32_16x16x32_bf16 v[104:107], v[166:169], v[194:197], v[104:107]
	v_mfma_f32_16x16x32_bf16 v[92:95], v[156:159], v[202:205], v[92:95]
	v_mfma_f32_16x16x32_bf16 v[88:91], v[166:169], v[202:205], v[88:91]
	v_mfma_f32_16x16x32_bf16 v[76:79], v[156:159], v[210:213], v[76:79]
	v_mfma_f32_16x16x32_bf16 v[72:75], v[166:169], v[210:213], v[72:75]
	s_barrier
	s_add_i32 s49, s42, s30
	v_lshl_add_u64 v[174:175], s[20:21], 0, v[130:131]
	s_mov_b32 m0, s49
	s_nop 0
	global_load_lds_dwordx4 v[174:175], off
	v_lshl_add_u64 v[186:187], s[20:21], 0, v[134:135]
	s_add_i32 m0, s49, 0x2000
	s_nop 0
	global_load_lds_dwordx4 v[186:187], off
	ds_read_b128 v[214:217], v154
	ds_read_b128 v[218:221], v154 offset:1024
	ds_read_b128 v[222:225], v154 offset:2048
	ds_read_b128 v[226:229], v154 offset:3072
	s_barrier
	s_waitcnt lgkmcnt(0)
	v_mfma_f32_16x16x32_bf16 v[116:119], v[214:217], v[170:173], v[116:119]
	v_mfma_f32_16x16x32_bf16 v[112:115], v[222:225], v[170:173], v[112:115]
	v_mfma_f32_16x16x32_bf16 v[100:103], v[214:217], v[190:193], v[100:103]
	v_mfma_f32_16x16x32_bf16 v[96:99], v[222:225], v[190:193], v[96:99]
	v_mfma_f32_16x16x32_bf16 v[84:87], v[214:217], v[198:201], v[84:87]
	v_mfma_f32_16x16x32_bf16 v[80:83], v[222:225], v[198:201], v[80:83]
	v_mfma_f32_16x16x32_bf16 v[68:71], v[214:217], v[206:209], v[68:71]
	v_mfma_f32_16x16x32_bf16 v[64:67], v[222:225], v[206:209], v[64:67]
	v_mfma_f32_16x16x32_bf16 v[116:119], v[218:221], v[182:185], v[116:119]
	v_mfma_f32_16x16x32_bf16 v[112:115], v[226:229], v[182:185], v[112:115]
	v_mfma_f32_16x16x32_bf16 v[100:103], v[218:221], v[194:197], v[100:103]
	v_mfma_f32_16x16x32_bf16 v[96:99], v[226:229], v[194:197], v[96:99]
	v_mfma_f32_16x16x32_bf16 v[84:87], v[218:221], v[202:205], v[84:87]
	v_mfma_f32_16x16x32_bf16 v[80:83], v[226:229], v[202:205], v[80:83]
	v_mfma_f32_16x16x32_bf16 v[68:71], v[218:221], v[210:213], v[68:71]
	v_mfma_f32_16x16x32_bf16 v[64:67], v[226:229], v[210:213], v[64:67]
	s_mov_b32 m0, s17
	v_lshl_add_u64 v[230:231], s[22:23], 0, v[128:129]
	s_barrier
	global_load_lds_dwordx4 v[230:231], off
	v_lshl_add_u64 v[232:233], s[22:23], 0, v[132:133]
	s_mov_b32 m0, s31
	s_nop 0
	global_load_lds_dwordx4 v[232:233], off
	ds_read_b128 v[170:173], v153 offset:16384
	ds_read_b128 v[182:185], v153 offset:17408
	ds_read_b128 v[190:193], v153 offset:18432
	ds_read_b128 v[194:197], v153 offset:19456
	ds_read_b128 v[198:201], v153 offset:20480
	ds_read_b128 v[202:205], v153 offset:21504
	ds_read_b128 v[206:209], v153 offset:22528
	ds_read_b128 v[210:213], v153 offset:23552
	s_barrier
	s_waitcnt lgkmcnt(0)
	v_mfma_f32_16x16x32_bf16 v[60:63], v[144:147], v[170:173], v[60:63]
	v_mfma_f32_16x16x32_bf16 v[56:59], v[160:163], v[170:173], v[56:59]
	v_mfma_f32_16x16x32_bf16 v[44:47], v[144:147], v[190:193], v[44:47]
	v_mfma_f32_16x16x32_bf16 v[40:43], v[160:163], v[190:193], v[40:43]
	v_mfma_f32_16x16x32_bf16 v[28:31], v[144:147], v[198:201], v[28:31]
	v_mfma_f32_16x16x32_bf16 v[24:27], v[160:163], v[198:201], v[24:27]
	v_mfma_f32_16x16x32_bf16 v[12:15], v[144:147], v[206:209], v[12:15]
	v_mfma_f32_16x16x32_bf16 v[8:11], v[160:163], v[206:209], v[8:11]
	v_mfma_f32_16x16x32_bf16 v[60:63], v[156:159], v[182:185], v[60:63]
	v_mfma_f32_16x16x32_bf16 v[56:59], v[166:169], v[182:185], v[56:59]
	v_mfma_f32_16x16x32_bf16 v[44:47], v[156:159], v[194:197], v[44:47]
	v_mfma_f32_16x16x32_bf16 v[40:43], v[166:169], v[194:197], v[40:43]
	v_mfma_f32_16x16x32_bf16 v[28:31], v[156:159], v[202:205], v[28:31]
	v_mfma_f32_16x16x32_bf16 v[24:27], v[166:169], v[202:205], v[24:27]
	v_mfma_f32_16x16x32_bf16 v[12:15], v[156:159], v[210:213], v[12:15]
	v_mfma_f32_16x16x32_bf16 v[8:11], v[166:169], v[210:213], v[8:11]
	s_barrier
; #define PG8_STAGE(bufoff, gbase, voff) do { _Pragma("unroll") for (int _i = 0; _i < 2; ++_i) \
;         __builtin_amdgcn_global_load_lds((const unsigned*)((const char*)(gbase) + (voff)[_i]), (PG8_LAS unsigned*)(lds + (bufoff) + ldsw + _i * 8192), 16, 0, 0); } while (0)
; #define PG8_LDA(dst, b, h) do { _Pragma("unroll") for (int m = 0; m < 4; ++m) _Pragma("unroll") for (int k = 0; k < 2; ++k) dst[m][k] = *(const PG8_LAS bf16x8*)(lds + PG8_SA(b, h) + aoff + m * 2048 + k * 1024); } while (0)
; #define PG8_LDB(dst, b, h) do { _Pragma("unroll") for (int n = 0; n < 2; ++n) _Pragma("unroll") for (int k = 0; k < 2; ++k) dst[n][k] = *(const PG8_LAS bf16x8*)(lds + PG8_SB(b, h) + boff + n * 2048 + k * 1024); } while (0)
; #define PG8_MMA(ai, bj, At, Bt) do { __builtin_amdgcn_s_setprio(1); _Pragma("unroll") for (int m = 0; m < 4; ++m) _Pragma("unroll") for (int n = 0; n < 2; ++n) _Pragma("unroll") for (int k = 0; k < 2; ++k) \
;         acc[ai][bj][m][n] = __builtin_amdgcn_mfma_f32_16x16x32_bf16(Bt[n][k], At[m][k], acc[ai][bj][m][n], 0, 0, 0); __builtin_amdgcn_s_setprio(0); } while (0)
; #define PG8_WAIT_V(n) asm volatile("s_waitcnt vmcnt(" #n ")" ::: "memory")
; #define PG8_WAIT_L(n) asm volatile("s_waitcnt lgkmcnt(" #n ")" ::: "memory")
; #define PG8_BAR __builtin_amdgcn_s_barrier()
; #define PG8_SCHED __builtin_amdgcn_sched_barrier(0)
; template <class Epi, class Sched>
; __device__ __forceinline__ void gemm_phase(PG8_LAS unsigned char* lds, const Gemm g, const Sched& S, const Epi& E) {
;     ...
;             PG8_BAR; PG8_WAIT_L(0); PG8_MMA(1, 0, At, B0); PG8_BAR; PG8_SCHED;
;             PG8_STAGE(PG8_SB(0, 1), b2 + hstep, voffB);
;             PG8_WAIT_V(6); PG8_BAR; PG8_MMA(1, 1, At, B1); PG8_BAR;
;             PG8_LDB(B0, 1, 0); PG8_SCHED; PG8_LDA(At, 1, 0); PG8_STAGE(PG8_SA(0, 1), a2 + hstep, voffA);
;             PG8_WAIT_L(8); PG8_BAR; PG8_WAIT_L(0); PG8_MMA(0, 0, At, B0); PG8_BAR; PG8_SCHED;
;             PG8_LDB(B1, 1, 1); PG8_STAGE(PG8_SB(1, 0), b3, voffB);
;             PG8_BAR; PG8_WAIT_L(0); PG8_MMA(0, 1, At, B1); PG8_BAR;
	s_add_u32 s50, s20, 0x40000
	s_addc_u32 s51, s21, 0
	s_add_i32 s49, s43, s30
	v_lshl_add_u64 v[144:145], s[50:51], 0, v[130:131]
	s_mov_b32 m0, s49
	s_nop 0
	global_load_lds_dwordx4 v[144:145], off
	v_lshl_add_u64 v[144:145], s[50:51], 0, v[134:135]
	s_add_i32 m0, s49, 0x2000
	s_nop 0
	global_load_lds_dwordx4 v[144:145], off
	s_waitcnt vmcnt(6)
	s_barrier
	v_mfma_f32_16x16x32_bf16 v[52:55], v[214:217], v[170:173], v[52:55]
	v_mfma_f32_16x16x32_bf16 v[48:51], v[222:225], v[170:173], v[48:51]
	v_mfma_f32_16x16x32_bf16 v[36:39], v[214:217], v[190:193], v[36:39]
	v_mfma_f32_16x16x32_bf16 v[32:35], v[222:225], v[190:193], v[32:35]
	v_mfma_f32_16x16x32_bf16 v[20:23], v[214:217], v[198:201], v[20:23]
	v_mfma_f32_16x16x32_bf16 v[16:19], v[222:225], v[198:201], v[16:19]
	v_mfma_f32_16x16x32_bf16 v[4:7], v[214:217], v[206:209], v[4:7]
	v_mfma_f32_16x16x32_bf16 v[0:3], v[222:225], v[206:209], v[0:3]
	v_mfma_f32_16x16x32_bf16 v[52:55], v[218:221], v[182:185], v[52:55]
	v_mfma_f32_16x16x32_bf16 v[48:51], v[226:229], v[182:185], v[48:51]
	v_mfma_f32_16x16x32_bf16 v[36:39], v[218:221], v[194:197], v[36:39]
	v_mfma_f32_16x16x32_bf16 v[32:35], v[226:229], v[194:197], v[32:35]
	v_mfma_f32_16x16x32_bf16 v[20:23], v[218:221], v[202:205], v[20:23]
	v_mfma_f32_16x16x32_bf16 v[16:19], v[226:229], v[202:205], v[16:19]
	v_mfma_f32_16x16x32_bf16 v[4:7], v[218:221], v[210:213], v[4:7]
	v_mfma_f32_16x16x32_bf16 v[0:3], v[226:229], v[210:213], v[0:3]
	s_add_i32 s49, 0, 0x18000
	v_add_u32_e32 v155, s49, v149
	s_barrier
	s_add_u32 s22, s22, 0x40000
	s_addc_u32 s23, s23, 0
	s_mov_b32 m0, s34
	v_lshl_add_u64 v[214:215], s[22:23], 0, v[128:129]
	global_load_lds_dwordx4 v[214:215], off
	v_lshl_add_u64 v[214:215], s[22:23], 0, v[132:133]
	s_mov_b32 m0, s35
	s_nop 0
	global_load_lds_dwordx4 v[214:215], off
	ds_read_b128 v[144:147], v155
	ds_read_b128 v[156:159], v155 offset:1024
	ds_read_b128 v[160:163], v155 offset:2048
	ds_read_b128 v[166:169], v155 offset:3072
	ds_read_b128 v[170:173], v153 offset:32768
	ds_read_b128 v[182:185], v153 offset:33792
	ds_read_b128 v[190:193], v153 offset:34816
	ds_read_b128 v[194:197], v153 offset:35840
	ds_read_b128 v[198:201], v153 offset:36864
	ds_read_b128 v[202:205], v153 offset:37888
	ds_read_b128 v[206:209], v153 offset:38912
	ds_read_b128 v[210:213], v153 offset:39936
	s_waitcnt lgkmcnt(8)
	s_barrier
	s_waitcnt lgkmcnt(0)
	v_mfma_f32_16x16x32_bf16 v[124:127], v[144:147], v[170:173], v[124:127]
	v_mfma_f32_16x16x32_bf16 v[120:123], v[160:163], v[170:173], v[120:123]
	v_mfma_f32_16x16x32_bf16 v[108:111], v[144:147], v[190:193], v[108:111]
	v_mfma_f32_16x16x32_bf16 v[104:107], v[160:163], v[190:193], v[104:107]
	v_mfma_f32_16x16x32_bf16 v[92:95], v[144:147], v[198:201], v[92:95]
	v_mfma_f32_16x16x32_bf16 v[88:91], v[160:163], v[198:201], v[88:91]
	v_mfma_f32_16x16x32_bf16 v[76:79], v[144:147], v[206:209], v[76:79]
	v_mfma_f32_16x16x32_bf16 v[72:75], v[160:163], v[206:209], v[72:75]
	v_mfma_f32_16x16x32_bf16 v[124:127], v[156:159], v[182:185], v[124:127]
	v_mfma_f32_16x16x32_bf16 v[120:123], v[166:169], v[182:185], v[120:123]
	v_mfma_f32_16x16x32_bf16 v[108:111], v[156:159], v[194:197], v[108:111]
	v_mfma_f32_16x16x32_bf16 v[104:107], v[166:169], v[194:197], v[104:107]
	v_mfma_f32_16x16x32_bf16 v[92:95], v[156:159], v[202:205], v[92:95]
	v_mfma_f32_16x16x32_bf16 v[88:91], v[166:169], v[202:205], v[88:91]
	v_mfma_f32_16x16x32_bf16 v[76:79], v[156:159], v[210:213], v[76:79]
	v_mfma_f32_16x16x32_bf16 v[72:75], v[166:169], v[210:213], v[72:75]
	s_barrier
	s_add_i32 s22, 0, 0x1c000
	s_add_i32 s23, s49, s30
	v_add_u32_e32 v155, s22, v149
	v_lshl_add_u64 v[174:175], v[174:175], 0, s[6:7]
	s_mov_b32 m0, s23
	s_nop 0
	global_load_lds_dwordx4 v[174:175], off
	v_lshl_add_u64 v[174:175], v[186:187], 0, s[6:7]
	s_add_i32 m0, s23, 0x2000
	s_nop 0
	global_load_lds_dwordx4 v[174:175], off
	ds_read_b128 v[214:217], v155
	ds_read_b128 v[218:221], v155 offset:1024
	ds_read_b128 v[222:225], v155 offset:2048
	ds_read_b128 v[226:229], v155 offset:3072
	s_barrier
	s_waitcnt lgkmcnt(0)
	v_mfma_f32_16x16x32_bf16 v[116:119], v[214:217], v[170:173], v[116:119]
	v_mfma_f32_16x16x32_bf16 v[112:115], v[222:225], v[170:173], v[112:115]
	v_mfma_f32_16x16x32_bf16 v[100:103], v[214:217], v[190:193], v[100:103]
	v_mfma_f32_16x16x32_bf16 v[96:99], v[222:225], v[190:193], v[96:99]
	v_mfma_f32_16x16x32_bf16 v[84:87], v[214:217], v[198:201], v[84:87]
	v_mfma_f32_16x16x32_bf16 v[80:83], v[222:225], v[198:201], v[80:83]
	v_mfma_f32_16x16x32_bf16 v[68:71], v[214:217], v[206:209], v[68:71]
	v_mfma_f32_16x16x32_bf16 v[64:67], v[222:225], v[206:209], v[64:67]
	v_mfma_f32_16x16x32_bf16 v[116:119], v[218:221], v[182:185], v[116:119]
	v_mfma_f32_16x16x32_bf16 v[112:115], v[226:229], v[182:185], v[112:115]
	v_mfma_f32_16x16x32_bf16 v[100:103], v[218:221], v[194:197], v[100:103]
	v_mfma_f32_16x16x32_bf16 v[96:99], v[226:229], v[194:197], v[96:99]
	v_mfma_f32_16x16x32_bf16 v[84:87], v[218:221], v[202:205], v[84:87]
	v_mfma_f32_16x16x32_bf16 v[80:83], v[226:229], v[202:205], v[80:83]
	v_mfma_f32_16x16x32_bf16 v[68:71], v[218:221], v[210:213], v[68:71]
	v_mfma_f32_16x16x32_bf16 v[64:67], v[226:229], v[210:213], v[64:67]
	s_mov_b32 m0, s37
	v_lshl_add_u64 v[174:175], v[230:231], 0, s[6:7]
	s_barrier
	global_load_lds_dwordx4 v[174:175], off
	v_lshl_add_u64 v[174:175], v[232:233], 0, s[6:7]
	s_mov_b32 m0, s38
	s_nop 0
	global_load_lds_dwordx4 v[174:175], off
	ds_read_b128 v[170:173], v153 offset:49152
	ds_read_b128 v[182:185], v153 offset:50176
	ds_read_b128 v[190:193], v153 offset:51200
	ds_read_b128 v[194:197], v153 offset:52224
	ds_read_b128 v[198:201], v153 offset:53248
	ds_read_b128 v[202:205], v153 offset:54272
	ds_read_b128 v[206:209], v153 offset:55296
	ds_read_b128 v[210:213], v153 offset:56320
	s_barrier
; #define PG8_STAGE(bufoff, gbase, voff) do { _Pragma("unroll") for (int _i = 0; _i < 2; ++_i) \
;         __builtin_amdgcn_global_load_lds((const unsigned*)((const char*)(gbase) + (voff)[_i]), (PG8_LAS unsigned*)(lds + (bufoff) + ldsw + _i * 8192), 16, 0, 0); } while (0)
; #define PG8_MMA(ai, bj, At, Bt) do { __builtin_amdgcn_s_setprio(1); _Pragma("unroll") for (int m = 0; m < 4; ++m) _Pragma("unroll") for (int n = 0; n < 2; ++n) _Pragma("unroll") for (int k = 0; k < 2; ++k) \
;         acc[ai][bj][m][n] = __builtin_amdgcn_mfma_f32_16x16x32_bf16(Bt[n][k], At[m][k], acc[ai][bj][m][n], 0, 0, 0); __builtin_amdgcn_s_setprio(0); } while (0)
; #define PG8_WAIT_V(n) asm volatile("s_waitcnt vmcnt(" #n ")" ::: "memory")
; #define PG8_WAIT_L(n) asm volatile("s_waitcnt lgkmcnt(" #n ")" ::: "memory")
; #define PG8_BAR __builtin_amdgcn_s_barrier()
; #define PG8_SCHED __builtin_amdgcn_sched_barrier(0)
; __device__ __forceinline__ f32x4 sigmoid4(f32x4 x) {
;     f32x4 d;
; #pragma unroll
;     for (int j = 0; j < 4; ++j) d[j] = 1.0f + __expf(-fmaxf(x[j], -20.0f));
;     const float p01 = d[0] * d[1], p23 = d[2] * d[3], r = __builtin_amdgcn_rcpf(p01 * p23), r01 = r * p23, r23 = r * p01;
;     return (f32x4){r01 * d[1], r01 * d[0], r23 * d[3], r23 * d[2]};
; }
; template <class Epi, class Sched>
; __device__ __forceinline__ void gemm_phase(PG8_LAS unsigned char* lds, const Gemm g, const Sched& S, const Epi& E) {
;     ...
;             PG8_BAR; PG8_WAIT_L(0); PG8_MMA(1, 0, At, B0); PG8_BAR; PG8_SCHED;
;             PG8_STAGE(PG8_SB(1, 1), b3 + hstep, voffB);
;             PG8_WAIT_V(6); PG8_BAR; PG8_MMA(1, 1, At, B1); PG8_BAR;
	s_waitcnt lgkmcnt(0)
	v_mfma_f32_16x16x32_bf16 v[60:63], v[144:147], v[170:173], v[60:63]
	v_mfma_f32_16x16x32_bf16 v[56:59], v[160:163], v[170:173], v[56:59]
	v_mfma_f32_16x16x32_bf16 v[44:47], v[144:147], v[190:193], v[44:47]
	v_mfma_f32_16x16x32_bf16 v[40:43], v[160:163], v[190:193], v[40:43]
	v_mfma_f32_16x16x32_bf16 v[28:31], v[144:147], v[198:201], v[28:31]
	v_mfma_f32_16x16x32_bf16 v[24:27], v[160:163], v[198:201], v[24:27]
	v_mfma_f32_16x16x32_bf16 v[12:15], v[144:147], v[206:209], v[12:15]
	v_mfma_f32_16x16x32_bf16 v[8:11], v[160:163], v[206:209], v[8:11]
	v_mfma_f32_16x16x32_bf16 v[60:63], v[156:159], v[182:185], v[60:63]
	v_mfma_f32_16x16x32_bf16 v[56:59], v[166:169], v[182:185], v[56:59]
	v_mfma_f32_16x16x32_bf16 v[44:47], v[156:159], v[194:197], v[44:47]
	v_mfma_f32_16x16x32_bf16 v[40:43], v[166:169], v[194:197], v[40:43]
	v_mfma_f32_16x16x32_bf16 v[28:31], v[156:159], v[202:205], v[28:31]
	v_mfma_f32_16x16x32_bf16 v[24:27], v[166:169], v[202:205], v[24:27]
	v_mfma_f32_16x16x32_bf16 v[12:15], v[156:159], v[210:213], v[12:15]
	v_mfma_f32_16x16x32_bf16 v[8:11], v[166:169], v[210:213], v[8:11]
	s_barrier
	s_add_u32 s20, s20, 0x40080
	s_addc_u32 s21, s21, 0
	s_add_i32 s22, s22, s30
	v_lshl_add_u64 v[144:145], s[20:21], 0, v[130:131]
	s_mov_b32 m0, s22
	s_nop 0
	global_load_lds_dwordx4 v[144:145], off
	v_lshl_add_u64 v[144:145], s[20:21], 0, v[134:135]
	s_add_i32 m0, s22, 0x2000
	s_nop 0
	global_load_lds_dwordx4 v[144:145], off
	s_waitcnt vmcnt(6)
	s_barrier
	v_mfma_f32_16x16x32_bf16 v[52:55], v[214:217], v[170:173], v[52:55]
	v_mfma_f32_16x16x32_bf16 v[48:51], v[222:225], v[170:173], v[48:51]
	v_mfma_f32_16x16x32_bf16 v[36:39], v[214:217], v[190:193], v[36:39]
	v_mfma_f32_16x16x32_bf16 v[32:35], v[222:225], v[190:193], v[32:35]
	v_mfma_f32_16x16x32_bf16 v[20:23], v[214:217], v[198:201], v[20:23]
	v_mfma_f32_16x16x32_bf16 v[16:19], v[222:225], v[198:201], v[16:19]
	v_mfma_f32_16x16x32_bf16 v[4:7], v[214:217], v[206:209], v[4:7]
	v_mfma_f32_16x16x32_bf16 v[0:3], v[222:225], v[206:209], v[0:3]
	v_mfma_f32_16x16x32_bf16 v[52:55], v[218:221], v[182:185], v[52:55]
	v_mfma_f32_16x16x32_bf16 v[48:51], v[226:229], v[182:185], v[48:51]
	v_mfma_f32_16x16x32_bf16 v[36:39], v[218:221], v[194:197], v[36:39]
	v_mfma_f32_16x16x32_bf16 v[32:35], v[226:229], v[194:197], v[32:35]
	v_mfma_f32_16x16x32_bf16 v[20:23], v[218:221], v[202:205], v[20:23]
	v_mfma_f32_16x16x32_bf16 v[16:19], v[226:229], v[202:205], v[16:19]
	v_mfma_f32_16x16x32_bf16 v[4:7], v[218:221], v[210:213], v[4:7]
	v_mfma_f32_16x16x32_bf16 v[0:3], v[226:229], v[210:213], v[0:3]
	s_add_i32 s48, s48, 2
	s_add_u32 s18, s18, 0x100
	s_addc_u32 s19, s19, 0
	s_add_u32 s46, s46, 0x100
	s_addc_u32 s47, s47, 0
	s_cmp_gt_u32 s48, 13
	s_barrier
	s_cbranch_scc0 .LBB0_724
	s_cmp_gt_i32 s4, 5
	s_cselect_b64 s[18:19], -1, 0
	s_cmp_lt_i32 s4, 6
	v_pk_add_f32 v[144:145], v[126:127], 0 op_sel_hi:[1,0]
	v_pk_add_f32 v[146:147], v[124:125], 0 op_sel_hi:[1,0]
	v_pk_add_f32 v[124:125], v[122:123], 0 op_sel_hi:[1,0]
	v_pk_add_f32 v[126:127], v[120:121], 0 op_sel_hi:[1,0]
	s_cbranch_scc1 .LBB0_727
	v_max_f32_e32 v122, v144, v144
	v_max_f32_e32 v122, 0xc1a00000, v122
	v_mul_f32_e32 v122, 0xbfb8aa3b, v122
	v_max_f32_e32 v120, v146, v146
	v_max_f32_e32 v121, v147, v147
	v_exp_f32_e32 v123, v122
	v_max_f32_e32 v122, v145, v145
	v_max_f32_e32 v120, 0xc1a00000, v120
	v_max_f32_e32 v121, 0xc1a00000, v121
	v_max_f32_e32 v122, 0xc1a00000, v122
	v_mul_f32_e32 v120, 0xbfb8aa3b, v120
	v_mul_f32_e32 v121, 0xbfb8aa3b, v121
	v_mul_f32_e32 v122, 0xbfb8aa3b, v122
	v_exp_f32_e32 v120, v120
	v_exp_f32_e32 v121, v121
	v_exp_f32_e32 v122, v122
	v_max_f32_e32 v124, v124, v124
	v_max_f32_e32 v124, 0xc1a00000, v124
	v_pk_add_f32 v[120:121], v[120:121], 1.0 op_sel_hi:[1,0]
	v_pk_add_f32 v[122:123], v[122:123], 1.0 op_sel_hi:[1,0]
	v_mov_b32_e32 v144, v120
	v_mov_b32_e32 v145, v123
	v_pk_mov_b32 v[146:147], v[120:121], v[122:123] op_sel:[1,0]
	v_mul_f32_e32 v124, 0xbfb8aa3b, v124
	v_pk_mul_f32 v[144:145], v[144:145], v[146:147]
	v_max_f32_e32 v126, v126, v126
	v_max_f32_e32 v127, v127, v127
	v_exp_f32_e32 v147, v124
	v_max_f32_e32 v124, v125, v125
	v_max_f32_e32 v126, 0xc1a00000, v126
	v_max_f32_e32 v127, 0xc1a00000, v127
	v_max_f32_e32 v124, 0xc1a00000, v124
	v_mul_f32_e32 v146, v144, v145
	v_mul_f32_e32 v126, 0xbfb8aa3b, v126
	v_mul_f32_e32 v127, 0xbfb8aa3b, v127
	v_mul_f32_e32 v124, 0xbfb8aa3b, v124
	v_rcp_f32_e32 v155, v146
	v_exp_f32_e32 v126, v126
	v_exp_f32_e32 v127, v127
	v_exp_f32_e32 v146, v124
	v_mul_f32_e32 v124, v145, v155
	v_mul_f32_e32 v144, v144, v155
	v_pk_add_f32 v[126:127], v[126:127], 1.0 op_sel_hi:[1,0]
	v_pk_add_f32 v[156:157], v[146:147], 1.0 op_sel_hi:[1,0]
	v_mov_b32_e32 v146, v126
	v_mov_b32_e32 v147, v157
	v_pk_mov_b32 v[158:159], v[126:127], v[156:157] op_sel:[1,0]
	v_pk_mul_f32 v[144:145], v[122:123], v[144:145] op_sel_hi:[1,0]
	v_pk_mul_f32 v[158:159], v[146:147], v[158:159]
	s_nop 0
	v_mul_f32_e32 v125, v158, v159
	v_rcp_f32_e32 v125, v125
	s_nop 0
	v_pk_mul_f32 v[146:147], v[120:121], v[124:125] op_sel:[1,0] op_sel_hi:[0,0]
	v_mul_f32_e32 v120, v159, v125
	v_mul_f32_e32 v122, v158, v125
	v_pk_mul_f32 v[124:125], v[156:157], v[122:123] op_sel_hi:[1,0]
	v_pk_mul_f32 v[126:127], v[126:127], v[120:121] op_sel:[1,0] op_sel_hi:[0,0]

; #define PG8_STAGE(bufoff, gbase, voff) do { _Pragma("unroll") for (int _i = 0; _i < 2; ++_i) \
;         __builtin_amdgcn_global_load_lds((const unsigned*)((const char*)(gbase) + (voff)[_i]), (PG8_LAS unsigned*)(lds + (bufoff) + ldsw + _i * 8192), 16, 0, 0); } while (0)
; #define PG8_LDA(dst, b, h) do { _Pragma("unroll") for (int m = 0; m < 4; ++m) _Pragma("unroll") for (int k = 0; k < 2; ++k) dst[m][k] = *(const PG8_LAS bf16x8*)(lds + PG8_SA(b, h) + aoff + m * 2048 + k * 1024); } while (0)
; #define PG8_LDB(dst, b, h) do { _Pragma("unroll") for (int n = 0; n < 2; ++n) _Pragma("unroll") for (int k = 0; k < 2; ++k) dst[n][k] = *(const PG8_LAS bf16x8*)(lds + PG8_SB(b, h) + boff + n * 2048 + k * 1024); } while (0)
; #define PG8_MMA(ai, bj, At, Bt) do { __builtin_amdgcn_s_setprio(1); _Pragma("unroll") for (int m = 0; m < 4; ++m) _Pragma("unroll") for (int n = 0; n < 2; ++n) _Pragma("unroll") for (int k = 0; k < 2; ++k) \
;         acc[ai][bj][m][n] = __builtin_amdgcn_mfma_f32_16x16x32_bf16(Bt[n][k], At[m][k], acc[ai][bj][m][n], 0, 0, 0); __builtin_amdgcn_s_setprio(0); } while (0)
; #define PG8_WAIT_L(n) asm volatile("s_waitcnt lgkmcnt(" #n ")" ::: "memory")
; #define PG8_BAR __builtin_amdgcn_s_barrier()
; #define PG8_SCHED __builtin_amdgcn_sched_barrier(0)
; template <class Epi, class Sched>
; __device__ __forceinline__ void gemm_phase(PG8_LAS unsigned char* lds, const Gemm g, const Sched& S, const Epi& E) {
;     ...
;             PG8_LDB(B0, 0, 0); PG8_SCHED; PG8_LDA(At, 0, 0); PG8_STAGE(PG8_SA(1, 1), a1 + hstep, voffA);
;             PG8_WAIT_L(8); PG8_BAR; PG8_WAIT_L(0); PG8_MMA(0, 0, At, B0); PG8_BAR; PG8_SCHED;
;             PG8_LDB(B1, 0, 1); PG8_STAGE(PG8_SB(0, 0), b2, voffB);
;             PG8_BAR; PG8_WAIT_L(0); PG8_MMA(0, 1, At, B1); PG8_BAR;
;             PG8_LDA(At, 0, 1); PG8_STAGE(PG8_SA(0, 0), a2, voffA);
;             PG8_BAR; PG8_WAIT_L(0); PG8_MMA(1, 0, At, B0); PG8_BAR; PG8_SCHED;
.LBB0_991:
	s_add_u32 s20, s18, 0xfffc0080
	s_addc_u32 s21, s19, -1
	s_cmp_eq_u32 s47, 12
	s_cselect_b32 s23, s11, s21
	s_cselect_b32 s22, s43, s20
	s_cselect_b32 s21, s9, s46
	s_cselect_b32 s20, s44, s45
	v_lshl_add_u64 v[148:149], s[18:19], 0, v[136:137]
	s_add_i32 m0, s17, 0xc000
	s_nop 0
	global_load_lds_dwordx4 v[148:149], off
	v_lshl_add_u64 v[148:149], s[18:19], 0, v[138:139]
	s_add_i32 m0, s17, 0xe000
	s_nop 0
	global_load_lds_dwordx4 v[148:149], off
	ds_read_b128 v[144:147], v153
	ds_read_b128 v[156:159], v153 offset:1024
	ds_read_b128 v[160:163], v153 offset:2048
	ds_read_b128 v[164:167], v153 offset:3072
	ds_read_b128 v[168:171], v154
	ds_read_b128 v[172:175], v154 offset:1024
	ds_read_b128 v[182:185], v154 offset:2048
	ds_read_b128 v[190:193], v154 offset:3072
	ds_read_b128 v[194:197], v154 offset:4096
	ds_read_b128 v[198:201], v154 offset:5120
	ds_read_b128 v[202:205], v154 offset:6144
	ds_read_b128 v[206:209], v154 offset:7168
	s_waitcnt lgkmcnt(8)
	s_barrier
	s_waitcnt lgkmcnt(0)
	v_mfma_f32_16x16x32_bf16 v[124:127], v[144:147], v[168:171], v[124:127]
	v_mfma_f32_16x16x32_bf16 v[120:123], v[160:163], v[168:171], v[120:123]
	v_mfma_f32_16x16x32_bf16 v[112:115], v[144:147], v[182:185], v[112:115]
	v_mfma_f32_16x16x32_bf16 v[104:107], v[160:163], v[182:185], v[104:107]
	v_mfma_f32_16x16x32_bf16 v[96:99], v[144:147], v[194:197], v[96:99]
	v_mfma_f32_16x16x32_bf16 v[88:91], v[160:163], v[194:197], v[88:91]
	v_mfma_f32_16x16x32_bf16 v[80:83], v[144:147], v[202:205], v[80:83]
	v_mfma_f32_16x16x32_bf16 v[72:75], v[160:163], v[202:205], v[72:75]
	v_mfma_f32_16x16x32_bf16 v[124:127], v[156:159], v[172:175], v[124:127]
	v_mfma_f32_16x16x32_bf16 v[120:123], v[164:167], v[172:175], v[120:123]
	v_mfma_f32_16x16x32_bf16 v[112:115], v[156:159], v[190:193], v[112:115]
	v_mfma_f32_16x16x32_bf16 v[104:107], v[164:167], v[190:193], v[104:107]
	v_mfma_f32_16x16x32_bf16 v[96:99], v[156:159], v[198:201], v[96:99]
	v_mfma_f32_16x16x32_bf16 v[88:91], v[164:167], v[198:201], v[88:91]
	v_mfma_f32_16x16x32_bf16 v[80:83], v[156:159], v[206:209], v[80:83]
	v_mfma_f32_16x16x32_bf16 v[72:75], v[164:167], v[206:209], v[72:75]
	s_barrier
	s_add_i32 s48, s39, s29
	v_lshl_add_u64 v[148:149], s[20:21], 0, v[130:131]
	s_mov_b32 m0, s48
	s_nop 0
	global_load_lds_dwordx4 v[148:149], off
	v_lshl_add_u64 v[186:187], s[20:21], 0, v[134:135]
	s_add_i32 m0, s48, 0x2000
	s_nop 0
	global_load_lds_dwordx4 v[186:187], off
	ds_read_b128 v[210:213], v155
	ds_read_b128 v[214:217], v155 offset:1024
	ds_read_b128 v[218:221], v155 offset:2048
	ds_read_b128 v[222:225], v155 offset:3072
	s_barrier
	s_waitcnt lgkmcnt(0)
	v_mfma_f32_16x16x32_bf16 v[116:119], v[210:213], v[168:171], v[116:119]
	v_mfma_f32_16x16x32_bf16 v[108:111], v[218:221], v[168:171], v[108:111]
	v_mfma_f32_16x16x32_bf16 v[100:103], v[210:213], v[182:185], v[100:103]
	v_mfma_f32_16x16x32_bf16 v[92:95], v[218:221], v[182:185], v[92:95]
	v_mfma_f32_16x16x32_bf16 v[84:87], v[210:213], v[194:197], v[84:87]
	v_mfma_f32_16x16x32_bf16 v[76:79], v[218:221], v[194:197], v[76:79]
	v_mfma_f32_16x16x32_bf16 v[68:71], v[210:213], v[202:205], v[68:71]
	v_mfma_f32_16x16x32_bf16 v[64:67], v[218:221], v[202:205], v[64:67]
	v_mfma_f32_16x16x32_bf16 v[116:119], v[214:217], v[172:175], v[116:119]
	v_mfma_f32_16x16x32_bf16 v[108:111], v[222:225], v[172:175], v[108:111]
	v_mfma_f32_16x16x32_bf16 v[100:103], v[214:217], v[190:193], v[100:103]
	v_mfma_f32_16x16x32_bf16 v[92:95], v[222:225], v[190:193], v[92:95]
	v_mfma_f32_16x16x32_bf16 v[84:87], v[214:217], v[198:201], v[84:87]
	v_mfma_f32_16x16x32_bf16 v[76:79], v[222:225], v[198:201], v[76:79]
	v_mfma_f32_16x16x32_bf16 v[68:71], v[214:217], v[206:209], v[68:71]
	v_mfma_f32_16x16x32_bf16 v[64:67], v[222:225], v[206:209], v[64:67]
	s_mov_b32 m0, s17
	v_lshl_add_u64 v[226:227], s[22:23], 0, v[128:129]
	s_barrier
	global_load_lds_dwordx4 v[226:227], off
	v_lshl_add_u64 v[228:229], s[22:23], 0, v[132:133]
	s_mov_b32 m0, s30
	s_nop 0
	global_load_lds_dwordx4 v[228:229], off
	ds_read_b128 v[168:171], v154 offset:16384
	ds_read_b128 v[172:175], v154 offset:17408
	ds_read_b128 v[182:185], v154 offset:18432
	ds_read_b128 v[190:193], v154 offset:19456
	ds_read_b128 v[194:197], v154 offset:20480
	ds_read_b128 v[198:201], v154 offset:21504
	ds_read_b128 v[202:205], v154 offset:22528
	ds_read_b128 v[206:209], v154 offset:23552
	s_barrier
	s_waitcnt lgkmcnt(0)
	v_mfma_f32_16x16x32_bf16 v[60:63], v[144:147], v[168:171], v[60:63]
	v_mfma_f32_16x16x32_bf16 v[56:59], v[160:163], v[168:171], v[56:59]
	v_mfma_f32_16x16x32_bf16 v[48:51], v[144:147], v[182:185], v[48:51]
	v_mfma_f32_16x16x32_bf16 v[40:43], v[160:163], v[182:185], v[40:43]
	v_mfma_f32_16x16x32_bf16 v[32:35], v[144:147], v[194:197], v[32:35]
	v_mfma_f32_16x16x32_bf16 v[24:27], v[160:163], v[194:197], v[24:27]
	v_mfma_f32_16x16x32_bf16 v[16:19], v[144:147], v[202:205], v[16:19]
	v_mfma_f32_16x16x32_bf16 v[8:11], v[160:163], v[202:205], v[8:11]
	v_mfma_f32_16x16x32_bf16 v[60:63], v[156:159], v[172:175], v[60:63]
	v_mfma_f32_16x16x32_bf16 v[56:59], v[164:167], v[172:175], v[56:59]
	v_mfma_f32_16x16x32_bf16 v[48:51], v[156:159], v[190:193], v[48:51]
	v_mfma_f32_16x16x32_bf16 v[40:43], v[164:167], v[190:193], v[40:43]
	v_mfma_f32_16x16x32_bf16 v[32:35], v[156:159], v[198:201], v[32:35]
	v_mfma_f32_16x16x32_bf16 v[24:27], v[164:167], v[198:201], v[24:27]
	v_mfma_f32_16x16x32_bf16 v[16:19], v[156:159], v[206:209], v[16:19]
	v_mfma_f32_16x16x32_bf16 v[8:11], v[164:167], v[206:209], v[8:11]
	s_barrier
; #define PG8_STAGE(bufoff, gbase, voff) do { _Pragma("unroll") for (int _i = 0; _i < 2; ++_i) \
;         __builtin_amdgcn_global_load_lds((const unsigned*)((const char*)(gbase) + (voff)[_i]), (PG8_LAS unsigned*)(lds + (bufoff) + ldsw + _i * 8192), 16, 0, 0); } while (0)
; #define PG8_LDA(dst, b, h) do { _Pragma("unroll") for (int m = 0; m < 4; ++m) _Pragma("unroll") for (int k = 0; k < 2; ++k) dst[m][k] = *(const PG8_LAS bf16x8*)(lds + PG8_SA(b, h) + aoff + m * 2048 + k * 1024); } while (0)
; #define PG8_LDB(dst, b, h) do { _Pragma("unroll") for (int n = 0; n < 2; ++n) _Pragma("unroll") for (int k = 0; k < 2; ++k) dst[n][k] = *(const PG8_LAS bf16x8*)(lds + PG8_SB(b, h) + boff + n * 2048 + k * 1024); } while (0)
; #define PG8_MMA(ai, bj, At, Bt) do { __builtin_amdgcn_s_setprio(1); _Pragma("unroll") for (int m = 0; m < 4; ++m) _Pragma("unroll") for (int n = 0; n < 2; ++n) _Pragma("unroll") for (int k = 0; k < 2; ++k) \
;         acc[ai][bj][m][n] = __builtin_amdgcn_mfma_f32_16x16x32_bf16(Bt[n][k], At[m][k], acc[ai][bj][m][n], 0, 0, 0); __builtin_amdgcn_s_setprio(0); } while (0)
; #define PG8_WAIT_V(n) asm volatile("s_waitcnt vmcnt(" #n ")" ::: "memory")
; #define PG8_WAIT_L(n) asm volatile("s_waitcnt lgkmcnt(" #n ")" ::: "memory")
; #define PG8_BAR __builtin_amdgcn_s_barrier()
; #define PG8_SCHED __builtin_amdgcn_sched_barrier(0)
; template <class Epi, class Sched>
; __device__ __forceinline__ void gemm_phase(PG8_LAS unsigned char* lds, const Gemm g, const Sched& S, const Epi& E) {
;     ...
;             PG8_BAR; PG8_WAIT_L(0); PG8_MMA(1, 0, At, B0); PG8_BAR; PG8_SCHED;
;             PG8_STAGE(PG8_SB(0, 1), b2 + hstep, voffB);
;             PG8_WAIT_V(6); PG8_BAR; PG8_MMA(1, 1, At, B1); PG8_BAR;
;             PG8_LDB(B0, 1, 0); PG8_SCHED; PG8_LDA(At, 1, 0); PG8_STAGE(PG8_SA(0, 1), a2 + hstep, voffA);
;             PG8_WAIT_L(8); PG8_BAR; PG8_WAIT_L(0); PG8_MMA(0, 0, At, B0); PG8_BAR; PG8_SCHED;
;             PG8_LDB(B1, 1, 1); PG8_STAGE(PG8_SB(1, 0), b3, voffB);
;             PG8_BAR; PG8_WAIT_L(0); PG8_MMA(0, 1, At, B1); PG8_BAR;
	s_add_u32 s48, s20, 0x40000
	s_addc_u32 s49, s21, 0
	s_add_i32 s50, s40, s29
	v_lshl_add_u64 v[144:145], s[48:49], 0, v[130:131]
	s_mov_b32 m0, s50
	s_nop 0
	global_load_lds_dwordx4 v[144:145], off
	v_lshl_add_u64 v[144:145], s[48:49], 0, v[134:135]
	s_add_i32 m0, s50, 0x2000
	s_nop 0
	global_load_lds_dwordx4 v[144:145], off
	s_waitcnt vmcnt(6)
	s_barrier
	v_mfma_f32_16x16x32_bf16 v[52:55], v[210:213], v[168:171], v[52:55]
	v_mfma_f32_16x16x32_bf16 v[44:47], v[218:221], v[168:171], v[44:47]
	v_mfma_f32_16x16x32_bf16 v[36:39], v[210:213], v[182:185], v[36:39]
	v_mfma_f32_16x16x32_bf16 v[28:31], v[218:221], v[182:185], v[28:31]
	v_mfma_f32_16x16x32_bf16 v[20:23], v[210:213], v[194:197], v[20:23]
	v_mfma_f32_16x16x32_bf16 v[12:15], v[218:221], v[194:197], v[12:15]
	v_mfma_f32_16x16x32_bf16 v[4:7], v[210:213], v[202:205], v[4:7]
	v_mfma_f32_16x16x32_bf16 v[0:3], v[218:221], v[202:205], v[0:3]
	v_mfma_f32_16x16x32_bf16 v[52:55], v[214:217], v[172:175], v[52:55]
	v_mfma_f32_16x16x32_bf16 v[44:47], v[222:225], v[172:175], v[44:47]
	v_mfma_f32_16x16x32_bf16 v[36:39], v[214:217], v[190:193], v[36:39]
	v_mfma_f32_16x16x32_bf16 v[28:31], v[222:225], v[190:193], v[28:31]
	v_mfma_f32_16x16x32_bf16 v[20:23], v[214:217], v[198:201], v[20:23]
	v_mfma_f32_16x16x32_bf16 v[12:15], v[222:225], v[198:201], v[12:15]
	v_mfma_f32_16x16x32_bf16 v[4:7], v[214:217], v[206:209], v[4:7]
	v_mfma_f32_16x16x32_bf16 v[0:3], v[222:225], v[206:209], v[0:3]
	s_add_i32 s48, 0, 0x18000
	v_add_u32_e32 v164, s48, v151
	s_barrier
	s_add_u32 s22, s22, 0x40000
	s_addc_u32 s23, s23, 0
	s_mov_b32 m0, s31
	v_lshl_add_u64 v[210:211], s[22:23], 0, v[128:129]
	global_load_lds_dwordx4 v[210:211], off
	v_lshl_add_u64 v[210:211], s[22:23], 0, v[132:133]
	s_mov_b32 m0, s34
	s_nop 0
	global_load_lds_dwordx4 v[210:211], off
	ds_read_b128 v[144:147], v164
	ds_read_b128 v[156:159], v164 offset:1024
	ds_read_b128 v[160:163], v164 offset:2048
	ds_read_b128 v[164:167], v164 offset:3072
	ds_read_b128 v[168:171], v154 offset:32768
	ds_read_b128 v[172:175], v154 offset:33792
	ds_read_b128 v[182:185], v154 offset:34816
	ds_read_b128 v[190:193], v154 offset:35840
	ds_read_b128 v[194:197], v154 offset:36864
	ds_read_b128 v[198:201], v154 offset:37888
	ds_read_b128 v[202:205], v154 offset:38912
	ds_read_b128 v[206:209], v154 offset:39936
	s_waitcnt lgkmcnt(8)
	s_barrier
	s_waitcnt lgkmcnt(0)
	v_mfma_f32_16x16x32_bf16 v[124:127], v[144:147], v[168:171], v[124:127]
	v_mfma_f32_16x16x32_bf16 v[120:123], v[160:163], v[168:171], v[120:123]
	v_mfma_f32_16x16x32_bf16 v[112:115], v[144:147], v[182:185], v[112:115]
	v_mfma_f32_16x16x32_bf16 v[104:107], v[160:163], v[182:185], v[104:107]
	v_mfma_f32_16x16x32_bf16 v[96:99], v[144:147], v[194:197], v[96:99]
	v_mfma_f32_16x16x32_bf16 v[88:91], v[160:163], v[194:197], v[88:91]
	v_mfma_f32_16x16x32_bf16 v[80:83], v[144:147], v[202:205], v[80:83]
	v_mfma_f32_16x16x32_bf16 v[72:75], v[160:163], v[202:205], v[72:75]
	v_mfma_f32_16x16x32_bf16 v[124:127], v[156:159], v[172:175], v[124:127]
	v_mfma_f32_16x16x32_bf16 v[120:123], v[164:167], v[172:175], v[120:123]
	v_mfma_f32_16x16x32_bf16 v[112:115], v[156:159], v[190:193], v[112:115]
	v_mfma_f32_16x16x32_bf16 v[104:107], v[164:167], v[190:193], v[104:107]
	v_mfma_f32_16x16x32_bf16 v[96:99], v[156:159], v[198:201], v[96:99]
	v_mfma_f32_16x16x32_bf16 v[88:91], v[164:167], v[198:201], v[88:91]
	v_mfma_f32_16x16x32_bf16 v[80:83], v[156:159], v[206:209], v[80:83]
	v_mfma_f32_16x16x32_bf16 v[72:75], v[164:167], v[206:209], v[72:75]
	s_barrier
	s_add_i32 s22, 0, 0x1c000
	s_add_i32 s23, s48, s29
	v_add_u32_e32 v179, s22, v151
	v_lshl_add_u64 v[148:149], v[148:149], 0, s[6:7]
	s_mov_b32 m0, s23
	s_nop 0
	global_load_lds_dwordx4 v[148:149], off
	v_lshl_add_u64 v[148:149], v[186:187], 0, s[6:7]
	s_add_i32 m0, s23, 0x2000
	s_nop 0
	global_load_lds_dwordx4 v[148:149], off
	ds_read_b128 v[210:213], v179
	ds_read_b128 v[214:217], v179 offset:1024
	ds_read_b128 v[218:221], v179 offset:2048
	ds_read_b128 v[222:225], v179 offset:3072
	s_barrier
	s_waitcnt lgkmcnt(0)
	v_mfma_f32_16x16x32_bf16 v[116:119], v[210:213], v[168:171], v[116:119]
	v_mfma_f32_16x16x32_bf16 v[108:111], v[218:221], v[168:171], v[108:111]
	v_mfma_f32_16x16x32_bf16 v[100:103], v[210:213], v[182:185], v[100:103]
	v_mfma_f32_16x16x32_bf16 v[92:95], v[218:221], v[182:185], v[92:95]
	v_mfma_f32_16x16x32_bf16 v[84:87], v[210:213], v[194:197], v[84:87]
	v_mfma_f32_16x16x32_bf16 v[76:79], v[218:221], v[194:197], v[76:79]
	v_mfma_f32_16x16x32_bf16 v[68:71], v[210:213], v[202:205], v[68:71]
	v_mfma_f32_16x16x32_bf16 v[64:67], v[218:221], v[202:205], v[64:67]
	v_mfma_f32_16x16x32_bf16 v[116:119], v[214:217], v[172:175], v[116:119]
	v_mfma_f32_16x16x32_bf16 v[108:111], v[222:225], v[172:175], v[108:111]
	v_mfma_f32_16x16x32_bf16 v[100:103], v[214:217], v[190:193], v[100:103]
	v_mfma_f32_16x16x32_bf16 v[92:95], v[222:225], v[190:193], v[92:95]
	v_mfma_f32_16x16x32_bf16 v[84:87], v[214:217], v[198:201], v[84:87]
	v_mfma_f32_16x16x32_bf16 v[76:79], v[222:225], v[198:201], v[76:79]
	v_mfma_f32_16x16x32_bf16 v[68:71], v[214:217], v[206:209], v[68:71]
	v_mfma_f32_16x16x32_bf16 v[64:67], v[222:225], v[206:209], v[64:67]
	s_mov_b32 m0, s36
	v_lshl_add_u64 v[148:149], v[226:227], 0, s[6:7]
	s_barrier
	global_load_lds_dwordx4 v[148:149], off
	v_lshl_add_u64 v[148:149], v[228:229], 0, s[6:7]
	s_mov_b32 m0, s37
	s_nop 0
	global_load_lds_dwordx4 v[148:149], off
	ds_read_b128 v[168:171], v154 offset:49152
	ds_read_b128 v[172:175], v154 offset:50176
	ds_read_b128 v[182:185], v154 offset:51200
	ds_read_b128 v[190:193], v154 offset:52224
	ds_read_b128 v[194:197], v154 offset:53248
	ds_read_b128 v[198:201], v154 offset:54272
	ds_read_b128 v[202:205], v154 offset:55296
	ds_read_b128 v[206:209], v154 offset:56320
	s_barrier
; __device__ __forceinline__ unsigned cvt_pk_bf16(float lo, float hi) { unsigned r; asm volatile("v_cvt_pk_bf16_f32 %0, %1, %2" : "=v"(r) : "v"(lo), "v"(hi)); return r; }
; __device__ __forceinline__ float bf_lo(unsigned u) { return __uint_as_float(u << 16); }
; __device__ __forceinline__ float bf_hi(unsigned u) { return __uint_as_float(u & 0xffff0000u); }
; #define PG8_STAGE(bufoff, gbase, voff) do { _Pragma("unroll") for (int _i = 0; _i < 2; ++_i) \
;         __builtin_amdgcn_global_load_lds((const unsigned*)((const char*)(gbase) + (voff)[_i]), (PG8_LAS unsigned*)(lds + (bufoff) + ldsw + _i * 8192), 16, 0, 0); } while (0)
; #define PG8_WAIT_V(n) asm volatile("s_waitcnt vmcnt(" #n ")" ::: "memory")
; #define PG8_BAR __builtin_amdgcn_s_barrier()
;     __device__ __forceinline__ void operator()(const f32x4 (&acc)[2][2][4][2], const Unit& u, int wr, int wc, int fr, int fq) const {
;     ...
;             for (int m = 0; m < 4; ++m) { const size_t r = (size_t)(row0 + ai * HALF + m * 16); bf16_t* rowp = O + r * ldc + col0; const bf16_t* gp = G + r * ldg + col0;
; #pragma unroll
;                 for (int bj = 0; bj < 2; ++bj) { const u32x4 gw = *(const u32x4*)(gp + bj * HALF);
;                     f32x4 v0 = acc[ai][bj][m][0], v1 = acc[ai][bj][m][1];
;                     v0[0] *= bf_lo(gw.x); v0[1] *= bf_hi(gw.x); v0[2] *= bf_lo(gw.y); v0[3] *= bf_hi(gw.y);
;                     v1[0] *= bf_lo(gw.z); v1[1] *= bf_hi(gw.z); v1[2] *= bf_lo(gw.w); v1[3] *= bf_hi(gw.w);
;                     if (ACCUM) { const u32x4 pw = *(const u32x4*)(rowp + bj * HALF);
;                         v0[0] += bf_lo(pw.x); v0[1] += bf_hi(pw.x); v0[2] += bf_lo(pw.y); v0[3] += bf_hi(pw.y);
;                         v1[0] += bf_lo(pw.z); v1[1] += bf_hi(pw.z); v1[2] += bf_lo(pw.w); v1[3] += bf_hi(pw.w); }
;                     u32x4 w; w.x = cvt_pk_bf16(v0[0], v0[1]); w.y = cvt_pk_bf16(v0[2], v0[3]); w.z = cvt_pk_bf16(v1[0], v1[1]); w.w = cvt_pk_bf16(v1[2], v1[3]);
;                     *(u32x4*)(rowp + bj * HALF) = w; } }
; template <class Epi, class Sched>
; __device__ __forceinline__ void gemm_phase(PG8_LAS unsigned char* lds, const Gemm g, const Sched& S, const Epi& E) {
;     ...
;             PG8_BAR; PG8_WAIT_L(0); PG8_MMA(1, 0, At, B0); PG8_BAR; PG8_SCHED;
;             PG8_STAGE(PG8_SB(1, 1), b3 + hstep, voffB);
;             PG8_WAIT_V(6); PG8_BAR; PG8_MMA(1, 1, At, B1); PG8_BAR;
	s_waitcnt lgkmcnt(0)
	v_mfma_f32_16x16x32_bf16 v[60:63], v[144:147], v[168:171], v[60:63]
	v_mfma_f32_16x16x32_bf16 v[56:59], v[160:163], v[168:171], v[56:59]
	v_mfma_f32_16x16x32_bf16 v[48:51], v[144:147], v[182:185], v[48:51]
	v_mfma_f32_16x16x32_bf16 v[40:43], v[160:163], v[182:185], v[40:43]
	v_mfma_f32_16x16x32_bf16 v[32:35], v[144:147], v[194:197], v[32:35]
	v_mfma_f32_16x16x32_bf16 v[24:27], v[160:163], v[194:197], v[24:27]
	v_mfma_f32_16x16x32_bf16 v[16:19], v[144:147], v[202:205], v[16:19]
	v_mfma_f32_16x16x32_bf16 v[8:11], v[160:163], v[202:205], v[8:11]
	v_mfma_f32_16x16x32_bf16 v[60:63], v[156:159], v[172:175], v[60:63]
	v_mfma_f32_16x16x32_bf16 v[56:59], v[164:167], v[172:175], v[56:59]
	v_mfma_f32_16x16x32_bf16 v[48:51], v[156:159], v[190:193], v[48:51]
	v_mfma_f32_16x16x32_bf16 v[40:43], v[164:167], v[190:193], v[40:43]
	v_mfma_f32_16x16x32_bf16 v[32:35], v[156:159], v[198:201], v[32:35]
	v_mfma_f32_16x16x32_bf16 v[24:27], v[164:167], v[198:201], v[24:27]
	v_mfma_f32_16x16x32_bf16 v[16:19], v[156:159], v[206:209], v[16:19]
	v_mfma_f32_16x16x32_bf16 v[8:11], v[164:167], v[206:209], v[8:11]
	s_barrier
	s_add_u32 s20, s20, 0x40080
	s_addc_u32 s21, s21, 0
	s_add_i32 s22, s22, s29
	v_lshl_add_u64 v[144:145], s[20:21], 0, v[130:131]
	s_mov_b32 m0, s22
	s_nop 0
	global_load_lds_dwordx4 v[144:145], off
	v_lshl_add_u64 v[144:145], s[20:21], 0, v[134:135]
	s_add_i32 m0, s22, 0x2000
	s_nop 0
	global_load_lds_dwordx4 v[144:145], off
	s_waitcnt vmcnt(6)
	s_barrier
	v_mfma_f32_16x16x32_bf16 v[52:55], v[210:213], v[168:171], v[52:55]
	v_mfma_f32_16x16x32_bf16 v[44:47], v[218:221], v[168:171], v[44:47]
	v_mfma_f32_16x16x32_bf16 v[36:39], v[210:213], v[182:185], v[36:39]
	v_mfma_f32_16x16x32_bf16 v[28:31], v[218:221], v[182:185], v[28:31]
	v_mfma_f32_16x16x32_bf16 v[20:23], v[210:213], v[194:197], v[20:23]
	v_mfma_f32_16x16x32_bf16 v[12:15], v[218:221], v[194:197], v[12:15]
	v_mfma_f32_16x16x32_bf16 v[4:7], v[210:213], v[202:205], v[4:7]
	v_mfma_f32_16x16x32_bf16 v[0:3], v[218:221], v[202:205], v[0:3]
	v_mfma_f32_16x16x32_bf16 v[52:55], v[214:217], v[172:175], v[52:55]
	v_mfma_f32_16x16x32_bf16 v[44:47], v[222:225], v[172:175], v[44:47]
	v_mfma_f32_16x16x32_bf16 v[36:39], v[214:217], v[190:193], v[36:39]
	v_mfma_f32_16x16x32_bf16 v[28:31], v[222:225], v[190:193], v[28:31]
	v_mfma_f32_16x16x32_bf16 v[20:23], v[214:217], v[198:201], v[20:23]
	v_mfma_f32_16x16x32_bf16 v[12:15], v[222:225], v[198:201], v[12:15]
	v_mfma_f32_16x16x32_bf16 v[4:7], v[214:217], v[206:209], v[4:7]
	v_mfma_f32_16x16x32_bf16 v[0:3], v[222:225], v[206:209], v[0:3]
	s_add_i32 s47, s47, 2
	s_add_u32 s18, s18, 0x100
	s_addc_u32 s19, s19, 0
	s_add_u32 s45, s45, 0x100
	s_addc_u32 s46, s46, 0
	s_cmp_gt_u32 s47, 13
	s_barrier
	s_cbranch_scc0 .LBB0_991
	v_lshl_or_b32 v144, s42, 8, v152
	v_lshl_add_u32 v146, s16, 8, v150
	v_ashrrev_i32_e32 v145, 31, v144
	v_mov_b64_e32 v[148:149], s[4:5]
	v_lshlrev_b64 v[144:145], 1, v[144:145]
	v_mad_i64_i32 v[156:157], s[18:19], v146, s41, v[148:149]
	v_lshl_add_u64 v[160:161], v[156:157], 0, v[144:145]
	global_load_dwordx4 v[156:159], v[160:161], off offset:3072
	s_and_b64 vcc, exec, s[2:3]
	s_mov_b32 s42, s8
	s_mov_b32 s16, s10
	s_mov_b64 s[20:21], s[14:15]
	s_waitcnt vmcnt(0)
	v_lshlrev_b32_e32 v147, 16, v156
	v_and_b32_e32 v156, 0xffff0000, v156
	v_lshlrev_b32_e32 v162, 16, v157
	v_and_b32_e32 v157, 0xffff0000, v157
	v_lshlrev_b32_e32 v164, 16, v159
	v_and_b32_e32 v159, 0xffff0000, v159
	v_lshlrev_b32_e32 v163, 16, v158
	v_and_b32_e32 v158, 0xffff0000, v158
	v_mul_f32_e32 v124, v124, v147
	v_mul_f32_e32 v125, v125, v156
	v_mul_f32_e32 v126, v126, v162
	v_mul_f32_e32 v127, v127, v157
	v_mul_f32_e32 v123, v123, v159
	v_mul_f32_e32 v147, v120, v163
	v_mul_f32_e32 v156, v121, v158
	v_mul_f32_e32 v157, v122, v164
	v_cvt_pk_bf16_f32 v120, v124, v125
	v_cvt_pk_bf16_f32 v121, v126, v127
	v_cvt_pk_bf16_f32 v122, v147, v156
	v_cvt_pk_bf16_f32 v123, v157, v123
	global_load_dwordx4 v[124:127], v[160:161], off offset:3328
	v_ashrrev_i32_e32 v147, 31, v146
	v_lshlrev_b64 v[158:159], 11, v[146:147]
	v_lshl_add_u64 v[158:159], s[0:1], 0, v[158:159]
	v_or_b32_e32 v156, 16, v146
	v_lshl_add_u64 v[158:159], v[158:159], 0, v[144:145]
	v_mad_i64_i32 v[160:161], s[18:19], v156, s41, v[148:149]
	global_store_dwordx4 v[158:159], v[120:123], off
	v_lshl_add_u64 v[160:161], v[160:161], 0, v[144:145]
	v_ashrrev_i32_e32 v157, 31, v156
	s_waitcnt vmcnt(0)
	v_lshlrev_b32_e32 v120, 16, v124
	v_and_b32_e32 v121, 0xffff0000, v124
	v_lshlrev_b32_e32 v122, 16, v125
	v_and_b32_e32 v123, 0xffff0000, v125
	v_lshlrev_b32_e32 v124, 16, v126
	v_and_b32_e32 v125, 0xffff0000, v126
	v_lshlrev_b32_e32 v126, 16, v127
	v_and_b32_e32 v127, 0xffff0000, v127
	v_mul_f32_e32 v116, v116, v120
	v_mul_f32_e32 v117, v117, v121
	v_mul_f32_e32 v118, v118, v122
	v_mul_f32_e32 v119, v119, v123
	v_mul_f32_e32 v111, v111, v127
	v_mul_f32_e32 v120, v108, v124
	v_mul_f32_e32 v121, v109, v125
	v_mul_f32_e32 v122, v110, v126
	v_cvt_pk_bf16_f32 v108, v116, v117
	v_cvt_pk_bf16_f32 v109, v118, v119
	v_cvt_pk_bf16_f32 v110, v120, v121
	v_cvt_pk_bf16_f32 v111, v122, v111
	global_load_dwordx4 v[116:119], v[160:161], off offset:3072
	s_nop 0
	global_store_dwordx4 v[158:159], v[108:111], off offset:256
	s_waitcnt vmcnt(0)
; __device__ __forceinline__ unsigned cvt_pk_bf16(float lo, float hi) { unsigned r; asm volatile("v_cvt_pk_bf16_f32 %0, %1, %2" : "=v"(r) : "v"(lo), "v"(hi)); return r; }
; __device__ __forceinline__ float bf_lo(unsigned u) { return __uint_as_float(u << 16); }
; __device__ __forceinline__ float bf_hi(unsigned u) { return __uint_as_float(u & 0xffff0000u); }
;     __device__ __forceinline__ void operator()(const f32x4 (&acc)[2][2][4][2], const Unit& u, int wr, int wc, int fr, int fq) const {
;     ...
;             for (int m = 0; m < 4; ++m) { const size_t r = (size_t)(row0 + ai * HALF + m * 16); bf16_t* rowp = O + r * ldc + col0; const bf16_t* gp = G + r * ldg + col0;
; #pragma unroll
;                 for (int bj = 0; bj < 2; ++bj) { const u32x4 gw = *(const u32x4*)(gp + bj * HALF);
;                     f32x4 v0 = acc[ai][bj][m][0], v1 = acc[ai][bj][m][1];
;                     v0[0] *= bf_lo(gw.x); v0[1] *= bf_hi(gw.x); v0[2] *= bf_lo(gw.y); v0[3] *= bf_hi(gw.y);
;                     v1[0] *= bf_lo(gw.z); v1[1] *= bf_hi(gw.z); v1[2] *= bf_lo(gw.w); v1[3] *= bf_hi(gw.w);
;                     if (ACCUM) { const u32x4 pw = *(const u32x4*)(rowp + bj * HALF);
;                         v0[0] += bf_lo(pw.x); v0[1] += bf_hi(pw.x); v0[2] += bf_lo(pw.y); v0[3] += bf_hi(pw.y);
;                         v1[0] += bf_lo(pw.z); v1[1] += bf_hi(pw.z); v1[2] += bf_lo(pw.w); v1[3] += bf_hi(pw.w); }
;                     u32x4 w; w.x = cvt_pk_bf16(v0[0], v0[1]); w.y = cvt_pk_bf16(v0[2], v0[3]); w.z = cvt_pk_bf16(v1[0], v1[1]); w.w = cvt_pk_bf16(v1[2], v1[3]);
;                     *(u32x4*)(rowp + bj * HALF) = w; } }
	s_nop 0
	v_lshlrev_b32_e32 v108, 16, v116
	v_and_b32_e32 v109, 0xffff0000, v116
	v_lshlrev_b32_e32 v110, 16, v117
	v_and_b32_e32 v111, 0xffff0000, v117
	v_lshlrev_b32_e32 v116, 16, v118
	v_and_b32_e32 v117, 0xffff0000, v118
	v_lshlrev_b32_e32 v118, 16, v119
	v_and_b32_e32 v119, 0xffff0000, v119
	v_mul_f32_e32 v108, v112, v108
	v_mul_f32_e32 v109, v113, v109
	v_mul_f32_e32 v110, v114, v110
	v_mul_f32_e32 v111, v115, v111
	v_mul_f32_e32 v107, v107, v119
	v_mul_f32_e32 v112, v104, v116
	v_mul_f32_e32 v113, v105, v117
	v_mul_f32_e32 v114, v106, v118
	v_cvt_pk_bf16_f32 v104, v108, v109
	v_cvt_pk_bf16_f32 v105, v110, v111
	v_cvt_pk_bf16_f32 v106, v112, v113
	v_cvt_pk_bf16_f32 v107, v114, v107
	global_load_dwordx4 v[108:111], v[160:161], off offset:3328
	v_lshlrev_b64 v[116:117], 11, v[156:157]
	v_lshl_add_u64 v[116:117], s[0:1], 0, v[116:117]
	v_or_b32_e32 v112, 32, v146
	v_lshl_add_u64 v[116:117], v[116:117], 0, v[144:145]
	v_mad_i64_i32 v[114:115], s[18:19], v112, s41, v[148:149]
	global_store_dwordx4 v[116:117], v[104:107], off
	v_lshl_add_u64 v[114:115], v[114:115], 0, v[144:145]
	v_ashrrev_i32_e32 v113, 31, v112
	s_waitcnt vmcnt(0)
	v_lshlrev_b32_e32 v104, 16, v108
	v_and_b32_e32 v105, 0xffff0000, v108
	v_lshlrev_b32_e32 v106, 16, v109
	v_and_b32_e32 v107, 0xffff0000, v109
	v_lshlrev_b32_e32 v108, 16, v110
	v_and_b32_e32 v109, 0xffff0000, v110
	v_lshlrev_b32_e32 v110, 16, v111
	v_and_b32_e32 v111, 0xffff0000, v111
	v_mul_f32_e32 v100, v100, v104
	v_mul_f32_e32 v101, v101, v105
	v_mul_f32_e32 v102, v102, v106
	v_mul_f32_e32 v103, v103, v107
	v_mul_f32_e32 v95, v95, v111
	v_mul_f32_e32 v104, v92, v108
	v_mul_f32_e32 v105, v93, v109
	v_mul_f32_e32 v106, v94, v110
	v_cvt_pk_bf16_f32 v92, v100, v101
	v_cvt_pk_bf16_f32 v93, v102, v103
	v_cvt_pk_bf16_f32 v94, v104, v105
	v_cvt_pk_bf16_f32 v95, v106, v95
	global_load_dwordx4 v[100:103], v[114:115], off offset:3072
	s_nop 0
	global_store_dwordx4 v[116:117], v[92:95], off offset:256
	s_waitcnt vmcnt(0)
	s_nop 0
	v_lshlrev_b32_e32 v92, 16, v100
	v_and_b32_e32 v93, 0xffff0000, v100
	v_lshlrev_b32_e32 v94, 16, v101
	v_and_b32_e32 v95, 0xffff0000, v101
	v_lshlrev_b32_e32 v100, 16, v102
	v_and_b32_e32 v101, 0xffff0000, v102
	v_lshlrev_b32_e32 v102, 16, v103
	v_and_b32_e32 v103, 0xffff0000, v103
	v_mul_f32_e32 v92, v96, v92
	v_mul_f32_e32 v93, v97, v93
	v_mul_f32_e32 v94, v98, v94
	v_mul_f32_e32 v95, v99, v95
	v_mul_f32_e32 v91, v91, v103
	v_mul_f32_e32 v96, v88, v100
	v_mul_f32_e32 v97, v89, v101
	v_mul_f32_e32 v98, v90, v102
	v_cvt_pk_bf16_f32 v88, v92, v93
	v_cvt_pk_bf16_f32 v89, v94, v95
	v_cvt_pk_bf16_f32 v90, v96, v97
	v_cvt_pk_bf16_f32 v91, v98, v91
	global_load_dwordx4 v[92:95], v[114:115], off offset:3328
	v_lshlrev_b64 v[100:101], 11, v[112:113]
	v_lshl_add_u64 v[100:101], s[0:1], 0, v[100:101]
	v_or_b32_e32 v96, 48, v146
	v_lshl_add_u64 v[100:101], v[100:101], 0, v[144:145]
	v_mad_i64_i32 v[98:99], s[18:19], v96, s41, v[148:149]
	global_store_dwordx4 v[100:101], v[88:91], off
	v_lshl_add_u64 v[98:99], v[98:99], 0, v[144:145]
	v_ashrrev_i32_e32 v97, 31, v96
	s_waitcnt vmcnt(0)
	v_lshlrev_b32_e32 v88, 16, v92
	v_and_b32_e32 v89, 0xffff0000, v92
	v_lshlrev_b32_e32 v90, 16, v93
	v_and_b32_e32 v91, 0xffff0000, v93
	v_lshlrev_b32_e32 v92, 16, v94
	v_and_b32_e32 v93, 0xffff0000, v94
	v_lshlrev_b32_e32 v94, 16, v95
	v_and_b32_e32 v95, 0xffff0000, v95
	v_mul_f32_e32 v84, v84, v88
	v_mul_f32_e32 v85, v85, v89
	v_mul_f32_e32 v86, v86, v90
	v_mul_f32_e32 v87, v87, v91
	v_mul_f32_e32 v79, v79, v95
	v_mul_f32_e32 v88, v76, v92
	v_mul_f32_e32 v89, v77, v93
	v_mul_f32_e32 v90, v78, v94
	v_cvt_pk_bf16_f32 v76, v84, v85
	v_cvt_pk_bf16_f32 v77, v86, v87
	v_cvt_pk_bf16_f32 v78, v88, v89
	v_cvt_pk_bf16_f32 v79, v90, v79
	global_load_dwordx4 v[84:87], v[98:99], off offset:3072
	s_nop 0
	global_store_dwordx4 v[100:101], v[76:79], off offset:256
	s_waitcnt vmcnt(0)
	s_nop 0
	v_lshlrev_b32_e32 v76, 16, v84
	v_and_b32_e32 v77, 0xffff0000, v84
	v_lshlrev_b32_e32 v78, 16, v85
	v_and_b32_e32 v79, 0xffff0000, v85
	v_lshlrev_b32_e32 v84, 16, v86
	v_and_b32_e32 v85, 0xffff0000, v86
	v_lshlrev_b32_e32 v86, 16, v87
	v_and_b32_e32 v87, 0xffff0000, v87
	v_mul_f32_e32 v76, v80, v76
	v_mul_f32_e32 v77, v81, v77
	v_mul_f32_e32 v78, v82, v78
	v_mul_f32_e32 v79, v83, v79
	v_mul_f32_e32 v75, v75, v87
	v_mul_f32_e32 v80, v72, v84
	v_mul_f32_e32 v81, v73, v85
	v_mul_f32_e32 v82, v74, v86
	v_cvt_pk_bf16_f32 v72, v76, v77
	v_cvt_pk_bf16_f32 v73, v78, v79
	v_cvt_pk_bf16_f32 v74, v80, v81
	v_cvt_pk_bf16_f32 v75, v82, v75
	global_load_dwordx4 v[76:79], v[98:99], off offset:3328
	v_lshlrev_b64 v[84:85], 11, v[96:97]
	v_lshl_add_u64 v[84:85], s[0:1], 0, v[84:85]
	v_add_u32_e32 v80, 0x80, v146
	v_lshl_add_u64 v[84:85], v[84:85], 0, v[144:145]
	v_mad_i64_i32 v[82:83], s[18:19], v80, s41, v[148:149]
	global_store_dwordx4 v[84:85], v[72:75], off
	v_lshl_add_u64 v[82:83], v[82:83], 0, v[144:145]
	v_ashrrev_i32_e32 v81, 31, v80
	s_waitcnt vmcnt(0)
	v_lshlrev_b32_e32 v72, 16, v76
	v_and_b32_e32 v73, 0xffff0000, v76
	v_lshlrev_b32_e32 v74, 16, v77
	v_and_b32_e32 v75, 0xffff0000, v77
	v_lshlrev_b32_e32 v76, 16, v78
	v_and_b32_e32 v77, 0xffff0000, v78
	v_lshlrev_b32_e32 v78, 16, v79
	v_and_b32_e32 v79, 0xffff0000, v79
	v_mul_f32_e32 v68, v68, v72
	v_mul_f32_e32 v69, v69, v73
	v_mul_f32_e32 v70, v70, v74
	v_mul_f32_e32 v71, v71, v75
	v_mul_f32_e32 v67, v67, v79
	v_mul_f32_e32 v72, v64, v76
	v_mul_f32_e32 v73, v65, v77
	v_mul_f32_e32 v74, v66, v78
	v_cvt_pk_bf16_f32 v64, v68, v69
	v_cvt_pk_bf16_f32 v65, v70, v71
	v_cvt_pk_bf16_f32 v66, v72, v73
	v_cvt_pk_bf16_f32 v67, v74, v67
	global_load_dwordx4 v[68:71], v[82:83], off offset:3072
	s_nop 0
	global_store_dwordx4 v[84:85], v[64:67], off offset:256
	s_waitcnt vmcnt(0)
; __device__ __forceinline__ unsigned cvt_pk_bf16(float lo, float hi) { unsigned r; asm volatile("v_cvt_pk_bf16_f32 %0, %1, %2" : "=v"(r) : "v"(lo), "v"(hi)); return r; }
; __device__ __forceinline__ float bf_lo(unsigned u) { return __uint_as_float(u << 16); }
; __device__ __forceinline__ float bf_hi(unsigned u) { return __uint_as_float(u & 0xffff0000u); }
;     __device__ __forceinline__ void operator()(const f32x4 (&acc)[2][2][4][2], const Unit& u, int wr, int wc, int fr, int fq) const {
;     ...
;             for (int m = 0; m < 4; ++m) { const size_t r = (size_t)(row0 + ai * HALF + m * 16); bf16_t* rowp = O + r * ldc + col0; const bf16_t* gp = G + r * ldg + col0;
; #pragma unroll
;                 for (int bj = 0; bj < 2; ++bj) { const u32x4 gw = *(const u32x4*)(gp + bj * HALF);
;                     f32x4 v0 = acc[ai][bj][m][0], v1 = acc[ai][bj][m][1];
;                     v0[0] *= bf_lo(gw.x); v0[1] *= bf_hi(gw.x); v0[2] *= bf_lo(gw.y); v0[3] *= bf_hi(gw.y);
;                     v1[0] *= bf_lo(gw.z); v1[1] *= bf_hi(gw.z); v1[2] *= bf_lo(gw.w); v1[3] *= bf_hi(gw.w);
;                     if (ACCUM) { const u32x4 pw = *(const u32x4*)(rowp + bj * HALF);
;                         v0[0] += bf_lo(pw.x); v0[1] += bf_hi(pw.x); v0[2] += bf_lo(pw.y); v0[3] += bf_hi(pw.y);
;                         v1[0] += bf_lo(pw.z); v1[1] += bf_hi(pw.z); v1[2] += bf_lo(pw.w); v1[3] += bf_hi(pw.w); }
;                     u32x4 w; w.x = cvt_pk_bf16(v0[0], v0[1]); w.y = cvt_pk_bf16(v0[2], v0[3]); w.z = cvt_pk_bf16(v1[0], v1[1]); w.w = cvt_pk_bf16(v1[2], v1[3]);
;                     *(u32x4*)(rowp + bj * HALF) = w; } }
	s_nop 0
	v_lshlrev_b32_e32 v64, 16, v68
	v_and_b32_e32 v65, 0xffff0000, v68
	v_lshlrev_b32_e32 v66, 16, v69
	v_and_b32_e32 v67, 0xffff0000, v69
	v_lshlrev_b32_e32 v68, 16, v70
	v_and_b32_e32 v69, 0xffff0000, v70
	v_lshlrev_b32_e32 v70, 16, v71
	v_and_b32_e32 v71, 0xffff0000, v71
	v_mul_f32_e32 v60, v60, v64
	v_mul_f32_e32 v61, v61, v65
	v_mul_f32_e32 v62, v62, v66
	v_mul_f32_e32 v63, v63, v67
	v_mul_f32_e32 v59, v59, v71
	v_mul_f32_e32 v64, v56, v68
	v_mul_f32_e32 v65, v57, v69
	v_mul_f32_e32 v66, v58, v70
	v_cvt_pk_bf16_f32 v56, v60, v61
	v_cvt_pk_bf16_f32 v57, v62, v63
	v_cvt_pk_bf16_f32 v58, v64, v65
	v_cvt_pk_bf16_f32 v59, v66, v59
	global_load_dwordx4 v[60:63], v[82:83], off offset:3328
	v_lshlrev_b64 v[68:69], 11, v[80:81]
	v_lshl_add_u64 v[68:69], s[0:1], 0, v[68:69]
	v_add_u32_e32 v64, 0x90, v146
	v_lshl_add_u64 v[68:69], v[68:69], 0, v[144:145]
	v_mad_i64_i32 v[66:67], s[18:19], v64, s41, v[148:149]
	global_store_dwordx4 v[68:69], v[56:59], off
	v_lshl_add_u64 v[66:67], v[66:67], 0, v[144:145]
	v_ashrrev_i32_e32 v65, 31, v64
	s_waitcnt vmcnt(0)
	v_lshlrev_b32_e32 v56, 16, v60
	v_and_b32_e32 v57, 0xffff0000, v60
	v_lshlrev_b32_e32 v58, 16, v61
	v_and_b32_e32 v59, 0xffff0000, v61
	v_lshlrev_b32_e32 v60, 16, v62
	v_and_b32_e32 v61, 0xffff0000, v62
	v_lshlrev_b32_e32 v62, 16, v63
	v_and_b32_e32 v63, 0xffff0000, v63
	v_mul_f32_e32 v52, v52, v56
	v_mul_f32_e32 v53, v53, v57
	v_mul_f32_e32 v54, v54, v58
	v_mul_f32_e32 v55, v55, v59
	v_mul_f32_e32 v47, v47, v63
	v_mul_f32_e32 v56, v44, v60
	v_mul_f32_e32 v57, v45, v61
	v_mul_f32_e32 v58, v46, v62
	v_cvt_pk_bf16_f32 v44, v52, v53
	v_cvt_pk_bf16_f32 v45, v54, v55
	v_cvt_pk_bf16_f32 v46, v56, v57
	v_cvt_pk_bf16_f32 v47, v58, v47
	global_load_dwordx4 v[52:55], v[66:67], off offset:3072
	s_nop 0
	global_store_dwordx4 v[68:69], v[44:47], off offset:256
	s_waitcnt vmcnt(0)
	s_nop 0
	v_lshlrev_b32_e32 v44, 16, v52
	v_and_b32_e32 v45, 0xffff0000, v52
	v_lshlrev_b32_e32 v46, 16, v53
	v_and_b32_e32 v47, 0xffff0000, v53
	v_lshlrev_b32_e32 v52, 16, v54
	v_and_b32_e32 v53, 0xffff0000, v54
	v_lshlrev_b32_e32 v54, 16, v55
	v_and_b32_e32 v55, 0xffff0000, v55
	v_mul_f32_e32 v44, v48, v44
	v_mul_f32_e32 v45, v49, v45
	v_mul_f32_e32 v46, v50, v46
	v_mul_f32_e32 v47, v51, v47
	v_mul_f32_e32 v43, v43, v55
	v_mul_f32_e32 v48, v40, v52
	v_mul_f32_e32 v49, v41, v53
	v_mul_f32_e32 v50, v42, v54
	v_cvt_pk_bf16_f32 v40, v44, v45
	v_cvt_pk_bf16_f32 v41, v46, v47
	v_cvt_pk_bf16_f32 v42, v48, v49
	v_cvt_pk_bf16_f32 v43, v50, v43
	global_load_dwordx4 v[44:47], v[66:67], off offset:3328
	v_lshlrev_b64 v[52:53], 11, v[64:65]
	v_lshl_add_u64 v[52:53], s[0:1], 0, v[52:53]
	v_add_u32_e32 v48, 0xa0, v146
	v_lshl_add_u64 v[52:53], v[52:53], 0, v[144:145]
	v_mad_i64_i32 v[50:51], s[18:19], v48, s41, v[148:149]
	global_store_dwordx4 v[52:53], v[40:43], off
	v_lshl_add_u64 v[50:51], v[50:51], 0, v[144:145]
	v_ashrrev_i32_e32 v49, 31, v48
	s_waitcnt vmcnt(0)
	v_lshlrev_b32_e32 v40, 16, v44
	v_and_b32_e32 v41, 0xffff0000, v44
	v_lshlrev_b32_e32 v42, 16, v45
	v_and_b32_e32 v43, 0xffff0000, v45
	v_lshlrev_b32_e32 v44, 16, v46
	v_and_b32_e32 v45, 0xffff0000, v46
	v_lshlrev_b32_e32 v46, 16, v47
	v_and_b32_e32 v47, 0xffff0000, v47
	v_mul_f32_e32 v36, v36, v40
	v_mul_f32_e32 v37, v37, v41
	v_mul_f32_e32 v38, v38, v42
	v_mul_f32_e32 v39, v39, v43
	v_mul_f32_e32 v31, v31, v47
	v_mul_f32_e32 v40, v28, v44
	v_mul_f32_e32 v41, v29, v45
	v_mul_f32_e32 v42, v30, v46
	v_cvt_pk_bf16_f32 v28, v36, v37
	v_cvt_pk_bf16_f32 v29, v38, v39
	v_cvt_pk_bf16_f32 v30, v40, v41
	v_cvt_pk_bf16_f32 v31, v42, v31
	global_load_dwordx4 v[36:39], v[50:51], off offset:3072
	s_nop 0
	global_store_dwordx4 v[52:53], v[28:31], off offset:256
	s_waitcnt vmcnt(0)
; __device__ __forceinline__ unsigned cvt_pk_bf16(float lo, float hi) { unsigned r; asm volatile("v_cvt_pk_bf16_f32 %0, %1, %2" : "=v"(r) : "v"(lo), "v"(hi)); return r; }
; __device__ __forceinline__ float bf_lo(unsigned u) { return __uint_as_float(u << 16); }
; __device__ __forceinline__ float bf_hi(unsigned u) { return __uint_as_float(u & 0xffff0000u); }
; #define PG8_WAIT_V(n) asm volatile("s_waitcnt vmcnt(" #n ")" ::: "memory")
; #define PG8_BAR __builtin_amdgcn_s_barrier()
;     __device__ __forceinline__ void operator()(const f32x4 (&acc)[2][2][4][2], const Unit& u, int wr, int wc, int fr, int fq) const {
;     ...
;             for (int m = 0; m < 4; ++m) { const size_t r = (size_t)(row0 + ai * HALF + m * 16); bf16_t* rowp = O + r * ldc + col0; const bf16_t* gp = G + r * ldg + col0;
; #pragma unroll
;                 for (int bj = 0; bj < 2; ++bj) { const u32x4 gw = *(const u32x4*)(gp + bj * HALF);
;                     f32x4 v0 = acc[ai][bj][m][0], v1 = acc[ai][bj][m][1];
;                     v0[0] *= bf_lo(gw.x); v0[1] *= bf_hi(gw.x); v0[2] *= bf_lo(gw.y); v0[3] *= bf_hi(gw.y);
;                     v1[0] *= bf_lo(gw.z); v1[1] *= bf_hi(gw.z); v1[2] *= bf_lo(gw.w); v1[3] *= bf_hi(gw.w);
;                     if (ACCUM) { const u32x4 pw = *(const u32x4*)(rowp + bj * HALF);
;                         v0[0] += bf_lo(pw.x); v0[1] += bf_hi(pw.x); v0[2] += bf_lo(pw.y); v0[3] += bf_hi(pw.y);
;                         v1[0] += bf_lo(pw.z); v1[1] += bf_hi(pw.z); v1[2] += bf_lo(pw.w); v1[3] += bf_hi(pw.w); }
;                     u32x4 w; w.x = cvt_pk_bf16(v0[0], v0[1]); w.y = cvt_pk_bf16(v0[2], v0[3]); w.z = cvt_pk_bf16(v1[0], v1[1]); w.w = cvt_pk_bf16(v1[2], v1[3]);
;                     *(u32x4*)(rowp + bj * HALF) = w; } }
; template <class Epi, class Sched>
; __device__ __forceinline__ void gemm_phase(PG8_LAS unsigned char* lds, const Gemm g, const Sched& S, const Epi& E) {
;     ...
;         if (!has_next) break;
; #pragma unroll
;         for (int a = 0; a < 2; ++a)
; #pragma unroll
;             for (int b = 0; b < 2; ++b)
; #pragma unroll
;                 for (int m = 0; m < 4; ++m)
; #pragma unroll
;                     for (int n = 0; n < 2; ++n) acc[a][b][m][n] = (f32x4){0.f, 0.f, 0.f, 0.f};
;         cur = nxt; cA = nA; cB = nB; ++ui;
;     }
;     PG8_WAIT_V(0);
;     if (wr == 0) PG8_BAR;
;     PG8_BAR;
	s_nop 0
	v_lshlrev_b32_e32 v28, 16, v36
	v_and_b32_e32 v29, 0xffff0000, v36
	v_lshlrev_b32_e32 v30, 16, v37
	v_and_b32_e32 v31, 0xffff0000, v37
	v_lshlrev_b32_e32 v36, 16, v38
	v_and_b32_e32 v37, 0xffff0000, v38
	v_lshlrev_b32_e32 v38, 16, v39
	v_and_b32_e32 v39, 0xffff0000, v39
	v_mul_f32_e32 v28, v32, v28
	v_mul_f32_e32 v29, v33, v29
	v_mul_f32_e32 v30, v34, v30
	v_mul_f32_e32 v31, v35, v31
	v_mul_f32_e32 v27, v27, v39
	v_mul_f32_e32 v32, v24, v36
	v_mul_f32_e32 v33, v25, v37
	v_mul_f32_e32 v34, v26, v38
	v_cvt_pk_bf16_f32 v24, v28, v29
	v_cvt_pk_bf16_f32 v25, v30, v31
	v_cvt_pk_bf16_f32 v26, v32, v33
	v_cvt_pk_bf16_f32 v27, v34, v27
	global_load_dwordx4 v[28:31], v[50:51], off offset:3328
	v_lshlrev_b64 v[36:37], 11, v[48:49]
	v_lshl_add_u64 v[36:37], s[0:1], 0, v[36:37]
	v_add_u32_e32 v32, 0xb0, v146
	v_lshl_add_u64 v[36:37], v[36:37], 0, v[144:145]
	v_mad_i64_i32 v[34:35], s[18:19], v32, s41, v[148:149]
	global_store_dwordx4 v[36:37], v[24:27], off
	v_lshl_add_u64 v[34:35], v[34:35], 0, v[144:145]
	v_ashrrev_i32_e32 v33, 31, v32
	s_mov_b64 s[18:19], s[12:13]
	s_waitcnt vmcnt(0)
	v_lshlrev_b32_e32 v24, 16, v28
	v_and_b32_e32 v25, 0xffff0000, v28
	v_lshlrev_b32_e32 v26, 16, v29
	v_and_b32_e32 v27, 0xffff0000, v29
	v_lshlrev_b32_e32 v28, 16, v30
	v_and_b32_e32 v29, 0xffff0000, v30
	v_lshlrev_b32_e32 v30, 16, v31
	v_and_b32_e32 v31, 0xffff0000, v31
	v_mul_f32_e32 v20, v20, v24
	v_mul_f32_e32 v21, v21, v25
	v_mul_f32_e32 v22, v22, v26
	v_mul_f32_e32 v23, v23, v27
	v_mul_f32_e32 v15, v15, v31
	v_mul_f32_e32 v24, v12, v28
	v_mul_f32_e32 v25, v13, v29
	v_mul_f32_e32 v26, v14, v30
	v_cvt_pk_bf16_f32 v12, v20, v21
	v_cvt_pk_bf16_f32 v13, v22, v23
	v_cvt_pk_bf16_f32 v14, v24, v25
	v_cvt_pk_bf16_f32 v15, v26, v15
	global_load_dwordx4 v[20:23], v[34:35], off offset:3072
	s_nop 0
	global_store_dwordx4 v[36:37], v[12:15], off offset:256
	s_waitcnt vmcnt(0)
	s_nop 0
	v_lshlrev_b32_e32 v12, 16, v20
	v_and_b32_e32 v13, 0xffff0000, v20
	v_lshlrev_b32_e32 v14, 16, v21
	v_and_b32_e32 v15, 0xffff0000, v21
	v_lshlrev_b32_e32 v20, 16, v22
	v_and_b32_e32 v21, 0xffff0000, v22
	v_lshlrev_b32_e32 v22, 16, v23
	v_and_b32_e32 v23, 0xffff0000, v23
	v_mul_f32_e32 v12, v16, v12
	v_mul_f32_e32 v13, v17, v13
	v_mul_f32_e32 v14, v18, v14
	v_mul_f32_e32 v15, v19, v15
	v_mul_f32_e32 v11, v11, v23
	v_mul_f32_e32 v16, v8, v20
	v_mul_f32_e32 v17, v9, v21
	v_mul_f32_e32 v18, v10, v22
	v_cvt_pk_bf16_f32 v8, v12, v13
	v_cvt_pk_bf16_f32 v9, v14, v15
	v_cvt_pk_bf16_f32 v10, v16, v17
	v_cvt_pk_bf16_f32 v11, v18, v11
	global_load_dwordx4 v[12:15], v[34:35], off offset:3328
	v_lshlrev_b64 v[16:17], 11, v[32:33]
	v_lshl_add_u64 v[16:17], s[0:1], 0, v[16:17]
	v_lshl_add_u64 v[16:17], v[16:17], 0, v[144:145]
	global_store_dwordx4 v[16:17], v[8:11], off
	s_waitcnt vmcnt(0)
	s_nop 0
	v_lshlrev_b32_e32 v8, 16, v12
	v_and_b32_e32 v9, 0xffff0000, v12
	v_lshlrev_b32_e32 v10, 16, v13
	v_and_b32_e32 v11, 0xffff0000, v13
	v_lshlrev_b32_e32 v12, 16, v14
	v_and_b32_e32 v13, 0xffff0000, v14
	v_lshlrev_b32_e32 v14, 16, v15
	v_and_b32_e32 v15, 0xffff0000, v15
	v_mul_f32_e32 v3, v3, v15
	v_mul_f32_e32 v4, v4, v8
	v_mul_f32_e32 v5, v5, v9
	v_mul_f32_e32 v6, v6, v10
	v_mul_f32_e32 v7, v7, v11
	v_mul_f32_e32 v8, v0, v12
	v_mul_f32_e32 v9, v1, v13
	v_mul_f32_e32 v10, v2, v14
	v_cvt_pk_bf16_f32 v0, v4, v5
	v_cvt_pk_bf16_f32 v1, v6, v7
	v_cvt_pk_bf16_f32 v2, v8, v9
	v_cvt_pk_bf16_f32 v3, v10, v3
	global_store_dwordx4 v[16:17], v[0:3], off offset:256
	s_cbranch_vccz .LBB0_984
	s_waitcnt vmcnt(0)
	s_cmpk_gt_u32 s25, 0xff
	s_cbranch_scc1 .LBB0_995
	s_barrier

; #define PG8_STAGE(bufoff, gbase, voff) do { _Pragma("unroll") for (int _i = 0; _i < 2; ++_i) \
;         __builtin_amdgcn_global_load_lds((const unsigned*)((const char*)(gbase) + (voff)[_i]), (PG8_LAS unsigned*)(lds + (bufoff) + ldsw + _i * 8192), 16, 0, 0); } while (0)
; #define PG8_LDA(dst, b, h) do { _Pragma("unroll") for (int m = 0; m < 4; ++m) _Pragma("unroll") for (int k = 0; k < 2; ++k) dst[m][k] = *(const PG8_LAS bf16x8*)(lds + PG8_SA(b, h) + aoff + m * 2048 + k * 1024); } while (0)
; #define PG8_LDB(dst, b, h) do { _Pragma("unroll") for (int n = 0; n < 2; ++n) _Pragma("unroll") for (int k = 0; k < 2; ++k) dst[n][k] = *(const PG8_LAS bf16x8*)(lds + PG8_SB(b, h) + boff + n * 2048 + k * 1024); } while (0)
; #define PG8_MMA(ai, bj, At, Bt) do { __builtin_amdgcn_s_setprio(1); _Pragma("unroll") for (int m = 0; m < 4; ++m) _Pragma("unroll") for (int n = 0; n < 2; ++n) _Pragma("unroll") for (int k = 0; k < 2; ++k) \
;         acc[ai][bj][m][n] = __builtin_amdgcn_mfma_f32_16x16x32_bf16(Bt[n][k], At[m][k], acc[ai][bj][m][n], 0, 0, 0); __builtin_amdgcn_s_setprio(0); } while (0)
; #define PG8_WAIT_L(n) asm volatile("s_waitcnt lgkmcnt(" #n ")" ::: "memory")
; #define PG8_BAR __builtin_amdgcn_s_barrier()
; #define PG8_SCHED __builtin_amdgcn_sched_barrier(0)
; template <class Epi, class Sched>
; __device__ __forceinline__ void gemm_phase(PG8_LAS unsigned char* lds, const Gemm g, const Sched& S, const Epi& E) {
;     ...
;             PG8_LDB(B0, 0, 0); PG8_SCHED; PG8_LDA(At, 0, 0); PG8_STAGE(PG8_SA(1, 1), a1 + hstep, voffA);
;             PG8_WAIT_L(8); PG8_BAR; PG8_WAIT_L(0); PG8_MMA(0, 0, At, B0); PG8_BAR; PG8_SCHED;
;             PG8_LDB(B1, 0, 1); PG8_STAGE(PG8_SB(0, 0), b2, voffB);
;             PG8_BAR; PG8_WAIT_L(0); PG8_MMA(0, 1, At, B1); PG8_BAR;
;             PG8_LDA(At, 0, 1); PG8_STAGE(PG8_SA(0, 0), a2, voffA);
;             PG8_BAR; PG8_WAIT_L(0); PG8_MMA(1, 0, At, B0); PG8_BAR; PG8_SCHED;
.LBB0_1011:
	s_add_u32 s20, s18, 0xfffc0080
	s_addc_u32 s21, s19, -1
	s_cmp_eq_u32 s47, 12
	s_cselect_b32 s23, s11, s21
	s_cselect_b32 s22, s43, s20
	s_cselect_b32 s21, s9, s46
	s_cselect_b32 s20, s44, s45
	v_lshl_add_u64 v[148:149], s[18:19], 0, v[136:137]
	s_add_i32 m0, s17, 0xc000
	s_nop 0
	global_load_lds_dwordx4 v[148:149], off
	v_lshl_add_u64 v[148:149], s[18:19], 0, v[138:139]
	s_add_i32 m0, s17, 0xe000
	s_nop 0
	global_load_lds_dwordx4 v[148:149], off
	ds_read_b128 v[144:147], v153
	ds_read_b128 v[156:159], v153 offset:1024
	ds_read_b128 v[160:163], v153 offset:2048
	ds_read_b128 v[164:167], v153 offset:3072
	ds_read_b128 v[168:171], v154
	ds_read_b128 v[172:175], v154 offset:1024
	ds_read_b128 v[182:185], v154 offset:2048
	ds_read_b128 v[190:193], v154 offset:3072
	ds_read_b128 v[194:197], v154 offset:4096
	ds_read_b128 v[198:201], v154 offset:5120
	ds_read_b128 v[202:205], v154 offset:6144
	ds_read_b128 v[206:209], v154 offset:7168
	s_waitcnt lgkmcnt(8)
	s_barrier
	s_waitcnt lgkmcnt(0)
	v_mfma_f32_16x16x32_bf16 v[124:127], v[144:147], v[168:171], v[124:127]
	v_mfma_f32_16x16x32_bf16 v[120:123], v[160:163], v[168:171], v[120:123]
	v_mfma_f32_16x16x32_bf16 v[108:111], v[144:147], v[182:185], v[108:111]
	v_mfma_f32_16x16x32_bf16 v[104:107], v[160:163], v[182:185], v[104:107]
	v_mfma_f32_16x16x32_bf16 v[92:95], v[144:147], v[194:197], v[92:95]
	v_mfma_f32_16x16x32_bf16 v[88:91], v[160:163], v[194:197], v[88:91]
	v_mfma_f32_16x16x32_bf16 v[76:79], v[144:147], v[202:205], v[76:79]
	v_mfma_f32_16x16x32_bf16 v[72:75], v[160:163], v[202:205], v[72:75]
	v_mfma_f32_16x16x32_bf16 v[124:127], v[156:159], v[172:175], v[124:127]
	v_mfma_f32_16x16x32_bf16 v[120:123], v[164:167], v[172:175], v[120:123]
	v_mfma_f32_16x16x32_bf16 v[108:111], v[156:159], v[190:193], v[108:111]
	v_mfma_f32_16x16x32_bf16 v[104:107], v[164:167], v[190:193], v[104:107]
	v_mfma_f32_16x16x32_bf16 v[92:95], v[156:159], v[198:201], v[92:95]
	v_mfma_f32_16x16x32_bf16 v[88:91], v[164:167], v[198:201], v[88:91]
	v_mfma_f32_16x16x32_bf16 v[76:79], v[156:159], v[206:209], v[76:79]
	v_mfma_f32_16x16x32_bf16 v[72:75], v[164:167], v[206:209], v[72:75]
	s_barrier
	s_add_i32 s48, s39, s29
	v_lshl_add_u64 v[148:149], s[20:21], 0, v[130:131]
	s_mov_b32 m0, s48
	s_nop 0
	global_load_lds_dwordx4 v[148:149], off
	v_lshl_add_u64 v[186:187], s[20:21], 0, v[134:135]
	s_add_i32 m0, s48, 0x2000
	s_nop 0
	global_load_lds_dwordx4 v[186:187], off
	ds_read_b128 v[210:213], v155
	ds_read_b128 v[214:217], v155 offset:1024
	ds_read_b128 v[218:221], v155 offset:2048
	ds_read_b128 v[222:225], v155 offset:3072
	s_barrier
	s_waitcnt lgkmcnt(0)
	v_mfma_f32_16x16x32_bf16 v[116:119], v[210:213], v[168:171], v[116:119]
	v_mfma_f32_16x16x32_bf16 v[112:115], v[218:221], v[168:171], v[112:115]
	v_mfma_f32_16x16x32_bf16 v[100:103], v[210:213], v[182:185], v[100:103]
	v_mfma_f32_16x16x32_bf16 v[96:99], v[218:221], v[182:185], v[96:99]
	v_mfma_f32_16x16x32_bf16 v[84:87], v[210:213], v[194:197], v[84:87]
	v_mfma_f32_16x16x32_bf16 v[80:83], v[218:221], v[194:197], v[80:83]
	v_mfma_f32_16x16x32_bf16 v[68:71], v[210:213], v[202:205], v[68:71]
	v_mfma_f32_16x16x32_bf16 v[64:67], v[218:221], v[202:205], v[64:67]
	v_mfma_f32_16x16x32_bf16 v[116:119], v[214:217], v[172:175], v[116:119]
	v_mfma_f32_16x16x32_bf16 v[112:115], v[222:225], v[172:175], v[112:115]
	v_mfma_f32_16x16x32_bf16 v[100:103], v[214:217], v[190:193], v[100:103]
	v_mfma_f32_16x16x32_bf16 v[96:99], v[222:225], v[190:193], v[96:99]
	v_mfma_f32_16x16x32_bf16 v[84:87], v[214:217], v[198:201], v[84:87]
	v_mfma_f32_16x16x32_bf16 v[80:83], v[222:225], v[198:201], v[80:83]
	v_mfma_f32_16x16x32_bf16 v[68:71], v[214:217], v[206:209], v[68:71]
	v_mfma_f32_16x16x32_bf16 v[64:67], v[222:225], v[206:209], v[64:67]
	s_mov_b32 m0, s17
	v_lshl_add_u64 v[226:227], s[22:23], 0, v[128:129]
	s_barrier
	global_load_lds_dwordx4 v[226:227], off
	v_lshl_add_u64 v[228:229], s[22:23], 0, v[132:133]
	s_mov_b32 m0, s30
	s_nop 0
	global_load_lds_dwordx4 v[228:229], off
	ds_read_b128 v[168:171], v154 offset:16384
	ds_read_b128 v[172:175], v154 offset:17408
	ds_read_b128 v[182:185], v154 offset:18432
	ds_read_b128 v[190:193], v154 offset:19456
	ds_read_b128 v[194:197], v154 offset:20480
	ds_read_b128 v[198:201], v154 offset:21504
	ds_read_b128 v[202:205], v154 offset:22528
	ds_read_b128 v[206:209], v154 offset:23552
	s_barrier
	s_waitcnt lgkmcnt(0)
	v_mfma_f32_16x16x32_bf16 v[60:63], v[144:147], v[168:171], v[60:63]
	v_mfma_f32_16x16x32_bf16 v[56:59], v[160:163], v[168:171], v[56:59]
	v_mfma_f32_16x16x32_bf16 v[44:47], v[144:147], v[182:185], v[44:47]
	v_mfma_f32_16x16x32_bf16 v[40:43], v[160:163], v[182:185], v[40:43]
	v_mfma_f32_16x16x32_bf16 v[28:31], v[144:147], v[194:197], v[28:31]
	v_mfma_f32_16x16x32_bf16 v[24:27], v[160:163], v[194:197], v[24:27]
	v_mfma_f32_16x16x32_bf16 v[12:15], v[144:147], v[202:205], v[12:15]
	v_mfma_f32_16x16x32_bf16 v[8:11], v[160:163], v[202:205], v[8:11]
	v_mfma_f32_16x16x32_bf16 v[60:63], v[156:159], v[172:175], v[60:63]
	v_mfma_f32_16x16x32_bf16 v[56:59], v[164:167], v[172:175], v[56:59]
	v_mfma_f32_16x16x32_bf16 v[44:47], v[156:159], v[190:193], v[44:47]
	v_mfma_f32_16x16x32_bf16 v[40:43], v[164:167], v[190:193], v[40:43]
	v_mfma_f32_16x16x32_bf16 v[28:31], v[156:159], v[198:201], v[28:31]
	v_mfma_f32_16x16x32_bf16 v[24:27], v[164:167], v[198:201], v[24:27]
	v_mfma_f32_16x16x32_bf16 v[12:15], v[156:159], v[206:209], v[12:15]
	v_mfma_f32_16x16x32_bf16 v[8:11], v[164:167], v[206:209], v[8:11]
	s_barrier
; #define PG8_STAGE(bufoff, gbase, voff) do { _Pragma("unroll") for (int _i = 0; _i < 2; ++_i) \
;         __builtin_amdgcn_global_load_lds((const unsigned*)((const char*)(gbase) + (voff)[_i]), (PG8_LAS unsigned*)(lds + (bufoff) + ldsw + _i * 8192), 16, 0, 0); } while (0)
; #define PG8_LDA(dst, b, h) do { _Pragma("unroll") for (int m = 0; m < 4; ++m) _Pragma("unroll") for (int k = 0; k < 2; ++k) dst[m][k] = *(const PG8_LAS bf16x8*)(lds + PG8_SA(b, h) + aoff + m * 2048 + k * 1024); } while (0)
; #define PG8_LDB(dst, b, h) do { _Pragma("unroll") for (int n = 0; n < 2; ++n) _Pragma("unroll") for (int k = 0; k < 2; ++k) dst[n][k] = *(const PG8_LAS bf16x8*)(lds + PG8_SB(b, h) + boff + n * 2048 + k * 1024); } while (0)
; #define PG8_MMA(ai, bj, At, Bt) do { __builtin_amdgcn_s_setprio(1); _Pragma("unroll") for (int m = 0; m < 4; ++m) _Pragma("unroll") for (int n = 0; n < 2; ++n) _Pragma("unroll") for (int k = 0; k < 2; ++k) \
;         acc[ai][bj][m][n] = __builtin_amdgcn_mfma_f32_16x16x32_bf16(Bt[n][k], At[m][k], acc[ai][bj][m][n], 0, 0, 0); __builtin_amdgcn_s_setprio(0); } while (0)
; #define PG8_WAIT_V(n) asm volatile("s_waitcnt vmcnt(" #n ")" ::: "memory")
; #define PG8_WAIT_L(n) asm volatile("s_waitcnt lgkmcnt(" #n ")" ::: "memory")
; #define PG8_BAR __builtin_amdgcn_s_barrier()
; #define PG8_SCHED __builtin_amdgcn_sched_barrier(0)
; template <class Epi, class Sched>
; __device__ __forceinline__ void gemm_phase(PG8_LAS unsigned char* lds, const Gemm g, const Sched& S, const Epi& E) {
;     ...
;             PG8_BAR; PG8_WAIT_L(0); PG8_MMA(1, 0, At, B0); PG8_BAR; PG8_SCHED;
;             PG8_STAGE(PG8_SB(0, 1), b2 + hstep, voffB);
;             PG8_WAIT_V(6); PG8_BAR; PG8_MMA(1, 1, At, B1); PG8_BAR;
;             PG8_LDB(B0, 1, 0); PG8_SCHED; PG8_LDA(At, 1, 0); PG8_STAGE(PG8_SA(0, 1), a2 + hstep, voffA);
;             PG8_WAIT_L(8); PG8_BAR; PG8_WAIT_L(0); PG8_MMA(0, 0, At, B0); PG8_BAR; PG8_SCHED;
;             PG8_LDB(B1, 1, 1); PG8_STAGE(PG8_SB(1, 0), b3, voffB);
;             PG8_BAR; PG8_WAIT_L(0); PG8_MMA(0, 1, At, B1); PG8_BAR;
	s_add_u32 s48, s20, 0x40000
	s_addc_u32 s49, s21, 0
	s_add_i32 s50, s40, s29
	v_lshl_add_u64 v[144:145], s[48:49], 0, v[130:131]
	s_mov_b32 m0, s50
	s_nop 0
	global_load_lds_dwordx4 v[144:145], off
	v_lshl_add_u64 v[144:145], s[48:49], 0, v[134:135]
	s_add_i32 m0, s50, 0x2000
	s_nop 0
	global_load_lds_dwordx4 v[144:145], off
	s_waitcnt vmcnt(6)
	s_barrier
	v_mfma_f32_16x16x32_bf16 v[52:55], v[210:213], v[168:171], v[52:55]
	v_mfma_f32_16x16x32_bf16 v[48:51], v[218:221], v[168:171], v[48:51]
	v_mfma_f32_16x16x32_bf16 v[36:39], v[210:213], v[182:185], v[36:39]
	v_mfma_f32_16x16x32_bf16 v[32:35], v[218:221], v[182:185], v[32:35]
	v_mfma_f32_16x16x32_bf16 v[20:23], v[210:213], v[194:197], v[20:23]
	v_mfma_f32_16x16x32_bf16 v[16:19], v[218:221], v[194:197], v[16:19]
	v_mfma_f32_16x16x32_bf16 v[4:7], v[210:213], v[202:205], v[4:7]
	v_mfma_f32_16x16x32_bf16 v[0:3], v[218:221], v[202:205], v[0:3]
	v_mfma_f32_16x16x32_bf16 v[52:55], v[214:217], v[172:175], v[52:55]
	v_mfma_f32_16x16x32_bf16 v[48:51], v[222:225], v[172:175], v[48:51]
	v_mfma_f32_16x16x32_bf16 v[36:39], v[214:217], v[190:193], v[36:39]
	v_mfma_f32_16x16x32_bf16 v[32:35], v[222:225], v[190:193], v[32:35]
	v_mfma_f32_16x16x32_bf16 v[20:23], v[214:217], v[198:201], v[20:23]
	v_mfma_f32_16x16x32_bf16 v[16:19], v[222:225], v[198:201], v[16:19]
	v_mfma_f32_16x16x32_bf16 v[4:7], v[214:217], v[206:209], v[4:7]
	v_mfma_f32_16x16x32_bf16 v[0:3], v[222:225], v[206:209], v[0:3]
	s_add_i32 s48, 0, 0x18000
	v_add_u32_e32 v164, s48, v151
	s_barrier
	s_add_u32 s22, s22, 0x40000
	s_addc_u32 s23, s23, 0
	s_mov_b32 m0, s31
	v_lshl_add_u64 v[210:211], s[22:23], 0, v[128:129]
	global_load_lds_dwordx4 v[210:211], off
	v_lshl_add_u64 v[210:211], s[22:23], 0, v[132:133]
	s_mov_b32 m0, s34
	s_nop 0
	global_load_lds_dwordx4 v[210:211], off
	ds_read_b128 v[144:147], v164
	ds_read_b128 v[156:159], v164 offset:1024
	ds_read_b128 v[160:163], v164 offset:2048
	ds_read_b128 v[164:167], v164 offset:3072
	ds_read_b128 v[168:171], v154 offset:32768
	ds_read_b128 v[172:175], v154 offset:33792
	ds_read_b128 v[182:185], v154 offset:34816
	ds_read_b128 v[190:193], v154 offset:35840
	ds_read_b128 v[194:197], v154 offset:36864
	ds_read_b128 v[198:201], v154 offset:37888
	ds_read_b128 v[202:205], v154 offset:38912
	ds_read_b128 v[206:209], v154 offset:39936
	s_waitcnt lgkmcnt(8)
	s_barrier
	s_waitcnt lgkmcnt(0)
	v_mfma_f32_16x16x32_bf16 v[124:127], v[144:147], v[168:171], v[124:127]
	v_mfma_f32_16x16x32_bf16 v[120:123], v[160:163], v[168:171], v[120:123]
	v_mfma_f32_16x16x32_bf16 v[108:111], v[144:147], v[182:185], v[108:111]
	v_mfma_f32_16x16x32_bf16 v[104:107], v[160:163], v[182:185], v[104:107]
	v_mfma_f32_16x16x32_bf16 v[92:95], v[144:147], v[194:197], v[92:95]
	v_mfma_f32_16x16x32_bf16 v[88:91], v[160:163], v[194:197], v[88:91]
	v_mfma_f32_16x16x32_bf16 v[76:79], v[144:147], v[202:205], v[76:79]
	v_mfma_f32_16x16x32_bf16 v[72:75], v[160:163], v[202:205], v[72:75]
	v_mfma_f32_16x16x32_bf16 v[124:127], v[156:159], v[172:175], v[124:127]
	v_mfma_f32_16x16x32_bf16 v[120:123], v[164:167], v[172:175], v[120:123]
	v_mfma_f32_16x16x32_bf16 v[108:111], v[156:159], v[190:193], v[108:111]
	v_mfma_f32_16x16x32_bf16 v[104:107], v[164:167], v[190:193], v[104:107]
	v_mfma_f32_16x16x32_bf16 v[92:95], v[156:159], v[198:201], v[92:95]
	v_mfma_f32_16x16x32_bf16 v[88:91], v[164:167], v[198:201], v[88:91]
	v_mfma_f32_16x16x32_bf16 v[76:79], v[156:159], v[206:209], v[76:79]
	v_mfma_f32_16x16x32_bf16 v[72:75], v[164:167], v[206:209], v[72:75]
	s_barrier
	s_add_i32 s22, 0, 0x1c000
	s_add_i32 s23, s48, s29
	v_add_u32_e32 v179, s22, v151
	v_lshl_add_u64 v[148:149], v[148:149], 0, s[6:7]
	s_mov_b32 m0, s23
	s_nop 0
	global_load_lds_dwordx4 v[148:149], off
	v_lshl_add_u64 v[148:149], v[186:187], 0, s[6:7]
	s_add_i32 m0, s23, 0x2000
	s_nop 0
	global_load_lds_dwordx4 v[148:149], off
	ds_read_b128 v[210:213], v179
	ds_read_b128 v[214:217], v179 offset:1024
	ds_read_b128 v[218:221], v179 offset:2048
	ds_read_b128 v[222:225], v179 offset:3072
	s_barrier
	s_waitcnt lgkmcnt(0)
	v_mfma_f32_16x16x32_bf16 v[116:119], v[210:213], v[168:171], v[116:119]
	v_mfma_f32_16x16x32_bf16 v[112:115], v[218:221], v[168:171], v[112:115]
	v_mfma_f32_16x16x32_bf16 v[100:103], v[210:213], v[182:185], v[100:103]
	v_mfma_f32_16x16x32_bf16 v[96:99], v[218:221], v[182:185], v[96:99]
	v_mfma_f32_16x16x32_bf16 v[84:87], v[210:213], v[194:197], v[84:87]
	v_mfma_f32_16x16x32_bf16 v[80:83], v[218:221], v[194:197], v[80:83]
	v_mfma_f32_16x16x32_bf16 v[68:71], v[210:213], v[202:205], v[68:71]
	v_mfma_f32_16x16x32_bf16 v[64:67], v[218:221], v[202:205], v[64:67]
	v_mfma_f32_16x16x32_bf16 v[116:119], v[214:217], v[172:175], v[116:119]
	v_mfma_f32_16x16x32_bf16 v[112:115], v[222:225], v[172:175], v[112:115]
	v_mfma_f32_16x16x32_bf16 v[100:103], v[214:217], v[190:193], v[100:103]
	v_mfma_f32_16x16x32_bf16 v[96:99], v[222:225], v[190:193], v[96:99]
	v_mfma_f32_16x16x32_bf16 v[84:87], v[214:217], v[198:201], v[84:87]
	v_mfma_f32_16x16x32_bf16 v[80:83], v[222:225], v[198:201], v[80:83]
	v_mfma_f32_16x16x32_bf16 v[68:71], v[214:217], v[206:209], v[68:71]
	v_mfma_f32_16x16x32_bf16 v[64:67], v[222:225], v[206:209], v[64:67]
	s_mov_b32 m0, s36
	v_lshl_add_u64 v[148:149], v[226:227], 0, s[6:7]
	s_barrier
	global_load_lds_dwordx4 v[148:149], off
	v_lshl_add_u64 v[148:149], v[228:229], 0, s[6:7]
	s_mov_b32 m0, s37
	s_nop 0
	global_load_lds_dwordx4 v[148:149], off
	ds_read_b128 v[168:171], v154 offset:49152
	ds_read_b128 v[172:175], v154 offset:50176
	ds_read_b128 v[182:185], v154 offset:51200
	ds_read_b128 v[190:193], v154 offset:52224
	ds_read_b128 v[194:197], v154 offset:53248
	ds_read_b128 v[198:201], v154 offset:54272
	ds_read_b128 v[202:205], v154 offset:55296
	ds_read_b128 v[206:209], v154 offset:56320
	s_barrier
; __device__ __forceinline__ unsigned cvt_pk_bf16(float lo, float hi) { unsigned r; asm volatile("v_cvt_pk_bf16_f32 %0, %1, %2" : "=v"(r) : "v"(lo), "v"(hi)); return r; }
; __device__ __forceinline__ float bf_lo(unsigned u) { return __uint_as_float(u << 16); }
; __device__ __forceinline__ float bf_hi(unsigned u) { return __uint_as_float(u & 0xffff0000u); }
; #define PG8_STAGE(bufoff, gbase, voff) do { _Pragma("unroll") for (int _i = 0; _i < 2; ++_i) \
;         __builtin_amdgcn_global_load_lds((const unsigned*)((const char*)(gbase) + (voff)[_i]), (PG8_LAS unsigned*)(lds + (bufoff) + ldsw + _i * 8192), 16, 0, 0); } while (0)
; #define PG8_WAIT_V(n) asm volatile("s_waitcnt vmcnt(" #n ")" ::: "memory")
; #define PG8_BAR __builtin_amdgcn_s_barrier()
;     __device__ __forceinline__ void operator()(const f32x4 (&acc)[2][2][4][2], const Unit& u, int wr, int wc, int fr, int fq) const {
;     ...
;             for (int m = 0; m < 4; ++m) { const size_t r = (size_t)(row0 + ai * HALF + m * 16); bf16_t* rowp = O + r * ldc + col0; const bf16_t* gp = G + r * ldg + col0;
; #pragma unroll
;                 for (int bj = 0; bj < 2; ++bj) { const u32x4 gw = *(const u32x4*)(gp + bj * HALF);
;                     f32x4 v0 = acc[ai][bj][m][0], v1 = acc[ai][bj][m][1];
;                     v0[0] *= bf_lo(gw.x); v0[1] *= bf_hi(gw.x); v0[2] *= bf_lo(gw.y); v0[3] *= bf_hi(gw.y);
;                     v1[0] *= bf_lo(gw.z); v1[1] *= bf_hi(gw.z); v1[2] *= bf_lo(gw.w); v1[3] *= bf_hi(gw.w);
;                     if (ACCUM) { const u32x4 pw = *(const u32x4*)(rowp + bj * HALF);
;                         v0[0] += bf_lo(pw.x); v0[1] += bf_hi(pw.x); v0[2] += bf_lo(pw.y); v0[3] += bf_hi(pw.y);
;                         v1[0] += bf_lo(pw.z); v1[1] += bf_hi(pw.z); v1[2] += bf_lo(pw.w); v1[3] += bf_hi(pw.w); }
;                     u32x4 w; w.x = cvt_pk_bf16(v0[0], v0[1]); w.y = cvt_pk_bf16(v0[2], v0[3]); w.z = cvt_pk_bf16(v1[0], v1[1]); w.w = cvt_pk_bf16(v1[2], v1[3]);
;                     *(u32x4*)(rowp + bj * HALF) = w; } }
; template <class Epi, class Sched>
; __device__ __forceinline__ void gemm_phase(PG8_LAS unsigned char* lds, const Gemm g, const Sched& S, const Epi& E) {
;     ...
;             PG8_BAR; PG8_WAIT_L(0); PG8_MMA(1, 0, At, B0); PG8_BAR; PG8_SCHED;
;             PG8_STAGE(PG8_SB(1, 1), b3 + hstep, voffB);
;             PG8_WAIT_V(6); PG8_BAR; PG8_MMA(1, 1, At, B1); PG8_BAR;
	s_waitcnt lgkmcnt(0)
	v_mfma_f32_16x16x32_bf16 v[60:63], v[144:147], v[168:171], v[60:63]
	v_mfma_f32_16x16x32_bf16 v[56:59], v[160:163], v[168:171], v[56:59]
	v_mfma_f32_16x16x32_bf16 v[44:47], v[144:147], v[182:185], v[44:47]
	v_mfma_f32_16x16x32_bf16 v[40:43], v[160:163], v[182:185], v[40:43]
	v_mfma_f32_16x16x32_bf16 v[28:31], v[144:147], v[194:197], v[28:31]
	v_mfma_f32_16x16x32_bf16 v[24:27], v[160:163], v[194:197], v[24:27]
	v_mfma_f32_16x16x32_bf16 v[12:15], v[144:147], v[202:205], v[12:15]
	v_mfma_f32_16x16x32_bf16 v[8:11], v[160:163], v[202:205], v[8:11]
	v_mfma_f32_16x16x32_bf16 v[60:63], v[156:159], v[172:175], v[60:63]
	v_mfma_f32_16x16x32_bf16 v[56:59], v[164:167], v[172:175], v[56:59]
	v_mfma_f32_16x16x32_bf16 v[44:47], v[156:159], v[190:193], v[44:47]
	v_mfma_f32_16x16x32_bf16 v[40:43], v[164:167], v[190:193], v[40:43]
	v_mfma_f32_16x16x32_bf16 v[28:31], v[156:159], v[198:201], v[28:31]
	v_mfma_f32_16x16x32_bf16 v[24:27], v[164:167], v[198:201], v[24:27]
	v_mfma_f32_16x16x32_bf16 v[12:15], v[156:159], v[206:209], v[12:15]
	v_mfma_f32_16x16x32_bf16 v[8:11], v[164:167], v[206:209], v[8:11]
	s_barrier
	s_add_u32 s20, s20, 0x40080
	s_addc_u32 s21, s21, 0
	s_add_i32 s22, s22, s29
	v_lshl_add_u64 v[144:145], s[20:21], 0, v[130:131]
	s_mov_b32 m0, s22
	s_nop 0
	global_load_lds_dwordx4 v[144:145], off
	v_lshl_add_u64 v[144:145], s[20:21], 0, v[134:135]
	s_add_i32 m0, s22, 0x2000
	s_nop 0
	global_load_lds_dwordx4 v[144:145], off
	s_waitcnt vmcnt(6)
	s_barrier
	v_mfma_f32_16x16x32_bf16 v[52:55], v[210:213], v[168:171], v[52:55]
	v_mfma_f32_16x16x32_bf16 v[48:51], v[218:221], v[168:171], v[48:51]
	v_mfma_f32_16x16x32_bf16 v[36:39], v[210:213], v[182:185], v[36:39]
	v_mfma_f32_16x16x32_bf16 v[32:35], v[218:221], v[182:185], v[32:35]
	v_mfma_f32_16x16x32_bf16 v[20:23], v[210:213], v[194:197], v[20:23]
	v_mfma_f32_16x16x32_bf16 v[16:19], v[218:221], v[194:197], v[16:19]
	v_mfma_f32_16x16x32_bf16 v[4:7], v[210:213], v[202:205], v[4:7]
	v_mfma_f32_16x16x32_bf16 v[0:3], v[218:221], v[202:205], v[0:3]
	v_mfma_f32_16x16x32_bf16 v[52:55], v[214:217], v[172:175], v[52:55]
	v_mfma_f32_16x16x32_bf16 v[48:51], v[222:225], v[172:175], v[48:51]
	v_mfma_f32_16x16x32_bf16 v[36:39], v[214:217], v[190:193], v[36:39]
	v_mfma_f32_16x16x32_bf16 v[32:35], v[222:225], v[190:193], v[32:35]
	v_mfma_f32_16x16x32_bf16 v[20:23], v[214:217], v[198:201], v[20:23]
	v_mfma_f32_16x16x32_bf16 v[16:19], v[222:225], v[198:201], v[16:19]
	v_mfma_f32_16x16x32_bf16 v[4:7], v[214:217], v[206:209], v[4:7]
	v_mfma_f32_16x16x32_bf16 v[0:3], v[222:225], v[206:209], v[0:3]
	s_add_i32 s47, s47, 2
	s_add_u32 s18, s18, 0x100
	s_addc_u32 s19, s19, 0
	s_add_u32 s45, s45, 0x100
	s_addc_u32 s46, s46, 0
	s_cmp_gt_u32 s47, 13
	s_barrier
	s_cbranch_scc0 .LBB0_1011
	v_lshl_add_u32 v146, s16, 8, v150
	v_lshl_or_b32 v144, s42, 8, v152
	v_ashrrev_i32_e32 v147, 31, v146
	v_ashrrev_i32_e32 v145, 31, v144
	v_mov_b64_e32 v[148:149], s[4:5]
	v_lshlrev_b64 v[160:161], 11, v[146:147]
	v_lshlrev_b64 v[144:145], 1, v[144:145]
	v_mad_i64_i32 v[156:157], s[18:19], v146, s41, v[148:149]
	v_lshl_add_u64 v[160:161], s[0:1], 0, v[160:161]
	v_lshl_add_u64 v[164:165], v[156:157], 0, v[144:145]
	v_lshl_add_u64 v[166:167], v[160:161], 0, v[144:145]
	global_load_dwordx4 v[156:159], v[164:165], off
	global_load_dwordx4 v[160:163], v[166:167], off
	s_and_b64 vcc, exec, s[2:3]
	s_mov_b32 s42, s8
	s_mov_b32 s16, s10
	s_mov_b64 s[20:21], s[14:15]
	s_waitcnt vmcnt(0)
	v_lshlrev_b32_e32 v147, 16, v156
	v_and_b32_e32 v156, 0xffff0000, v156
	v_lshlrev_b32_e32 v168, 16, v157
	v_and_b32_e32 v157, 0xffff0000, v157
	v_lshlrev_b32_e32 v169, 16, v158
	v_and_b32_e32 v158, 0xffff0000, v158
	v_lshlrev_b32_e32 v170, 16, v159
	v_and_b32_e32 v159, 0xffff0000, v159
	v_lshlrev_b32_e32 v171, 16, v160
	v_and_b32_e32 v160, 0xffff0000, v160
	v_lshlrev_b32_e32 v172, 16, v161
	v_and_b32_e32 v161, 0xffff0000, v161
	v_lshlrev_b32_e32 v173, 16, v162
	v_and_b32_e32 v162, 0xffff0000, v162
	v_lshlrev_b32_e32 v174, 16, v163
	v_and_b32_e32 v163, 0xffff0000, v163
	v_fmac_f32_e32 v171, v124, v147
	v_fmac_f32_e32 v160, v125, v156
	v_fmac_f32_e32 v172, v126, v168
	v_fmac_f32_e32 v161, v127, v157
	v_fmac_f32_e32 v173, v120, v169
	v_fmac_f32_e32 v162, v121, v158
	v_fmac_f32_e32 v174, v122, v170
	v_fmac_f32_e32 v163, v123, v159
	v_cvt_pk_bf16_f32 v120, v171, v160
	v_cvt_pk_bf16_f32 v121, v172, v161
	v_cvt_pk_bf16_f32 v122, v173, v162
	v_cvt_pk_bf16_f32 v123, v174, v163
	global_load_dwordx4 v[124:127], v[164:165], off offset:256
	global_load_dwordx4 v[156:159], v[166:167], off offset:256
	v_or_b32_e32 v160, 16, v146
	global_store_dwordx4 v[166:167], v[120:123], off
	v_mad_i64_i32 v[162:163], s[18:19], v160, s41, v[148:149]
	v_lshl_add_u64 v[162:163], v[162:163], 0, v[144:145]
	s_waitcnt vmcnt(0)
	v_lshlrev_b32_e32 v122, 16, v125
	v_lshlrev_b32_e32 v161, 16, v157
	v_lshlrev_b32_e32 v120, 16, v124
	v_and_b32_e32 v121, 0xffff0000, v124
	v_and_b32_e32 v123, 0xffff0000, v125
	v_lshlrev_b32_e32 v124, 16, v126
	v_and_b32_e32 v125, 0xffff0000, v126
	v_lshlrev_b32_e32 v147, 16, v156
	v_and_b32_e32 v156, 0xffff0000, v156
	v_and_b32_e32 v157, 0xffff0000, v157
	v_lshlrev_b32_e32 v164, 16, v158
	v_and_b32_e32 v158, 0xffff0000, v158
	v_fmac_f32_e32 v161, v118, v122
	v_fmac_f32_e32 v147, v116, v120
	v_fmac_f32_e32 v156, v117, v121
	v_fmac_f32_e32 v157, v119, v123
	v_fmac_f32_e32 v164, v112, v124
	v_fmac_f32_e32 v158, v113, v125
	v_cvt_pk_bf16_f32 v112, v147, v156
	v_cvt_pk_bf16_f32 v113, v161, v157
	v_ashrrev_i32_e32 v161, 31, v160
	v_lshlrev_b64 v[120:121], 11, v[160:161]
	v_lshl_add_u64 v[120:121], s[0:1], 0, v[120:121]
	v_lshlrev_b32_e32 v126, 16, v127
	v_and_b32_e32 v127, 0xffff0000, v127
	v_lshlrev_b32_e32 v165, 16, v159
	v_and_b32_e32 v159, 0xffff0000, v159
	v_lshl_add_u64 v[124:125], v[120:121], 0, v[144:145]
	v_fmac_f32_e32 v165, v114, v126
	v_fmac_f32_e32 v159, v115, v127
	v_cvt_pk_bf16_f32 v114, v164, v158
	v_cvt_pk_bf16_f32 v115, v165, v159
	global_load_dwordx4 v[116:119], v[162:163], off
	global_load_dwordx4 v[120:123], v[124:125], off
	s_waitcnt vmcnt(0)
; __device__ __forceinline__ unsigned cvt_pk_bf16(float lo, float hi) { unsigned r; asm volatile("v_cvt_pk_bf16_f32 %0, %1, %2" : "=v"(r) : "v"(lo), "v"(hi)); return r; }
; __device__ __forceinline__ float bf_lo(unsigned u) { return __uint_as_float(u << 16); }
; __device__ __forceinline__ float bf_hi(unsigned u) { return __uint_as_float(u & 0xffff0000u); }
;     __device__ __forceinline__ void operator()(const f32x4 (&acc)[2][2][4][2], const Unit& u, int wr, int wc, int fr, int fq) const {
;     ...
;             for (int m = 0; m < 4; ++m) { const size_t r = (size_t)(row0 + ai * HALF + m * 16); bf16_t* rowp = O + r * ldc + col0; const bf16_t* gp = G + r * ldg + col0;
; #pragma unroll
;                 for (int bj = 0; bj < 2; ++bj) { const u32x4 gw = *(const u32x4*)(gp + bj * HALF);
;                     f32x4 v0 = acc[ai][bj][m][0], v1 = acc[ai][bj][m][1];
;                     v0[0] *= bf_lo(gw.x); v0[1] *= bf_hi(gw.x); v0[2] *= bf_lo(gw.y); v0[3] *= bf_hi(gw.y);
;                     v1[0] *= bf_lo(gw.z); v1[1] *= bf_hi(gw.z); v1[2] *= bf_lo(gw.w); v1[3] *= bf_hi(gw.w);
;                     if (ACCUM) { const u32x4 pw = *(const u32x4*)(rowp + bj * HALF);
;                         v0[0] += bf_lo(pw.x); v0[1] += bf_hi(pw.x); v0[2] += bf_lo(pw.y); v0[3] += bf_hi(pw.y);
;                         v1[0] += bf_lo(pw.z); v1[1] += bf_hi(pw.z); v1[2] += bf_lo(pw.w); v1[3] += bf_hi(pw.w); }
;                     u32x4 w; w.x = cvt_pk_bf16(v0[0], v0[1]); w.y = cvt_pk_bf16(v0[2], v0[3]); w.z = cvt_pk_bf16(v1[0], v1[1]); w.w = cvt_pk_bf16(v1[2], v1[3]);
;                     *(u32x4*)(rowp + bj * HALF) = w; } }
	v_lshlrev_b32_e32 v126, 16, v120
	global_store_dwordx4 v[166:167], v[112:115], off offset:256
	v_and_b32_e32 v120, 0xffff0000, v120
	v_lshlrev_b32_e32 v127, 16, v121
	v_lshlrev_b32_e32 v112, 16, v116
	v_and_b32_e32 v113, 0xffff0000, v116
	v_lshlrev_b32_e32 v114, 16, v117
	v_and_b32_e32 v115, 0xffff0000, v117
	v_lshlrev_b32_e32 v116, 16, v118
	v_and_b32_e32 v117, 0xffff0000, v118
	v_lshlrev_b32_e32 v118, 16, v119
	v_and_b32_e32 v119, 0xffff0000, v119
	v_and_b32_e32 v121, 0xffff0000, v121
	v_lshlrev_b32_e32 v147, 16, v122
	v_and_b32_e32 v122, 0xffff0000, v122
	v_lshlrev_b32_e32 v156, 16, v123
	v_and_b32_e32 v123, 0xffff0000, v123
	v_fmac_f32_e32 v126, v108, v112
	v_fmac_f32_e32 v120, v109, v113
	v_fmac_f32_e32 v127, v110, v114
	v_fmac_f32_e32 v121, v111, v115
	v_fmac_f32_e32 v147, v104, v116
	v_fmac_f32_e32 v122, v105, v117
	v_fmac_f32_e32 v156, v106, v118
	v_fmac_f32_e32 v123, v107, v119
	v_cvt_pk_bf16_f32 v104, v126, v120
	v_cvt_pk_bf16_f32 v105, v127, v121
	v_cvt_pk_bf16_f32 v106, v147, v122
	v_cvt_pk_bf16_f32 v107, v156, v123
	global_load_dwordx4 v[108:111], v[162:163], off offset:256
	global_load_dwordx4 v[112:115], v[124:125], off offset:256
	v_or_b32_e32 v116, 32, v146
	global_store_dwordx4 v[124:125], v[104:107], off
	v_mad_i64_i32 v[118:119], s[18:19], v116, s41, v[148:149]
	v_lshl_add_u64 v[118:119], v[118:119], 0, v[144:145]
	s_waitcnt vmcnt(0)
	v_lshlrev_b32_e32 v104, 16, v108
	v_lshlrev_b32_e32 v117, 16, v112
	v_and_b32_e32 v105, 0xffff0000, v108
	v_lshlrev_b32_e32 v108, 16, v110
	v_and_b32_e32 v112, 0xffff0000, v112
	v_lshlrev_b32_e32 v121, 16, v114
	v_fmac_f32_e32 v117, v100, v104
	v_fmac_f32_e32 v112, v101, v105
	v_fmac_f32_e32 v121, v96, v108
	v_cvt_pk_bf16_f32 v96, v117, v112
	v_ashrrev_i32_e32 v117, 31, v116
	v_lshlrev_b64 v[104:105], 11, v[116:117]
	v_lshlrev_b32_e32 v106, 16, v109
	v_and_b32_e32 v107, 0xffff0000, v109
	v_and_b32_e32 v109, 0xffff0000, v110
	v_and_b32_e32 v114, 0xffff0000, v114
	v_lshl_add_u64 v[104:105], s[0:1], 0, v[104:105]
	v_lshlrev_b32_e32 v110, 16, v111
	v_and_b32_e32 v111, 0xffff0000, v111
	v_lshlrev_b32_e32 v120, 16, v113
	v_and_b32_e32 v113, 0xffff0000, v113
	v_lshlrev_b32_e32 v122, 16, v115
	v_and_b32_e32 v115, 0xffff0000, v115
	v_fmac_f32_e32 v114, v97, v109
	v_lshl_add_u64 v[108:109], v[104:105], 0, v[144:145]
	v_fmac_f32_e32 v120, v102, v106
	v_fmac_f32_e32 v113, v103, v107
	v_fmac_f32_e32 v122, v98, v110
	v_fmac_f32_e32 v115, v99, v111
	v_cvt_pk_bf16_f32 v97, v120, v113
	v_cvt_pk_bf16_f32 v98, v121, v114
	v_cvt_pk_bf16_f32 v99, v122, v115
	global_load_dwordx4 v[100:103], v[118:119], off
	global_load_dwordx4 v[104:107], v[108:109], off
	s_waitcnt vmcnt(0)
	v_lshlrev_b32_e32 v110, 16, v104
	global_store_dwordx4 v[124:125], v[96:99], off offset:256
	v_and_b32_e32 v104, 0xffff0000, v104
	v_lshlrev_b32_e32 v111, 16, v105
	v_lshlrev_b32_e32 v96, 16, v100
	v_and_b32_e32 v97, 0xffff0000, v100
	v_lshlrev_b32_e32 v98, 16, v101
	v_and_b32_e32 v99, 0xffff0000, v101
	v_lshlrev_b32_e32 v100, 16, v102
	v_and_b32_e32 v101, 0xffff0000, v102
	v_lshlrev_b32_e32 v102, 16, v103
	v_and_b32_e32 v103, 0xffff0000, v103
	v_and_b32_e32 v105, 0xffff0000, v105
	v_lshlrev_b32_e32 v112, 16, v106
	v_and_b32_e32 v106, 0xffff0000, v106
	v_lshlrev_b32_e32 v113, 16, v107
	v_and_b32_e32 v107, 0xffff0000, v107
	v_fmac_f32_e32 v110, v92, v96
	v_fmac_f32_e32 v104, v93, v97
	v_fmac_f32_e32 v111, v94, v98
	v_fmac_f32_e32 v105, v95, v99
	v_fmac_f32_e32 v112, v88, v100
	v_fmac_f32_e32 v106, v89, v101
	v_fmac_f32_e32 v113, v90, v102
	v_fmac_f32_e32 v107, v91, v103
	v_cvt_pk_bf16_f32 v88, v110, v104
	v_cvt_pk_bf16_f32 v89, v111, v105
	v_cvt_pk_bf16_f32 v90, v112, v106
	v_cvt_pk_bf16_f32 v91, v113, v107
	global_load_dwordx4 v[92:95], v[118:119], off offset:256
	global_load_dwordx4 v[96:99], v[108:109], off offset:256
	v_or_b32_e32 v100, 48, v146
	global_store_dwordx4 v[108:109], v[88:91], off
	v_mad_i64_i32 v[102:103], s[18:19], v100, s41, v[148:149]
	v_lshl_add_u64 v[102:103], v[102:103], 0, v[144:145]
	s_waitcnt vmcnt(0)
	v_lshlrev_b32_e32 v88, 16, v92
	v_lshlrev_b32_e32 v101, 16, v96
	v_and_b32_e32 v89, 0xffff0000, v92
	v_lshlrev_b32_e32 v92, 16, v94
	v_and_b32_e32 v96, 0xffff0000, v96
	v_lshlrev_b32_e32 v105, 16, v98
	v_fmac_f32_e32 v101, v84, v88
	v_fmac_f32_e32 v96, v85, v89
	v_fmac_f32_e32 v105, v80, v92
	v_cvt_pk_bf16_f32 v80, v101, v96
	v_ashrrev_i32_e32 v101, 31, v100
	v_lshlrev_b64 v[88:89], 11, v[100:101]
	v_lshlrev_b32_e32 v90, 16, v93
	v_and_b32_e32 v91, 0xffff0000, v93
	v_and_b32_e32 v93, 0xffff0000, v94
	v_and_b32_e32 v98, 0xffff0000, v98
	v_lshl_add_u64 v[88:89], s[0:1], 0, v[88:89]
	v_lshlrev_b32_e32 v94, 16, v95
	v_and_b32_e32 v95, 0xffff0000, v95
	v_lshlrev_b32_e32 v104, 16, v97
	v_and_b32_e32 v97, 0xffff0000, v97
	v_lshlrev_b32_e32 v106, 16, v99
	v_and_b32_e32 v99, 0xffff0000, v99
	v_fmac_f32_e32 v98, v81, v93
	v_lshl_add_u64 v[92:93], v[88:89], 0, v[144:145]
	v_fmac_f32_e32 v104, v86, v90
	v_fmac_f32_e32 v97, v87, v91
	v_fmac_f32_e32 v106, v82, v94
	v_fmac_f32_e32 v99, v83, v95
	v_cvt_pk_bf16_f32 v81, v104, v97
	v_cvt_pk_bf16_f32 v82, v105, v98
	v_cvt_pk_bf16_f32 v83, v106, v99
	global_load_dwordx4 v[84:87], v[102:103], off
	global_load_dwordx4 v[88:91], v[92:93], off
	s_waitcnt vmcnt(0)
; __device__ __forceinline__ unsigned cvt_pk_bf16(float lo, float hi) { unsigned r; asm volatile("v_cvt_pk_bf16_f32 %0, %1, %2" : "=v"(r) : "v"(lo), "v"(hi)); return r; }
; __device__ __forceinline__ float bf_lo(unsigned u) { return __uint_as_float(u << 16); }
; __device__ __forceinline__ float bf_hi(unsigned u) { return __uint_as_float(u & 0xffff0000u); }
;     __device__ __forceinline__ void operator()(const f32x4 (&acc)[2][2][4][2], const Unit& u, int wr, int wc, int fr, int fq) const {
;     ...
;             for (int m = 0; m < 4; ++m) { const size_t r = (size_t)(row0 + ai * HALF + m * 16); bf16_t* rowp = O + r * ldc + col0; const bf16_t* gp = G + r * ldg + col0;
; #pragma unroll
;                 for (int bj = 0; bj < 2; ++bj) { const u32x4 gw = *(const u32x4*)(gp + bj * HALF);
;                     f32x4 v0 = acc[ai][bj][m][0], v1 = acc[ai][bj][m][1];
;                     v0[0] *= bf_lo(gw.x); v0[1] *= bf_hi(gw.x); v0[2] *= bf_lo(gw.y); v0[3] *= bf_hi(gw.y);
;                     v1[0] *= bf_lo(gw.z); v1[1] *= bf_hi(gw.z); v1[2] *= bf_lo(gw.w); v1[3] *= bf_hi(gw.w);
;                     if (ACCUM) { const u32x4 pw = *(const u32x4*)(rowp + bj * HALF);
;                         v0[0] += bf_lo(pw.x); v0[1] += bf_hi(pw.x); v0[2] += bf_lo(pw.y); v0[3] += bf_hi(pw.y);
;                         v1[0] += bf_lo(pw.z); v1[1] += bf_hi(pw.z); v1[2] += bf_lo(pw.w); v1[3] += bf_hi(pw.w); }
;                     u32x4 w; w.x = cvt_pk_bf16(v0[0], v0[1]); w.y = cvt_pk_bf16(v0[2], v0[3]); w.z = cvt_pk_bf16(v1[0], v1[1]); w.w = cvt_pk_bf16(v1[2], v1[3]);
;                     *(u32x4*)(rowp + bj * HALF) = w; } }
	v_lshlrev_b32_e32 v94, 16, v88
	global_store_dwordx4 v[108:109], v[80:83], off offset:256
	v_and_b32_e32 v88, 0xffff0000, v88
	v_lshlrev_b32_e32 v95, 16, v89
	v_lshlrev_b32_e32 v80, 16, v84
	v_and_b32_e32 v81, 0xffff0000, v84
	v_lshlrev_b32_e32 v82, 16, v85
	v_and_b32_e32 v83, 0xffff0000, v85
	v_lshlrev_b32_e32 v84, 16, v86
	v_and_b32_e32 v85, 0xffff0000, v86
	v_lshlrev_b32_e32 v86, 16, v87
	v_and_b32_e32 v87, 0xffff0000, v87
	v_and_b32_e32 v89, 0xffff0000, v89
	v_lshlrev_b32_e32 v96, 16, v90
	v_and_b32_e32 v90, 0xffff0000, v90
	v_lshlrev_b32_e32 v97, 16, v91
	v_and_b32_e32 v91, 0xffff0000, v91
	v_fmac_f32_e32 v94, v76, v80
	v_fmac_f32_e32 v88, v77, v81
	v_fmac_f32_e32 v95, v78, v82
	v_fmac_f32_e32 v89, v79, v83
	v_fmac_f32_e32 v96, v72, v84
	v_fmac_f32_e32 v90, v73, v85
	v_fmac_f32_e32 v97, v74, v86
	v_fmac_f32_e32 v91, v75, v87
	v_cvt_pk_bf16_f32 v72, v94, v88
	v_cvt_pk_bf16_f32 v73, v95, v89
	v_cvt_pk_bf16_f32 v74, v96, v90
	v_cvt_pk_bf16_f32 v75, v97, v91
	global_load_dwordx4 v[76:79], v[102:103], off offset:256
	global_load_dwordx4 v[80:83], v[92:93], off offset:256
	v_add_u32_e32 v84, 0x80, v146
	global_store_dwordx4 v[92:93], v[72:75], off
	v_mad_i64_i32 v[86:87], s[18:19], v84, s41, v[148:149]
	v_lshl_add_u64 v[86:87], v[86:87], 0, v[144:145]
	s_waitcnt vmcnt(0)
	v_lshlrev_b32_e32 v72, 16, v76
	v_lshlrev_b32_e32 v85, 16, v80
	v_and_b32_e32 v73, 0xffff0000, v76
	v_lshlrev_b32_e32 v76, 16, v78
	v_and_b32_e32 v80, 0xffff0000, v80
	v_lshlrev_b32_e32 v89, 16, v82
	v_fmac_f32_e32 v85, v68, v72
	v_fmac_f32_e32 v80, v69, v73
	v_fmac_f32_e32 v89, v64, v76
	v_cvt_pk_bf16_f32 v64, v85, v80
	v_ashrrev_i32_e32 v85, 31, v84
	v_lshlrev_b64 v[72:73], 11, v[84:85]
	v_lshlrev_b32_e32 v74, 16, v77
	v_and_b32_e32 v75, 0xffff0000, v77
	v_and_b32_e32 v77, 0xffff0000, v78
	v_and_b32_e32 v82, 0xffff0000, v82
	v_lshl_add_u64 v[72:73], s[0:1], 0, v[72:73]
	v_lshlrev_b32_e32 v78, 16, v79
	v_and_b32_e32 v79, 0xffff0000, v79
	v_lshlrev_b32_e32 v88, 16, v81
	v_and_b32_e32 v81, 0xffff0000, v81
	v_lshlrev_b32_e32 v90, 16, v83
	v_and_b32_e32 v83, 0xffff0000, v83
	v_fmac_f32_e32 v82, v65, v77
	v_lshl_add_u64 v[76:77], v[72:73], 0, v[144:145]
	v_fmac_f32_e32 v88, v70, v74
	v_fmac_f32_e32 v81, v71, v75
	v_fmac_f32_e32 v90, v66, v78
	v_fmac_f32_e32 v83, v67, v79
	v_cvt_pk_bf16_f32 v65, v88, v81
	v_cvt_pk_bf16_f32 v66, v89, v82
	v_cvt_pk_bf16_f32 v67, v90, v83
	global_load_dwordx4 v[68:71], v[86:87], off
	global_load_dwordx4 v[72:75], v[76:77], off
	s_waitcnt vmcnt(0)
	v_lshlrev_b32_e32 v78, 16, v72
	global_store_dwordx4 v[92:93], v[64:67], off offset:256
	v_and_b32_e32 v72, 0xffff0000, v72
	v_lshlrev_b32_e32 v79, 16, v73
	v_lshlrev_b32_e32 v64, 16, v68
	v_and_b32_e32 v65, 0xffff0000, v68
	v_lshlrev_b32_e32 v66, 16, v69
	v_and_b32_e32 v67, 0xffff0000, v69
	v_lshlrev_b32_e32 v68, 16, v70
	v_and_b32_e32 v69, 0xffff0000, v70
	v_lshlrev_b32_e32 v70, 16, v71
	v_and_b32_e32 v71, 0xffff0000, v71
	v_and_b32_e32 v73, 0xffff0000, v73
	v_lshlrev_b32_e32 v80, 16, v74
	v_and_b32_e32 v74, 0xffff0000, v74
	v_lshlrev_b32_e32 v81, 16, v75
	v_and_b32_e32 v75, 0xffff0000, v75
	v_fmac_f32_e32 v78, v60, v64
	v_fmac_f32_e32 v72, v61, v65
	v_fmac_f32_e32 v79, v62, v66
	v_fmac_f32_e32 v73, v63, v67
	v_fmac_f32_e32 v80, v56, v68
	v_fmac_f32_e32 v74, v57, v69
	v_fmac_f32_e32 v81, v58, v70
	v_fmac_f32_e32 v75, v59, v71
	v_cvt_pk_bf16_f32 v56, v78, v72
	v_cvt_pk_bf16_f32 v57, v79, v73
	v_cvt_pk_bf16_f32 v58, v80, v74
	v_cvt_pk_bf16_f32 v59, v81, v75
	global_load_dwordx4 v[60:63], v[86:87], off offset:256
	global_load_dwordx4 v[64:67], v[76:77], off offset:256
	v_add_u32_e32 v68, 0x90, v146
	global_store_dwordx4 v[76:77], v[56:59], off
	v_mad_i64_i32 v[70:71], s[18:19], v68, s41, v[148:149]
	v_lshl_add_u64 v[70:71], v[70:71], 0, v[144:145]
	s_waitcnt vmcnt(0)
	v_lshlrev_b32_e32 v56, 16, v60
	v_lshlrev_b32_e32 v69, 16, v64
	v_and_b32_e32 v57, 0xffff0000, v60
	v_lshlrev_b32_e32 v60, 16, v62
	v_and_b32_e32 v64, 0xffff0000, v64
	v_lshlrev_b32_e32 v73, 16, v66
	v_fmac_f32_e32 v69, v52, v56
	v_fmac_f32_e32 v64, v53, v57
	v_fmac_f32_e32 v73, v48, v60
	v_cvt_pk_bf16_f32 v48, v69, v64
	v_ashrrev_i32_e32 v69, 31, v68
	v_lshlrev_b64 v[56:57], 11, v[68:69]
	v_lshlrev_b32_e32 v58, 16, v61
	v_and_b32_e32 v59, 0xffff0000, v61
	v_and_b32_e32 v61, 0xffff0000, v62
	v_and_b32_e32 v66, 0xffff0000, v66
	v_lshl_add_u64 v[56:57], s[0:1], 0, v[56:57]
	v_lshlrev_b32_e32 v62, 16, v63
	v_and_b32_e32 v63, 0xffff0000, v63
	v_lshlrev_b32_e32 v72, 16, v65
	v_and_b32_e32 v65, 0xffff0000, v65
	v_lshlrev_b32_e32 v74, 16, v67
	v_and_b32_e32 v67, 0xffff0000, v67
	v_fmac_f32_e32 v66, v49, v61
	v_lshl_add_u64 v[60:61], v[56:57], 0, v[144:145]
	v_fmac_f32_e32 v72, v54, v58
	v_fmac_f32_e32 v65, v55, v59
	v_fmac_f32_e32 v74, v50, v62
	v_fmac_f32_e32 v67, v51, v63
	v_cvt_pk_bf16_f32 v49, v72, v65
	v_cvt_pk_bf16_f32 v50, v73, v66
	v_cvt_pk_bf16_f32 v51, v74, v67
	global_load_dwordx4 v[52:55], v[70:71], off
	global_load_dwordx4 v[56:59], v[60:61], off
	s_waitcnt vmcnt(0)
	v_lshlrev_b32_e32 v62, 16, v56
	global_store_dwordx4 v[76:77], v[48:51], off offset:256
	v_and_b32_e32 v56, 0xffff0000, v56
	v_lshlrev_b32_e32 v63, 16, v57
	v_lshlrev_b32_e32 v48, 16, v52
	v_and_b32_e32 v49, 0xffff0000, v52
	v_lshlrev_b32_e32 v50, 16, v53
	v_and_b32_e32 v51, 0xffff0000, v53
	v_lshlrev_b32_e32 v52, 16, v54
	v_and_b32_e32 v53, 0xffff0000, v54
	v_lshlrev_b32_e32 v54, 16, v55
	v_and_b32_e32 v55, 0xffff0000, v55
	v_and_b32_e32 v57, 0xffff0000, v57
	v_lshlrev_b32_e32 v64, 16, v58
	v_and_b32_e32 v58, 0xffff0000, v58
	v_lshlrev_b32_e32 v65, 16, v59
	v_and_b32_e32 v59, 0xffff0000, v59
	v_fmac_f32_e32 v62, v44, v48
	v_fmac_f32_e32 v56, v45, v49
	v_fmac_f32_e32 v63, v46, v50
	v_fmac_f32_e32 v57, v47, v51
	v_fmac_f32_e32 v64, v40, v52
	v_fmac_f32_e32 v58, v41, v53
	v_fmac_f32_e32 v65, v42, v54
	v_fmac_f32_e32 v59, v43, v55
	v_cvt_pk_bf16_f32 v40, v62, v56
	v_cvt_pk_bf16_f32 v41, v63, v57
	v_cvt_pk_bf16_f32 v42, v64, v58
	v_cvt_pk_bf16_f32 v43, v65, v59
	global_load_dwordx4 v[44:47], v[70:71], off offset:256
	global_load_dwordx4 v[48:51], v[60:61], off offset:256
	v_add_u32_e32 v52, 0xa0, v146
	global_store_dwordx4 v[60:61], v[40:43], off
	v_mad_i64_i32 v[54:55], s[18:19], v52, s41, v[148:149]
	v_lshl_add_u64 v[54:55], v[54:55], 0, v[144:145]
	s_waitcnt vmcnt(0)
; __device__ __forceinline__ unsigned cvt_pk_bf16(float lo, float hi) { unsigned r; asm volatile("v_cvt_pk_bf16_f32 %0, %1, %2" : "=v"(r) : "v"(lo), "v"(hi)); return r; }
; __device__ __forceinline__ float bf_lo(unsigned u) { return __uint_as_float(u << 16); }
; __device__ __forceinline__ float bf_hi(unsigned u) { return __uint_as_float(u & 0xffff0000u); }
; #define PG8_WAIT_V(n) asm volatile("s_waitcnt vmcnt(" #n ")" ::: "memory")
; #define PG8_BAR __builtin_amdgcn_s_barrier()
;     __device__ __forceinline__ void operator()(const f32x4 (&acc)[2][2][4][2], const Unit& u, int wr, int wc, int fr, int fq) const {
;     ...
;             for (int m = 0; m < 4; ++m) { const size_t r = (size_t)(row0 + ai * HALF + m * 16); bf16_t* rowp = O + r * ldc + col0; const bf16_t* gp = G + r * ldg + col0;
; #pragma unroll
;                 for (int bj = 0; bj < 2; ++bj) { const u32x4 gw = *(const u32x4*)(gp + bj * HALF);
;                     f32x4 v0 = acc[ai][bj][m][0], v1 = acc[ai][bj][m][1];
;                     v0[0] *= bf_lo(gw.x); v0[1] *= bf_hi(gw.x); v0[2] *= bf_lo(gw.y); v0[3] *= bf_hi(gw.y);
;                     v1[0] *= bf_lo(gw.z); v1[1] *= bf_hi(gw.z); v1[2] *= bf_lo(gw.w); v1[3] *= bf_hi(gw.w);
;                     if (ACCUM) { const u32x4 pw = *(const u32x4*)(rowp + bj * HALF);
;                         v0[0] += bf_lo(pw.x); v0[1] += bf_hi(pw.x); v0[2] += bf_lo(pw.y); v0[3] += bf_hi(pw.y);
;                         v1[0] += bf_lo(pw.z); v1[1] += bf_hi(pw.z); v1[2] += bf_lo(pw.w); v1[3] += bf_hi(pw.w); }
;                     u32x4 w; w.x = cvt_pk_bf16(v0[0], v0[1]); w.y = cvt_pk_bf16(v0[2], v0[3]); w.z = cvt_pk_bf16(v1[0], v1[1]); w.w = cvt_pk_bf16(v1[2], v1[3]);
;                     *(u32x4*)(rowp + bj * HALF) = w; } }
; template <class Epi, class Sched>
; __device__ __forceinline__ void gemm_phase(PG8_LAS unsigned char* lds, const Gemm g, const Sched& S, const Epi& E) {
;     ...
;         if (!has_next) break;
; #pragma unroll
;         for (int a = 0; a < 2; ++a)
; #pragma unroll
;             for (int b = 0; b < 2; ++b)
; #pragma unroll
;                 for (int m = 0; m < 4; ++m)
; #pragma unroll
;                     for (int n = 0; n < 2; ++n) acc[a][b][m][n] = (f32x4){0.f, 0.f, 0.f, 0.f};
;         cur = nxt; cA = nA; cB = nB; ++ui;
;     }
;     PG8_WAIT_V(0);
;     if (wr == 0) PG8_BAR;
;     PG8_BAR;
	v_lshlrev_b32_e32 v40, 16, v44
	v_lshlrev_b32_e32 v53, 16, v48
	v_and_b32_e32 v41, 0xffff0000, v44
	v_lshlrev_b32_e32 v44, 16, v46
	v_and_b32_e32 v48, 0xffff0000, v48
	v_lshlrev_b32_e32 v57, 16, v50
	v_fmac_f32_e32 v53, v36, v40
	v_fmac_f32_e32 v48, v37, v41
	v_fmac_f32_e32 v57, v32, v44
	v_cvt_pk_bf16_f32 v32, v53, v48
	v_ashrrev_i32_e32 v53, 31, v52
	v_lshlrev_b64 v[40:41], 11, v[52:53]
	v_lshlrev_b32_e32 v42, 16, v45
	v_and_b32_e32 v43, 0xffff0000, v45
	v_and_b32_e32 v45, 0xffff0000, v46
	v_and_b32_e32 v50, 0xffff0000, v50
	v_lshl_add_u64 v[40:41], s[0:1], 0, v[40:41]
	v_lshlrev_b32_e32 v46, 16, v47
	v_and_b32_e32 v47, 0xffff0000, v47
	v_lshlrev_b32_e32 v56, 16, v49
	v_and_b32_e32 v49, 0xffff0000, v49
	v_lshlrev_b32_e32 v58, 16, v51
	v_and_b32_e32 v51, 0xffff0000, v51
	v_fmac_f32_e32 v50, v33, v45
	v_lshl_add_u64 v[44:45], v[40:41], 0, v[144:145]
	v_fmac_f32_e32 v56, v38, v42
	v_fmac_f32_e32 v49, v39, v43
	v_fmac_f32_e32 v58, v34, v46
	v_fmac_f32_e32 v51, v35, v47
	v_cvt_pk_bf16_f32 v33, v56, v49
	v_cvt_pk_bf16_f32 v34, v57, v50
	v_cvt_pk_bf16_f32 v35, v58, v51
	global_load_dwordx4 v[36:39], v[54:55], off
	global_load_dwordx4 v[40:43], v[44:45], off
	s_waitcnt vmcnt(0)
	v_lshlrev_b32_e32 v46, 16, v40
	global_store_dwordx4 v[60:61], v[32:35], off offset:256
	v_and_b32_e32 v40, 0xffff0000, v40
	v_lshlrev_b32_e32 v47, 16, v41
	v_lshlrev_b32_e32 v32, 16, v36
	v_and_b32_e32 v33, 0xffff0000, v36
	v_lshlrev_b32_e32 v34, 16, v37
	v_and_b32_e32 v35, 0xffff0000, v37
	v_lshlrev_b32_e32 v36, 16, v38
	v_and_b32_e32 v37, 0xffff0000, v38
	v_lshlrev_b32_e32 v38, 16, v39
	v_and_b32_e32 v39, 0xffff0000, v39
	v_and_b32_e32 v41, 0xffff0000, v41
	v_lshlrev_b32_e32 v48, 16, v42
	v_and_b32_e32 v42, 0xffff0000, v42
	v_lshlrev_b32_e32 v49, 16, v43
	v_and_b32_e32 v43, 0xffff0000, v43
	v_fmac_f32_e32 v46, v28, v32
	v_fmac_f32_e32 v40, v29, v33
	v_fmac_f32_e32 v47, v30, v34
	v_fmac_f32_e32 v41, v31, v35
	v_fmac_f32_e32 v48, v24, v36
	v_fmac_f32_e32 v42, v25, v37
	v_fmac_f32_e32 v49, v26, v38
	v_fmac_f32_e32 v43, v27, v39
	v_cvt_pk_bf16_f32 v24, v46, v40
	v_cvt_pk_bf16_f32 v25, v47, v41
	v_cvt_pk_bf16_f32 v26, v48, v42
	v_cvt_pk_bf16_f32 v27, v49, v43
	global_load_dwordx4 v[28:31], v[54:55], off offset:256
	global_load_dwordx4 v[32:35], v[44:45], off offset:256
	v_add_u32_e32 v36, 0xb0, v146
	global_store_dwordx4 v[44:45], v[24:27], off
	v_mad_i64_i32 v[38:39], s[18:19], v36, s41, v[148:149]
	v_lshl_add_u64 v[38:39], v[38:39], 0, v[144:145]
	s_mov_b64 s[18:19], s[12:13]
	s_waitcnt vmcnt(0)
	v_lshlrev_b32_e32 v24, 16, v28
	v_lshlrev_b32_e32 v37, 16, v32
	v_and_b32_e32 v25, 0xffff0000, v28
	v_lshlrev_b32_e32 v28, 16, v30
	v_and_b32_e32 v32, 0xffff0000, v32
	v_lshlrev_b32_e32 v41, 16, v34
	v_fmac_f32_e32 v37, v20, v24
	v_fmac_f32_e32 v32, v21, v25
	v_fmac_f32_e32 v41, v16, v28
	v_cvt_pk_bf16_f32 v16, v37, v32
	v_ashrrev_i32_e32 v37, 31, v36
	v_lshlrev_b64 v[24:25], 11, v[36:37]
	v_lshlrev_b32_e32 v26, 16, v29
	v_and_b32_e32 v27, 0xffff0000, v29
	v_and_b32_e32 v29, 0xffff0000, v30
	v_and_b32_e32 v34, 0xffff0000, v34
	v_lshl_add_u64 v[24:25], s[0:1], 0, v[24:25]
	v_lshlrev_b32_e32 v30, 16, v31
	v_and_b32_e32 v31, 0xffff0000, v31
	v_lshlrev_b32_e32 v40, 16, v33
	v_and_b32_e32 v33, 0xffff0000, v33
	v_lshlrev_b32_e32 v42, 16, v35
	v_and_b32_e32 v35, 0xffff0000, v35
	v_fmac_f32_e32 v34, v17, v29
	v_lshl_add_u64 v[28:29], v[24:25], 0, v[144:145]
	v_fmac_f32_e32 v40, v22, v26
	v_fmac_f32_e32 v33, v23, v27
	v_fmac_f32_e32 v42, v18, v30
	v_fmac_f32_e32 v35, v19, v31
	v_cvt_pk_bf16_f32 v17, v40, v33
	v_cvt_pk_bf16_f32 v18, v41, v34
	v_cvt_pk_bf16_f32 v19, v42, v35
	global_load_dwordx4 v[20:23], v[38:39], off
	global_load_dwordx4 v[24:27], v[28:29], off
	s_waitcnt vmcnt(0)
	v_lshlrev_b32_e32 v30, 16, v24
	global_store_dwordx4 v[44:45], v[16:19], off offset:256
	v_and_b32_e32 v24, 0xffff0000, v24
	v_lshlrev_b32_e32 v31, 16, v25
	v_lshlrev_b32_e32 v16, 16, v20
	v_and_b32_e32 v17, 0xffff0000, v20
	v_lshlrev_b32_e32 v18, 16, v21
	v_and_b32_e32 v19, 0xffff0000, v21
	v_lshlrev_b32_e32 v20, 16, v22
	v_and_b32_e32 v21, 0xffff0000, v22
	v_lshlrev_b32_e32 v22, 16, v23
	v_and_b32_e32 v23, 0xffff0000, v23
	v_and_b32_e32 v25, 0xffff0000, v25
	v_lshlrev_b32_e32 v32, 16, v26
	v_and_b32_e32 v26, 0xffff0000, v26
	v_lshlrev_b32_e32 v33, 16, v27
	v_and_b32_e32 v27, 0xffff0000, v27
	v_fmac_f32_e32 v30, v12, v16
	v_fmac_f32_e32 v24, v13, v17
	v_fmac_f32_e32 v31, v14, v18
	v_fmac_f32_e32 v25, v15, v19
	v_fmac_f32_e32 v32, v8, v20
	v_fmac_f32_e32 v26, v9, v21
	v_fmac_f32_e32 v33, v10, v22
	v_fmac_f32_e32 v27, v11, v23
	v_cvt_pk_bf16_f32 v8, v30, v24
	v_cvt_pk_bf16_f32 v9, v31, v25
	v_cvt_pk_bf16_f32 v10, v32, v26
	v_cvt_pk_bf16_f32 v11, v33, v27
	global_load_dwordx4 v[12:15], v[38:39], off offset:256
	global_load_dwordx4 v[16:19], v[28:29], off offset:256
	s_waitcnt vmcnt(0)
	v_lshlrev_b32_e32 v20, 16, v16
	global_store_dwordx4 v[28:29], v[8:11], off
	v_and_b32_e32 v16, 0xffff0000, v16
	v_lshlrev_b32_e32 v21, 16, v17
	v_lshlrev_b32_e32 v8, 16, v12
	v_and_b32_e32 v9, 0xffff0000, v12
	v_lshlrev_b32_e32 v10, 16, v13
	v_and_b32_e32 v11, 0xffff0000, v13
	v_lshlrev_b32_e32 v12, 16, v14
	v_and_b32_e32 v13, 0xffff0000, v14
	v_lshlrev_b32_e32 v14, 16, v15
	v_and_b32_e32 v15, 0xffff0000, v15
	v_and_b32_e32 v17, 0xffff0000, v17
	v_lshlrev_b32_e32 v22, 16, v18
	v_and_b32_e32 v18, 0xffff0000, v18
	v_lshlrev_b32_e32 v23, 16, v19
	v_and_b32_e32 v19, 0xffff0000, v19
	v_fmac_f32_e32 v20, v4, v8
	v_fmac_f32_e32 v16, v5, v9
	v_fmac_f32_e32 v21, v6, v10
	v_fmac_f32_e32 v17, v7, v11
	v_fmac_f32_e32 v22, v0, v12
	v_fmac_f32_e32 v18, v1, v13
	v_fmac_f32_e32 v23, v2, v14
	v_fmac_f32_e32 v19, v3, v15
	v_cvt_pk_bf16_f32 v0, v20, v16
	v_cvt_pk_bf16_f32 v1, v21, v17
	v_cvt_pk_bf16_f32 v2, v22, v18
	v_cvt_pk_bf16_f32 v3, v23, v19
	global_store_dwordx4 v[28:29], v[0:3], off offset:256
	s_cbranch_vccz .LBB0_1004
	s_waitcnt vmcnt(0)
	s_cmpk_gt_u32 s25, 0xff
	s_cbranch_scc1 .LBB0_1015
	s_barrier

; #define PG8_STAGE(bufoff, gbase, voff) do { _Pragma("unroll") for (int _i = 0; _i < 2; ++_i) \
;         __builtin_amdgcn_global_load_lds((const unsigned*)((const char*)(gbase) + (voff)[_i]), (PG8_LAS unsigned*)(lds + (bufoff) + ldsw + _i * 8192), 16, 0, 0); } while (0)
; #define PG8_LDA(dst, b, h) do { _Pragma("unroll") for (int m = 0; m < 4; ++m) _Pragma("unroll") for (int k = 0; k < 2; ++k) dst[m][k] = *(const PG8_LAS bf16x8*)(lds + PG8_SA(b, h) + aoff + m * 2048 + k * 1024); } while (0)
; #define PG8_LDB(dst, b, h) do { _Pragma("unroll") for (int n = 0; n < 2; ++n) _Pragma("unroll") for (int k = 0; k < 2; ++k) dst[n][k] = *(const PG8_LAS bf16x8*)(lds + PG8_SB(b, h) + boff + n * 2048 + k * 1024); } while (0)
; #define PG8_MMA(ai, bj, At, Bt) do { __builtin_amdgcn_s_setprio(1); _Pragma("unroll") for (int m = 0; m < 4; ++m) _Pragma("unroll") for (int n = 0; n < 2; ++n) _Pragma("unroll") for (int k = 0; k < 2; ++k) \
;         acc[ai][bj][m][n] = __builtin_amdgcn_mfma_f32_16x16x32_bf16(Bt[n][k], At[m][k], acc[ai][bj][m][n], 0, 0, 0); __builtin_amdgcn_s_setprio(0); } while (0)
; #define PG8_WAIT_L(n) asm volatile("s_waitcnt lgkmcnt(" #n ")" ::: "memory")
; #define PG8_BAR __builtin_amdgcn_s_barrier()
; #define PG8_SCHED __builtin_amdgcn_sched_barrier(0)
; template <class Epi, class Sched>
; __device__ __forceinline__ void gemm_phase(PG8_LAS unsigned char* lds, const Gemm g, const Sched& S, const Epi& E) {
;     ...
;             PG8_LDB(B0, 0, 0); PG8_SCHED; PG8_LDA(At, 0, 0); PG8_STAGE(PG8_SA(1, 1), a1 + hstep, voffA);
;             PG8_WAIT_L(8); PG8_BAR; PG8_WAIT_L(0); PG8_MMA(0, 0, At, B0); PG8_BAR; PG8_SCHED;
;             PG8_LDB(B1, 0, 1); PG8_STAGE(PG8_SB(0, 0), b2, voffB);
;             PG8_BAR; PG8_WAIT_L(0); PG8_MMA(0, 1, At, B1); PG8_BAR;
;             PG8_LDA(At, 0, 1); PG8_STAGE(PG8_SA(0, 0), a2, voffA);
;             PG8_BAR; PG8_WAIT_L(0); PG8_MMA(1, 0, At, B0); PG8_BAR; PG8_SCHED;
.LBB0_1083:
	s_add_u32 s26, s24, 0xfffc0080
	s_addc_u32 s27, s25, -1
	s_cmp_eq_u32 s56, 12
	s_cselect_b32 s29, s17, s27
	s_cselect_b32 s28, s52, s26
	s_cselect_b32 s27, s15, s55
	s_cselect_b32 s26, s53, s54
	v_lshl_add_u64 v[144:145], s[24:25], 0, v[136:137]
	s_add_i32 m0, s23, 0xc000
	s_nop 0
	global_load_lds_dwordx4 v[144:145], off
	v_lshl_add_u64 v[144:145], s[24:25], 0, v[138:139]
	s_add_i32 m0, s23, 0xe000
	s_nop 0
	global_load_lds_dwordx4 v[144:145], off
	ds_read_b128 v[152:155], v149
	ds_read_b128 v[156:159], v149 offset:1024
	ds_read_b128 v[160:163], v149 offset:2048
	ds_read_b128 v[164:167], v149 offset:3072
	ds_read_b128 v[168:171], v150
	ds_read_b128 v[172:175], v150 offset:1024
	ds_read_b128 v[182:185], v150 offset:2048
	ds_read_b128 v[190:193], v150 offset:3072
	ds_read_b128 v[194:197], v150 offset:4096
	ds_read_b128 v[198:201], v150 offset:5120
	ds_read_b128 v[202:205], v150 offset:6144
	ds_read_b128 v[206:209], v150 offset:7168
	s_waitcnt lgkmcnt(8)
	s_barrier
	s_waitcnt lgkmcnt(0)
	v_mfma_f32_16x16x32_bf16 v[124:127], v[152:155], v[168:171], v[124:127]
	v_mfma_f32_16x16x32_bf16 v[120:123], v[160:163], v[168:171], v[120:123]
	v_mfma_f32_16x16x32_bf16 v[108:111], v[152:155], v[182:185], v[108:111]
	v_mfma_f32_16x16x32_bf16 v[104:107], v[160:163], v[182:185], v[104:107]
	v_mfma_f32_16x16x32_bf16 v[92:95], v[152:155], v[194:197], v[92:95]
	v_mfma_f32_16x16x32_bf16 v[88:91], v[160:163], v[194:197], v[88:91]
	v_mfma_f32_16x16x32_bf16 v[76:79], v[152:155], v[202:205], v[76:79]
	v_mfma_f32_16x16x32_bf16 v[72:75], v[160:163], v[202:205], v[72:75]
	v_mfma_f32_16x16x32_bf16 v[124:127], v[156:159], v[172:175], v[124:127]
	v_mfma_f32_16x16x32_bf16 v[120:123], v[164:167], v[172:175], v[120:123]
	v_mfma_f32_16x16x32_bf16 v[108:111], v[156:159], v[190:193], v[108:111]
	v_mfma_f32_16x16x32_bf16 v[104:107], v[164:167], v[190:193], v[104:107]
	v_mfma_f32_16x16x32_bf16 v[92:95], v[156:159], v[198:201], v[92:95]
	v_mfma_f32_16x16x32_bf16 v[88:91], v[164:167], v[198:201], v[88:91]
	v_mfma_f32_16x16x32_bf16 v[76:79], v[156:159], v[206:209], v[76:79]
	v_mfma_f32_16x16x32_bf16 v[72:75], v[164:167], v[206:209], v[72:75]
	s_barrier
	s_add_i32 s57, s45, s37
	v_lshl_add_u64 v[144:145], s[26:27], 0, v[130:131]
	s_mov_b32 m0, s57
	s_nop 0
	global_load_lds_dwordx4 v[144:145], off
	v_lshl_add_u64 v[186:187], s[26:27], 0, v[134:135]
	s_add_i32 m0, s57, 0x2000
	s_nop 0
	global_load_lds_dwordx4 v[186:187], off
	ds_read_b128 v[210:213], v151
	ds_read_b128 v[214:217], v151 offset:1024
	ds_read_b128 v[218:221], v151 offset:2048
	ds_read_b128 v[222:225], v151 offset:3072
	s_barrier
	s_waitcnt lgkmcnt(0)
	v_mfma_f32_16x16x32_bf16 v[116:119], v[210:213], v[168:171], v[116:119]
	v_mfma_f32_16x16x32_bf16 v[112:115], v[218:221], v[168:171], v[112:115]
	v_mfma_f32_16x16x32_bf16 v[100:103], v[210:213], v[182:185], v[100:103]
	v_mfma_f32_16x16x32_bf16 v[96:99], v[218:221], v[182:185], v[96:99]
	v_mfma_f32_16x16x32_bf16 v[84:87], v[210:213], v[194:197], v[84:87]
	v_mfma_f32_16x16x32_bf16 v[80:83], v[218:221], v[194:197], v[80:83]
	v_mfma_f32_16x16x32_bf16 v[68:71], v[210:213], v[202:205], v[68:71]
	v_mfma_f32_16x16x32_bf16 v[64:67], v[218:221], v[202:205], v[64:67]
	v_mfma_f32_16x16x32_bf16 v[116:119], v[214:217], v[172:175], v[116:119]
	v_mfma_f32_16x16x32_bf16 v[112:115], v[222:225], v[172:175], v[112:115]
	v_mfma_f32_16x16x32_bf16 v[100:103], v[214:217], v[190:193], v[100:103]
	v_mfma_f32_16x16x32_bf16 v[96:99], v[222:225], v[190:193], v[96:99]
	v_mfma_f32_16x16x32_bf16 v[84:87], v[214:217], v[198:201], v[84:87]
	v_mfma_f32_16x16x32_bf16 v[80:83], v[222:225], v[198:201], v[80:83]
	v_mfma_f32_16x16x32_bf16 v[68:71], v[214:217], v[206:209], v[68:71]
	v_mfma_f32_16x16x32_bf16 v[64:67], v[222:225], v[206:209], v[64:67]
	s_mov_b32 m0, s23
	v_lshl_add_u64 v[226:227], s[28:29], 0, v[128:129]
	s_barrier
	global_load_lds_dwordx4 v[226:227], off
	v_lshl_add_u64 v[228:229], s[28:29], 0, v[132:133]
	s_mov_b32 m0, s38
	s_nop 0
	global_load_lds_dwordx4 v[228:229], off
	ds_read_b128 v[168:171], v150 offset:16384
	ds_read_b128 v[172:175], v150 offset:17408
	ds_read_b128 v[182:185], v150 offset:18432
	ds_read_b128 v[190:193], v150 offset:19456
	ds_read_b128 v[194:197], v150 offset:20480
	ds_read_b128 v[198:201], v150 offset:21504
	ds_read_b128 v[202:205], v150 offset:22528
	ds_read_b128 v[206:209], v150 offset:23552
	s_barrier
	s_waitcnt lgkmcnt(0)
	v_mfma_f32_16x16x32_bf16 v[60:63], v[152:155], v[168:171], v[60:63]
	v_mfma_f32_16x16x32_bf16 v[56:59], v[160:163], v[168:171], v[56:59]
	v_mfma_f32_16x16x32_bf16 v[48:51], v[152:155], v[182:185], v[48:51]
	v_mfma_f32_16x16x32_bf16 v[40:43], v[160:163], v[182:185], v[40:43]
	v_mfma_f32_16x16x32_bf16 v[32:35], v[152:155], v[194:197], v[32:35]
	v_mfma_f32_16x16x32_bf16 v[24:27], v[160:163], v[194:197], v[24:27]
	v_mfma_f32_16x16x32_bf16 v[16:19], v[152:155], v[202:205], v[16:19]
	v_mfma_f32_16x16x32_bf16 v[8:11], v[160:163], v[202:205], v[8:11]
	v_mfma_f32_16x16x32_bf16 v[60:63], v[156:159], v[172:175], v[60:63]
	v_mfma_f32_16x16x32_bf16 v[56:59], v[164:167], v[172:175], v[56:59]
	v_mfma_f32_16x16x32_bf16 v[48:51], v[156:159], v[190:193], v[48:51]
	v_mfma_f32_16x16x32_bf16 v[40:43], v[164:167], v[190:193], v[40:43]
	v_mfma_f32_16x16x32_bf16 v[32:35], v[156:159], v[198:201], v[32:35]
	v_mfma_f32_16x16x32_bf16 v[24:27], v[164:167], v[198:201], v[24:27]
	v_mfma_f32_16x16x32_bf16 v[16:19], v[156:159], v[206:209], v[16:19]
	v_mfma_f32_16x16x32_bf16 v[8:11], v[164:167], v[206:209], v[8:11]
	s_barrier
; #define PG8_STAGE(bufoff, gbase, voff) do { _Pragma("unroll") for (int _i = 0; _i < 2; ++_i) \
;         __builtin_amdgcn_global_load_lds((const unsigned*)((const char*)(gbase) + (voff)[_i]), (PG8_LAS unsigned*)(lds + (bufoff) + ldsw + _i * 8192), 16, 0, 0); } while (0)
; #define PG8_LDA(dst, b, h) do { _Pragma("unroll") for (int m = 0; m < 4; ++m) _Pragma("unroll") for (int k = 0; k < 2; ++k) dst[m][k] = *(const PG8_LAS bf16x8*)(lds + PG8_SA(b, h) + aoff + m * 2048 + k * 1024); } while (0)
; #define PG8_LDB(dst, b, h) do { _Pragma("unroll") for (int n = 0; n < 2; ++n) _Pragma("unroll") for (int k = 0; k < 2; ++k) dst[n][k] = *(const PG8_LAS bf16x8*)(lds + PG8_SB(b, h) + boff + n * 2048 + k * 1024); } while (0)
; #define PG8_MMA(ai, bj, At, Bt) do { __builtin_amdgcn_s_setprio(1); _Pragma("unroll") for (int m = 0; m < 4; ++m) _Pragma("unroll") for (int n = 0; n < 2; ++n) _Pragma("unroll") for (int k = 0; k < 2; ++k) \
;         acc[ai][bj][m][n] = __builtin_amdgcn_mfma_f32_16x16x32_bf16(Bt[n][k], At[m][k], acc[ai][bj][m][n], 0, 0, 0); __builtin_amdgcn_s_setprio(0); } while (0)
; #define PG8_WAIT_V(n) asm volatile("s_waitcnt vmcnt(" #n ")" ::: "memory")
; #define PG8_WAIT_L(n) asm volatile("s_waitcnt lgkmcnt(" #n ")" ::: "memory")
; #define PG8_BAR __builtin_amdgcn_s_barrier()
; #define PG8_SCHED __builtin_amdgcn_sched_barrier(0)
; template <class Epi, class Sched>
; __device__ __forceinline__ void gemm_phase(PG8_LAS unsigned char* lds, const Gemm g, const Sched& S, const Epi& E) {
;     ...
;             PG8_STAGE(PG8_SB(0, 1), b2 + hstep, voffB);
;             PG8_WAIT_V(6); PG8_BAR; PG8_MMA(1, 1, At, B1); PG8_BAR;
;             PG8_LDB(B0, 1, 0); PG8_SCHED; PG8_LDA(At, 1, 0); PG8_STAGE(PG8_SA(0, 1), a2 + hstep, voffA);
;             PG8_WAIT_L(8); PG8_BAR; PG8_WAIT_L(0); PG8_MMA(0, 0, At, B0); PG8_BAR; PG8_SCHED;
;             PG8_LDB(B1, 1, 1); PG8_STAGE(PG8_SB(1, 0), b3, voffB);
;             PG8_BAR; PG8_WAIT_L(0); PG8_MMA(0, 1, At, B1); PG8_BAR;
;             PG8_LDA(At, 1, 1); PG8_STAGE(PG8_SA(1, 0), a3, voffA);
	s_add_u32 s58, s26, 0x40000
	s_addc_u32 s59, s27, 0
	s_add_i32 s57, s46, s37
	v_lshl_add_u64 v[152:153], s[58:59], 0, v[130:131]
	s_mov_b32 m0, s57
	s_nop 0
	global_load_lds_dwordx4 v[152:153], off
	v_lshl_add_u64 v[152:153], s[58:59], 0, v[134:135]
	s_add_i32 m0, s57, 0x2000
	s_nop 0
	global_load_lds_dwordx4 v[152:153], off
	s_waitcnt vmcnt(6)
	s_barrier
	v_mfma_f32_16x16x32_bf16 v[52:55], v[210:213], v[168:171], v[52:55]
	v_mfma_f32_16x16x32_bf16 v[44:47], v[218:221], v[168:171], v[44:47]
	v_mfma_f32_16x16x32_bf16 v[36:39], v[210:213], v[182:185], v[36:39]
	v_mfma_f32_16x16x32_bf16 v[28:31], v[218:221], v[182:185], v[28:31]
	v_mfma_f32_16x16x32_bf16 v[20:23], v[210:213], v[194:197], v[20:23]
	v_mfma_f32_16x16x32_bf16 v[12:15], v[218:221], v[194:197], v[12:15]
	v_mfma_f32_16x16x32_bf16 v[4:7], v[210:213], v[202:205], v[4:7]
	v_mfma_f32_16x16x32_bf16 v[0:3], v[218:221], v[202:205], v[0:3]
	v_mfma_f32_16x16x32_bf16 v[52:55], v[214:217], v[172:175], v[52:55]
	v_mfma_f32_16x16x32_bf16 v[44:47], v[222:225], v[172:175], v[44:47]
	v_mfma_f32_16x16x32_bf16 v[36:39], v[214:217], v[190:193], v[36:39]
	v_mfma_f32_16x16x32_bf16 v[28:31], v[222:225], v[190:193], v[28:31]
	v_mfma_f32_16x16x32_bf16 v[20:23], v[214:217], v[198:201], v[20:23]
	v_mfma_f32_16x16x32_bf16 v[12:15], v[222:225], v[198:201], v[12:15]
	v_mfma_f32_16x16x32_bf16 v[4:7], v[214:217], v[206:209], v[4:7]
	v_mfma_f32_16x16x32_bf16 v[0:3], v[222:225], v[206:209], v[0:3]
	s_add_i32 s57, 0, 0x18000
	v_add_u32_e32 v164, s57, v147
	s_barrier
	s_add_u32 s28, s28, 0x40000
	s_addc_u32 s29, s29, 0
	s_mov_b32 m0, s39
	v_lshl_add_u64 v[210:211], s[28:29], 0, v[128:129]
	global_load_lds_dwordx4 v[210:211], off
	v_lshl_add_u64 v[210:211], s[28:29], 0, v[132:133]
	s_mov_b32 m0, s40
	s_nop 0
	global_load_lds_dwordx4 v[210:211], off
	ds_read_b128 v[152:155], v164
	ds_read_b128 v[156:159], v164 offset:1024
	ds_read_b128 v[160:163], v164 offset:2048
	ds_read_b128 v[164:167], v164 offset:3072
	ds_read_b128 v[168:171], v150 offset:32768
	ds_read_b128 v[172:175], v150 offset:33792
	ds_read_b128 v[182:185], v150 offset:34816
	ds_read_b128 v[190:193], v150 offset:35840
	ds_read_b128 v[194:197], v150 offset:36864
	ds_read_b128 v[198:201], v150 offset:37888
	ds_read_b128 v[202:205], v150 offset:38912
	ds_read_b128 v[206:209], v150 offset:39936
	s_waitcnt lgkmcnt(8)
	s_barrier
	s_waitcnt lgkmcnt(0)
	v_mfma_f32_16x16x32_bf16 v[124:127], v[152:155], v[168:171], v[124:127]
	v_mfma_f32_16x16x32_bf16 v[120:123], v[160:163], v[168:171], v[120:123]
	v_mfma_f32_16x16x32_bf16 v[108:111], v[152:155], v[182:185], v[108:111]
	v_mfma_f32_16x16x32_bf16 v[104:107], v[160:163], v[182:185], v[104:107]
	v_mfma_f32_16x16x32_bf16 v[92:95], v[152:155], v[194:197], v[92:95]
	v_mfma_f32_16x16x32_bf16 v[88:91], v[160:163], v[194:197], v[88:91]
	v_mfma_f32_16x16x32_bf16 v[76:79], v[152:155], v[202:205], v[76:79]
	v_mfma_f32_16x16x32_bf16 v[72:75], v[160:163], v[202:205], v[72:75]
	v_mfma_f32_16x16x32_bf16 v[124:127], v[156:159], v[172:175], v[124:127]
	v_mfma_f32_16x16x32_bf16 v[120:123], v[164:167], v[172:175], v[120:123]
	v_mfma_f32_16x16x32_bf16 v[108:111], v[156:159], v[190:193], v[108:111]
	v_mfma_f32_16x16x32_bf16 v[104:107], v[164:167], v[190:193], v[104:107]
	v_mfma_f32_16x16x32_bf16 v[92:95], v[156:159], v[198:201], v[92:95]
	v_mfma_f32_16x16x32_bf16 v[88:91], v[164:167], v[198:201], v[88:91]
	v_mfma_f32_16x16x32_bf16 v[76:79], v[156:159], v[206:209], v[76:79]
	v_mfma_f32_16x16x32_bf16 v[72:75], v[164:167], v[206:209], v[72:75]
	s_barrier
	s_add_i32 s28, 0, 0x1c000
	s_add_i32 s29, s57, s37
	v_add_u32_e32 v179, s28, v147
	v_lshl_add_u64 v[144:145], v[144:145], 0, s[6:7]
	s_mov_b32 m0, s29
	s_nop 0
	global_load_lds_dwordx4 v[144:145], off
	v_lshl_add_u64 v[144:145], v[186:187], 0, s[6:7]
	s_add_i32 m0, s29, 0x2000
	s_nop 0
	global_load_lds_dwordx4 v[144:145], off
	ds_read_b128 v[210:213], v179
	ds_read_b128 v[214:217], v179 offset:1024
	ds_read_b128 v[218:221], v179 offset:2048
	ds_read_b128 v[222:225], v179 offset:3072
	s_barrier
	s_waitcnt lgkmcnt(0)
	v_mfma_f32_16x16x32_bf16 v[116:119], v[210:213], v[168:171], v[116:119]
	v_mfma_f32_16x16x32_bf16 v[112:115], v[218:221], v[168:171], v[112:115]
	v_mfma_f32_16x16x32_bf16 v[100:103], v[210:213], v[182:185], v[100:103]
	v_mfma_f32_16x16x32_bf16 v[96:99], v[218:221], v[182:185], v[96:99]
	v_mfma_f32_16x16x32_bf16 v[84:87], v[210:213], v[194:197], v[84:87]
	v_mfma_f32_16x16x32_bf16 v[80:83], v[218:221], v[194:197], v[80:83]
	v_mfma_f32_16x16x32_bf16 v[68:71], v[210:213], v[202:205], v[68:71]
	v_mfma_f32_16x16x32_bf16 v[64:67], v[218:221], v[202:205], v[64:67]
	v_mfma_f32_16x16x32_bf16 v[116:119], v[214:217], v[172:175], v[116:119]
	v_mfma_f32_16x16x32_bf16 v[112:115], v[222:225], v[172:175], v[112:115]
	v_mfma_f32_16x16x32_bf16 v[100:103], v[214:217], v[190:193], v[100:103]
	v_mfma_f32_16x16x32_bf16 v[96:99], v[222:225], v[190:193], v[96:99]
	v_mfma_f32_16x16x32_bf16 v[84:87], v[214:217], v[198:201], v[84:87]
	v_mfma_f32_16x16x32_bf16 v[80:83], v[222:225], v[198:201], v[80:83]
	v_mfma_f32_16x16x32_bf16 v[68:71], v[214:217], v[206:209], v[68:71]
	v_mfma_f32_16x16x32_bf16 v[64:67], v[222:225], v[206:209], v[64:67]
	s_mov_b32 m0, s42
	v_lshl_add_u64 v[144:145], v[226:227], 0, s[6:7]
	s_barrier
	global_load_lds_dwordx4 v[144:145], off
	v_lshl_add_u64 v[144:145], v[228:229], 0, s[6:7]
	s_mov_b32 m0, s43
	s_nop 0
	global_load_lds_dwordx4 v[144:145], off
	ds_read_b128 v[168:171], v150 offset:49152
	ds_read_b128 v[172:175], v150 offset:50176
	ds_read_b128 v[182:185], v150 offset:51200
	ds_read_b128 v[190:193], v150 offset:52224
	ds_read_b128 v[194:197], v150 offset:53248
	ds_read_b128 v[198:201], v150 offset:54272
	ds_read_b128 v[202:205], v150 offset:55296
	ds_read_b128 v[206:209], v150 offset:56320
	s_barrier
; __device__ __forceinline__ unsigned cvt_pk_bf16(float lo, float hi) { unsigned r; asm volatile("v_cvt_pk_bf16_f32 %0, %1, %2" : "=v"(r) : "v"(lo), "v"(hi)); return r; }
; __device__ __forceinline__ float flogsig16(float x) { return (fminf(x, 0.f) - __logf(1.0f + __expf(-fabsf(x)))) * 0.0625f; }
; #define PG8_WAIT_V(n) asm volatile("s_waitcnt vmcnt(" #n ")" ::: "memory")
; #define PG8_WAIT_L(n) asm volatile("s_waitcnt lgkmcnt(" #n ")" ::: "memory")
;     __device__ __forceinline__ void operator()(const f32x4 (&acc)[2][2][4][2], const Unit& u, int wr, int wc, int fr, int fq) const {
;     ...
;         const int row0 = u.pm * BM + wr * 64 + fr, col0 = u.pn * BM + wc * 32 + 8 * fq, bcol0 = wc * 32 + 8 * fq;
;         f32x4 bv[2][2];
; #pragma unroll
;         for (int bj = 0; bj < 2; ++bj)
; #pragma unroll
;             for (int n = 0; n < 2; ++n) bv[bj][n] = bias ? *(const f32x4*)(bias + bcol0 + bj * HALF + 4 * n) : (f32x4){0.f, 0.f, 0.f, 0.f};
; #pragma unroll
;         for (int ai = 0; ai < 2; ++ai)
; #pragma unroll
;             for (int m = 0; m < 4; ++m) { bf16_t* rowp = O + (size_t)(row0 + ai * HALF + m * 16) * ldc + col0;
; #pragma unroll
;                 for (int bj = 0; bj < 2; ++bj) { f32x4 v0 = acc[ai][bj][m][0] + bv[bj][0], v1 = acc[ai][bj][m][1] + bv[bj][1];
;                     if (act == 1) {
; #pragma unroll
;                         for (int j = 0; j < 1; ++j) { v0 = v0 * sigmoid4(v0); v1 = v1 * sigmoid4(v1); } }
;                     else if (act == 2) {
; #pragma unroll
;                         for (int j = 0; j < 1; ++j) { v0 = sigmoid4(v0); v1 = sigmoid4(v1); } }
;                     else if (act == 3) {
; #pragma unroll
;                         for (int j = 0; j < 4; ++j) { v0[j] = flogsig16(v0[j]); v1[j] = flogsig16(v1[j]); } }
;                     u32x4 w; w.x = cvt_pk_bf16(v0[0], v0[1]); w.y = cvt_pk_bf16(v0[2], v0[3]); w.z = cvt_pk_bf16(v1[0], v1[1]); w.w = cvt_pk_bf16(v1[2], v1[3]);
;                     *(u32x4*)(rowp + bj * HALF) = w; } }
; template <class Epi, class Sched>
; __device__ __forceinline__ void gemm_phase(PG8_LAS unsigned char* lds, const Gemm g, const Sched& S, const Epi& E) {
;     ...
;             PG8_BAR; PG8_WAIT_L(0); PG8_MMA(1, 0, At, B0); PG8_BAR; PG8_SCHED;
;             PG8_STAGE(PG8_SB(1, 1), b3 + hstep, voffB);
;             PG8_WAIT_V(6); PG8_BAR; PG8_MMA(1, 1, At, B1); PG8_BAR;
	s_waitcnt lgkmcnt(0)
	v_mfma_f32_16x16x32_bf16 v[60:63], v[152:155], v[168:171], v[60:63]
	v_mfma_f32_16x16x32_bf16 v[56:59], v[160:163], v[168:171], v[56:59]
	v_mfma_f32_16x16x32_bf16 v[48:51], v[152:155], v[182:185], v[48:51]
	v_mfma_f32_16x16x32_bf16 v[40:43], v[160:163], v[182:185], v[40:43]
	v_mfma_f32_16x16x32_bf16 v[32:35], v[152:155], v[194:197], v[32:35]
	v_mfma_f32_16x16x32_bf16 v[24:27], v[160:163], v[194:197], v[24:27]
	v_mfma_f32_16x16x32_bf16 v[16:19], v[152:155], v[202:205], v[16:19]
	v_mfma_f32_16x16x32_bf16 v[8:11], v[160:163], v[202:205], v[8:11]
	v_mfma_f32_16x16x32_bf16 v[60:63], v[156:159], v[172:175], v[60:63]
	v_mfma_f32_16x16x32_bf16 v[56:59], v[164:167], v[172:175], v[56:59]
	v_mfma_f32_16x16x32_bf16 v[48:51], v[156:159], v[190:193], v[48:51]
	v_mfma_f32_16x16x32_bf16 v[40:43], v[164:167], v[190:193], v[40:43]
	v_mfma_f32_16x16x32_bf16 v[32:35], v[156:159], v[198:201], v[32:35]
	v_mfma_f32_16x16x32_bf16 v[24:27], v[164:167], v[198:201], v[24:27]
	v_mfma_f32_16x16x32_bf16 v[16:19], v[156:159], v[206:209], v[16:19]
	v_mfma_f32_16x16x32_bf16 v[8:11], v[164:167], v[206:209], v[8:11]
	s_barrier
	s_add_u32 s26, s26, 0x40080
	s_addc_u32 s27, s27, 0
	s_add_i32 s28, s28, s37
	v_lshl_add_u64 v[144:145], s[26:27], 0, v[130:131]
	s_mov_b32 m0, s28
	s_nop 0
	global_load_lds_dwordx4 v[144:145], off
	v_lshl_add_u64 v[144:145], s[26:27], 0, v[134:135]
	s_add_i32 m0, s28, 0x2000
	s_nop 0
	global_load_lds_dwordx4 v[144:145], off
	s_waitcnt vmcnt(6)
	s_barrier
	v_mfma_f32_16x16x32_bf16 v[52:55], v[210:213], v[168:171], v[52:55]
	v_mfma_f32_16x16x32_bf16 v[44:47], v[218:221], v[168:171], v[44:47]
	v_mfma_f32_16x16x32_bf16 v[36:39], v[210:213], v[182:185], v[36:39]
	v_mfma_f32_16x16x32_bf16 v[28:31], v[218:221], v[182:185], v[28:31]
	v_mfma_f32_16x16x32_bf16 v[20:23], v[210:213], v[194:197], v[20:23]
	v_mfma_f32_16x16x32_bf16 v[12:15], v[218:221], v[194:197], v[12:15]
	v_mfma_f32_16x16x32_bf16 v[4:7], v[210:213], v[202:205], v[4:7]
	v_mfma_f32_16x16x32_bf16 v[0:3], v[218:221], v[202:205], v[0:3]
	v_mfma_f32_16x16x32_bf16 v[52:55], v[214:217], v[172:175], v[52:55]
	v_mfma_f32_16x16x32_bf16 v[44:47], v[222:225], v[172:175], v[44:47]
	v_mfma_f32_16x16x32_bf16 v[36:39], v[214:217], v[190:193], v[36:39]
	v_mfma_f32_16x16x32_bf16 v[28:31], v[222:225], v[190:193], v[28:31]
	v_mfma_f32_16x16x32_bf16 v[20:23], v[214:217], v[198:201], v[20:23]
	v_mfma_f32_16x16x32_bf16 v[12:15], v[222:225], v[198:201], v[12:15]
	v_mfma_f32_16x16x32_bf16 v[4:7], v[214:217], v[206:209], v[4:7]
	v_mfma_f32_16x16x32_bf16 v[0:3], v[222:225], v[206:209], v[0:3]
	s_add_i32 s56, s56, 2
	s_add_u32 s24, s24, 0x100
	s_addc_u32 s25, s25, 0
	s_add_u32 s54, s54, 0x100
	s_addc_u32 s55, s55, 0
	s_cmp_gt_u32 s56, 13
	s_barrier
	s_cbranch_scc0 .LBB0_1083
	v_lshl_add_u32 v152, s22, 8, v146
	v_lshl_or_b32 v144, s51, 8, v148
	v_ashrrev_i32_e32 v153, 31, v152
	v_ashrrev_i32_e32 v145, 31, v144
	v_lshlrev_b64 v[154:155], 11, v[152:153]
	v_lshl_add_u64 v[154:155], s[4:5], 0, v[154:155]
	v_lshlrev_b64 v[156:157], 1, v[144:145]
	v_lshl_add_u64 v[144:145], v[154:155], 0, v[156:157]
	v_pk_add_f32 v[126:127], v[126:127], 0 op_sel_hi:[1,0]
	v_pk_add_f32 v[124:125], v[124:125], 0 op_sel_hi:[1,0]
	v_pk_add_f32 v[154:155], v[122:123], 0 op_sel_hi:[1,0]
	v_pk_add_f32 v[122:123], v[120:121], 0 op_sel_hi:[1,0]
	v_cvt_pk_bf16_f32 v120, v124, v125
	v_cvt_pk_bf16_f32 v121, v126, v127
	v_pk_add_f32 v[116:117], v[116:117], 0 op_sel_hi:[1,0]
	v_cvt_pk_bf16_f32 v122, v122, v123
	v_cvt_pk_bf16_f32 v123, v154, v155
	global_store_dwordx4 v[144:145], v[120:123], off
	v_pk_add_f32 v[118:119], v[118:119], 0 op_sel_hi:[1,0]
	v_pk_add_f32 v[110:111], v[110:111], 0 op_sel_hi:[1,0]
	v_pk_add_f32 v[120:121], v[114:115], 0 op_sel_hi:[1,0]
	v_pk_add_f32 v[114:115], v[112:113], 0 op_sel_hi:[1,0]
	v_cvt_pk_bf16_f32 v112, v116, v117
	v_cvt_pk_bf16_f32 v113, v118, v119
	v_pk_add_f32 v[108:109], v[108:109], 0 op_sel_hi:[1,0]
	v_cvt_pk_bf16_f32 v114, v114, v115
	v_cvt_pk_bf16_f32 v115, v120, v121
	global_store_dwordx4 v[144:145], v[112:115], off offset:256
	v_pk_add_f32 v[100:101], v[100:101], 0 op_sel_hi:[1,0]
	v_pk_add_f32 v[102:103], v[102:103], 0 op_sel_hi:[1,0]
	v_or_b32_e32 v112, 16, v152
	v_ashrrev_i32_e32 v113, 31, v112
	v_lshlrev_b64 v[112:113], 11, v[112:113]
	v_lshl_add_u64 v[112:113], s[4:5], 0, v[112:113]
	v_lshl_add_u64 v[112:113], v[112:113], 0, v[156:157]
	v_pk_add_f32 v[114:115], v[106:107], 0 op_sel_hi:[1,0]
	v_pk_add_f32 v[106:107], v[104:105], 0 op_sel_hi:[1,0]
	v_cvt_pk_bf16_f32 v104, v108, v109
	v_cvt_pk_bf16_f32 v105, v110, v111
	v_pk_add_f32 v[94:95], v[94:95], 0 op_sel_hi:[1,0]
	v_cvt_pk_bf16_f32 v106, v106, v107
	v_cvt_pk_bf16_f32 v107, v114, v115
	global_store_dwordx4 v[112:113], v[104:107], off
	v_pk_add_f32 v[92:93], v[92:93], 0 op_sel_hi:[1,0]
	v_pk_add_f32 v[84:85], v[84:85], 0 op_sel_hi:[1,0]
	v_pk_add_f32 v[104:105], v[98:99], 0 op_sel_hi:[1,0]
	v_pk_add_f32 v[98:99], v[96:97], 0 op_sel_hi:[1,0]
	v_cvt_pk_bf16_f32 v96, v100, v101
	v_cvt_pk_bf16_f32 v97, v102, v103
	v_pk_add_f32 v[86:87], v[86:87], 0 op_sel_hi:[1,0]
	v_cvt_pk_bf16_f32 v98, v98, v99
	v_cvt_pk_bf16_f32 v99, v104, v105
	global_store_dwordx4 v[112:113], v[96:99], off offset:256
	v_pk_add_f32 v[78:79], v[78:79], 0 op_sel_hi:[1,0]
	v_pk_add_f32 v[76:77], v[76:77], 0 op_sel_hi:[1,0]
	v_or_b32_e32 v96, 32, v152
	v_ashrrev_i32_e32 v97, 31, v96
	v_lshlrev_b64 v[96:97], 11, v[96:97]
	v_lshl_add_u64 v[96:97], s[4:5], 0, v[96:97]
; __device__ __forceinline__ unsigned cvt_pk_bf16(float lo, float hi) { unsigned r; asm volatile("v_cvt_pk_bf16_f32 %0, %1, %2" : "=v"(r) : "v"(lo), "v"(hi)); return r; }
; __device__ __forceinline__ float flogsig16(float x) { return (fminf(x, 0.f) - __logf(1.0f + __expf(-fabsf(x)))) * 0.0625f; }
; #define PG8_WAIT_V(n) asm volatile("s_waitcnt vmcnt(" #n ")" ::: "memory")
; #define PG8_BAR __builtin_amdgcn_s_barrier()
;     __device__ __forceinline__ void operator()(const f32x4 (&acc)[2][2][4][2], const Unit& u, int wr, int wc, int fr, int fq) const {
;     ...
;             for (int m = 0; m < 4; ++m) { bf16_t* rowp = O + (size_t)(row0 + ai * HALF + m * 16) * ldc + col0;
; #pragma unroll
;                 for (int bj = 0; bj < 2; ++bj) { f32x4 v0 = acc[ai][bj][m][0] + bv[bj][0], v1 = acc[ai][bj][m][1] + bv[bj][1];
;                     if (act == 1) {
; #pragma unroll
;                         for (int j = 0; j < 1; ++j) { v0 = v0 * sigmoid4(v0); v1 = v1 * sigmoid4(v1); } }
;                     else if (act == 2) {
; #pragma unroll
;                         for (int j = 0; j < 1; ++j) { v0 = sigmoid4(v0); v1 = sigmoid4(v1); } }
;                     else if (act == 3) {
; #pragma unroll
;                         for (int j = 0; j < 4; ++j) { v0[j] = flogsig16(v0[j]); v1[j] = flogsig16(v1[j]); } }
;                     u32x4 w; w.x = cvt_pk_bf16(v0[0], v0[1]); w.y = cvt_pk_bf16(v0[2], v0[3]); w.z = cvt_pk_bf16(v1[0], v1[1]); w.w = cvt_pk_bf16(v1[2], v1[3]);
;                     *(u32x4*)(rowp + bj * HALF) = w; } }
; template <class Epi, class Sched>
; __device__ __forceinline__ void gemm_phase(PG8_LAS unsigned char* lds, const Gemm g, const Sched& S, const Epi& E) {
;     ...
;         if (!has_next) break;
; #pragma unroll
;         for (int a = 0; a < 2; ++a)
; #pragma unroll
;             for (int b = 0; b < 2; ++b)
; #pragma unroll
;                 for (int m = 0; m < 4; ++m)
; #pragma unroll
;                     for (int n = 0; n < 2; ++n) acc[a][b][m][n] = (f32x4){0.f, 0.f, 0.f, 0.f};
;         cur = nxt; cA = nA; cB = nB; ++ui;
;     }
;     PG8_WAIT_V(0);
;     if (wr == 0) PG8_BAR;
;     PG8_BAR;
	v_lshl_add_u64 v[96:97], v[96:97], 0, v[156:157]
	v_pk_add_f32 v[98:99], v[90:91], 0 op_sel_hi:[1,0]
	v_pk_add_f32 v[90:91], v[88:89], 0 op_sel_hi:[1,0]
	v_cvt_pk_bf16_f32 v88, v92, v93
	v_cvt_pk_bf16_f32 v89, v94, v95
	v_pk_add_f32 v[70:71], v[70:71], 0 op_sel_hi:[1,0]
	v_cvt_pk_bf16_f32 v90, v90, v91
	v_cvt_pk_bf16_f32 v91, v98, v99
	global_store_dwordx4 v[96:97], v[88:91], off
	v_pk_add_f32 v[68:69], v[68:69], 0 op_sel_hi:[1,0]
	v_pk_add_f32 v[60:61], v[60:61], 0 op_sel_hi:[1,0]
	v_pk_add_f32 v[88:89], v[82:83], 0 op_sel_hi:[1,0]
	v_pk_add_f32 v[82:83], v[80:81], 0 op_sel_hi:[1,0]
	v_cvt_pk_bf16_f32 v80, v84, v85
	v_cvt_pk_bf16_f32 v81, v86, v87
	v_pk_add_f32 v[62:63], v[62:63], 0 op_sel_hi:[1,0]
	v_cvt_pk_bf16_f32 v82, v82, v83
	v_cvt_pk_bf16_f32 v83, v88, v89
	global_store_dwordx4 v[96:97], v[80:83], off offset:256
	v_pk_add_f32 v[54:55], v[54:55], 0 op_sel_hi:[1,0]
	v_pk_add_f32 v[52:53], v[52:53], 0 op_sel_hi:[1,0]
	v_or_b32_e32 v80, 48, v152
	v_ashrrev_i32_e32 v81, 31, v80
	v_lshlrev_b64 v[80:81], 11, v[80:81]
	v_lshl_add_u64 v[80:81], s[4:5], 0, v[80:81]
	v_lshl_add_u64 v[80:81], v[80:81], 0, v[156:157]
	v_pk_add_f32 v[82:83], v[74:75], 0 op_sel_hi:[1,0]
	v_pk_add_f32 v[74:75], v[72:73], 0 op_sel_hi:[1,0]
	v_cvt_pk_bf16_f32 v72, v76, v77
	v_cvt_pk_bf16_f32 v73, v78, v79
	v_pk_add_f32 v[48:49], v[48:49], 0 op_sel_hi:[1,0]
	v_cvt_pk_bf16_f32 v74, v74, v75
	v_cvt_pk_bf16_f32 v75, v82, v83
	global_store_dwordx4 v[80:81], v[72:75], off
	v_pk_add_f32 v[38:39], v[38:39], 0 op_sel_hi:[1,0]
	v_pk_add_f32 v[36:37], v[36:37], 0 op_sel_hi:[1,0]
	v_pk_add_f32 v[72:73], v[66:67], 0 op_sel_hi:[1,0]
	v_pk_add_f32 v[66:67], v[64:65], 0 op_sel_hi:[1,0]
	v_cvt_pk_bf16_f32 v64, v68, v69
	v_cvt_pk_bf16_f32 v65, v70, v71
	v_pk_add_f32 v[32:33], v[32:33], 0 op_sel_hi:[1,0]
	v_cvt_pk_bf16_f32 v66, v66, v67
	v_cvt_pk_bf16_f32 v67, v72, v73
	global_store_dwordx4 v[80:81], v[64:67], off offset:256
	v_pk_add_f32 v[22:23], v[22:23], 0 op_sel_hi:[1,0]
	v_pk_add_f32 v[20:21], v[20:21], 0 op_sel_hi:[1,0]
	v_pk_add_f32 v[66:67], v[58:59], 0 op_sel_hi:[1,0]
	v_pk_add_f32 v[58:59], v[56:57], 0 op_sel_hi:[1,0]
	v_cvt_pk_bf16_f32 v56, v60, v61
	v_add_co_u32_e32 v60, vcc, s47, v144
	v_cvt_pk_bf16_f32 v57, v62, v63
	v_cvt_pk_bf16_f32 v58, v58, v59
	v_cvt_pk_bf16_f32 v59, v66, v67
	v_lshl_add_u64 v[64:65], v[144:145], 0, s[0:1]
	s_nop 0
	v_addc_co_u32_e32 v61, vcc, 0, v145, vcc
	global_store_dwordx4 v[60:61], v[56:59], off
	v_pk_add_f32 v[16:17], v[16:17], 0 op_sel_hi:[1,0]
	s_mov_b32 s51, s14
	v_pk_add_f32 v[56:57], v[46:47], 0 op_sel_hi:[1,0]
	v_pk_add_f32 v[46:47], v[44:45], 0 op_sel_hi:[1,0]
	v_cvt_pk_bf16_f32 v44, v52, v53
	v_cvt_pk_bf16_f32 v45, v54, v55
	s_mov_b32 s22, s16
	v_cvt_pk_bf16_f32 v46, v46, v47
	v_cvt_pk_bf16_f32 v47, v56, v57
	global_store_dwordx4 v[64:65], v[44:47], off offset:256
	s_mov_b64 s[26:27], s[20:21]
	s_mov_b64 s[24:25], s[18:19]
	v_pk_add_f32 v[46:47], v[50:51], 0 op_sel_hi:[1,0]
	v_pk_add_f32 v[50:51], v[42:43], 0 op_sel_hi:[1,0]
	v_pk_add_f32 v[42:43], v[40:41], 0 op_sel_hi:[1,0]
	v_cvt_pk_bf16_f32 v40, v48, v49
	v_cvt_pk_bf16_f32 v41, v46, v47
	v_add_co_u32_e32 v46, vcc, s48, v144
	v_cvt_pk_bf16_f32 v42, v42, v43
	v_cvt_pk_bf16_f32 v43, v50, v51
	v_lshl_add_u64 v[44:45], v[144:145], 0, s[8:9]
	s_nop 0
	v_addc_co_u32_e32 v47, vcc, 0, v145, vcc
	global_store_dwordx4 v[46:47], v[40:43], off
	v_pk_add_f32 v[6:7], v[6:7], 0 op_sel_hi:[1,0]
	v_pk_add_f32 v[4:5], v[4:5], 0 op_sel_hi:[1,0]
	v_pk_add_f32 v[40:41], v[30:31], 0 op_sel_hi:[1,0]
	v_pk_add_f32 v[30:31], v[28:29], 0 op_sel_hi:[1,0]
	v_cvt_pk_bf16_f32 v28, v36, v37
	v_cvt_pk_bf16_f32 v29, v38, v39
	s_nop 0
	v_cvt_pk_bf16_f32 v30, v30, v31
	v_cvt_pk_bf16_f32 v31, v40, v41
	global_store_dwordx4 v[44:45], v[28:31], off offset:256
	s_nop 1
	v_pk_add_f32 v[30:31], v[34:35], 0 op_sel_hi:[1,0]
	v_pk_add_f32 v[34:35], v[26:27], 0 op_sel_hi:[1,0]
	v_pk_add_f32 v[26:27], v[24:25], 0 op_sel_hi:[1,0]
	v_cvt_pk_bf16_f32 v24, v32, v33
	v_cvt_pk_bf16_f32 v25, v30, v31
	v_add_co_u32_e32 v30, vcc, s49, v144
	v_cvt_pk_bf16_f32 v26, v26, v27
	v_cvt_pk_bf16_f32 v27, v34, v35
	v_lshl_add_u64 v[28:29], v[144:145], 0, s[10:11]
	s_nop 0
	v_addc_co_u32_e32 v31, vcc, 0, v145, vcc
	global_store_dwordx4 v[30:31], v[24:27], off
	s_nop 1
	v_pk_add_f32 v[24:25], v[14:15], 0 op_sel_hi:[1,0]
	v_pk_add_f32 v[14:15], v[12:13], 0 op_sel_hi:[1,0]
	v_cvt_pk_bf16_f32 v12, v20, v21
	v_cvt_pk_bf16_f32 v13, v22, v23
	s_nop 0
	v_cvt_pk_bf16_f32 v14, v14, v15
	v_cvt_pk_bf16_f32 v15, v24, v25
	global_store_dwordx4 v[28:29], v[12:15], off offset:256
	s_nop 1
	v_pk_add_f32 v[14:15], v[18:19], 0 op_sel_hi:[1,0]
	v_pk_add_f32 v[18:19], v[10:11], 0 op_sel_hi:[1,0]
	v_pk_add_f32 v[10:11], v[8:9], 0 op_sel_hi:[1,0]
	v_cvt_pk_bf16_f32 v8, v16, v17
	v_cvt_pk_bf16_f32 v9, v14, v15
	v_add_co_u32_e32 v14, vcc, s50, v144
	v_lshl_add_u64 v[12:13], v[144:145], 0, s[12:13]
	s_nop 0
	v_addc_co_u32_e32 v15, vcc, 0, v145, vcc
	v_cvt_pk_bf16_f32 v10, v10, v11
	v_cvt_pk_bf16_f32 v11, v18, v19
	global_store_dwordx4 v[14:15], v[8:11], off
	s_and_b64 vcc, exec, s[2:3]
	s_nop 0
	v_pk_add_f32 v[8:9], v[2:3], 0 op_sel_hi:[1,0]
	v_pk_add_f32 v[2:3], v[0:1], 0 op_sel_hi:[1,0]
	v_cvt_pk_bf16_f32 v0, v4, v5
	v_cvt_pk_bf16_f32 v1, v6, v7
	s_nop 0
	v_cvt_pk_bf16_f32 v2, v2, v3
	v_cvt_pk_bf16_f32 v3, v8, v9
	global_store_dwordx4 v[12:13], v[0:3], off offset:256
	s_cbranch_vccz .LBB0_1076
	s_waitcnt vmcnt(0)
	s_cmpk_gt_u32 s31, 0xff
	s_cbranch_scc1 .LBB0_1087
	s_barrier

; #define PG8_STAGE(bufoff, gbase, voff) do { _Pragma("unroll") for (int _i = 0; _i < 2; ++_i) \
;         __builtin_amdgcn_global_load_lds((const unsigned*)((const char*)(gbase) + (voff)[_i]), (PG8_LAS unsigned*)(lds + (bufoff) + ldsw + _i * 8192), 16, 0, 0); } while (0)
; #define PG8_LDA(dst, b, h) do { _Pragma("unroll") for (int m = 0; m < 4; ++m) _Pragma("unroll") for (int k = 0; k < 2; ++k) dst[m][k] = *(const PG8_LAS bf16x8*)(lds + PG8_SA(b, h) + aoff + m * 2048 + k * 1024); } while (0)
; #define PG8_LDB(dst, b, h) do { _Pragma("unroll") for (int n = 0; n < 2; ++n) _Pragma("unroll") for (int k = 0; k < 2; ++k) dst[n][k] = *(const PG8_LAS bf16x8*)(lds + PG8_SB(b, h) + boff + n * 2048 + k * 1024); } while (0)
; #define PG8_MMA(ai, bj, At, Bt) do { __builtin_amdgcn_s_setprio(1); _Pragma("unroll") for (int m = 0; m < 4; ++m) _Pragma("unroll") for (int n = 0; n < 2; ++n) _Pragma("unroll") for (int k = 0; k < 2; ++k) \
;         acc[ai][bj][m][n] = __builtin_amdgcn_mfma_f32_16x16x32_bf16(Bt[n][k], At[m][k], acc[ai][bj][m][n], 0, 0, 0); __builtin_amdgcn_s_setprio(0); } while (0)
; #define PG8_WAIT_L(n) asm volatile("s_waitcnt lgkmcnt(" #n ")" ::: "memory")
; #define PG8_BAR __builtin_amdgcn_s_barrier()
; #define PG8_SCHED __builtin_amdgcn_sched_barrier(0)
; template <class Epi, class Sched>
; __device__ __forceinline__ void gemm_phase(PG8_LAS unsigned char* lds, const Gemm g, const Sched& S, const Epi& E) {
;     ...
;             const bool last = (t == nt - 2);
;             const char* a1 = cA + (size_t)(t + 1) * kstep;
;             const char* a2 = last ? nA : cA + (size_t)(t + 2) * kstep; const char* b2 = last ? nB : cB + (size_t)(t + 2) * kstep;
;             const char* a3 = a2 + kstep; const char* b3 = b2 + kstep;
;             if (last && has_next) S.a_ready(nxt);
;             PG8_LDB(B0, 0, 0); PG8_SCHED; PG8_LDA(At, 0, 0); PG8_STAGE(PG8_SA(1, 1), a1 + hstep, voffA);
;             PG8_WAIT_L(8); PG8_BAR; PG8_WAIT_L(0); PG8_MMA(0, 0, At, B0); PG8_BAR; PG8_SCHED;
;             PG8_LDB(B1, 0, 1); PG8_STAGE(PG8_SB(0, 0), b2, voffB);
;             PG8_BAR; PG8_WAIT_L(0); PG8_MMA(0, 1, At, B1); PG8_BAR;
;             PG8_LDA(At, 0, 1); PG8_STAGE(PG8_SA(0, 0), a2, voffA);
;             PG8_BAR; PG8_WAIT_L(0); PG8_MMA(1, 0, At, B0); PG8_BAR; PG8_SCHED;
.LBB0_1202:
	s_add_u32 s18, s16, 0xfffc0080
	s_addc_u32 s19, s17, -1
	s_cmp_eq_u32 s46, 12
	s_cselect_b32 s21, s9, s19
	s_cselect_b32 s20, s42, s18
	s_cselect_b32 s19, s7, s45
	s_cselect_b32 s18, s43, s44
	v_lshl_add_u64 v[174:175], s[16:17], 0, v[136:137]
	s_add_i32 m0, s15, 0xc000
	s_nop 0
	global_load_lds_dwordx4 v[174:175], off
	v_lshl_add_u64 v[174:175], s[16:17], 0, v[138:139]
	s_add_i32 m0, s15, 0xe000
	s_nop 0
	global_load_lds_dwordx4 v[174:175], off
	ds_read_b128 v[144:147], v151
	ds_read_b128 v[154:157], v151 offset:1024
	ds_read_b128 v[158:161], v151 offset:2048
	ds_read_b128 v[162:165], v151 offset:3072
	ds_read_b128 v[166:169], v152
	ds_read_b128 v[170:173], v152 offset:1024
	ds_read_b128 v[182:185], v152 offset:2048
	ds_read_b128 v[190:193], v152 offset:3072
	ds_read_b128 v[194:197], v152 offset:4096
	ds_read_b128 v[198:201], v152 offset:5120
	ds_read_b128 v[202:205], v152 offset:6144
	ds_read_b128 v[206:209], v152 offset:7168
	s_waitcnt lgkmcnt(8)
	s_barrier
	s_waitcnt lgkmcnt(0)
	v_mfma_f32_16x16x32_bf16 v[124:127], v[144:147], v[166:169], v[124:127]
	v_mfma_f32_16x16x32_bf16 v[120:123], v[158:161], v[166:169], v[120:123]
	v_mfma_f32_16x16x32_bf16 v[108:111], v[144:147], v[182:185], v[108:111]
	v_mfma_f32_16x16x32_bf16 v[104:107], v[158:161], v[182:185], v[104:107]
	v_mfma_f32_16x16x32_bf16 v[92:95], v[144:147], v[194:197], v[92:95]
	v_mfma_f32_16x16x32_bf16 v[88:91], v[158:161], v[194:197], v[88:91]
	v_mfma_f32_16x16x32_bf16 v[76:79], v[144:147], v[202:205], v[76:79]
	v_mfma_f32_16x16x32_bf16 v[72:75], v[158:161], v[202:205], v[72:75]
	v_mfma_f32_16x16x32_bf16 v[124:127], v[154:157], v[170:173], v[124:127]
	v_mfma_f32_16x16x32_bf16 v[120:123], v[162:165], v[170:173], v[120:123]
	v_mfma_f32_16x16x32_bf16 v[108:111], v[154:157], v[190:193], v[108:111]
	v_mfma_f32_16x16x32_bf16 v[104:107], v[162:165], v[190:193], v[104:107]
	v_mfma_f32_16x16x32_bf16 v[92:95], v[154:157], v[198:201], v[92:95]
	v_mfma_f32_16x16x32_bf16 v[88:91], v[162:165], v[198:201], v[88:91]
	v_mfma_f32_16x16x32_bf16 v[76:79], v[154:157], v[206:209], v[76:79]
	v_mfma_f32_16x16x32_bf16 v[72:75], v[162:165], v[206:209], v[72:75]
	s_barrier
	s_add_i32 s47, s38, s26
	v_lshl_add_u64 v[174:175], s[18:19], 0, v[132:133]
	s_mov_b32 m0, s47
	s_nop 0
	global_load_lds_dwordx4 v[174:175], off
	v_lshl_add_u64 v[186:187], s[18:19], 0, v[128:129]
	s_add_i32 m0, s47, 0x2000
	s_nop 0
	global_load_lds_dwordx4 v[186:187], off
	ds_read_b128 v[210:213], v153
	ds_read_b128 v[214:217], v153 offset:1024
	ds_read_b128 v[218:221], v153 offset:2048
	ds_read_b128 v[222:225], v153 offset:3072
	s_barrier
	s_waitcnt lgkmcnt(0)
	v_mfma_f32_16x16x32_bf16 v[116:119], v[210:213], v[166:169], v[116:119]
	v_mfma_f32_16x16x32_bf16 v[112:115], v[218:221], v[166:169], v[112:115]
	v_mfma_f32_16x16x32_bf16 v[100:103], v[210:213], v[182:185], v[100:103]
	v_mfma_f32_16x16x32_bf16 v[96:99], v[218:221], v[182:185], v[96:99]
	v_mfma_f32_16x16x32_bf16 v[84:87], v[210:213], v[194:197], v[84:87]
	v_mfma_f32_16x16x32_bf16 v[80:83], v[218:221], v[194:197], v[80:83]
	v_mfma_f32_16x16x32_bf16 v[68:71], v[210:213], v[202:205], v[68:71]
	v_mfma_f32_16x16x32_bf16 v[64:67], v[218:221], v[202:205], v[64:67]
	v_mfma_f32_16x16x32_bf16 v[116:119], v[214:217], v[170:173], v[116:119]
	v_mfma_f32_16x16x32_bf16 v[112:115], v[222:225], v[170:173], v[112:115]
	v_mfma_f32_16x16x32_bf16 v[100:103], v[214:217], v[190:193], v[100:103]
	v_mfma_f32_16x16x32_bf16 v[96:99], v[222:225], v[190:193], v[96:99]
	v_mfma_f32_16x16x32_bf16 v[84:87], v[214:217], v[198:201], v[84:87]
	v_mfma_f32_16x16x32_bf16 v[80:83], v[222:225], v[198:201], v[80:83]
	v_mfma_f32_16x16x32_bf16 v[68:71], v[214:217], v[206:209], v[68:71]
	v_mfma_f32_16x16x32_bf16 v[64:67], v[222:225], v[206:209], v[64:67]
	s_mov_b32 m0, s15
	v_lshl_add_u64 v[226:227], s[20:21], 0, v[134:135]
	s_barrier
	global_load_lds_dwordx4 v[226:227], off
	v_lshl_add_u64 v[228:229], s[20:21], 0, v[130:131]
	s_mov_b32 m0, s29
	s_nop 0
	global_load_lds_dwordx4 v[228:229], off
	ds_read_b128 v[166:169], v152 offset:16384
	ds_read_b128 v[170:173], v152 offset:17408
	ds_read_b128 v[182:185], v152 offset:18432
	ds_read_b128 v[190:193], v152 offset:19456
	ds_read_b128 v[194:197], v152 offset:20480
	ds_read_b128 v[198:201], v152 offset:21504
	ds_read_b128 v[202:205], v152 offset:22528
	ds_read_b128 v[206:209], v152 offset:23552
	s_barrier
	s_waitcnt lgkmcnt(0)
	v_mfma_f32_16x16x32_bf16 v[60:63], v[144:147], v[166:169], v[60:63]
	v_mfma_f32_16x16x32_bf16 v[56:59], v[158:161], v[166:169], v[56:59]
	v_mfma_f32_16x16x32_bf16 v[44:47], v[144:147], v[182:185], v[44:47]
	v_mfma_f32_16x16x32_bf16 v[40:43], v[158:161], v[182:185], v[40:43]
	v_mfma_f32_16x16x32_bf16 v[28:31], v[144:147], v[194:197], v[28:31]
	v_mfma_f32_16x16x32_bf16 v[24:27], v[158:161], v[194:197], v[24:27]
	v_mfma_f32_16x16x32_bf16 v[12:15], v[144:147], v[202:205], v[12:15]
	v_mfma_f32_16x16x32_bf16 v[8:11], v[158:161], v[202:205], v[8:11]
	v_mfma_f32_16x16x32_bf16 v[60:63], v[154:157], v[170:173], v[60:63]
	v_mfma_f32_16x16x32_bf16 v[56:59], v[162:165], v[170:173], v[56:59]
	v_mfma_f32_16x16x32_bf16 v[44:47], v[154:157], v[190:193], v[44:47]
	v_mfma_f32_16x16x32_bf16 v[40:43], v[162:165], v[190:193], v[40:43]
	v_mfma_f32_16x16x32_bf16 v[28:31], v[154:157], v[198:201], v[28:31]
	v_mfma_f32_16x16x32_bf16 v[24:27], v[162:165], v[198:201], v[24:27]
	v_mfma_f32_16x16x32_bf16 v[12:15], v[154:157], v[206:209], v[12:15]
	v_mfma_f32_16x16x32_bf16 v[8:11], v[162:165], v[206:209], v[8:11]
	s_barrier
; #define PG8_STAGE(bufoff, gbase, voff) do { _Pragma("unroll") for (int _i = 0; _i < 2; ++_i) \
;         __builtin_amdgcn_global_load_lds((const unsigned*)((const char*)(gbase) + (voff)[_i]), (PG8_LAS unsigned*)(lds + (bufoff) + ldsw + _i * 8192), 16, 0, 0); } while (0)
; #define PG8_LDA(dst, b, h) do { _Pragma("unroll") for (int m = 0; m < 4; ++m) _Pragma("unroll") for (int k = 0; k < 2; ++k) dst[m][k] = *(const PG8_LAS bf16x8*)(lds + PG8_SA(b, h) + aoff + m * 2048 + k * 1024); } while (0)
; #define PG8_LDB(dst, b, h) do { _Pragma("unroll") for (int n = 0; n < 2; ++n) _Pragma("unroll") for (int k = 0; k < 2; ++k) dst[n][k] = *(const PG8_LAS bf16x8*)(lds + PG8_SB(b, h) + boff + n * 2048 + k * 1024); } while (0)
; #define PG8_MMA(ai, bj, At, Bt) do { __builtin_amdgcn_s_setprio(1); _Pragma("unroll") for (int m = 0; m < 4; ++m) _Pragma("unroll") for (int n = 0; n < 2; ++n) _Pragma("unroll") for (int k = 0; k < 2; ++k) \
;         acc[ai][bj][m][n] = __builtin_amdgcn_mfma_f32_16x16x32_bf16(Bt[n][k], At[m][k], acc[ai][bj][m][n], 0, 0, 0); __builtin_amdgcn_s_setprio(0); } while (0)
; #define PG8_WAIT_V(n) asm volatile("s_waitcnt vmcnt(" #n ")" ::: "memory")
; #define PG8_WAIT_L(n) asm volatile("s_waitcnt lgkmcnt(" #n ")" ::: "memory")
; #define PG8_BAR __builtin_amdgcn_s_barrier()
; #define PG8_SCHED __builtin_amdgcn_sched_barrier(0)
; template <class Epi, class Sched>
; __device__ __forceinline__ void gemm_phase(PG8_LAS unsigned char* lds, const Gemm g, const Sched& S, const Epi& E) {
;     ...
;             PG8_STAGE(PG8_SB(0, 1), b2 + hstep, voffB);
;             PG8_WAIT_V(6); PG8_BAR; PG8_MMA(1, 1, At, B1); PG8_BAR;
;             PG8_LDB(B0, 1, 0); PG8_SCHED; PG8_LDA(At, 1, 0); PG8_STAGE(PG8_SA(0, 1), a2 + hstep, voffA);
;             PG8_WAIT_L(8); PG8_BAR; PG8_WAIT_L(0); PG8_MMA(0, 0, At, B0); PG8_BAR; PG8_SCHED;
;             PG8_LDB(B1, 1, 1); PG8_STAGE(PG8_SB(1, 0), b3, voffB);
;             PG8_BAR; PG8_WAIT_L(0); PG8_MMA(0, 1, At, B1); PG8_BAR;
;             PG8_LDA(At, 1, 1); PG8_STAGE(PG8_SA(1, 0), a3, voffA);
	s_add_u32 s48, s18, 0x40000
	s_addc_u32 s49, s19, 0
	s_add_i32 s47, s39, s26
	v_lshl_add_u64 v[144:145], s[48:49], 0, v[132:133]
	s_mov_b32 m0, s47
	s_nop 0
	global_load_lds_dwordx4 v[144:145], off
	v_lshl_add_u64 v[144:145], s[48:49], 0, v[128:129]
	s_add_i32 m0, s47, 0x2000
	s_nop 0
	global_load_lds_dwordx4 v[144:145], off
	s_waitcnt vmcnt(6)
	s_barrier
	v_mfma_f32_16x16x32_bf16 v[52:55], v[210:213], v[166:169], v[52:55]
	v_mfma_f32_16x16x32_bf16 v[48:51], v[218:221], v[166:169], v[48:51]
	v_mfma_f32_16x16x32_bf16 v[36:39], v[210:213], v[182:185], v[36:39]
	v_mfma_f32_16x16x32_bf16 v[32:35], v[218:221], v[182:185], v[32:35]
	v_mfma_f32_16x16x32_bf16 v[20:23], v[210:213], v[194:197], v[20:23]
	v_mfma_f32_16x16x32_bf16 v[16:19], v[218:221], v[194:197], v[16:19]
	v_mfma_f32_16x16x32_bf16 v[4:7], v[210:213], v[202:205], v[4:7]
	v_mfma_f32_16x16x32_bf16 v[0:3], v[218:221], v[202:205], v[0:3]
	v_mfma_f32_16x16x32_bf16 v[52:55], v[214:217], v[170:173], v[52:55]
	v_mfma_f32_16x16x32_bf16 v[48:51], v[222:225], v[170:173], v[48:51]
	v_mfma_f32_16x16x32_bf16 v[36:39], v[214:217], v[190:193], v[36:39]
	v_mfma_f32_16x16x32_bf16 v[32:35], v[222:225], v[190:193], v[32:35]
	v_mfma_f32_16x16x32_bf16 v[20:23], v[214:217], v[198:201], v[20:23]
	v_mfma_f32_16x16x32_bf16 v[16:19], v[222:225], v[198:201], v[16:19]
	v_mfma_f32_16x16x32_bf16 v[4:7], v[214:217], v[206:209], v[4:7]
	v_mfma_f32_16x16x32_bf16 v[0:3], v[222:225], v[206:209], v[0:3]
	s_add_i32 s47, 0, 0x18000
	v_add_u32_e32 v162, s47, v149
	s_barrier
	s_add_u32 s20, s20, 0x40000
	s_addc_u32 s21, s21, 0
	s_mov_b32 m0, s30
	v_lshl_add_u64 v[210:211], s[20:21], 0, v[134:135]
	global_load_lds_dwordx4 v[210:211], off
	v_lshl_add_u64 v[210:211], s[20:21], 0, v[130:131]
	s_mov_b32 m0, s31
	s_nop 0
	global_load_lds_dwordx4 v[210:211], off
	ds_read_b128 v[144:147], v162
	ds_read_b128 v[154:157], v162 offset:1024
	ds_read_b128 v[158:161], v162 offset:2048
	ds_read_b128 v[162:165], v162 offset:3072
	ds_read_b128 v[166:169], v152 offset:32768
	ds_read_b128 v[170:173], v152 offset:33792
	ds_read_b128 v[182:185], v152 offset:34816
	ds_read_b128 v[190:193], v152 offset:35840
	ds_read_b128 v[194:197], v152 offset:36864
	ds_read_b128 v[198:201], v152 offset:37888
	ds_read_b128 v[202:205], v152 offset:38912
	ds_read_b128 v[206:209], v152 offset:39936
	s_waitcnt lgkmcnt(8)
	s_barrier
	s_waitcnt lgkmcnt(0)
	v_mfma_f32_16x16x32_bf16 v[124:127], v[144:147], v[166:169], v[124:127]
	v_mfma_f32_16x16x32_bf16 v[120:123], v[158:161], v[166:169], v[120:123]
	v_mfma_f32_16x16x32_bf16 v[108:111], v[144:147], v[182:185], v[108:111]
	v_mfma_f32_16x16x32_bf16 v[104:107], v[158:161], v[182:185], v[104:107]
	v_mfma_f32_16x16x32_bf16 v[92:95], v[144:147], v[194:197], v[92:95]
	v_mfma_f32_16x16x32_bf16 v[88:91], v[158:161], v[194:197], v[88:91]
	v_mfma_f32_16x16x32_bf16 v[76:79], v[144:147], v[202:205], v[76:79]
	v_mfma_f32_16x16x32_bf16 v[72:75], v[158:161], v[202:205], v[72:75]
	v_mfma_f32_16x16x32_bf16 v[124:127], v[154:157], v[170:173], v[124:127]
	v_mfma_f32_16x16x32_bf16 v[120:123], v[162:165], v[170:173], v[120:123]
	v_mfma_f32_16x16x32_bf16 v[108:111], v[154:157], v[190:193], v[108:111]
	v_mfma_f32_16x16x32_bf16 v[104:107], v[162:165], v[190:193], v[104:107]
	v_mfma_f32_16x16x32_bf16 v[92:95], v[154:157], v[198:201], v[92:95]
	v_mfma_f32_16x16x32_bf16 v[88:91], v[162:165], v[198:201], v[88:91]
	v_mfma_f32_16x16x32_bf16 v[76:79], v[154:157], v[206:209], v[76:79]
	v_mfma_f32_16x16x32_bf16 v[72:75], v[162:165], v[206:209], v[72:75]
	s_barrier
	s_add_i32 s20, 0, 0x1c000
	s_add_i32 s21, s47, s26
	v_add_u32_e32 v179, s20, v149
	v_lshl_add_u64 v[174:175], v[174:175], 0, s[4:5]
	s_mov_b32 m0, s21
	s_nop 0
	global_load_lds_dwordx4 v[174:175], off
	v_lshl_add_u64 v[174:175], v[186:187], 0, s[4:5]
	s_add_i32 m0, s21, 0x2000
	s_nop 0
	global_load_lds_dwordx4 v[174:175], off
	ds_read_b128 v[210:213], v179
	ds_read_b128 v[214:217], v179 offset:1024
	ds_read_b128 v[218:221], v179 offset:2048
	ds_read_b128 v[222:225], v179 offset:3072
	s_barrier
	s_waitcnt lgkmcnt(0)
	v_mfma_f32_16x16x32_bf16 v[116:119], v[210:213], v[166:169], v[116:119]
	v_mfma_f32_16x16x32_bf16 v[112:115], v[218:221], v[166:169], v[112:115]
	v_mfma_f32_16x16x32_bf16 v[100:103], v[210:213], v[182:185], v[100:103]
	v_mfma_f32_16x16x32_bf16 v[96:99], v[218:221], v[182:185], v[96:99]
	v_mfma_f32_16x16x32_bf16 v[84:87], v[210:213], v[194:197], v[84:87]
	v_mfma_f32_16x16x32_bf16 v[80:83], v[218:221], v[194:197], v[80:83]
	v_mfma_f32_16x16x32_bf16 v[68:71], v[210:213], v[202:205], v[68:71]
	v_mfma_f32_16x16x32_bf16 v[64:67], v[218:221], v[202:205], v[64:67]
	v_mfma_f32_16x16x32_bf16 v[116:119], v[214:217], v[170:173], v[116:119]
	v_mfma_f32_16x16x32_bf16 v[112:115], v[222:225], v[170:173], v[112:115]
	v_mfma_f32_16x16x32_bf16 v[100:103], v[214:217], v[190:193], v[100:103]
	v_mfma_f32_16x16x32_bf16 v[96:99], v[222:225], v[190:193], v[96:99]
	v_mfma_f32_16x16x32_bf16 v[84:87], v[214:217], v[198:201], v[84:87]
	v_mfma_f32_16x16x32_bf16 v[80:83], v[222:225], v[198:201], v[80:83]
	v_mfma_f32_16x16x32_bf16 v[68:71], v[214:217], v[206:209], v[68:71]
	v_mfma_f32_16x16x32_bf16 v[64:67], v[222:225], v[206:209], v[64:67]
	s_mov_b32 m0, s35
	v_lshl_add_u64 v[174:175], v[226:227], 0, s[4:5]
	s_barrier
	global_load_lds_dwordx4 v[174:175], off
	v_lshl_add_u64 v[174:175], v[228:229], 0, s[4:5]
	s_mov_b32 m0, s36
	s_nop 0
	global_load_lds_dwordx4 v[174:175], off
	ds_read_b128 v[166:169], v152 offset:49152
	ds_read_b128 v[170:173], v152 offset:50176
	ds_read_b128 v[182:185], v152 offset:51200
	ds_read_b128 v[190:193], v152 offset:52224
	ds_read_b128 v[194:197], v152 offset:53248
	ds_read_b128 v[198:201], v152 offset:54272
	ds_read_b128 v[202:205], v152 offset:55296
	ds_read_b128 v[206:209], v152 offset:56320
	s_barrier
; __device__ __forceinline__ unsigned cvt_pk_bf16(float lo, float hi) { unsigned r; asm volatile("v_cvt_pk_bf16_f32 %0, %1, %2" : "=v"(r) : "v"(lo), "v"(hi)); return r; }
; #define PG8_STAGE(bufoff, gbase, voff) do { _Pragma("unroll") for (int _i = 0; _i < 2; ++_i) \
;         __builtin_amdgcn_global_load_lds((const unsigned*)((const char*)(gbase) + (voff)[_i]), (PG8_LAS unsigned*)(lds + (bufoff) + ldsw + _i * 8192), 16, 0, 0); } while (0)
; #define PG8_MMA(ai, bj, At, Bt) do { __builtin_amdgcn_s_setprio(1); _Pragma("unroll") for (int m = 0; m < 4; ++m) _Pragma("unroll") for (int n = 0; n < 2; ++n) _Pragma("unroll") for (int k = 0; k < 2; ++k) \
;         acc[ai][bj][m][n] = __builtin_amdgcn_mfma_f32_16x16x32_bf16(Bt[n][k], At[m][k], acc[ai][bj][m][n], 0, 0, 0); __builtin_amdgcn_s_setprio(0); } while (0)
; #define PG8_WAIT_V(n) asm volatile("s_waitcnt vmcnt(" #n ")" ::: "memory")
; #define PG8_WAIT_L(n) asm volatile("s_waitcnt lgkmcnt(" #n ")" ::: "memory")
; #define PG8_BAR __builtin_amdgcn_s_barrier()
; #define PG8_SCHED __builtin_amdgcn_sched_barrier(0)
;     __device__ __forceinline__ void operator()(const f32x4 (&acc)[2][2][4][2], const Unit& u, int wr, int wc, int fr, int fq) const {
;         const int row0 = u.pm * BM + wr * 64 + fr, col0 = u.pn * HALF + wc * 32 + 8 * fq;
; #pragma unroll
;         for (int ai = 0; ai < 2; ++ai)
; #pragma unroll
;             for (int m = 0; m < 4; ++m) { bf16_t* rowp = O + (size_t)(row0 + ai * HALF + m * 16) * ldc + col0;
;                 f32x4 v0, v1;
; #pragma unroll
;                 for (int j = 0; j < 1; ++j) { v0 = acc[ai][0][m][0] * sigmoid4(acc[ai][0][m][0]) * acc[ai][1][m][0]; v1 = acc[ai][0][m][1] * sigmoid4(acc[ai][0][m][1]) * acc[ai][1][m][1]; }
;                 u32x4 w; w.x = cvt_pk_bf16(v0[0], v0[1]); w.y = cvt_pk_bf16(v0[2], v0[3]); w.z = cvt_pk_bf16(v1[0], v1[1]); w.w = cvt_pk_bf16(v1[2], v1[3]);
;                 *(u32x4*)rowp = w; }
; template <class Epi, class Sched>
; __device__ __forceinline__ void gemm_phase(PG8_LAS unsigned char* lds, const Gemm g, const Sched& S, const Epi& E) {
;     ...
;             PG8_BAR; PG8_WAIT_L(0); PG8_MMA(1, 0, At, B0); PG8_BAR; PG8_SCHED;
;             PG8_STAGE(PG8_SB(1, 1), b3 + hstep, voffB);
;             PG8_WAIT_V(6); PG8_BAR; PG8_MMA(1, 1, At, B1); PG8_BAR;
	s_waitcnt lgkmcnt(0)
	v_mfma_f32_16x16x32_bf16 v[60:63], v[144:147], v[166:169], v[60:63]
	v_mfma_f32_16x16x32_bf16 v[56:59], v[158:161], v[166:169], v[56:59]
	v_mfma_f32_16x16x32_bf16 v[44:47], v[144:147], v[182:185], v[44:47]
	v_mfma_f32_16x16x32_bf16 v[40:43], v[158:161], v[182:185], v[40:43]
	v_mfma_f32_16x16x32_bf16 v[28:31], v[144:147], v[194:197], v[28:31]
	v_mfma_f32_16x16x32_bf16 v[24:27], v[158:161], v[194:197], v[24:27]
	v_mfma_f32_16x16x32_bf16 v[12:15], v[144:147], v[202:205], v[12:15]
	v_mfma_f32_16x16x32_bf16 v[8:11], v[158:161], v[202:205], v[8:11]
	v_mfma_f32_16x16x32_bf16 v[60:63], v[154:157], v[170:173], v[60:63]
	v_mfma_f32_16x16x32_bf16 v[56:59], v[162:165], v[170:173], v[56:59]
	v_mfma_f32_16x16x32_bf16 v[44:47], v[154:157], v[190:193], v[44:47]
	v_mfma_f32_16x16x32_bf16 v[40:43], v[162:165], v[190:193], v[40:43]
	v_mfma_f32_16x16x32_bf16 v[28:31], v[154:157], v[198:201], v[28:31]
	v_mfma_f32_16x16x32_bf16 v[24:27], v[162:165], v[198:201], v[24:27]
	v_mfma_f32_16x16x32_bf16 v[12:15], v[154:157], v[206:209], v[12:15]
	v_mfma_f32_16x16x32_bf16 v[8:11], v[162:165], v[206:209], v[8:11]
	s_barrier
	s_add_u32 s18, s18, 0x40080
	s_addc_u32 s19, s19, 0
	s_add_i32 s20, s20, s26
	v_lshl_add_u64 v[144:145], s[18:19], 0, v[132:133]
	s_mov_b32 m0, s20
	s_nop 0
	global_load_lds_dwordx4 v[144:145], off
	v_lshl_add_u64 v[144:145], s[18:19], 0, v[128:129]
	s_add_i32 m0, s20, 0x2000
	s_nop 0
	global_load_lds_dwordx4 v[144:145], off
	s_waitcnt vmcnt(6)
	s_barrier
	v_mfma_f32_16x16x32_bf16 v[52:55], v[210:213], v[166:169], v[52:55]
	v_mfma_f32_16x16x32_bf16 v[48:51], v[218:221], v[166:169], v[48:51]
	v_mfma_f32_16x16x32_bf16 v[36:39], v[210:213], v[182:185], v[36:39]
	v_mfma_f32_16x16x32_bf16 v[32:35], v[218:221], v[182:185], v[32:35]
	v_mfma_f32_16x16x32_bf16 v[20:23], v[210:213], v[194:197], v[20:23]
	v_mfma_f32_16x16x32_bf16 v[16:19], v[218:221], v[194:197], v[16:19]
	v_mfma_f32_16x16x32_bf16 v[4:7], v[210:213], v[202:205], v[4:7]
	v_mfma_f32_16x16x32_bf16 v[0:3], v[218:221], v[202:205], v[0:3]
	v_mfma_f32_16x16x32_bf16 v[52:55], v[214:217], v[170:173], v[52:55]
	v_mfma_f32_16x16x32_bf16 v[48:51], v[222:225], v[170:173], v[48:51]
	v_mfma_f32_16x16x32_bf16 v[36:39], v[214:217], v[190:193], v[36:39]
	v_mfma_f32_16x16x32_bf16 v[32:35], v[222:225], v[190:193], v[32:35]
	v_mfma_f32_16x16x32_bf16 v[20:23], v[214:217], v[198:201], v[20:23]
	v_mfma_f32_16x16x32_bf16 v[16:19], v[222:225], v[198:201], v[16:19]
	v_mfma_f32_16x16x32_bf16 v[4:7], v[214:217], v[206:209], v[4:7]
	v_mfma_f32_16x16x32_bf16 v[0:3], v[222:225], v[206:209], v[0:3]
	s_add_i32 s46, s46, 2
	s_add_u32 s16, s16, 0x100
	s_addc_u32 s17, s17, 0
	s_add_u32 s44, s44, 0x100
	s_addc_u32 s45, s45, 0
	s_cmp_gt_u32 s46, 13
	s_barrier
	s_cbranch_scc0 .LBB0_1202
	v_max_f32_e32 v144, v124, v124
	v_max_f32_e32 v144, 0xc1a00000, v144
	v_mul_f32_e32 v144, 0xbfb8aa3b, v144
	v_exp_f32_e32 v157, v144
	v_max_f32_e32 v144, v125, v125
	v_max_f32_e32 v144, 0xc1a00000, v144
	v_mul_f32_e32 v144, 0xbfb8aa3b, v144
	v_exp_f32_e32 v156, v144
	v_max_f32_e32 v144, v126, v126
	v_max_f32_e32 v144, 0xc1a00000, v144
	v_mul_f32_e32 v144, 0xbfb8aa3b, v144
	v_exp_f32_e32 v159, v144
	v_max_f32_e32 v144, v127, v127
	v_max_f32_e32 v144, 0xc1a00000, v144
	v_mul_f32_e32 v144, 0xbfb8aa3b, v144
	v_exp_f32_e32 v158, v144
	v_pk_add_f32 v[156:157], v[156:157], 1.0 op_sel_hi:[1,0]
	v_lshl_or_b32 v146, s41, 7, v150
	v_mov_b32_e32 v160, v157
	v_pk_add_f32 v[158:159], v[158:159], 1.0 op_sel_hi:[1,0]
	v_mov_b32_e32 v162, v156
	v_mov_b32_e32 v161, v159
	v_mov_b32_e32 v163, v158
	v_pk_mul_f32 v[160:161], v[160:161], v[162:163]
	v_lshl_add_u32 v154, s14, 8, v148
	v_mul_f32_e32 v155, v160, v161
	v_rcp_f32_e32 v155, v155
	v_ashrrev_i32_e32 v147, 31, v146
	v_mov_b64_e32 v[144:145], s[0:1]
	v_mad_i64_i32 v[162:163], s[16:17], v154, s40, v[144:145]
	v_mul_f32_e32 v164, v161, v155
	v_mul_f32_e32 v160, v160, v155
	v_max_f32_e32 v155, v120, v120
	v_max_f32_e32 v155, 0xc1a00000, v155
	v_mul_f32_e32 v155, 0xbfb8aa3b, v155
	v_pk_mul_f32 v[158:159], v[158:159], v[160:161] op_sel_hi:[1,0]
	v_exp_f32_e32 v161, v155
	v_max_f32_e32 v155, v121, v121
	v_max_f32_e32 v155, 0xc1a00000, v155
	v_mul_f32_e32 v155, 0xbfb8aa3b, v155
	v_exp_f32_e32 v160, v155
	v_max_f32_e32 v155, v122, v122
	v_max_f32_e32 v155, 0xc1a00000, v155
	v_mul_f32_e32 v155, 0xbfb8aa3b, v155
	v_exp_f32_e32 v167, v155
	v_max_f32_e32 v155, v123, v123
	v_max_f32_e32 v155, 0xc1a00000, v155
	v_mul_f32_e32 v155, 0xbfb8aa3b, v155
	v_exp_f32_e32 v166, v155
	v_pk_mul_f32 v[156:157], v[156:157], v[164:165] op_sel_hi:[1,0]
	v_pk_mul_f32 v[126:127], v[126:127], v[158:159]
	v_pk_mul_f32 v[124:125], v[124:125], v[156:157]
	v_pk_add_f32 v[156:157], v[160:161], 1.0 op_sel_hi:[1,0]
	v_pk_add_f32 v[160:161], v[166:167], 1.0 op_sel_hi:[1,0]
	v_mov_b32_e32 v164, v157
	v_mov_b32_e32 v165, v161
	v_mov_b32_e32 v166, v156
	v_mov_b32_e32 v167, v160
	v_pk_mul_f32 v[164:165], v[164:165], v[166:167]
	v_pk_mul_f32 v[118:119], v[126:127], v[118:119]
	v_mul_f32_e32 v155, v164, v165
	v_rcp_f32_e32 v155, v155
	v_pk_mul_f32 v[116:117], v[124:125], v[116:117]
	v_lshlrev_b64 v[146:147], 1, v[146:147]
	v_lshl_add_u64 v[162:163], v[162:163], 0, v[146:147]
	v_mul_f32_e32 v124, v165, v155
	v_mul_f32_e32 v126, v164, v155
	v_pk_mul_f32 v[126:127], v[160:161], v[126:127] op_sel_hi:[1,0]
	v_pk_mul_f32 v[124:125], v[156:157], v[124:125] op_sel_hi:[1,0]
	v_pk_mul_f32 v[122:123], v[122:123], v[126:127]
	v_pk_mul_f32 v[120:121], v[120:121], v[124:125]
	v_pk_mul_f32 v[122:123], v[122:123], v[114:115]
	v_pk_mul_f32 v[114:115], v[120:121], v[112:113]
	v_cvt_pk_bf16_f32 v112, v116, v117
	v_cvt_pk_bf16_f32 v113, v118, v119
; __device__ __forceinline__ unsigned cvt_pk_bf16(float lo, float hi) { unsigned r; asm volatile("v_cvt_pk_bf16_f32 %0, %1, %2" : "=v"(r) : "v"(lo), "v"(hi)); return r; }
; __device__ __forceinline__ f32x4 sigmoid4(f32x4 x) {
;     f32x4 d;
; #pragma unroll
;     for (int j = 0; j < 4; ++j) d[j] = 1.0f + __expf(-fmaxf(x[j], -20.0f));
;     const float p01 = d[0] * d[1], p23 = d[2] * d[3], r = __builtin_amdgcn_rcpf(p01 * p23), r01 = r * p23, r23 = r * p01;
;     return (f32x4){r01 * d[1], r01 * d[0], r23 * d[3], r23 * d[2]};
; }
;     __device__ __forceinline__ void operator()(const f32x4 (&acc)[2][2][4][2], const Unit& u, int wr, int wc, int fr, int fq) const {
;     ...
;         for (int ai = 0; ai < 2; ++ai)
; #pragma unroll
;             for (int m = 0; m < 4; ++m) { bf16_t* rowp = O + (size_t)(row0 + ai * HALF + m * 16) * ldc + col0;
;                 f32x4 v0, v1;
; #pragma unroll
;                 for (int j = 0; j < 1; ++j) { v0 = acc[ai][0][m][0] * sigmoid4(acc[ai][0][m][0]) * acc[ai][1][m][0]; v1 = acc[ai][0][m][1] * sigmoid4(acc[ai][0][m][1]) * acc[ai][1][m][1]; }
;                 u32x4 w; w.x = cvt_pk_bf16(v0[0], v0[1]); w.y = cvt_pk_bf16(v0[2], v0[3]); w.z = cvt_pk_bf16(v1[0], v1[1]); w.w = cvt_pk_bf16(v1[2], v1[3]);
;                 *(u32x4*)rowp = w; }
	v_max_f32_e32 v116, v108, v108
	v_max_f32_e32 v118, v110, v110
	v_max_f32_e32 v116, 0xc1a00000, v116
	v_max_f32_e32 v118, 0xc1a00000, v118
	v_mul_f32_e32 v116, 0xbfb8aa3b, v116
	v_mul_f32_e32 v118, 0xbfb8aa3b, v118
	v_exp_f32_e32 v117, v116
	v_max_f32_e32 v116, v109, v109
	v_exp_f32_e32 v119, v118
	v_max_f32_e32 v118, v111, v111
	v_max_f32_e32 v116, 0xc1a00000, v116
	v_max_f32_e32 v118, 0xc1a00000, v118
	v_mul_f32_e32 v116, 0xbfb8aa3b, v116
	v_mul_f32_e32 v118, 0xbfb8aa3b, v118
	v_exp_f32_e32 v116, v116
	v_exp_f32_e32 v118, v118
	v_cvt_pk_bf16_f32 v114, v114, v115
	v_cvt_pk_bf16_f32 v115, v122, v123
	global_store_dwordx4 v[162:163], v[112:115], off
	v_or_b32_e32 v120, 16, v154
	s_and_b64 vcc, exec, s[2:3]
	v_pk_add_f32 v[112:113], v[116:117], 1.0 op_sel_hi:[1,0]
	v_pk_add_f32 v[114:115], v[118:119], 1.0 op_sel_hi:[1,0]
	v_mov_b32_e32 v116, v113
	v_mov_b32_e32 v117, v115
	v_mov_b32_e32 v118, v112
	v_mov_b32_e32 v119, v114
	v_pk_mul_f32 v[116:117], v[116:117], v[118:119]
	s_mov_b32 s41, s6
	v_mul_f32_e32 v118, v116, v117
	v_rcp_f32_e32 v121, v118
	v_mad_i64_i32 v[118:119], s[16:17], v120, s40, v[144:145]
	v_lshl_add_u64 v[118:119], v[118:119], 0, v[146:147]
	v_mul_f32_e32 v116, v116, v121
	v_mul_f32_e32 v120, v117, v121
	v_pk_mul_f32 v[114:115], v[114:115], v[116:117] op_sel_hi:[1,0]
	v_max_f32_e32 v116, v104, v104
	v_max_f32_e32 v121, v106, v106
	v_max_f32_e32 v116, 0xc1a00000, v116
	v_max_f32_e32 v121, 0xc1a00000, v121
	v_mul_f32_e32 v116, 0xbfb8aa3b, v116
	v_mul_f32_e32 v121, 0xbfb8aa3b, v121
	v_exp_f32_e32 v117, v116
	v_max_f32_e32 v116, v105, v105
	v_exp_f32_e32 v123, v121
	v_max_f32_e32 v121, v107, v107
	v_max_f32_e32 v116, 0xc1a00000, v116
	v_max_f32_e32 v121, 0xc1a00000, v121
	v_mul_f32_e32 v116, 0xbfb8aa3b, v116
	v_mul_f32_e32 v121, 0xbfb8aa3b, v121
	v_exp_f32_e32 v116, v116
	v_exp_f32_e32 v122, v121
	v_pk_mul_f32 v[112:113], v[112:113], v[120:121] op_sel_hi:[1,0]
	v_pk_mul_f32 v[110:111], v[110:111], v[114:115]
	v_pk_mul_f32 v[108:109], v[108:109], v[112:113]
	v_pk_add_f32 v[112:113], v[116:117], 1.0 op_sel_hi:[1,0]
	v_pk_add_f32 v[116:117], v[122:123], 1.0 op_sel_hi:[1,0]
	v_mov_b32_e32 v120, v113
	v_mov_b32_e32 v121, v117
	v_mov_b32_e32 v122, v112
	v_mov_b32_e32 v123, v116
	v_pk_mul_f32 v[120:121], v[120:121], v[122:123]
	v_pk_mul_f32 v[102:103], v[110:111], v[102:103]
	v_mul_f32_e32 v122, v120, v121
	v_rcp_f32_e32 v122, v122
	v_pk_mul_f32 v[100:101], v[108:109], v[100:101]
	s_mov_b32 s14, s8
	s_mov_b64 s[18:19], s[12:13]
	v_mul_f32_e32 v108, v121, v122
	v_mul_f32_e32 v110, v120, v122
	v_pk_mul_f32 v[110:111], v[116:117], v[110:111] op_sel_hi:[1,0]
	v_pk_mul_f32 v[108:109], v[112:113], v[108:109] op_sel_hi:[1,0]
	v_pk_mul_f32 v[106:107], v[106:107], v[110:111]
	v_pk_mul_f32 v[104:105], v[104:105], v[108:109]
	v_pk_mul_f32 v[106:107], v[106:107], v[98:99]
	v_pk_mul_f32 v[98:99], v[104:105], v[96:97]
	v_cvt_pk_bf16_f32 v96, v100, v101
	v_cvt_pk_bf16_f32 v97, v102, v103
	v_max_f32_e32 v100, v92, v92
	v_max_f32_e32 v102, v94, v94
	v_max_f32_e32 v100, 0xc1a00000, v100
	v_max_f32_e32 v102, 0xc1a00000, v102
	v_mul_f32_e32 v100, 0xbfb8aa3b, v100
	v_mul_f32_e32 v102, 0xbfb8aa3b, v102
	v_exp_f32_e32 v101, v100
	v_max_f32_e32 v100, v93, v93
	v_exp_f32_e32 v103, v102
	v_max_f32_e32 v102, v95, v95
	v_max_f32_e32 v100, 0xc1a00000, v100
	v_max_f32_e32 v102, 0xc1a00000, v102
	v_mul_f32_e32 v100, 0xbfb8aa3b, v100
	v_mul_f32_e32 v102, 0xbfb8aa3b, v102
	v_exp_f32_e32 v100, v100
	v_exp_f32_e32 v102, v102
	v_cvt_pk_bf16_f32 v98, v98, v99
	v_cvt_pk_bf16_f32 v99, v106, v107
	global_store_dwordx4 v[118:119], v[96:99], off
	v_or_b32_e32 v104, 32, v154
	s_nop 0
	v_pk_add_f32 v[96:97], v[100:101], 1.0 op_sel_hi:[1,0]
	v_pk_add_f32 v[98:99], v[102:103], 1.0 op_sel_hi:[1,0]
	v_mov_b32_e32 v100, v97
	v_mov_b32_e32 v101, v99
	v_mov_b32_e32 v102, v96
	v_mov_b32_e32 v103, v98
	v_pk_mul_f32 v[100:101], v[100:101], v[102:103]
	s_nop 0
	v_mul_f32_e32 v102, v100, v101
	v_rcp_f32_e32 v105, v102
	v_mad_i64_i32 v[102:103], s[16:17], v104, s40, v[144:145]
	v_lshl_add_u64 v[102:103], v[102:103], 0, v[146:147]
	v_mul_f32_e32 v100, v100, v105
	v_mul_f32_e32 v104, v101, v105
	v_pk_mul_f32 v[98:99], v[98:99], v[100:101] op_sel_hi:[1,0]
	v_max_f32_e32 v100, v88, v88
	v_max_f32_e32 v105, v90, v90
	v_max_f32_e32 v100, 0xc1a00000, v100
	v_max_f32_e32 v105, 0xc1a00000, v105
	v_mul_f32_e32 v100, 0xbfb8aa3b, v100
	v_mul_f32_e32 v105, 0xbfb8aa3b, v105
	v_exp_f32_e32 v101, v100
	v_max_f32_e32 v100, v89, v89
	v_exp_f32_e32 v107, v105
	v_max_f32_e32 v105, v91, v91
	v_max_f32_e32 v100, 0xc1a00000, v100
	v_max_f32_e32 v105, 0xc1a00000, v105
	v_mul_f32_e32 v100, 0xbfb8aa3b, v100
	v_mul_f32_e32 v105, 0xbfb8aa3b, v105
	v_exp_f32_e32 v100, v100
	v_exp_f32_e32 v106, v105
	v_pk_mul_f32 v[96:97], v[96:97], v[104:105] op_sel_hi:[1,0]
	v_pk_mul_f32 v[94:95], v[94:95], v[98:99]
	v_pk_mul_f32 v[92:93], v[92:93], v[96:97]
	v_pk_add_f32 v[96:97], v[100:101], 1.0 op_sel_hi:[1,0]
	v_pk_add_f32 v[100:101], v[106:107], 1.0 op_sel_hi:[1,0]
	v_mov_b32_e32 v104, v97
	v_mov_b32_e32 v105, v101
	v_mov_b32_e32 v106, v96
	v_mov_b32_e32 v107, v100
	v_pk_mul_f32 v[104:105], v[104:105], v[106:107]
	v_pk_mul_f32 v[86:87], v[94:95], v[86:87]
	v_mul_f32_e32 v106, v104, v105
	v_rcp_f32_e32 v106, v106
	v_pk_mul_f32 v[84:85], v[92:93], v[84:85]
	v_mul_f32_e32 v92, v105, v106
	v_mul_f32_e32 v94, v104, v106
	v_pk_mul_f32 v[94:95], v[100:101], v[94:95] op_sel_hi:[1,0]
	v_pk_mul_f32 v[92:93], v[96:97], v[92:93] op_sel_hi:[1,0]
	v_pk_mul_f32 v[90:91], v[90:91], v[94:95]
	v_pk_mul_f32 v[88:89], v[88:89], v[92:93]
	v_pk_mul_f32 v[90:91], v[90:91], v[82:83]
	v_pk_mul_f32 v[82:83], v[88:89], v[80:81]
	v_cvt_pk_bf16_f32 v80, v84, v85
; __device__ __forceinline__ unsigned cvt_pk_bf16(float lo, float hi) { unsigned r; asm volatile("v_cvt_pk_bf16_f32 %0, %1, %2" : "=v"(r) : "v"(lo), "v"(hi)); return r; }
; __device__ __forceinline__ f32x4 sigmoid4(f32x4 x) {
;     f32x4 d;
; #pragma unroll
;     for (int j = 0; j < 4; ++j) d[j] = 1.0f + __expf(-fmaxf(x[j], -20.0f));
;     const float p01 = d[0] * d[1], p23 = d[2] * d[3], r = __builtin_amdgcn_rcpf(p01 * p23), r01 = r * p23, r23 = r * p01;
;     return (f32x4){r01 * d[1], r01 * d[0], r23 * d[3], r23 * d[2]};
; }
;     __device__ __forceinline__ void operator()(const f32x4 (&acc)[2][2][4][2], const Unit& u, int wr, int wc, int fr, int fq) const {
;     ...
;         for (int ai = 0; ai < 2; ++ai)
; #pragma unroll
;             for (int m = 0; m < 4; ++m) { bf16_t* rowp = O + (size_t)(row0 + ai * HALF + m * 16) * ldc + col0;
;                 f32x4 v0, v1;
; #pragma unroll
;                 for (int j = 0; j < 1; ++j) { v0 = acc[ai][0][m][0] * sigmoid4(acc[ai][0][m][0]) * acc[ai][1][m][0]; v1 = acc[ai][0][m][1] * sigmoid4(acc[ai][0][m][1]) * acc[ai][1][m][1]; }
;                 u32x4 w; w.x = cvt_pk_bf16(v0[0], v0[1]); w.y = cvt_pk_bf16(v0[2], v0[3]); w.z = cvt_pk_bf16(v1[0], v1[1]); w.w = cvt_pk_bf16(v1[2], v1[3]);
;                 *(u32x4*)rowp = w; }
	v_cvt_pk_bf16_f32 v81, v86, v87
	v_max_f32_e32 v84, v76, v76
	v_max_f32_e32 v86, v78, v78
	v_max_f32_e32 v84, 0xc1a00000, v84
	v_max_f32_e32 v86, 0xc1a00000, v86
	v_mul_f32_e32 v84, 0xbfb8aa3b, v84
	v_mul_f32_e32 v86, 0xbfb8aa3b, v86
	v_exp_f32_e32 v85, v84
	v_max_f32_e32 v84, v77, v77
	v_exp_f32_e32 v87, v86
	v_max_f32_e32 v86, v79, v79
	v_max_f32_e32 v84, 0xc1a00000, v84
	v_max_f32_e32 v86, 0xc1a00000, v86
	v_mul_f32_e32 v84, 0xbfb8aa3b, v84
	v_mul_f32_e32 v86, 0xbfb8aa3b, v86
	v_exp_f32_e32 v84, v84
	v_exp_f32_e32 v86, v86
	v_cvt_pk_bf16_f32 v82, v82, v83
	v_cvt_pk_bf16_f32 v83, v90, v91
	global_store_dwordx4 v[102:103], v[80:83], off
	v_or_b32_e32 v88, 48, v154
	s_nop 0
	v_pk_add_f32 v[80:81], v[84:85], 1.0 op_sel_hi:[1,0]
	v_pk_add_f32 v[82:83], v[86:87], 1.0 op_sel_hi:[1,0]
	v_mov_b32_e32 v84, v81
	v_mov_b32_e32 v85, v83
	v_mov_b32_e32 v86, v80
	v_mov_b32_e32 v87, v82
	v_pk_mul_f32 v[84:85], v[84:85], v[86:87]
	s_nop 0
	v_mul_f32_e32 v86, v84, v85
	v_rcp_f32_e32 v89, v86
	v_mad_i64_i32 v[86:87], s[16:17], v88, s40, v[144:145]
	v_lshl_add_u64 v[86:87], v[86:87], 0, v[146:147]
	v_mul_f32_e32 v84, v84, v89
	v_mul_f32_e32 v88, v85, v89
	v_pk_mul_f32 v[82:83], v[82:83], v[84:85] op_sel_hi:[1,0]
	v_max_f32_e32 v84, v72, v72
	v_max_f32_e32 v89, v74, v74
	v_max_f32_e32 v84, 0xc1a00000, v84
	v_max_f32_e32 v89, 0xc1a00000, v89
	v_mul_f32_e32 v84, 0xbfb8aa3b, v84
	v_mul_f32_e32 v89, 0xbfb8aa3b, v89
	v_exp_f32_e32 v85, v84
	v_max_f32_e32 v84, v73, v73
	v_exp_f32_e32 v91, v89
	v_max_f32_e32 v89, v75, v75
	v_max_f32_e32 v84, 0xc1a00000, v84
	v_max_f32_e32 v89, 0xc1a00000, v89
	v_mul_f32_e32 v84, 0xbfb8aa3b, v84
	v_mul_f32_e32 v89, 0xbfb8aa3b, v89
	v_exp_f32_e32 v84, v84
	v_exp_f32_e32 v90, v89
	v_pk_mul_f32 v[80:81], v[80:81], v[88:89] op_sel_hi:[1,0]
	v_pk_mul_f32 v[78:79], v[78:79], v[82:83]
	v_pk_mul_f32 v[76:77], v[76:77], v[80:81]
	v_pk_add_f32 v[80:81], v[84:85], 1.0 op_sel_hi:[1,0]
	v_pk_add_f32 v[84:85], v[90:91], 1.0 op_sel_hi:[1,0]
	v_mov_b32_e32 v88, v81
	v_mov_b32_e32 v89, v85
	v_mov_b32_e32 v90, v80
	v_mov_b32_e32 v91, v84
	v_pk_mul_f32 v[88:89], v[88:89], v[90:91]
	v_pk_mul_f32 v[70:71], v[78:79], v[70:71]
	v_mul_f32_e32 v90, v88, v89
	v_rcp_f32_e32 v90, v90
	v_pk_mul_f32 v[68:69], v[76:77], v[68:69]
	v_mul_f32_e32 v76, v89, v90
	v_mul_f32_e32 v78, v88, v90
	v_pk_mul_f32 v[78:79], v[84:85], v[78:79] op_sel_hi:[1,0]
	v_pk_mul_f32 v[76:77], v[80:81], v[76:77] op_sel_hi:[1,0]
	v_pk_mul_f32 v[74:75], v[74:75], v[78:79]
	v_pk_mul_f32 v[72:73], v[72:73], v[76:77]
	v_pk_mul_f32 v[74:75], v[74:75], v[66:67]
	v_pk_mul_f32 v[66:67], v[72:73], v[64:65]
	v_cvt_pk_bf16_f32 v64, v68, v69
	v_cvt_pk_bf16_f32 v65, v70, v71
	v_max_f32_e32 v68, v60, v60
	v_max_f32_e32 v70, v62, v62
	v_max_f32_e32 v68, 0xc1a00000, v68
	v_max_f32_e32 v70, 0xc1a00000, v70
	v_mul_f32_e32 v68, 0xbfb8aa3b, v68
	v_mul_f32_e32 v70, 0xbfb8aa3b, v70
	v_exp_f32_e32 v69, v68
	v_max_f32_e32 v68, v61, v61
	v_exp_f32_e32 v71, v70
	v_max_f32_e32 v70, v63, v63
	v_max_f32_e32 v68, 0xc1a00000, v68
	v_max_f32_e32 v70, 0xc1a00000, v70
	v_mul_f32_e32 v68, 0xbfb8aa3b, v68
	v_mul_f32_e32 v70, 0xbfb8aa3b, v70
	v_exp_f32_e32 v68, v68
	v_exp_f32_e32 v70, v70
	v_cvt_pk_bf16_f32 v66, v66, v67
	v_cvt_pk_bf16_f32 v67, v74, v75
	global_store_dwordx4 v[86:87], v[64:67], off
	v_add_u32_e32 v72, 0x80, v154
	s_nop 0
	v_pk_add_f32 v[64:65], v[68:69], 1.0 op_sel_hi:[1,0]
	v_pk_add_f32 v[66:67], v[70:71], 1.0 op_sel_hi:[1,0]
	v_mov_b32_e32 v68, v65
	v_mov_b32_e32 v69, v67
	v_mov_b32_e32 v70, v64
	v_mov_b32_e32 v71, v66
	v_pk_mul_f32 v[68:69], v[68:69], v[70:71]
	s_nop 0
	v_mul_f32_e32 v70, v68, v69
	v_rcp_f32_e32 v73, v70
	v_mad_i64_i32 v[70:71], s[16:17], v72, s40, v[144:145]
	v_lshl_add_u64 v[70:71], v[70:71], 0, v[146:147]
	v_mul_f32_e32 v68, v68, v73
	v_mul_f32_e32 v72, v69, v73
	v_pk_mul_f32 v[66:67], v[66:67], v[68:69] op_sel_hi:[1,0]
	v_max_f32_e32 v68, v56, v56
	v_max_f32_e32 v73, v58, v58
	v_max_f32_e32 v68, 0xc1a00000, v68
	v_max_f32_e32 v73, 0xc1a00000, v73
	v_mul_f32_e32 v68, 0xbfb8aa3b, v68
	v_mul_f32_e32 v73, 0xbfb8aa3b, v73
	v_exp_f32_e32 v69, v68
	v_max_f32_e32 v68, v57, v57
	v_exp_f32_e32 v75, v73
	v_max_f32_e32 v73, v59, v59
	v_max_f32_e32 v68, 0xc1a00000, v68
	v_max_f32_e32 v73, 0xc1a00000, v73
	v_mul_f32_e32 v68, 0xbfb8aa3b, v68
	v_mul_f32_e32 v73, 0xbfb8aa3b, v73
	v_exp_f32_e32 v68, v68
	v_exp_f32_e32 v74, v73
	v_pk_mul_f32 v[64:65], v[64:65], v[72:73] op_sel_hi:[1,0]
	v_pk_mul_f32 v[62:63], v[62:63], v[66:67]
	v_pk_mul_f32 v[60:61], v[60:61], v[64:65]
	v_pk_add_f32 v[64:65], v[68:69], 1.0 op_sel_hi:[1,0]
	v_pk_add_f32 v[68:69], v[74:75], 1.0 op_sel_hi:[1,0]
	v_mov_b32_e32 v72, v65
	v_mov_b32_e32 v73, v69
	v_mov_b32_e32 v74, v64
	v_mov_b32_e32 v75, v68
	v_pk_mul_f32 v[72:73], v[72:73], v[74:75]
	v_pk_mul_f32 v[54:55], v[62:63], v[54:55]
	v_mul_f32_e32 v74, v72, v73
	v_rcp_f32_e32 v74, v74
	v_pk_mul_f32 v[52:53], v[60:61], v[52:53]
	v_mul_f32_e32 v60, v73, v74
	v_mul_f32_e32 v62, v72, v74
	v_pk_mul_f32 v[62:63], v[68:69], v[62:63] op_sel_hi:[1,0]
	v_pk_mul_f32 v[60:61], v[64:65], v[60:61] op_sel_hi:[1,0]
	v_pk_mul_f32 v[58:59], v[58:59], v[62:63]
	v_pk_mul_f32 v[56:57], v[56:57], v[60:61]
	v_pk_mul_f32 v[58:59], v[58:59], v[50:51]
	v_pk_mul_f32 v[50:51], v[56:57], v[48:49]
	v_cvt_pk_bf16_f32 v48, v52, v53
	v_cvt_pk_bf16_f32 v49, v54, v55
	v_max_f32_e32 v52, v44, v44
	v_max_f32_e32 v54, v46, v46
	v_max_f32_e32 v52, 0xc1a00000, v52
	v_max_f32_e32 v54, 0xc1a00000, v54
	v_mul_f32_e32 v52, 0xbfb8aa3b, v52
	v_mul_f32_e32 v54, 0xbfb8aa3b, v54
	v_exp_f32_e32 v53, v52
	v_max_f32_e32 v52, v45, v45
	v_exp_f32_e32 v55, v54
	v_max_f32_e32 v54, v47, v47
	v_max_f32_e32 v52, 0xc1a00000, v52
; __device__ __forceinline__ unsigned cvt_pk_bf16(float lo, float hi) { unsigned r; asm volatile("v_cvt_pk_bf16_f32 %0, %1, %2" : "=v"(r) : "v"(lo), "v"(hi)); return r; }
; __device__ __forceinline__ f32x4 sigmoid4(f32x4 x) {
;     f32x4 d;
; #pragma unroll
;     for (int j = 0; j < 4; ++j) d[j] = 1.0f + __expf(-fmaxf(x[j], -20.0f));
;     const float p01 = d[0] * d[1], p23 = d[2] * d[3], r = __builtin_amdgcn_rcpf(p01 * p23), r01 = r * p23, r23 = r * p01;
;     return (f32x4){r01 * d[1], r01 * d[0], r23 * d[3], r23 * d[2]};
; }
;     __device__ __forceinline__ void operator()(const f32x4 (&acc)[2][2][4][2], const Unit& u, int wr, int wc, int fr, int fq) const {
;     ...
;         for (int ai = 0; ai < 2; ++ai)
; #pragma unroll
;             for (int m = 0; m < 4; ++m) { bf16_t* rowp = O + (size_t)(row0 + ai * HALF + m * 16) * ldc + col0;
;                 f32x4 v0, v1;
; #pragma unroll
;                 for (int j = 0; j < 1; ++j) { v0 = acc[ai][0][m][0] * sigmoid4(acc[ai][0][m][0]) * acc[ai][1][m][0]; v1 = acc[ai][0][m][1] * sigmoid4(acc[ai][0][m][1]) * acc[ai][1][m][1]; }
;                 u32x4 w; w.x = cvt_pk_bf16(v0[0], v0[1]); w.y = cvt_pk_bf16(v0[2], v0[3]); w.z = cvt_pk_bf16(v1[0], v1[1]); w.w = cvt_pk_bf16(v1[2], v1[3]);
;                 *(u32x4*)rowp = w; }
	v_max_f32_e32 v54, 0xc1a00000, v54
	v_mul_f32_e32 v52, 0xbfb8aa3b, v52
	v_mul_f32_e32 v54, 0xbfb8aa3b, v54
	v_exp_f32_e32 v52, v52
	v_exp_f32_e32 v54, v54
	v_cvt_pk_bf16_f32 v50, v50, v51
	v_cvt_pk_bf16_f32 v51, v58, v59
	global_store_dwordx4 v[70:71], v[48:51], off
	v_add_u32_e32 v56, 0x90, v154
	s_nop 0
	v_pk_add_f32 v[48:49], v[52:53], 1.0 op_sel_hi:[1,0]
	v_pk_add_f32 v[50:51], v[54:55], 1.0 op_sel_hi:[1,0]
	v_mov_b32_e32 v52, v49
	v_mov_b32_e32 v53, v51
	v_mov_b32_e32 v54, v48
	v_mov_b32_e32 v55, v50
	v_pk_mul_f32 v[52:53], v[52:53], v[54:55]
	s_nop 0
	v_mul_f32_e32 v54, v52, v53
	v_rcp_f32_e32 v57, v54
	v_mad_i64_i32 v[54:55], s[16:17], v56, s40, v[144:145]
	v_lshl_add_u64 v[54:55], v[54:55], 0, v[146:147]
	v_mul_f32_e32 v52, v52, v57
	v_mul_f32_e32 v56, v53, v57
	v_pk_mul_f32 v[50:51], v[50:51], v[52:53] op_sel_hi:[1,0]
	v_max_f32_e32 v52, v40, v40
	v_max_f32_e32 v57, v42, v42
	v_max_f32_e32 v52, 0xc1a00000, v52
	v_max_f32_e32 v57, 0xc1a00000, v57
	v_mul_f32_e32 v52, 0xbfb8aa3b, v52
	v_mul_f32_e32 v57, 0xbfb8aa3b, v57
	v_exp_f32_e32 v53, v52
	v_max_f32_e32 v52, v41, v41
	v_exp_f32_e32 v59, v57
	v_max_f32_e32 v57, v43, v43
	v_max_f32_e32 v52, 0xc1a00000, v52
	v_max_f32_e32 v57, 0xc1a00000, v57
	v_mul_f32_e32 v52, 0xbfb8aa3b, v52
	v_mul_f32_e32 v57, 0xbfb8aa3b, v57
	v_exp_f32_e32 v52, v52
	v_exp_f32_e32 v58, v57
	v_pk_mul_f32 v[48:49], v[48:49], v[56:57] op_sel_hi:[1,0]
	v_pk_mul_f32 v[46:47], v[46:47], v[50:51]
	v_pk_mul_f32 v[44:45], v[44:45], v[48:49]
	v_pk_add_f32 v[48:49], v[52:53], 1.0 op_sel_hi:[1,0]
	v_pk_add_f32 v[52:53], v[58:59], 1.0 op_sel_hi:[1,0]
	v_mov_b32_e32 v56, v49
	v_mov_b32_e32 v57, v53
	v_mov_b32_e32 v58, v48
	v_mov_b32_e32 v59, v52
	v_pk_mul_f32 v[56:57], v[56:57], v[58:59]
	v_pk_mul_f32 v[38:39], v[46:47], v[38:39]
	v_mul_f32_e32 v58, v56, v57
	v_rcp_f32_e32 v58, v58
	v_pk_mul_f32 v[36:37], v[44:45], v[36:37]
	v_mul_f32_e32 v44, v57, v58
	v_mul_f32_e32 v46, v56, v58
	v_pk_mul_f32 v[46:47], v[52:53], v[46:47] op_sel_hi:[1,0]
	v_pk_mul_f32 v[44:45], v[48:49], v[44:45] op_sel_hi:[1,0]
	v_pk_mul_f32 v[42:43], v[42:43], v[46:47]
	v_pk_mul_f32 v[40:41], v[40:41], v[44:45]
	v_pk_mul_f32 v[42:43], v[42:43], v[34:35]
	v_pk_mul_f32 v[34:35], v[40:41], v[32:33]
	v_cvt_pk_bf16_f32 v32, v36, v37
	v_cvt_pk_bf16_f32 v33, v38, v39
	v_max_f32_e32 v36, v28, v28
	v_max_f32_e32 v38, v30, v30
	v_max_f32_e32 v36, 0xc1a00000, v36
	v_max_f32_e32 v38, 0xc1a00000, v38
	v_mul_f32_e32 v36, 0xbfb8aa3b, v36
	v_mul_f32_e32 v38, 0xbfb8aa3b, v38
	v_exp_f32_e32 v37, v36
	v_max_f32_e32 v36, v29, v29
	v_exp_f32_e32 v39, v38
	v_max_f32_e32 v38, v31, v31
	v_max_f32_e32 v36, 0xc1a00000, v36
	v_max_f32_e32 v38, 0xc1a00000, v38
	v_mul_f32_e32 v36, 0xbfb8aa3b, v36
	v_mul_f32_e32 v38, 0xbfb8aa3b, v38
	v_exp_f32_e32 v36, v36
	v_exp_f32_e32 v38, v38
	v_cvt_pk_bf16_f32 v34, v34, v35
	v_cvt_pk_bf16_f32 v35, v42, v43
	global_store_dwordx4 v[54:55], v[32:35], off
	v_add_u32_e32 v40, 0xa0, v154
	s_nop 0
	v_pk_add_f32 v[32:33], v[36:37], 1.0 op_sel_hi:[1,0]
	v_pk_add_f32 v[34:35], v[38:39], 1.0 op_sel_hi:[1,0]
	v_mov_b32_e32 v36, v33
	v_mov_b32_e32 v37, v35
	v_mov_b32_e32 v38, v32
	v_mov_b32_e32 v39, v34
	v_pk_mul_f32 v[36:37], v[36:37], v[38:39]
	s_nop 0
	v_mul_f32_e32 v38, v36, v37
	v_rcp_f32_e32 v41, v38
	v_mad_i64_i32 v[38:39], s[16:17], v40, s40, v[144:145]
	v_lshl_add_u64 v[38:39], v[38:39], 0, v[146:147]
	v_mul_f32_e32 v36, v36, v41
	v_mul_f32_e32 v40, v37, v41
	v_pk_mul_f32 v[34:35], v[34:35], v[36:37] op_sel_hi:[1,0]
	v_max_f32_e32 v36, v24, v24
	v_max_f32_e32 v41, v26, v26
	v_max_f32_e32 v36, 0xc1a00000, v36
	v_max_f32_e32 v41, 0xc1a00000, v41
	v_mul_f32_e32 v36, 0xbfb8aa3b, v36
	v_mul_f32_e32 v41, 0xbfb8aa3b, v41
	v_exp_f32_e32 v37, v36
	v_max_f32_e32 v36, v25, v25
	v_exp_f32_e32 v43, v41
	v_max_f32_e32 v41, v27, v27
	v_max_f32_e32 v36, 0xc1a00000, v36
	v_max_f32_e32 v41, 0xc1a00000, v41
	v_mul_f32_e32 v36, 0xbfb8aa3b, v36
; __device__ __forceinline__ unsigned cvt_pk_bf16(float lo, float hi) { unsigned r; asm volatile("v_cvt_pk_bf16_f32 %0, %1, %2" : "=v"(r) : "v"(lo), "v"(hi)); return r; }
; __device__ __forceinline__ f32x4 sigmoid4(f32x4 x) {
;     f32x4 d;
; #pragma unroll
;     for (int j = 0; j < 4; ++j) d[j] = 1.0f + __expf(-fmaxf(x[j], -20.0f));
;     const float p01 = d[0] * d[1], p23 = d[2] * d[3], r = __builtin_amdgcn_rcpf(p01 * p23), r01 = r * p23, r23 = r * p01;
;     return (f32x4){r01 * d[1], r01 * d[0], r23 * d[3], r23 * d[2]};
; }
;     __device__ __forceinline__ void operator()(const f32x4 (&acc)[2][2][4][2], const Unit& u, int wr, int wc, int fr, int fq) const {
;     ...
;         for (int ai = 0; ai < 2; ++ai)
; #pragma unroll
;             for (int m = 0; m < 4; ++m) { bf16_t* rowp = O + (size_t)(row0 + ai * HALF + m * 16) * ldc + col0;
;                 f32x4 v0, v1;
; #pragma unroll
;                 for (int j = 0; j < 1; ++j) { v0 = acc[ai][0][m][0] * sigmoid4(acc[ai][0][m][0]) * acc[ai][1][m][0]; v1 = acc[ai][0][m][1] * sigmoid4(acc[ai][0][m][1]) * acc[ai][1][m][1]; }
;                 u32x4 w; w.x = cvt_pk_bf16(v0[0], v0[1]); w.y = cvt_pk_bf16(v0[2], v0[3]); w.z = cvt_pk_bf16(v1[0], v1[1]); w.w = cvt_pk_bf16(v1[2], v1[3]);
;                 *(u32x4*)rowp = w; }
	v_mul_f32_e32 v41, 0xbfb8aa3b, v41
	v_exp_f32_e32 v36, v36
	v_exp_f32_e32 v42, v41
	v_pk_mul_f32 v[32:33], v[32:33], v[40:41] op_sel_hi:[1,0]
	v_pk_mul_f32 v[30:31], v[30:31], v[34:35]
	v_pk_mul_f32 v[28:29], v[28:29], v[32:33]
	v_pk_add_f32 v[32:33], v[36:37], 1.0 op_sel_hi:[1,0]
	v_pk_add_f32 v[36:37], v[42:43], 1.0 op_sel_hi:[1,0]
	v_mov_b32_e32 v40, v33
	v_mov_b32_e32 v41, v37
	v_mov_b32_e32 v42, v32
	v_mov_b32_e32 v43, v36
	v_pk_mul_f32 v[40:41], v[40:41], v[42:43]
	v_pk_mul_f32 v[22:23], v[30:31], v[22:23]
	v_mul_f32_e32 v42, v40, v41
	v_rcp_f32_e32 v42, v42
	v_pk_mul_f32 v[20:21], v[28:29], v[20:21]
	v_mul_f32_e32 v28, v41, v42
	v_mul_f32_e32 v30, v40, v42
	v_pk_mul_f32 v[30:31], v[36:37], v[30:31] op_sel_hi:[1,0]
	v_pk_mul_f32 v[28:29], v[32:33], v[28:29] op_sel_hi:[1,0]
	v_pk_mul_f32 v[26:27], v[26:27], v[30:31]
	v_pk_mul_f32 v[24:25], v[24:25], v[28:29]
	v_pk_mul_f32 v[26:27], v[26:27], v[18:19]
	v_pk_mul_f32 v[18:19], v[24:25], v[16:17]
	v_cvt_pk_bf16_f32 v16, v20, v21
	v_cvt_pk_bf16_f32 v17, v22, v23
	v_max_f32_e32 v20, v12, v12
	v_max_f32_e32 v22, v14, v14
	v_max_f32_e32 v20, 0xc1a00000, v20
	v_max_f32_e32 v22, 0xc1a00000, v22
	v_mul_f32_e32 v20, 0xbfb8aa3b, v20
	v_mul_f32_e32 v22, 0xbfb8aa3b, v22
	v_exp_f32_e32 v21, v20
	v_max_f32_e32 v20, v13, v13
	v_exp_f32_e32 v23, v22
	v_max_f32_e32 v22, v15, v15
	v_max_f32_e32 v20, 0xc1a00000, v20
	v_max_f32_e32 v22, 0xc1a00000, v22
	v_mul_f32_e32 v20, 0xbfb8aa3b, v20
	v_mul_f32_e32 v22, 0xbfb8aa3b, v22
	v_exp_f32_e32 v20, v20
	v_exp_f32_e32 v22, v22
	v_cvt_pk_bf16_f32 v18, v18, v19
	v_cvt_pk_bf16_f32 v19, v26, v27
	global_store_dwordx4 v[38:39], v[16:19], off
	v_add_u32_e32 v24, 0xb0, v154
	s_nop 0
	v_pk_add_f32 v[16:17], v[20:21], 1.0 op_sel_hi:[1,0]
	v_pk_add_f32 v[18:19], v[22:23], 1.0 op_sel_hi:[1,0]
	v_mov_b32_e32 v20, v17
	v_mov_b32_e32 v21, v19
	v_mov_b32_e32 v22, v16
	v_mov_b32_e32 v23, v18
	v_pk_mul_f32 v[20:21], v[20:21], v[22:23]
	s_nop 0
	v_mul_f32_e32 v22, v20, v21
	v_rcp_f32_e32 v25, v22
	v_mad_i64_i32 v[22:23], s[16:17], v24, s40, v[144:145]
	v_lshl_add_u64 v[22:23], v[22:23], 0, v[146:147]
	v_mul_f32_e32 v20, v20, v25
	v_mul_f32_e32 v24, v21, v25
	v_pk_mul_f32 v[18:19], v[18:19], v[20:21] op_sel_hi:[1,0]
	v_max_f32_e32 v20, v8, v8
	v_max_f32_e32 v25, v10, v10
	v_max_f32_e32 v20, 0xc1a00000, v20
	v_max_f32_e32 v25, 0xc1a00000, v25
	v_mul_f32_e32 v20, 0xbfb8aa3b, v20
	v_mul_f32_e32 v25, 0xbfb8aa3b, v25
	v_exp_f32_e32 v21, v20
	v_max_f32_e32 v20, v9, v9
	v_exp_f32_e32 v27, v25
	v_max_f32_e32 v25, v11, v11
	v_max_f32_e32 v20, 0xc1a00000, v20
	v_max_f32_e32 v25, 0xc1a00000, v25
	v_mul_f32_e32 v20, 0xbfb8aa3b, v20
	v_mul_f32_e32 v25, 0xbfb8aa3b, v25
	v_exp_f32_e32 v20, v20
	v_exp_f32_e32 v26, v25
	v_pk_mul_f32 v[16:17], v[16:17], v[24:25] op_sel_hi:[1,0]
	v_pk_mul_f32 v[14:15], v[14:15], v[18:19]
	v_pk_mul_f32 v[12:13], v[12:13], v[16:17]
	v_pk_add_f32 v[16:17], v[20:21], 1.0 op_sel_hi:[1,0]
	v_pk_add_f32 v[20:21], v[26:27], 1.0 op_sel_hi:[1,0]
	v_mov_b32_e32 v24, v17
	v_mov_b32_e32 v25, v21
	v_mov_b32_e32 v26, v16
	v_mov_b32_e32 v27, v20
	v_pk_mul_f32 v[24:25], v[24:25], v[26:27]
	v_pk_mul_f32 v[6:7], v[14:15], v[6:7]
	v_mul_f32_e32 v26, v24, v25
	v_rcp_f32_e32 v26, v26
	v_pk_mul_f32 v[4:5], v[12:13], v[4:5]
	s_mov_b64 s[16:17], s[10:11]
	v_mul_f32_e32 v12, v25, v26
	v_mul_f32_e32 v14, v24, v26
	v_pk_mul_f32 v[14:15], v[20:21], v[14:15] op_sel_hi:[1,0]
	v_pk_mul_f32 v[12:13], v[16:17], v[12:13] op_sel_hi:[1,0]
	v_pk_mul_f32 v[10:11], v[10:11], v[14:15]
	v_pk_mul_f32 v[8:9], v[8:9], v[12:13]
	v_pk_mul_f32 v[10:11], v[10:11], v[2:3]
	v_pk_mul_f32 v[2:3], v[8:9], v[0:1]
	v_cvt_pk_bf16_f32 v0, v4, v5
	v_cvt_pk_bf16_f32 v1, v6, v7
	s_nop 0
	v_cvt_pk_bf16_f32 v2, v2, v3
	v_cvt_pk_bf16_f32 v3, v10, v11
	global_store_dwordx4 v[22:23], v[0:3], off
	s_cbranch_vccz .LBB0_1199
	s_waitcnt vmcnt(0)
	s_cmpk_gt_u32 s23, 0xff
	s_cbranch_scc1 .LBB0_1206
	s_barrier

; #define PG8_STAGE(bufoff, gbase, voff) do { _Pragma("unroll") for (int _i = 0; _i < 2; ++_i) \
;         __builtin_amdgcn_global_load_lds((const unsigned*)((const char*)(gbase) + (voff)[_i]), (PG8_LAS unsigned*)(lds + (bufoff) + ldsw + _i * 8192), 16, 0, 0); } while (0)
; #define PG8_LDA(dst, b, h) do { _Pragma("unroll") for (int m = 0; m < 4; ++m) _Pragma("unroll") for (int k = 0; k < 2; ++k) dst[m][k] = *(const PG8_LAS bf16x8*)(lds + PG8_SA(b, h) + aoff + m * 2048 + k * 1024); } while (0)
; #define PG8_LDB(dst, b, h) do { _Pragma("unroll") for (int n = 0; n < 2; ++n) _Pragma("unroll") for (int k = 0; k < 2; ++k) dst[n][k] = *(const PG8_LAS bf16x8*)(lds + PG8_SB(b, h) + boff + n * 2048 + k * 1024); } while (0)
; #define PG8_MMA(ai, bj, At, Bt) do { __builtin_amdgcn_s_setprio(1); _Pragma("unroll") for (int m = 0; m < 4; ++m) _Pragma("unroll") for (int n = 0; n < 2; ++n) _Pragma("unroll") for (int k = 0; k < 2; ++k) \
;         acc[ai][bj][m][n] = __builtin_amdgcn_mfma_f32_16x16x32_bf16(Bt[n][k], At[m][k], acc[ai][bj][m][n], 0, 0, 0); __builtin_amdgcn_s_setprio(0); } while (0)
; #define PG8_WAIT_L(n) asm volatile("s_waitcnt lgkmcnt(" #n ")" ::: "memory")
; #define PG8_BAR __builtin_amdgcn_s_barrier()
; #define PG8_SCHED __builtin_amdgcn_sched_barrier(0)
; template <class Epi, class Sched>
; __device__ __forceinline__ void gemm_phase(PG8_LAS unsigned char* lds, const Gemm g, const Sched& S, const Epi& E) {
;     ...
;             const bool last = (t == nt - 2);
;             const char* a1 = cA + (size_t)(t + 1) * kstep;
;             const char* a2 = last ? nA : cA + (size_t)(t + 2) * kstep; const char* b2 = last ? nB : cB + (size_t)(t + 2) * kstep;
;             const char* a3 = a2 + kstep; const char* b3 = b2 + kstep;
;             if (last && has_next) S.a_ready(nxt);
;             PG8_LDB(B0, 0, 0); PG8_SCHED; PG8_LDA(At, 0, 0); PG8_STAGE(PG8_SA(1, 1), a1 + hstep, voffA);
;             PG8_WAIT_L(8); PG8_BAR; PG8_WAIT_L(0); PG8_MMA(0, 0, At, B0); PG8_BAR; PG8_SCHED;
;             PG8_LDB(B1, 0, 1); PG8_STAGE(PG8_SB(0, 0), b2, voffB);
;             PG8_BAR; PG8_WAIT_L(0); PG8_MMA(0, 1, At, B1); PG8_BAR;
;             PG8_LDA(At, 0, 1); PG8_STAGE(PG8_SA(0, 0), a2, voffA);
;             PG8_BAR; PG8_WAIT_L(0); PG8_MMA(1, 0, At, B0); PG8_BAR; PG8_SCHED;
.LBB0_1278:
	s_add_u32 s20, s18, 0x100
	s_addc_u32 s21, s19, 0
	s_cmp_eq_u32 s54, 40
	s_cselect_b32 s25, s1, s21
	s_cselect_b32 s24, s0, s20
	s_cselect_b32 s23, s5, s53
	s_cselect_b32 s22, s4, s52
	v_lshl_add_u64 v[144:145], s[18:19], 0, v[136:137]
	s_add_i32 m0, s34, 0xc000
	s_nop 0
	global_load_lds_dwordx4 v[144:145], off
	v_lshl_add_u64 v[144:145], s[18:19], 0, v[138:139]
	s_add_i32 m0, s34, 0xe000
	s_nop 0
	global_load_lds_dwordx4 v[144:145], off
	ds_read_b128 v[152:155], v149
	ds_read_b128 v[156:159], v149 offset:1024
	ds_read_b128 v[160:163], v149 offset:2048
	ds_read_b128 v[164:167], v149 offset:3072
	ds_read_b128 v[168:171], v150
	ds_read_b128 v[172:175], v150 offset:1024
	ds_read_b128 v[182:185], v150 offset:2048
	ds_read_b128 v[190:193], v150 offset:3072
	ds_read_b128 v[194:197], v150 offset:4096
	ds_read_b128 v[198:201], v150 offset:5120
	ds_read_b128 v[202:205], v150 offset:6144
	ds_read_b128 v[206:209], v150 offset:7168
	s_waitcnt lgkmcnt(8)
	s_barrier
	s_waitcnt lgkmcnt(0)
	v_mfma_f32_16x16x32_bf16 v[124:127], v[152:155], v[168:171], v[124:127]
	v_mfma_f32_16x16x32_bf16 v[120:123], v[160:163], v[168:171], v[120:123]
	v_mfma_f32_16x16x32_bf16 v[108:111], v[152:155], v[182:185], v[108:111]
	v_mfma_f32_16x16x32_bf16 v[104:107], v[160:163], v[182:185], v[104:107]
	v_mfma_f32_16x16x32_bf16 v[92:95], v[152:155], v[194:197], v[92:95]
	v_mfma_f32_16x16x32_bf16 v[88:91], v[160:163], v[194:197], v[88:91]
	v_mfma_f32_16x16x32_bf16 v[76:79], v[152:155], v[202:205], v[76:79]
	v_mfma_f32_16x16x32_bf16 v[72:75], v[160:163], v[202:205], v[72:75]
	v_mfma_f32_16x16x32_bf16 v[124:127], v[156:159], v[172:175], v[124:127]
	v_mfma_f32_16x16x32_bf16 v[120:123], v[164:167], v[172:175], v[120:123]
	v_mfma_f32_16x16x32_bf16 v[108:111], v[156:159], v[190:193], v[108:111]
	v_mfma_f32_16x16x32_bf16 v[104:107], v[164:167], v[190:193], v[104:107]
	v_mfma_f32_16x16x32_bf16 v[92:95], v[156:159], v[198:201], v[92:95]
	v_mfma_f32_16x16x32_bf16 v[88:91], v[164:167], v[198:201], v[88:91]
	v_mfma_f32_16x16x32_bf16 v[76:79], v[156:159], v[206:209], v[76:79]
	v_mfma_f32_16x16x32_bf16 v[72:75], v[164:167], v[206:209], v[72:75]
	s_barrier
	s_add_i32 s18, s42, s31
	v_lshl_add_u64 v[144:145], s[22:23], 0, v[130:131]
	s_mov_b32 m0, s18
	s_nop 0
	global_load_lds_dwordx4 v[144:145], off
	v_lshl_add_u64 v[186:187], s[22:23], 0, v[134:135]
	s_add_i32 m0, s18, 0x2000
	s_nop 0
	global_load_lds_dwordx4 v[186:187], off
	ds_read_b128 v[210:213], v151
	ds_read_b128 v[214:217], v151 offset:1024
	ds_read_b128 v[218:221], v151 offset:2048
	ds_read_b128 v[222:225], v151 offset:3072
	s_barrier
	s_waitcnt lgkmcnt(0)
	v_mfma_f32_16x16x32_bf16 v[116:119], v[210:213], v[168:171], v[116:119]
	v_mfma_f32_16x16x32_bf16 v[112:115], v[218:221], v[168:171], v[112:115]
	v_mfma_f32_16x16x32_bf16 v[100:103], v[210:213], v[182:185], v[100:103]
	v_mfma_f32_16x16x32_bf16 v[96:99], v[218:221], v[182:185], v[96:99]
	v_mfma_f32_16x16x32_bf16 v[84:87], v[210:213], v[194:197], v[84:87]
	v_mfma_f32_16x16x32_bf16 v[80:83], v[218:221], v[194:197], v[80:83]
	v_mfma_f32_16x16x32_bf16 v[68:71], v[210:213], v[202:205], v[68:71]
	v_mfma_f32_16x16x32_bf16 v[64:67], v[218:221], v[202:205], v[64:67]
	v_mfma_f32_16x16x32_bf16 v[116:119], v[214:217], v[172:175], v[116:119]
	v_mfma_f32_16x16x32_bf16 v[112:115], v[222:225], v[172:175], v[112:115]
	v_mfma_f32_16x16x32_bf16 v[100:103], v[214:217], v[190:193], v[100:103]
	v_mfma_f32_16x16x32_bf16 v[96:99], v[222:225], v[190:193], v[96:99]
	v_mfma_f32_16x16x32_bf16 v[84:87], v[214:217], v[198:201], v[84:87]
	v_mfma_f32_16x16x32_bf16 v[80:83], v[222:225], v[198:201], v[80:83]
	v_mfma_f32_16x16x32_bf16 v[68:71], v[214:217], v[206:209], v[68:71]
	v_mfma_f32_16x16x32_bf16 v[64:67], v[222:225], v[206:209], v[64:67]
	s_mov_b32 m0, s34
	v_lshl_add_u64 v[226:227], s[24:25], 0, v[128:129]
	s_barrier
	global_load_lds_dwordx4 v[226:227], off
	v_lshl_add_u64 v[228:229], s[24:25], 0, v[132:133]
	s_mov_b32 m0, s35
	s_nop 0
	global_load_lds_dwordx4 v[228:229], off
	ds_read_b128 v[168:171], v150 offset:16384
	ds_read_b128 v[172:175], v150 offset:17408
	ds_read_b128 v[182:185], v150 offset:18432
	ds_read_b128 v[190:193], v150 offset:19456
	ds_read_b128 v[194:197], v150 offset:20480
	ds_read_b128 v[198:201], v150 offset:21504
	ds_read_b128 v[202:205], v150 offset:22528
	ds_read_b128 v[206:209], v150 offset:23552
	s_barrier
	s_waitcnt lgkmcnt(0)
	v_mfma_f32_16x16x32_bf16 v[60:63], v[152:155], v[168:171], v[60:63]
	v_mfma_f32_16x16x32_bf16 v[56:59], v[160:163], v[168:171], v[56:59]
	v_mfma_f32_16x16x32_bf16 v[48:51], v[152:155], v[182:185], v[48:51]
	v_mfma_f32_16x16x32_bf16 v[40:43], v[160:163], v[182:185], v[40:43]
	v_mfma_f32_16x16x32_bf16 v[32:35], v[152:155], v[194:197], v[32:35]
	v_mfma_f32_16x16x32_bf16 v[24:27], v[160:163], v[194:197], v[24:27]
	v_mfma_f32_16x16x32_bf16 v[16:19], v[152:155], v[202:205], v[16:19]
	v_mfma_f32_16x16x32_bf16 v[8:11], v[160:163], v[202:205], v[8:11]
	v_mfma_f32_16x16x32_bf16 v[60:63], v[156:159], v[172:175], v[60:63]
	v_mfma_f32_16x16x32_bf16 v[56:59], v[164:167], v[172:175], v[56:59]
	v_mfma_f32_16x16x32_bf16 v[48:51], v[156:159], v[190:193], v[48:51]
	v_mfma_f32_16x16x32_bf16 v[40:43], v[164:167], v[190:193], v[40:43]
	v_mfma_f32_16x16x32_bf16 v[32:35], v[156:159], v[198:201], v[32:35]
	v_mfma_f32_16x16x32_bf16 v[24:27], v[164:167], v[198:201], v[24:27]
	v_mfma_f32_16x16x32_bf16 v[16:19], v[156:159], v[206:209], v[16:19]
	v_mfma_f32_16x16x32_bf16 v[8:11], v[164:167], v[206:209], v[8:11]
	s_barrier
; #define PG8_STAGE(bufoff, gbase, voff) do { _Pragma("unroll") for (int _i = 0; _i < 2; ++_i) \
;         __builtin_amdgcn_global_load_lds((const unsigned*)((const char*)(gbase) + (voff)[_i]), (PG8_LAS unsigned*)(lds + (bufoff) + ldsw + _i * 8192), 16, 0, 0); } while (0)
; #define PG8_LDA(dst, b, h) do { _Pragma("unroll") for (int m = 0; m < 4; ++m) _Pragma("unroll") for (int k = 0; k < 2; ++k) dst[m][k] = *(const PG8_LAS bf16x8*)(lds + PG8_SA(b, h) + aoff + m * 2048 + k * 1024); } while (0)
; #define PG8_LDB(dst, b, h) do { _Pragma("unroll") for (int n = 0; n < 2; ++n) _Pragma("unroll") for (int k = 0; k < 2; ++k) dst[n][k] = *(const PG8_LAS bf16x8*)(lds + PG8_SB(b, h) + boff + n * 2048 + k * 1024); } while (0)
; #define PG8_MMA(ai, bj, At, Bt) do { __builtin_amdgcn_s_setprio(1); _Pragma("unroll") for (int m = 0; m < 4; ++m) _Pragma("unroll") for (int n = 0; n < 2; ++n) _Pragma("unroll") for (int k = 0; k < 2; ++k) \
;         acc[ai][bj][m][n] = __builtin_amdgcn_mfma_f32_16x16x32_bf16(Bt[n][k], At[m][k], acc[ai][bj][m][n], 0, 0, 0); __builtin_amdgcn_s_setprio(0); } while (0)
; #define PG8_WAIT_V(n) asm volatile("s_waitcnt vmcnt(" #n ")" ::: "memory")
; #define PG8_WAIT_L(n) asm volatile("s_waitcnt lgkmcnt(" #n ")" ::: "memory")
; #define PG8_BAR __builtin_amdgcn_s_barrier()
; #define PG8_SCHED __builtin_amdgcn_sched_barrier(0)
; template <class Epi, class Sched>
; __device__ __forceinline__ void gemm_phase(PG8_LAS unsigned char* lds, const Gemm g, const Sched& S, const Epi& E) {
;     ...
;             PG8_STAGE(PG8_SB(0, 1), b2 + hstep, voffB);
;             PG8_WAIT_V(6); PG8_BAR; PG8_MMA(1, 1, At, B1); PG8_BAR;
;             PG8_LDB(B0, 1, 0); PG8_SCHED; PG8_LDA(At, 1, 0); PG8_STAGE(PG8_SA(0, 1), a2 + hstep, voffA);
;             PG8_WAIT_L(8); PG8_BAR; PG8_WAIT_L(0); PG8_MMA(0, 0, At, B0); PG8_BAR; PG8_SCHED;
;             PG8_LDB(B1, 1, 1); PG8_STAGE(PG8_SB(1, 0), b3, voffB);
;             PG8_BAR; PG8_WAIT_L(0); PG8_MMA(0, 1, At, B1); PG8_BAR;
;             PG8_LDA(At, 1, 1); PG8_STAGE(PG8_SA(1, 0), a3, voffA);
	s_add_u32 s18, s22, 0xb0000
	s_addc_u32 s19, s23, 0
	s_add_i32 s55, s43, s31
	v_lshl_add_u64 v[152:153], s[18:19], 0, v[130:131]
	s_mov_b32 m0, s55
	s_nop 0
	global_load_lds_dwordx4 v[152:153], off
	v_lshl_add_u64 v[152:153], s[18:19], 0, v[134:135]
	s_add_i32 m0, s55, 0x2000
	s_nop 0
	global_load_lds_dwordx4 v[152:153], off
	s_waitcnt vmcnt(6)
	s_barrier
	v_mfma_f32_16x16x32_bf16 v[52:55], v[210:213], v[168:171], v[52:55]
	v_mfma_f32_16x16x32_bf16 v[44:47], v[218:221], v[168:171], v[44:47]
	v_mfma_f32_16x16x32_bf16 v[36:39], v[210:213], v[182:185], v[36:39]
	v_mfma_f32_16x16x32_bf16 v[28:31], v[218:221], v[182:185], v[28:31]
	v_mfma_f32_16x16x32_bf16 v[20:23], v[210:213], v[194:197], v[20:23]
	v_mfma_f32_16x16x32_bf16 v[12:15], v[218:221], v[194:197], v[12:15]
	v_mfma_f32_16x16x32_bf16 v[4:7], v[210:213], v[202:205], v[4:7]
	v_mfma_f32_16x16x32_bf16 v[0:3], v[218:221], v[202:205], v[0:3]
	v_mfma_f32_16x16x32_bf16 v[52:55], v[214:217], v[172:175], v[52:55]
	v_mfma_f32_16x16x32_bf16 v[44:47], v[222:225], v[172:175], v[44:47]
	v_mfma_f32_16x16x32_bf16 v[36:39], v[214:217], v[190:193], v[36:39]
	v_mfma_f32_16x16x32_bf16 v[28:31], v[222:225], v[190:193], v[28:31]
	v_mfma_f32_16x16x32_bf16 v[20:23], v[214:217], v[198:201], v[20:23]
	v_mfma_f32_16x16x32_bf16 v[12:15], v[222:225], v[198:201], v[12:15]
	v_mfma_f32_16x16x32_bf16 v[4:7], v[214:217], v[206:209], v[4:7]
	v_mfma_f32_16x16x32_bf16 v[0:3], v[222:225], v[206:209], v[0:3]
	s_add_i32 s55, 0, 0x18000
	v_add_u32_e32 v164, s55, v147
	s_barrier
	s_add_u32 s18, s24, 0xb0000
	s_addc_u32 s19, s25, 0
	s_mov_b32 m0, s36
	v_lshl_add_u64 v[210:211], s[18:19], 0, v[128:129]
	global_load_lds_dwordx4 v[210:211], off
	v_lshl_add_u64 v[210:211], s[18:19], 0, v[132:133]
	s_mov_b32 m0, s37
	s_nop 0
	global_load_lds_dwordx4 v[210:211], off
	ds_read_b128 v[152:155], v164
	ds_read_b128 v[156:159], v164 offset:1024
	ds_read_b128 v[160:163], v164 offset:2048
	ds_read_b128 v[164:167], v164 offset:3072
	ds_read_b128 v[168:171], v150 offset:32768
	ds_read_b128 v[172:175], v150 offset:33792
	ds_read_b128 v[182:185], v150 offset:34816
	ds_read_b128 v[190:193], v150 offset:35840
	ds_read_b128 v[194:197], v150 offset:36864
	ds_read_b128 v[198:201], v150 offset:37888
	ds_read_b128 v[202:205], v150 offset:38912
	ds_read_b128 v[206:209], v150 offset:39936
	s_waitcnt lgkmcnt(8)
	s_barrier
	s_waitcnt lgkmcnt(0)
	v_mfma_f32_16x16x32_bf16 v[124:127], v[152:155], v[168:171], v[124:127]
	v_mfma_f32_16x16x32_bf16 v[120:123], v[160:163], v[168:171], v[120:123]
	v_mfma_f32_16x16x32_bf16 v[108:111], v[152:155], v[182:185], v[108:111]
	v_mfma_f32_16x16x32_bf16 v[104:107], v[160:163], v[182:185], v[104:107]
	v_mfma_f32_16x16x32_bf16 v[92:95], v[152:155], v[194:197], v[92:95]
	v_mfma_f32_16x16x32_bf16 v[88:91], v[160:163], v[194:197], v[88:91]
	v_mfma_f32_16x16x32_bf16 v[76:79], v[152:155], v[202:205], v[76:79]
	v_mfma_f32_16x16x32_bf16 v[72:75], v[160:163], v[202:205], v[72:75]
	v_mfma_f32_16x16x32_bf16 v[124:127], v[156:159], v[172:175], v[124:127]
	v_mfma_f32_16x16x32_bf16 v[120:123], v[164:167], v[172:175], v[120:123]
	v_mfma_f32_16x16x32_bf16 v[108:111], v[156:159], v[190:193], v[108:111]
	v_mfma_f32_16x16x32_bf16 v[104:107], v[164:167], v[190:193], v[104:107]
	v_mfma_f32_16x16x32_bf16 v[92:95], v[156:159], v[198:201], v[92:95]
	v_mfma_f32_16x16x32_bf16 v[88:91], v[164:167], v[198:201], v[88:91]
	v_mfma_f32_16x16x32_bf16 v[76:79], v[156:159], v[206:209], v[76:79]
	v_mfma_f32_16x16x32_bf16 v[72:75], v[164:167], v[206:209], v[72:75]
	s_barrier
	s_add_i32 s24, 0, 0x1c000
	s_add_i32 s18, s55, s31
	v_add_u32_e32 v179, s24, v147
	v_lshl_add_u64 v[144:145], v[144:145], 0, s[8:9]
	s_mov_b32 m0, s18
	s_nop 0
	global_load_lds_dwordx4 v[144:145], off
	v_lshl_add_u64 v[144:145], v[186:187], 0, s[8:9]
	s_add_i32 m0, s18, 0x2000
	s_nop 0
	global_load_lds_dwordx4 v[144:145], off
	ds_read_b128 v[210:213], v179
	ds_read_b128 v[214:217], v179 offset:1024
	ds_read_b128 v[218:221], v179 offset:2048
	ds_read_b128 v[222:225], v179 offset:3072
	s_barrier
	s_waitcnt lgkmcnt(0)
	v_mfma_f32_16x16x32_bf16 v[116:119], v[210:213], v[168:171], v[116:119]
	v_mfma_f32_16x16x32_bf16 v[112:115], v[218:221], v[168:171], v[112:115]
	v_mfma_f32_16x16x32_bf16 v[100:103], v[210:213], v[182:185], v[100:103]
	v_mfma_f32_16x16x32_bf16 v[96:99], v[218:221], v[182:185], v[96:99]
	v_mfma_f32_16x16x32_bf16 v[84:87], v[210:213], v[194:197], v[84:87]
	v_mfma_f32_16x16x32_bf16 v[80:83], v[218:221], v[194:197], v[80:83]
	v_mfma_f32_16x16x32_bf16 v[68:71], v[210:213], v[202:205], v[68:71]
	v_mfma_f32_16x16x32_bf16 v[64:67], v[218:221], v[202:205], v[64:67]
	v_mfma_f32_16x16x32_bf16 v[116:119], v[214:217], v[172:175], v[116:119]
	v_mfma_f32_16x16x32_bf16 v[112:115], v[222:225], v[172:175], v[112:115]
	v_mfma_f32_16x16x32_bf16 v[100:103], v[214:217], v[190:193], v[100:103]
	v_mfma_f32_16x16x32_bf16 v[96:99], v[222:225], v[190:193], v[96:99]
	v_mfma_f32_16x16x32_bf16 v[84:87], v[214:217], v[198:201], v[84:87]
	v_mfma_f32_16x16x32_bf16 v[80:83], v[222:225], v[198:201], v[80:83]
	v_mfma_f32_16x16x32_bf16 v[68:71], v[214:217], v[206:209], v[68:71]
	v_mfma_f32_16x16x32_bf16 v[64:67], v[222:225], v[206:209], v[64:67]
	s_mov_b32 m0, s39
	v_lshl_add_u64 v[144:145], v[226:227], 0, s[8:9]
	s_barrier
	global_load_lds_dwordx4 v[144:145], off
	v_lshl_add_u64 v[144:145], v[228:229], 0, s[8:9]
	s_mov_b32 m0, s40
	s_nop 0
	global_load_lds_dwordx4 v[144:145], off
	ds_read_b128 v[168:171], v150 offset:49152
	ds_read_b128 v[172:175], v150 offset:50176
	ds_read_b128 v[182:185], v150 offset:51200
	ds_read_b128 v[190:193], v150 offset:52224
	ds_read_b128 v[194:197], v150 offset:53248
	ds_read_b128 v[198:201], v150 offset:54272
	ds_read_b128 v[202:205], v150 offset:55296
	ds_read_b128 v[206:209], v150 offset:56320
	s_barrier
; __device__ __forceinline__ unsigned cvt_pk_bf16(float lo, float hi) { unsigned r; asm volatile("v_cvt_pk_bf16_f32 %0, %1, %2" : "=v"(r) : "v"(lo), "v"(hi)); return r; }
; __device__ __forceinline__ float flogsig16(float x) { return (fminf(x, 0.f) - __logf(1.0f + __expf(-fabsf(x)))) * 0.0625f; }
; #define PG8_WAIT_V(n) asm volatile("s_waitcnt vmcnt(" #n ")" ::: "memory")
; #define PG8_WAIT_L(n) asm volatile("s_waitcnt lgkmcnt(" #n ")" ::: "memory")
;     __device__ __forceinline__ void operator()(const f32x4 (&acc)[2][2][4][2], const Unit& u, int wr, int wc, int fr, int fq) const {
;     ...
;         const int row0 = u.pm * BM + wr * 64 + fr, col0 = u.pn * BM + wc * 32 + 8 * fq, bcol0 = wc * 32 + 8 * fq;
;         f32x4 bv[2][2];
; #pragma unroll
;         for (int bj = 0; bj < 2; ++bj)
; #pragma unroll
;             for (int n = 0; n < 2; ++n) bv[bj][n] = bias ? *(const f32x4*)(bias + bcol0 + bj * HALF + 4 * n) : (f32x4){0.f, 0.f, 0.f, 0.f};
; #pragma unroll
;         for (int ai = 0; ai < 2; ++ai)
; #pragma unroll
;             for (int m = 0; m < 4; ++m) { bf16_t* rowp = O + (size_t)(row0 + ai * HALF + m * 16) * ldc + col0;
; #pragma unroll
;                 for (int bj = 0; bj < 2; ++bj) { f32x4 v0 = acc[ai][bj][m][0] + bv[bj][0], v1 = acc[ai][bj][m][1] + bv[bj][1];
;                     if (act == 1) {
; #pragma unroll
;                         for (int j = 0; j < 1; ++j) { v0 = v0 * sigmoid4(v0); v1 = v1 * sigmoid4(v1); } }
;                     else if (act == 2) {
; #pragma unroll
;                         for (int j = 0; j < 1; ++j) { v0 = sigmoid4(v0); v1 = sigmoid4(v1); } }
;                     else if (act == 3) {
; #pragma unroll
;                         for (int j = 0; j < 4; ++j) { v0[j] = flogsig16(v0[j]); v1[j] = flogsig16(v1[j]); } }
;                     u32x4 w; w.x = cvt_pk_bf16(v0[0], v0[1]); w.y = cvt_pk_bf16(v0[2], v0[3]); w.z = cvt_pk_bf16(v1[0], v1[1]); w.w = cvt_pk_bf16(v1[2], v1[3]);
;                     *(u32x4*)(rowp + bj * HALF) = w; } }
; template <class Epi, class Sched>
; __device__ __forceinline__ void gemm_phase(PG8_LAS unsigned char* lds, const Gemm g, const Sched& S, const Epi& E) {
;     ...
;             PG8_BAR; PG8_WAIT_L(0); PG8_MMA(1, 0, At, B0); PG8_BAR; PG8_SCHED;
;             PG8_STAGE(PG8_SB(1, 1), b3 + hstep, voffB);
;             PG8_WAIT_V(6); PG8_BAR; PG8_MMA(1, 1, At, B1); PG8_BAR;
	s_waitcnt lgkmcnt(0)
	v_mfma_f32_16x16x32_bf16 v[60:63], v[152:155], v[168:171], v[60:63]
	v_mfma_f32_16x16x32_bf16 v[56:59], v[160:163], v[168:171], v[56:59]
	v_mfma_f32_16x16x32_bf16 v[48:51], v[152:155], v[182:185], v[48:51]
	v_mfma_f32_16x16x32_bf16 v[40:43], v[160:163], v[182:185], v[40:43]
	v_mfma_f32_16x16x32_bf16 v[32:35], v[152:155], v[194:197], v[32:35]
	v_mfma_f32_16x16x32_bf16 v[24:27], v[160:163], v[194:197], v[24:27]
	v_mfma_f32_16x16x32_bf16 v[16:19], v[152:155], v[202:205], v[16:19]
	v_mfma_f32_16x16x32_bf16 v[8:11], v[160:163], v[202:205], v[8:11]
	v_mfma_f32_16x16x32_bf16 v[60:63], v[156:159], v[172:175], v[60:63]
	v_mfma_f32_16x16x32_bf16 v[56:59], v[164:167], v[172:175], v[56:59]
	v_mfma_f32_16x16x32_bf16 v[48:51], v[156:159], v[190:193], v[48:51]
	v_mfma_f32_16x16x32_bf16 v[40:43], v[164:167], v[190:193], v[40:43]
	v_mfma_f32_16x16x32_bf16 v[32:35], v[156:159], v[198:201], v[32:35]
	v_mfma_f32_16x16x32_bf16 v[24:27], v[164:167], v[198:201], v[24:27]
	v_mfma_f32_16x16x32_bf16 v[16:19], v[156:159], v[206:209], v[16:19]
	v_mfma_f32_16x16x32_bf16 v[8:11], v[164:167], v[206:209], v[8:11]
	s_barrier
	s_add_u32 s18, s22, 0xb0080
	s_addc_u32 s19, s23, 0
	s_add_i32 s22, s24, s31
	v_lshl_add_u64 v[144:145], s[18:19], 0, v[130:131]
	s_mov_b32 m0, s22
	s_nop 0
	global_load_lds_dwordx4 v[144:145], off
	v_lshl_add_u64 v[144:145], s[18:19], 0, v[134:135]
	s_add_i32 m0, s22, 0x2000
	s_nop 0
	global_load_lds_dwordx4 v[144:145], off
	s_waitcnt vmcnt(6)
	s_barrier
	v_mfma_f32_16x16x32_bf16 v[52:55], v[210:213], v[168:171], v[52:55]
	v_mfma_f32_16x16x32_bf16 v[44:47], v[218:221], v[168:171], v[44:47]
	v_mfma_f32_16x16x32_bf16 v[36:39], v[210:213], v[182:185], v[36:39]
	v_mfma_f32_16x16x32_bf16 v[28:31], v[218:221], v[182:185], v[28:31]
	v_mfma_f32_16x16x32_bf16 v[20:23], v[210:213], v[194:197], v[20:23]
	v_mfma_f32_16x16x32_bf16 v[12:15], v[218:221], v[194:197], v[12:15]
	v_mfma_f32_16x16x32_bf16 v[4:7], v[210:213], v[202:205], v[4:7]
	v_mfma_f32_16x16x32_bf16 v[0:3], v[218:221], v[202:205], v[0:3]
	v_mfma_f32_16x16x32_bf16 v[52:55], v[214:217], v[172:175], v[52:55]
	v_mfma_f32_16x16x32_bf16 v[44:47], v[222:225], v[172:175], v[44:47]
	v_mfma_f32_16x16x32_bf16 v[36:39], v[214:217], v[190:193], v[36:39]
	v_mfma_f32_16x16x32_bf16 v[28:31], v[222:225], v[190:193], v[28:31]
	v_mfma_f32_16x16x32_bf16 v[20:23], v[214:217], v[198:201], v[20:23]
	v_mfma_f32_16x16x32_bf16 v[12:15], v[222:225], v[198:201], v[12:15]
	v_mfma_f32_16x16x32_bf16 v[4:7], v[214:217], v[206:209], v[4:7]
	v_mfma_f32_16x16x32_bf16 v[0:3], v[222:225], v[206:209], v[0:3]
	s_add_i32 s54, s54, 2
	s_add_u32 s52, s52, 0x100
	s_addc_u32 s53, s53, 0
	s_cmp_gt_u32 s54, 41
	s_mov_b64 s[18:19], s[20:21]
	s_barrier
	s_cbranch_scc0 .LBB0_1278
	v_lshl_add_u32 v152, s50, 8, v146
	v_lshl_or_b32 v144, s51, 8, v148
	v_ashrrev_i32_e32 v153, 31, v152
	v_ashrrev_i32_e32 v145, 31, v144
	v_lshlrev_b64 v[154:155], 11, v[152:153]
	v_lshl_add_u64 v[154:155], s[6:7], 0, v[154:155]
	v_lshlrev_b64 v[156:157], 1, v[144:145]
	v_lshl_add_u64 v[144:145], v[154:155], 0, v[156:157]
	v_pk_add_f32 v[126:127], v[126:127], 0 op_sel_hi:[1,0]
	v_pk_add_f32 v[124:125], v[124:125], 0 op_sel_hi:[1,0]
	v_pk_add_f32 v[154:155], v[122:123], 0 op_sel_hi:[1,0]
	v_pk_add_f32 v[122:123], v[120:121], 0 op_sel_hi:[1,0]
	v_cvt_pk_bf16_f32 v120, v124, v125
	v_cvt_pk_bf16_f32 v121, v126, v127
	v_pk_add_f32 v[116:117], v[116:117], 0 op_sel_hi:[1,0]
	v_cvt_pk_bf16_f32 v122, v122, v123
	v_cvt_pk_bf16_f32 v123, v154, v155
	global_store_dwordx4 v[144:145], v[120:123], off
	v_pk_add_f32 v[118:119], v[118:119], 0 op_sel_hi:[1,0]
	v_pk_add_f32 v[110:111], v[110:111], 0 op_sel_hi:[1,0]
	v_pk_add_f32 v[120:121], v[114:115], 0 op_sel_hi:[1,0]
	v_pk_add_f32 v[114:115], v[112:113], 0 op_sel_hi:[1,0]
	v_cvt_pk_bf16_f32 v112, v116, v117
	v_cvt_pk_bf16_f32 v113, v118, v119
	v_pk_add_f32 v[108:109], v[108:109], 0 op_sel_hi:[1,0]
	v_cvt_pk_bf16_f32 v114, v114, v115
	v_cvt_pk_bf16_f32 v115, v120, v121
	global_store_dwordx4 v[144:145], v[112:115], off offset:256
	v_pk_add_f32 v[100:101], v[100:101], 0 op_sel_hi:[1,0]
	v_pk_add_f32 v[102:103], v[102:103], 0 op_sel_hi:[1,0]
	v_or_b32_e32 v112, 16, v152
	v_ashrrev_i32_e32 v113, 31, v112
	v_lshlrev_b64 v[112:113], 11, v[112:113]
	v_lshl_add_u64 v[112:113], s[6:7], 0, v[112:113]
	v_lshl_add_u64 v[112:113], v[112:113], 0, v[156:157]
	v_pk_add_f32 v[114:115], v[106:107], 0 op_sel_hi:[1,0]
	v_pk_add_f32 v[106:107], v[104:105], 0 op_sel_hi:[1,0]
	v_cvt_pk_bf16_f32 v104, v108, v109
	v_cvt_pk_bf16_f32 v105, v110, v111
	v_pk_add_f32 v[94:95], v[94:95], 0 op_sel_hi:[1,0]
	v_cvt_pk_bf16_f32 v106, v106, v107
	v_cvt_pk_bf16_f32 v107, v114, v115
	global_store_dwordx4 v[112:113], v[104:107], off
	v_pk_add_f32 v[92:93], v[92:93], 0 op_sel_hi:[1,0]
	v_pk_add_f32 v[84:85], v[84:85], 0 op_sel_hi:[1,0]
	v_pk_add_f32 v[104:105], v[98:99], 0 op_sel_hi:[1,0]
	v_pk_add_f32 v[98:99], v[96:97], 0 op_sel_hi:[1,0]
	v_cvt_pk_bf16_f32 v96, v100, v101
	v_cvt_pk_bf16_f32 v97, v102, v103
	v_pk_add_f32 v[86:87], v[86:87], 0 op_sel_hi:[1,0]
	v_cvt_pk_bf16_f32 v98, v98, v99
	v_cvt_pk_bf16_f32 v99, v104, v105
	global_store_dwordx4 v[112:113], v[96:99], off offset:256
	v_pk_add_f32 v[78:79], v[78:79], 0 op_sel_hi:[1,0]
	v_pk_add_f32 v[76:77], v[76:77], 0 op_sel_hi:[1,0]
	v_or_b32_e32 v96, 32, v152
	v_ashrrev_i32_e32 v97, 31, v96
	v_lshlrev_b64 v[96:97], 11, v[96:97]
	v_lshl_add_u64 v[96:97], s[6:7], 0, v[96:97]
; __device__ __forceinline__ unsigned cvt_pk_bf16(float lo, float hi) { unsigned r; asm volatile("v_cvt_pk_bf16_f32 %0, %1, %2" : "=v"(r) : "v"(lo), "v"(hi)); return r; }
; __device__ __forceinline__ float flogsig16(float x) { return (fminf(x, 0.f) - __logf(1.0f + __expf(-fabsf(x)))) * 0.0625f; }
; #define PG8_WAIT_V(n) asm volatile("s_waitcnt vmcnt(" #n ")" ::: "memory")
; #define PG8_BAR __builtin_amdgcn_s_barrier()
;     __device__ __forceinline__ void operator()(const f32x4 (&acc)[2][2][4][2], const Unit& u, int wr, int wc, int fr, int fq) const {
;     ...
;             for (int m = 0; m < 4; ++m) { bf16_t* rowp = O + (size_t)(row0 + ai * HALF + m * 16) * ldc + col0;
; #pragma unroll
;                 for (int bj = 0; bj < 2; ++bj) { f32x4 v0 = acc[ai][bj][m][0] + bv[bj][0], v1 = acc[ai][bj][m][1] + bv[bj][1];
;                     if (act == 1) {
; #pragma unroll
;                         for (int j = 0; j < 1; ++j) { v0 = v0 * sigmoid4(v0); v1 = v1 * sigmoid4(v1); } }
;                     else if (act == 2) {
; #pragma unroll
;                         for (int j = 0; j < 1; ++j) { v0 = sigmoid4(v0); v1 = sigmoid4(v1); } }
;                     else if (act == 3) {
; #pragma unroll
;                         for (int j = 0; j < 4; ++j) { v0[j] = flogsig16(v0[j]); v1[j] = flogsig16(v1[j]); } }
;                     u32x4 w; w.x = cvt_pk_bf16(v0[0], v0[1]); w.y = cvt_pk_bf16(v0[2], v0[3]); w.z = cvt_pk_bf16(v1[0], v1[1]); w.w = cvt_pk_bf16(v1[2], v1[3]);
;                     *(u32x4*)(rowp + bj * HALF) = w; } }
; template <class Epi, class Sched>
; __device__ __forceinline__ void gemm_phase(PG8_LAS unsigned char* lds, const Gemm g, const Sched& S, const Epi& E) {
;     ...
;         if (!has_next) break;
; #pragma unroll
;         for (int a = 0; a < 2; ++a)
; #pragma unroll
;             for (int b = 0; b < 2; ++b)
; #pragma unroll
;                 for (int m = 0; m < 4; ++m)
; #pragma unroll
;                     for (int n = 0; n < 2; ++n) acc[a][b][m][n] = (f32x4){0.f, 0.f, 0.f, 0.f};
;         cur = nxt; cA = nA; cB = nB; ++ui;
;     }
;     PG8_WAIT_V(0);
;     if (wr == 0) PG8_BAR;
;     PG8_BAR;
	v_lshl_add_u64 v[96:97], v[96:97], 0, v[156:157]
	v_pk_add_f32 v[98:99], v[90:91], 0 op_sel_hi:[1,0]
	v_pk_add_f32 v[90:91], v[88:89], 0 op_sel_hi:[1,0]
	v_cvt_pk_bf16_f32 v88, v92, v93
	v_cvt_pk_bf16_f32 v89, v94, v95
	v_pk_add_f32 v[70:71], v[70:71], 0 op_sel_hi:[1,0]
	v_cvt_pk_bf16_f32 v90, v90, v91
	v_cvt_pk_bf16_f32 v91, v98, v99
	global_store_dwordx4 v[96:97], v[88:91], off
	v_pk_add_f32 v[68:69], v[68:69], 0 op_sel_hi:[1,0]
	v_pk_add_f32 v[60:61], v[60:61], 0 op_sel_hi:[1,0]
	v_pk_add_f32 v[88:89], v[82:83], 0 op_sel_hi:[1,0]
	v_pk_add_f32 v[82:83], v[80:81], 0 op_sel_hi:[1,0]
	v_cvt_pk_bf16_f32 v80, v84, v85
	v_cvt_pk_bf16_f32 v81, v86, v87
	v_pk_add_f32 v[62:63], v[62:63], 0 op_sel_hi:[1,0]
	v_cvt_pk_bf16_f32 v82, v82, v83
	v_cvt_pk_bf16_f32 v83, v88, v89
	global_store_dwordx4 v[96:97], v[80:83], off offset:256
	v_pk_add_f32 v[54:55], v[54:55], 0 op_sel_hi:[1,0]
	v_pk_add_f32 v[52:53], v[52:53], 0 op_sel_hi:[1,0]
	v_or_b32_e32 v80, 48, v152
	v_ashrrev_i32_e32 v81, 31, v80
	v_lshlrev_b64 v[80:81], 11, v[80:81]
	v_lshl_add_u64 v[80:81], s[6:7], 0, v[80:81]
	v_lshl_add_u64 v[80:81], v[80:81], 0, v[156:157]
	v_pk_add_f32 v[82:83], v[74:75], 0 op_sel_hi:[1,0]
	v_pk_add_f32 v[74:75], v[72:73], 0 op_sel_hi:[1,0]
	v_cvt_pk_bf16_f32 v72, v76, v77
	v_cvt_pk_bf16_f32 v73, v78, v79
	v_pk_add_f32 v[48:49], v[48:49], 0 op_sel_hi:[1,0]
	v_cvt_pk_bf16_f32 v74, v74, v75
	v_cvt_pk_bf16_f32 v75, v82, v83
	global_store_dwordx4 v[80:81], v[72:75], off
	v_pk_add_f32 v[38:39], v[38:39], 0 op_sel_hi:[1,0]
	v_pk_add_f32 v[36:37], v[36:37], 0 op_sel_hi:[1,0]
	v_pk_add_f32 v[72:73], v[66:67], 0 op_sel_hi:[1,0]
	v_pk_add_f32 v[66:67], v[64:65], 0 op_sel_hi:[1,0]
	v_cvt_pk_bf16_f32 v64, v68, v69
	v_cvt_pk_bf16_f32 v65, v70, v71
	v_pk_add_f32 v[32:33], v[32:33], 0 op_sel_hi:[1,0]
	v_cvt_pk_bf16_f32 v66, v66, v67
	v_cvt_pk_bf16_f32 v67, v72, v73
	global_store_dwordx4 v[80:81], v[64:67], off offset:256
	v_pk_add_f32 v[22:23], v[22:23], 0 op_sel_hi:[1,0]
	v_pk_add_f32 v[20:21], v[20:21], 0 op_sel_hi:[1,0]
	v_pk_add_f32 v[66:67], v[58:59], 0 op_sel_hi:[1,0]
	v_pk_add_f32 v[58:59], v[56:57], 0 op_sel_hi:[1,0]
	v_cvt_pk_bf16_f32 v56, v60, v61
	v_add_co_u32_e32 v60, vcc, s44, v144
	v_cvt_pk_bf16_f32 v57, v62, v63
	v_cvt_pk_bf16_f32 v58, v58, v59
	v_cvt_pk_bf16_f32 v59, v66, v67
	v_lshl_add_u64 v[64:65], v[144:145], 0, s[10:11]
	s_nop 0
	v_addc_co_u32_e32 v61, vcc, 0, v145, vcc
	global_store_dwordx4 v[60:61], v[56:59], off
	v_pk_add_f32 v[16:17], v[16:17], 0 op_sel_hi:[1,0]
	s_mov_b32 s51, s48
	v_pk_add_f32 v[56:57], v[46:47], 0 op_sel_hi:[1,0]
	v_pk_add_f32 v[46:47], v[44:45], 0 op_sel_hi:[1,0]
	v_cvt_pk_bf16_f32 v44, v52, v53
	v_cvt_pk_bf16_f32 v45, v54, v55
	s_mov_b32 s50, s49
	v_cvt_pk_bf16_f32 v46, v46, v47
	v_cvt_pk_bf16_f32 v47, v56, v57
	global_store_dwordx4 v[64:65], v[44:47], off offset:256
	s_mov_b64 s[20:21], s[4:5]
	s_mov_b64 s[18:19], s[0:1]
	v_pk_add_f32 v[46:47], v[50:51], 0 op_sel_hi:[1,0]
	v_pk_add_f32 v[50:51], v[42:43], 0 op_sel_hi:[1,0]
	v_pk_add_f32 v[42:43], v[40:41], 0 op_sel_hi:[1,0]
	v_cvt_pk_bf16_f32 v40, v48, v49
	v_cvt_pk_bf16_f32 v41, v46, v47
	v_add_co_u32_e32 v46, vcc, s45, v144
	v_cvt_pk_bf16_f32 v42, v42, v43
	v_cvt_pk_bf16_f32 v43, v50, v51
	v_lshl_add_u64 v[44:45], v[144:145], 0, s[12:13]
	s_nop 0
	v_addc_co_u32_e32 v47, vcc, 0, v145, vcc
	global_store_dwordx4 v[46:47], v[40:43], off
	v_pk_add_f32 v[6:7], v[6:7], 0 op_sel_hi:[1,0]
	v_pk_add_f32 v[4:5], v[4:5], 0 op_sel_hi:[1,0]
	v_pk_add_f32 v[40:41], v[30:31], 0 op_sel_hi:[1,0]
	v_pk_add_f32 v[30:31], v[28:29], 0 op_sel_hi:[1,0]
	v_cvt_pk_bf16_f32 v28, v36, v37
	v_cvt_pk_bf16_f32 v29, v38, v39
	s_nop 0
	v_cvt_pk_bf16_f32 v30, v30, v31
	v_cvt_pk_bf16_f32 v31, v40, v41
	global_store_dwordx4 v[44:45], v[28:31], off offset:256
	s_nop 1
	v_pk_add_f32 v[30:31], v[34:35], 0 op_sel_hi:[1,0]
	v_pk_add_f32 v[34:35], v[26:27], 0 op_sel_hi:[1,0]
	v_pk_add_f32 v[26:27], v[24:25], 0 op_sel_hi:[1,0]
	v_cvt_pk_bf16_f32 v24, v32, v33
	v_cvt_pk_bf16_f32 v25, v30, v31
	v_add_co_u32_e32 v30, vcc, s46, v144
	v_cvt_pk_bf16_f32 v26, v26, v27
	v_cvt_pk_bf16_f32 v27, v34, v35
	v_lshl_add_u64 v[28:29], v[144:145], 0, s[14:15]
	s_nop 0
	v_addc_co_u32_e32 v31, vcc, 0, v145, vcc
	global_store_dwordx4 v[30:31], v[24:27], off
	s_nop 1
	v_pk_add_f32 v[24:25], v[14:15], 0 op_sel_hi:[1,0]
	v_pk_add_f32 v[14:15], v[12:13], 0 op_sel_hi:[1,0]
	v_cvt_pk_bf16_f32 v12, v20, v21
	v_cvt_pk_bf16_f32 v13, v22, v23
	s_nop 0
	v_cvt_pk_bf16_f32 v14, v14, v15
	v_cvt_pk_bf16_f32 v15, v24, v25
	global_store_dwordx4 v[28:29], v[12:15], off offset:256
	s_nop 1
	v_pk_add_f32 v[14:15], v[18:19], 0 op_sel_hi:[1,0]
	v_pk_add_f32 v[18:19], v[10:11], 0 op_sel_hi:[1,0]
	v_pk_add_f32 v[10:11], v[8:9], 0 op_sel_hi:[1,0]
	v_cvt_pk_bf16_f32 v8, v16, v17
	v_cvt_pk_bf16_f32 v9, v14, v15
	v_add_co_u32_e32 v14, vcc, s47, v144
	v_lshl_add_u64 v[12:13], v[144:145], 0, s[16:17]
	s_nop 0
	v_addc_co_u32_e32 v15, vcc, 0, v145, vcc
	v_cvt_pk_bf16_f32 v10, v10, v11
	v_cvt_pk_bf16_f32 v11, v18, v19
	global_store_dwordx4 v[14:15], v[8:11], off
	s_and_b64 vcc, exec, s[2:3]
	s_nop 0
	v_pk_add_f32 v[8:9], v[2:3], 0 op_sel_hi:[1,0]
	v_pk_add_f32 v[2:3], v[0:1], 0 op_sel_hi:[1,0]
	v_cvt_pk_bf16_f32 v0, v4, v5
	v_cvt_pk_bf16_f32 v1, v6, v7
	s_nop 0
	v_cvt_pk_bf16_f32 v2, v2, v3
	v_cvt_pk_bf16_f32 v3, v8, v9
	global_store_dwordx4 v[12:13], v[0:3], off offset:256
	s_cbranch_vccz .LBB0_1267
	s_waitcnt vmcnt(0)
	s_cmpk_gt_u32 s27, 0xff
	s_cbranch_scc1 .LBB0_1282
	s_barrier
